# combination: SGPR-base LDS-DMA loads + K-loop edge rotation + static GEMM priority (cluster flips removed) + scan recurrence priority
# speedup vs baseline: 1.0142x; 1.0142x over previous
.LBB0_152:
	s_andn2_b64 vcc, exec, s[4:5]
	s_cbranch_vccnz .LBB0_194
	v_ashrrev_i32_e32 v2, 31, v0
	v_lshrrev_b32_e32 v2, 26, v2
	v_lshlrev_b32_e32 v1, 4, v0
	v_add_u32_e32 v2, v0, v2
	v_bfe_i32 v0, v0, 27, 1
	v_lshrrev_b32_e32 v0, 22, v0
	v_add_u32_e32 v0, v1, v0
	v_and_b32_e32 v0, 0xfffffc00, v0
	v_sub_u32_e32 v0, v1, v0
	v_ashrrev_i32_e32 v9, 6, v2
	v_lshrrev_b32_e32 v2, 4, v0
	v_bitop3_b32 v0, v2, v0, 32 bitop3:0x6c
	v_ashrrev_i32_e32 v3, 31, v0
	v_lshrrev_b32_e32 v3, 26, v3
	v_add_u32_e32 v3, v0, v3
	v_lshlrev_b32_e32 v2, 3, v9
	v_ashrrev_i32_e32 v10, 6, v3
	v_and_b32_e32 v3, 0xc0, v3
	v_and_b32_e32 v2, -16, v2
	v_sub_u32_e32 v0, v0, v3
	v_mov_b32_e32 v3, 1
	v_add_u32_e32 v2, v10, v2
	v_ashrrev_i16_sdwa v0, v3, sext(v0) dst_sel:DWORD dst_unused:UNUSED_PAD src0_sel:DWORD src1_sel:BYTE_0
	v_lshlrev_b32_e32 v4, 5, v9
	v_bfe_i32 v11, v0, 0, 16
	v_lshlrev_b32_e32 v0, 1, v2
	v_lshrrev_b32_e32 v5, 2, v2
	v_and_b32_e32 v6, 3, v10
	s_mov_b32 s3, 0x1fffe0
	v_and_b32_e32 v4, 32, v4
	v_and_b32_e32 v0, 24, v0
	v_and_b32_e32 v5, 4, v5
	v_and_or_b32 v6, v2, s3, v6
	v_or3_b32 v0, v6, v5, v0
	v_add_lshl_u32 v4, v4, v11, 1
	v_lshl_add_u32 v130, v0, 11, v4
	v_add_u32_e32 v0, 0x2000, v1
	v_ashrrev_i32_e32 v1, 31, v0
	v_lshrrev_b32_e32 v1, 22, v1
	v_add_u32_e32 v1, v0, v1
	v_ashrrev_i32_e32 v12, 10, v1
	v_mul_i32_i24_e32 v1, 0x400, v12
	v_sub_u32_e32 v0, v0, v1
	v_lshrrev_b32_e32 v1, 4, v0
	v_bitop3_b32 v0, v1, v0, 32 bitop3:0x6c
	v_lshl_add_u32 v128, v2, 11, v4
	v_ashrrev_i32_e32 v2, 31, v0
	v_lshrrev_b32_e32 v2, 26, v2
	v_add_u32_e32 v2, v0, v2
	v_lshlrev_b32_e32 v1, 3, v12
	v_ashrrev_i32_e32 v13, 6, v2
	v_and_b32_e32 v2, 0xc0, v2
	v_and_b32_e32 v1, -16, v1
	v_sub_u32_e32 v0, v0, v2
	s_ashr_i32 s2, s6, 6
	v_add_u32_e32 v1, v13, v1
	v_ashrrev_i16_sdwa v0, v3, sext(v0) dst_sel:DWORD dst_unused:UNUSED_PAD src0_sel:DWORD src1_sel:BYTE_0
	v_and_b32_e32 v3, 3, v13
	v_and_or_b32 v3, v1, s3, v3
	s_ashr_i32 s3, s6, 8
	s_lshl_b32 s36, s2, 10
	s_add_u32 s37, s70, 0x400000
	s_addc_u32 s38, s71, 0
	s_ashr_i32 s27, s26, 31
	s_ashr_i32 s25, s24, 31
	s_lshl_b64 s[4:5], s[26:27], 19
	s_lshl_b64 s[8:9], s[24:25], 19
	s_add_u32 s30, s37, s8
	v_lshlrev_b32_e32 v4, 5, v12
	v_bfe_i32 v14, v0, 0, 16
	v_lshlrev_b32_e32 v0, 1, v1
	v_lshrrev_b32_e32 v2, 2, v1
	s_addc_u32 s31, s38, s9
	s_add_i32 s39, s36, 0
	v_and_b32_e32 v4, 32, v4
	v_and_b32_e32 v0, 24, v0
	v_and_b32_e32 v2, 4, v2
	s_add_i32 m0, s39, 0x10000
	v_or3_b32 v0, v3, v2, v0
	v_add_lshl_u32 v2, v4, v14, 1
	global_load_lds_dwordx4 v130, s[30:31]
	s_add_i32 m0, s39, 0x12000
	v_lshl_add_u32 v134, v0, 11, v2
	s_add_u32 s8, s30, 0x40000
	global_load_lds_dwordx4 v134, s[30:31]
	s_addc_u32 s9, s31, 0
	s_add_i32 m0, s39, 0x14000
	v_lshl_add_u32 v132, v1, 11, v2
	global_load_lds_dwordx4 v130, s[8:9]
	s_add_i32 m0, s39, 0x16000
	s_add_u32 s28, s76, s4
	s_addc_u32 s29, s77, s5
	s_add_i32 s40, s39, 0x2000
	global_load_lds_dwordx4 v134, s[8:9]
	s_mov_b32 m0, s39
	s_add_u32 s4, s28, 0x40000
	global_load_lds_dwordx4 v128, s[28:29]
	s_mov_b32 m0, s40
	s_addc_u32 s5, s29, 0
	s_add_i32 s41, s39, 0x4000
	global_load_lds_dwordx4 v132, s[28:29]
	s_mov_b32 m0, s41
	s_add_i32 s42, s39, 0x6000
	global_load_lds_dwordx4 v128, s[4:5]
	s_mov_b32 m0, s42
	v_mov_b32_e32 v137, 0
	global_load_lds_dwordx4 v132, s[4:5]
	v_mov_b32_e32 v131, v137
	v_mov_b32_e32 v135, v137
	v_mov_b32_e32 v129, v137
	v_mov_b32_e32 v133, v137
	s_cmp_eq_u32 s3, 1
	s_mov_b32 s7, 0
	v_lshl_add_u64 v[6:7], s[30:31], 0, v[130:131]
	v_lshl_add_u64 v[4:5], s[30:31], 0, v[134:135]
	v_lshl_add_u64 v[0:1], s[28:29], 0, v[128:129]
	s_cselect_b64 s[8:9], -1, 0
	s_cmp_lg_u32 s3, 1
	v_lshl_add_u64 v[2:3], s[28:29], 0, v[132:133]
	s_setprio 1
	s_cbranch_scc1 .LBB0_155
	s_barrier
	s_setprio 0

.LBB0_161:
	ds_read_b128 v[152:155], v143
	ds_read_b128 v[162:165], v143 offset:1024
	ds_read_b128 v[166:169], v143 offset:2048
	ds_read_b128 v[170:173], v143 offset:3072
	ds_read_b128 v[174:177], v158
	ds_read_b128 v[178:181], v158 offset:1024
	ds_read_b128 v[182:185], v158 offset:2048
	ds_read_b128 v[186:189], v158 offset:3072
	s_add_u32 s30, s28, 0xfffc0080
	s_addc_u32 s31, s29, -1
	s_cmp_eq_u32 s55, 12
	s_cselect_b32 s35, s19, s31
	s_cselect_b32 s34, s25, s30
	s_cselect_b32 s31, s17, s54
	s_cselect_b32 s30, s27, s53
	s_waitcnt lgkmcnt(0)
	s_add_i32 m0, s39, 0xc000
	ds_read_b128 v[190:193], v159
	ds_read_b128 v[194:197], v159 offset:1024
	ds_read_b128 v[198:201], v159 offset:2048
	ds_read_b128 v[202:205], v159 offset:3072
	ds_read_b128 v[206:209], v159 offset:4096
	ds_read_b128 v[210:213], v159 offset:5120
	ds_read_b128 v[214:217], v159 offset:6144
	ds_read_b128 v[218:221], v159 offset:7168
	global_load_lds_dwordx4 v144, s[28:29]
	s_add_i32 m0, s39, 0xe000
	s_nop 0
	global_load_lds_dwordx4 v146, s[28:29]
	s_waitcnt vmcnt(8)
	s_waitcnt lgkmcnt(0)
	s_barrier
	s_waitcnt lgkmcnt(0)
	v_mfma_f32_16x16x32_bf16 v[116:119], v[152:155], v[190:193], v[116:119]
	v_mfma_f32_16x16x32_bf16 v[112:115], v[166:169], v[190:193], v[112:115]
	v_mfma_f32_16x16x32_bf16 v[100:103], v[152:155], v[198:201], v[100:103]
	v_mfma_f32_16x16x32_bf16 v[96:99], v[166:169], v[198:201], v[96:99]
	v_mfma_f32_16x16x32_bf16 v[88:91], v[152:155], v[206:209], v[88:91]
	v_mfma_f32_16x16x32_bf16 v[84:87], v[166:169], v[206:209], v[84:87]
	v_mfma_f32_16x16x32_bf16 v[72:75], v[152:155], v[214:217], v[72:75]
	v_mfma_f32_16x16x32_bf16 v[68:71], v[166:169], v[214:217], v[68:71]
	v_mfma_f32_16x16x32_bf16 v[116:119], v[162:165], v[194:197], v[116:119]
	v_mfma_f32_16x16x32_bf16 v[112:115], v[170:173], v[194:197], v[112:115]
	v_mfma_f32_16x16x32_bf16 v[100:103], v[162:165], v[202:205], v[100:103]
	v_mfma_f32_16x16x32_bf16 v[96:99], v[170:173], v[202:205], v[96:99]
	v_mfma_f32_16x16x32_bf16 v[88:91], v[162:165], v[210:213], v[88:91]
	v_mfma_f32_16x16x32_bf16 v[84:87], v[170:173], v[210:213], v[84:87]
	v_mfma_f32_16x16x32_bf16 v[72:75], v[162:165], v[218:221], v[72:75]
	v_mfma_f32_16x16x32_bf16 v[68:71], v[170:173], v[218:221], v[68:71]
	v_mfma_f32_16x16x32_bf16 v[124:127], v[174:177], v[190:193], v[124:127]
	v_mfma_f32_16x16x32_bf16 v[120:123], v[182:185], v[190:193], v[120:123]
	v_mfma_f32_16x16x32_bf16 v[108:111], v[174:177], v[198:201], v[108:111]
	v_mfma_f32_16x16x32_bf16 v[104:107], v[182:185], v[198:201], v[104:107]
	v_mfma_f32_16x16x32_bf16 v[92:95], v[174:177], v[206:209], v[92:95]
	v_mfma_f32_16x16x32_bf16 v[80:83], v[182:185], v[206:209], v[80:83]
	v_mfma_f32_16x16x32_bf16 v[76:79], v[174:177], v[214:217], v[76:79]
	v_mfma_f32_16x16x32_bf16 v[64:67], v[182:185], v[214:217], v[64:67]
	v_mfma_f32_16x16x32_bf16 v[124:127], v[178:181], v[194:197], v[124:127]
	v_mfma_f32_16x16x32_bf16 v[120:123], v[186:189], v[194:197], v[120:123]
	v_mfma_f32_16x16x32_bf16 v[108:111], v[178:181], v[202:205], v[108:111]
	v_mfma_f32_16x16x32_bf16 v[104:107], v[186:189], v[202:205], v[104:107]
	v_mfma_f32_16x16x32_bf16 v[92:95], v[178:181], v[210:213], v[92:95]
	v_mfma_f32_16x16x32_bf16 v[80:83], v[186:189], v[210:213], v[80:83]
	v_mfma_f32_16x16x32_bf16 v[76:79], v[178:181], v[218:221], v[76:79]
	v_mfma_f32_16x16x32_bf16 v[64:67], v[186:189], v[218:221], v[64:67]
	s_barrier
	s_add_i32 s56, s49, s36
	v_lshl_add_u64 v[156:157], s[30:31], 0, v[130:131]
	s_mov_b32 m0, s56
	ds_read_b128 v[190:193], v159 offset:16384
	ds_read_b128 v[194:197], v159 offset:17408
	ds_read_b128 v[198:201], v159 offset:18432
	ds_read_b128 v[202:205], v159 offset:19456
	ds_read_b128 v[206:209], v159 offset:20480
	ds_read_b128 v[210:213], v159 offset:21504
	ds_read_b128 v[214:217], v159 offset:22528
	ds_read_b128 v[218:221], v159 offset:23552
	global_load_lds_dwordx4 v[156:157], off
	s_add_i32 m0, s56, 0x2000
	s_add_u32 s56, s30, 0x40000
	v_lshl_add_u64 v[222:223], s[30:31], 0, v[134:135]
	s_addc_u32 s57, s31, 0
	s_add_i32 s58, s50, s36
	global_load_lds_dwordx4 v[222:223], off
	s_mov_b32 m0, s58
	v_lshl_add_u64 v[226:227], s[34:35], 0, v[132:133]
	global_load_lds_dwordx4 v130, s[56:57]
	s_add_i32 m0, s58, 0x2000
	s_nop 0
	global_load_lds_dwordx4 v134, s[56:57]
	v_lshl_add_u64 v[224:225], s[34:35], 0, v[128:129]
	s_mov_b32 m0, s39
	s_nop 0
	global_load_lds_dwordx4 v[224:225], off
	s_mov_b32 m0, s40
	s_nop 0
	global_load_lds_dwordx4 v[226:227], off
	s_waitcnt vmcnt(8)
	s_waitcnt lgkmcnt(0)
	s_barrier
	s_waitcnt lgkmcnt(0)
	v_mfma_f32_16x16x32_bf16 v[56:59], v[152:155], v[190:193], v[56:59]
	v_mfma_f32_16x16x32_bf16 v[52:55], v[166:169], v[190:193], v[52:55]
	v_mfma_f32_16x16x32_bf16 v[40:43], v[152:155], v[198:201], v[40:43]
	v_mfma_f32_16x16x32_bf16 v[36:39], v[166:169], v[198:201], v[36:39]
	v_mfma_f32_16x16x32_bf16 v[24:27], v[152:155], v[206:209], v[24:27]
	v_mfma_f32_16x16x32_bf16 v[20:23], v[166:169], v[206:209], v[20:23]
	v_mfma_f32_16x16x32_bf16 v[8:11], v[152:155], v[214:217], v[8:11]
	v_mfma_f32_16x16x32_bf16 v[4:7], v[166:169], v[214:217], v[4:7]
	v_mfma_f32_16x16x32_bf16 v[56:59], v[162:165], v[194:197], v[56:59]
	v_mfma_f32_16x16x32_bf16 v[52:55], v[170:173], v[194:197], v[52:55]
	v_mfma_f32_16x16x32_bf16 v[40:43], v[162:165], v[202:205], v[40:43]
	v_mfma_f32_16x16x32_bf16 v[36:39], v[170:173], v[202:205], v[36:39]
	v_mfma_f32_16x16x32_bf16 v[24:27], v[162:165], v[210:213], v[24:27]
	v_mfma_f32_16x16x32_bf16 v[20:23], v[170:173], v[210:213], v[20:23]
	v_mfma_f32_16x16x32_bf16 v[8:11], v[162:165], v[218:221], v[8:11]
	v_mfma_f32_16x16x32_bf16 v[4:7], v[170:173], v[218:221], v[4:7]
	v_mfma_f32_16x16x32_bf16 v[60:63], v[174:177], v[190:193], v[60:63]
	v_mfma_f32_16x16x32_bf16 v[48:51], v[182:185], v[190:193], v[48:51]
	v_mfma_f32_16x16x32_bf16 v[44:47], v[174:177], v[198:201], v[44:47]
	v_mfma_f32_16x16x32_bf16 v[32:35], v[182:185], v[198:201], v[32:35]
	v_mfma_f32_16x16x32_bf16 v[28:31], v[174:177], v[206:209], v[28:31]
	v_mfma_f32_16x16x32_bf16 v[16:19], v[182:185], v[206:209], v[16:19]
	v_mfma_f32_16x16x32_bf16 v[12:15], v[174:177], v[214:217], v[12:15]
	v_mfma_f32_16x16x32_bf16 v[0:3], v[182:185], v[214:217], v[0:3]
	v_mfma_f32_16x16x32_bf16 v[60:63], v[178:181], v[194:197], v[60:63]
	v_mfma_f32_16x16x32_bf16 v[48:51], v[186:189], v[194:197], v[48:51]
	v_mfma_f32_16x16x32_bf16 v[44:47], v[178:181], v[202:205], v[44:47]
	v_mfma_f32_16x16x32_bf16 v[32:35], v[186:189], v[202:205], v[32:35]
	v_mfma_f32_16x16x32_bf16 v[28:31], v[178:181], v[210:213], v[28:31]
	v_mfma_f32_16x16x32_bf16 v[16:19], v[186:189], v[210:213], v[16:19]
	v_mfma_f32_16x16x32_bf16 v[12:15], v[178:181], v[218:221], v[12:15]
	v_mfma_f32_16x16x32_bf16 v[0:3], v[186:189], v[218:221], v[0:3]
	s_barrier
	s_add_i32 s56, 0, 0x18000
	s_add_i32 s57, 0, 0x1c000
	v_add_u32_e32 v170, s56, v141
	v_add_u32_e32 v186, s57, v141
	ds_read_b128 v[152:155], v170
	ds_read_b128 v[162:165], v170 offset:1024
	ds_read_b128 v[166:169], v170 offset:2048
	ds_read_b128 v[170:173], v170 offset:3072
	ds_read_b128 v[174:177], v186
	ds_read_b128 v[178:181], v186 offset:1024
	ds_read_b128 v[182:185], v186 offset:2048
	ds_read_b128 v[186:189], v186 offset:3072
	s_add_u32 s34, s34, 0x40000
	s_addc_u32 s35, s35, 0
	s_mov_b32 m0, s41
	ds_read_b128 v[190:193], v159 offset:32768
	ds_read_b128 v[194:197], v159 offset:33792
	ds_read_b128 v[198:201], v159 offset:34816
	ds_read_b128 v[202:205], v159 offset:35840
	ds_read_b128 v[206:209], v159 offset:36864
	ds_read_b128 v[210:213], v159 offset:37888
	ds_read_b128 v[214:217], v159 offset:38912
	ds_read_b128 v[218:221], v159 offset:39936
	global_load_lds_dwordx4 v128, s[34:35]
	v_lshl_add_u64 v[228:229], s[34:35], 0, v[132:133]
	s_mov_b32 m0, s42
	s_nop 0
	global_load_lds_dwordx4 v[228:229], off
	s_waitcnt vmcnt(8)
	s_waitcnt lgkmcnt(0)
	s_barrier
	s_waitcnt lgkmcnt(0)
	v_mfma_f32_16x16x32_bf16 v[116:119], v[152:155], v[190:193], v[116:119]
	v_mfma_f32_16x16x32_bf16 v[112:115], v[166:169], v[190:193], v[112:115]
	v_mfma_f32_16x16x32_bf16 v[100:103], v[152:155], v[198:201], v[100:103]
	v_mfma_f32_16x16x32_bf16 v[96:99], v[166:169], v[198:201], v[96:99]
	v_mfma_f32_16x16x32_bf16 v[88:91], v[152:155], v[206:209], v[88:91]
	v_mfma_f32_16x16x32_bf16 v[84:87], v[166:169], v[206:209], v[84:87]
	v_mfma_f32_16x16x32_bf16 v[72:75], v[152:155], v[214:217], v[72:75]
	v_mfma_f32_16x16x32_bf16 v[68:71], v[166:169], v[214:217], v[68:71]
	v_mfma_f32_16x16x32_bf16 v[116:119], v[162:165], v[194:197], v[116:119]
	v_mfma_f32_16x16x32_bf16 v[112:115], v[170:173], v[194:197], v[112:115]
	v_mfma_f32_16x16x32_bf16 v[100:103], v[162:165], v[202:205], v[100:103]
	v_mfma_f32_16x16x32_bf16 v[96:99], v[170:173], v[202:205], v[96:99]
	v_mfma_f32_16x16x32_bf16 v[88:91], v[162:165], v[210:213], v[88:91]
	v_mfma_f32_16x16x32_bf16 v[84:87], v[170:173], v[210:213], v[84:87]
	v_mfma_f32_16x16x32_bf16 v[72:75], v[162:165], v[218:221], v[72:75]
	v_mfma_f32_16x16x32_bf16 v[68:71], v[170:173], v[218:221], v[68:71]
	v_mfma_f32_16x16x32_bf16 v[124:127], v[174:177], v[190:193], v[124:127]
	v_mfma_f32_16x16x32_bf16 v[120:123], v[182:185], v[190:193], v[120:123]
	v_mfma_f32_16x16x32_bf16 v[108:111], v[174:177], v[198:201], v[108:111]
	v_mfma_f32_16x16x32_bf16 v[104:107], v[182:185], v[198:201], v[104:107]
	v_mfma_f32_16x16x32_bf16 v[92:95], v[174:177], v[206:209], v[92:95]
	v_mfma_f32_16x16x32_bf16 v[80:83], v[182:185], v[206:209], v[80:83]
	v_mfma_f32_16x16x32_bf16 v[76:79], v[174:177], v[214:217], v[76:79]
	v_mfma_f32_16x16x32_bf16 v[64:67], v[182:185], v[214:217], v[64:67]
	v_mfma_f32_16x16x32_bf16 v[124:127], v[178:181], v[194:197], v[124:127]
	v_mfma_f32_16x16x32_bf16 v[120:123], v[186:189], v[194:197], v[120:123]
	v_mfma_f32_16x16x32_bf16 v[108:111], v[178:181], v[202:205], v[108:111]
	v_mfma_f32_16x16x32_bf16 v[104:107], v[186:189], v[202:205], v[104:107]
	v_mfma_f32_16x16x32_bf16 v[92:95], v[178:181], v[210:213], v[92:95]
	v_mfma_f32_16x16x32_bf16 v[80:83], v[186:189], v[210:213], v[80:83]
	v_mfma_f32_16x16x32_bf16 v[76:79], v[178:181], v[218:221], v[76:79]
	v_mfma_f32_16x16x32_bf16 v[64:67], v[186:189], v[218:221], v[64:67]
	s_barrier
	s_add_i32 s34, s56, s36
	v_lshl_add_u64 v[156:157], v[156:157], 0, s[10:11]
	s_mov_b32 m0, s34
	ds_read_b128 v[190:193], v159 offset:49152
	ds_read_b128 v[194:197], v159 offset:50176
	ds_read_b128 v[198:201], v159 offset:51200
	ds_read_b128 v[202:205], v159 offset:52224
	ds_read_b128 v[206:209], v159 offset:53248
	ds_read_b128 v[210:213], v159 offset:54272
	ds_read_b128 v[214:217], v159 offset:55296
	ds_read_b128 v[218:221], v159 offset:56320
	global_load_lds_dwordx4 v[156:157], off
	s_add_i32 m0, s34, 0x2000
	s_add_u32 s30, s30, 0x40080
	v_lshl_add_u64 v[156:157], v[222:223], 0, s[10:11]
	s_addc_u32 s31, s31, 0
	s_add_i32 s34, s57, s36
	global_load_lds_dwordx4 v[156:157], off
	s_mov_b32 m0, s34
	s_nop 0
	global_load_lds_dwordx4 v130, s[30:31]
	s_add_i32 m0, s34, 0x2000
	s_nop 0
	global_load_lds_dwordx4 v134, s[30:31]
	v_lshl_add_u64 v[156:157], v[224:225], 0, s[10:11]
	s_mov_b32 m0, s43
	s_nop 0
	global_load_lds_dwordx4 v[156:157], off
	v_lshl_add_u64 v[156:157], v[226:227], 0, s[10:11]
	s_mov_b32 m0, s44
	s_nop 0
	global_load_lds_dwordx4 v[156:157], off
	s_waitcnt vmcnt(8)
	s_waitcnt lgkmcnt(0)
	s_barrier
	s_waitcnt lgkmcnt(0)
	v_mfma_f32_16x16x32_bf16 v[56:59], v[152:155], v[190:193], v[56:59]
	v_mfma_f32_16x16x32_bf16 v[52:55], v[166:169], v[190:193], v[52:55]
	v_mfma_f32_16x16x32_bf16 v[40:43], v[152:155], v[198:201], v[40:43]
	v_mfma_f32_16x16x32_bf16 v[36:39], v[166:169], v[198:201], v[36:39]
	v_mfma_f32_16x16x32_bf16 v[24:27], v[152:155], v[206:209], v[24:27]
	v_mfma_f32_16x16x32_bf16 v[20:23], v[166:169], v[206:209], v[20:23]
	v_mfma_f32_16x16x32_bf16 v[8:11], v[152:155], v[214:217], v[8:11]
	v_mfma_f32_16x16x32_bf16 v[4:7], v[166:169], v[214:217], v[4:7]
	v_mfma_f32_16x16x32_bf16 v[56:59], v[162:165], v[194:197], v[56:59]
	v_mfma_f32_16x16x32_bf16 v[52:55], v[170:173], v[194:197], v[52:55]
	v_mfma_f32_16x16x32_bf16 v[40:43], v[162:165], v[202:205], v[40:43]
	v_mfma_f32_16x16x32_bf16 v[36:39], v[170:173], v[202:205], v[36:39]
	v_mfma_f32_16x16x32_bf16 v[24:27], v[162:165], v[210:213], v[24:27]
	v_mfma_f32_16x16x32_bf16 v[20:23], v[170:173], v[210:213], v[20:23]
	v_mfma_f32_16x16x32_bf16 v[8:11], v[162:165], v[218:221], v[8:11]
	v_mfma_f32_16x16x32_bf16 v[4:7], v[170:173], v[218:221], v[4:7]
	v_mfma_f32_16x16x32_bf16 v[60:63], v[174:177], v[190:193], v[60:63]
	v_mfma_f32_16x16x32_bf16 v[48:51], v[182:185], v[190:193], v[48:51]
	v_mfma_f32_16x16x32_bf16 v[44:47], v[174:177], v[198:201], v[44:47]
	v_mfma_f32_16x16x32_bf16 v[32:35], v[182:185], v[198:201], v[32:35]
	v_mfma_f32_16x16x32_bf16 v[28:31], v[174:177], v[206:209], v[28:31]
	v_mfma_f32_16x16x32_bf16 v[16:19], v[182:185], v[206:209], v[16:19]
	v_mfma_f32_16x16x32_bf16 v[12:15], v[174:177], v[214:217], v[12:15]
	v_mfma_f32_16x16x32_bf16 v[0:3], v[182:185], v[214:217], v[0:3]
	v_mfma_f32_16x16x32_bf16 v[60:63], v[178:181], v[194:197], v[60:63]
	v_mfma_f32_16x16x32_bf16 v[48:51], v[186:189], v[194:197], v[48:51]
	v_mfma_f32_16x16x32_bf16 v[44:47], v[178:181], v[202:205], v[44:47]
	v_mfma_f32_16x16x32_bf16 v[32:35], v[186:189], v[202:205], v[32:35]
	v_mfma_f32_16x16x32_bf16 v[28:31], v[178:181], v[210:213], v[28:31]
	v_mfma_f32_16x16x32_bf16 v[16:19], v[186:189], v[210:213], v[16:19]
	v_mfma_f32_16x16x32_bf16 v[12:15], v[178:181], v[218:221], v[12:15]
	v_mfma_f32_16x16x32_bf16 v[0:3], v[186:189], v[218:221], v[0:3]
	s_add_i32 s55, s55, 2
	s_add_u32 s28, s28, 0x100
	s_addc_u32 s29, s29, 0
	s_add_u32 s53, s53, 0x100
	s_addc_u32 s54, s54, 0
	s_cmp_gt_u32 s55, 13
	s_barrier
	s_cbranch_scc0 .LBB0_161
	s_and_b64 vcc, exec, s[12:13]
	s_cbranch_vccz .LBB0_166
	s_barrier
	v_lshl_add_u32 v152, s26, 8, v139
	s_cmp_gt_i32 s24, 21
	s_mov_b64 s[26:27], -1
	s_cbranch_scc1 .LBB0_167

.LBB0_231:
	v_ashrrev_i32_e32 v2, 31, v0
	v_lshrrev_b32_e32 v2, 26, v2
	v_lshlrev_b32_e32 v1, 4, v0
	v_add_u32_e32 v2, v0, v2
	v_bfe_i32 v0, v0, 27, 1
	v_lshrrev_b32_e32 v0, 22, v0
	v_add_u32_e32 v0, v1, v0
	v_and_b32_e32 v0, 0xfffffc00, v0
	v_sub_u32_e32 v0, v1, v0
	v_ashrrev_i32_e32 v9, 6, v2
	v_lshrrev_b32_e32 v2, 4, v0
	v_bitop3_b32 v0, v2, v0, 32 bitop3:0x6c
	v_ashrrev_i32_e32 v3, 31, v0
	v_lshrrev_b32_e32 v3, 26, v3
	v_add_u32_e32 v3, v0, v3
	v_lshlrev_b32_e32 v2, 3, v9
	v_ashrrev_i32_e32 v11, 6, v3
	v_and_b32_e32 v3, 0xc0, v3
	s_ashr_i32 s3, s4, 6
	v_and_b32_e32 v2, 0xfffff0, v2
	v_sub_u32_e32 v0, v0, v3
	v_mov_b32_e32 v3, 1
	s_ashr_i32 s7, s5, 3
	v_add_u32_e32 v2, v11, v2
	v_lshlrev_b32_e32 v4, 5, v9
	v_ashrrev_i16_sdwa v0, v3, sext(v0) dst_sel:DWORD dst_unused:UNUSED_PAD src0_sel:DWORD src1_sel:BYTE_0
	s_movk_i32 s2, 0xb00
	s_ashr_i32 s5, s4, 8
	s_lshl_b32 s37, s3, 10
	v_and_b32_e32 v10, 32, v4
	v_bfe_i32 v12, v0, 0, 16
	v_mul_lo_u32 v0, v2, s2
	s_add_u32 s38, s70, 0x3400000
	v_or_b32_e32 v0, v0, v10
	s_addc_u32 s39, s71, 0
	s_add_i32 s6, s6, s7
	v_add_lshl_u32 v128, v0, v12, 1
	v_add_u32_e32 v0, 0x2000, v1
	s_ashr_i32 s7, s6, 31
	v_ashrrev_i32_e32 v1, 31, v0
	s_lshr_b32 s7, s7, 27
	v_lshrrev_b32_e32 v1, 22, v1
	s_add_i32 s7, s6, s7
	v_add_u32_e32 v1, v0, v1
	s_ashr_i32 s8, s7, 5
	s_andn2_b32 s7, s7, 31
	v_ashrrev_i32_e32 v13, 10, v1
	s_sub_i32 s6, s6, s7
	v_mul_i32_i24_e32 v1, 0x400, v13
	s_bfe_i32 s7, s6, 0x80000
	v_sub_u32_e32 v0, v0, v1
	s_bfe_u32 s7, s7, 0x3000c
	v_lshrrev_b32_e32 v1, 4, v0
	s_add_i32 s7, s6, s7
	v_bitop3_b32 v0, v1, v0, 32 bitop3:0x6c
	s_bfe_i32 s9, s7, 0x80000
	s_and_b32 s7, s7, 0xf8
	v_ashrrev_i32_e32 v2, 31, v0
	s_sub_i32 s6, s6, s7
	v_lshrrev_b32_e32 v2, 26, v2
	s_lshl_b32 s8, s8, 3
	s_sext_i32_i16 s9, s9
	s_sext_i32_i8 s6, s6
	v_add_u32_e32 v2, v0, v2
	s_add_i32 s52, s8, s6
	s_ashr_i32 s6, s9, 3
	v_lshlrev_b32_e32 v1, 3, v13
	v_ashrrev_i32_e32 v14, 6, v2
	v_and_b32_e32 v2, 0xc0, v2
	s_lshr_b32 s16, s9, 3
	s_mul_hi_i32 s7, s6, 0x160000
	s_mul_i32 s6, s6, 0x160000
	v_and_b32_e32 v1, 0xfffff0, v1
	v_sub_u32_e32 v0, v0, v2
	s_add_u32 s28, s38, s6
	v_add_u32_e32 v1, v14, v1
	v_lshlrev_b32_e32 v4, 5, v13
	v_ashrrev_i16_sdwa v0, v3, sext(v0) dst_sel:DWORD dst_unused:UNUSED_PAD src0_sel:DWORD src1_sel:BYTE_0
	s_addc_u32 s29, s39, s7
	s_add_i32 s40, s37, 0
	v_and_b32_e32 v15, 32, v4
	v_bfe_i32 v16, v0, 0, 16
	v_mul_lo_u32 v0, v1, s2
	s_add_i32 m0, s40, 0x10000
	v_or_b32_e32 v0, v0, v15
	global_load_lds_dwordx4 v128, s[28:29]
	s_add_i32 m0, s40, 0x12000
	v_add_lshl_u32 v130, v0, v16, 1
	s_add_u32 s6, s28, 0xb0000
	global_load_lds_dwordx4 v130, s[28:29]
	s_addc_u32 s7, s29, 0
	s_add_i32 m0, s40, 0x14000
	s_mul_i32 s10, s52, 0x160000
	global_load_lds_dwordx4 v128, s[6:7]
	s_add_i32 m0, s40, 0x16000
	s_mul_hi_i32 s8, s52, 0x160000
	s_add_u32 s26, s72, s10
	s_addc_u32 s27, s73, s8
	s_add_i32 s41, s40, 0x2000
	global_load_lds_dwordx4 v130, s[6:7]
	s_mov_b32 m0, s40
	s_add_u32 s6, s26, 0xb0000
	global_load_lds_dwordx4 v128, s[26:27]
	s_mov_b32 m0, s41
	s_addc_u32 s7, s27, 0
	s_add_i32 s42, s40, 0x4000
	global_load_lds_dwordx4 v130, s[26:27]
	s_mov_b32 m0, s42
	s_add_i32 s43, s40, 0x6000
	global_load_lds_dwordx4 v128, s[6:7]
	s_mov_b32 m0, s43
	v_mov_b32_e32 v129, 0
	global_load_lds_dwordx4 v130, s[6:7]
	s_load_dwordx2 s[6:7], s[0:1], 0x0
	s_load_dwordx2 s[8:9], s[0:1], 0x110
	v_mov_b32_e32 v131, v129
	s_cmp_eq_u32 s5, 1
	s_mov_b32 s44, 0
	v_lshl_add_u64 v[6:7], s[28:29], 0, v[128:129]
	v_lshl_add_u64 v[4:5], s[28:29], 0, v[130:131]
	s_mov_b64 s[10:11], 0xb0000
	v_lshl_add_u64 v[0:1], s[26:27], 0, v[128:129]
	s_cselect_b64 s[12:13], -1, 0
	s_cmp_lg_u32 s5, 1
	v_lshl_add_u64 v[2:3], s[26:27], 0, v[130:131]
	s_setprio 1
	s_cbranch_scc1 .LBB0_233
	s_barrier
	s_setprio 0

.LBB0_247:
	ds_read_b128 v[148:151], v145
	ds_read_b128 v[152:155], v145 offset:1024
	ds_read_b128 v[156:159], v145 offset:2048
	ds_read_b128 v[160:163], v145 offset:3072
	ds_read_b128 v[164:167], v146
	ds_read_b128 v[168:171], v146 offset:1024
	ds_read_b128 v[172:175], v146 offset:2048
	ds_read_b128 v[176:179], v146 offset:3072
	s_add_u32 s28, s26, 0x100
	s_addc_u32 s29, s27, 0
	s_cmp_eq_u32 s56, 40
	s_cselect_b32 s35, s5, s29
	s_cselect_b32 s34, s4, s28
	s_cselect_b32 s31, s25, s55
	s_cselect_b32 s30, s24, s54
	v_lshl_add_u64 v[140:141], s[26:27], 0, v[132:133]
	s_add_i32 m0, s40, 0xc000
	ds_read_b128 v[180:183], v147
	ds_read_b128 v[184:187], v147 offset:1024
	ds_read_b128 v[188:191], v147 offset:2048
	ds_read_b128 v[192:195], v147 offset:3072
	ds_read_b128 v[196:199], v147 offset:4096
	ds_read_b128 v[200:203], v147 offset:5120
	ds_read_b128 v[204:207], v147 offset:6144
	ds_read_b128 v[208:211], v147 offset:7168
	global_load_lds_dwordx4 v[140:141], off
	v_lshl_add_u64 v[140:141], s[26:27], 0, v[134:135]
	s_add_i32 m0, s40, 0xe000
	s_nop 0
	global_load_lds_dwordx4 v[140:141], off
	s_waitcnt vmcnt(8)
	s_waitcnt lgkmcnt(0)
	s_barrier
	s_waitcnt lgkmcnt(0)
	v_mfma_f32_16x16x32_bf16 v[124:127], v[148:151], v[180:183], v[124:127]
	v_mfma_f32_16x16x32_bf16 v[120:123], v[156:159], v[180:183], v[120:123]
	v_mfma_f32_16x16x32_bf16 v[112:115], v[148:151], v[188:191], v[112:115]
	v_mfma_f32_16x16x32_bf16 v[108:111], v[156:159], v[188:191], v[108:111]
	v_mfma_f32_16x16x32_bf16 v[96:99], v[148:151], v[196:199], v[96:99]
	v_mfma_f32_16x16x32_bf16 v[92:95], v[156:159], v[196:199], v[92:95]
	v_mfma_f32_16x16x32_bf16 v[80:83], v[148:151], v[204:207], v[80:83]
	v_mfma_f32_16x16x32_bf16 v[76:79], v[156:159], v[204:207], v[76:79]
	v_mfma_f32_16x16x32_bf16 v[124:127], v[152:155], v[184:187], v[124:127]
	v_mfma_f32_16x16x32_bf16 v[120:123], v[160:163], v[184:187], v[120:123]
	v_mfma_f32_16x16x32_bf16 v[112:115], v[152:155], v[192:195], v[112:115]
	v_mfma_f32_16x16x32_bf16 v[108:111], v[160:163], v[192:195], v[108:111]
	v_mfma_f32_16x16x32_bf16 v[96:99], v[152:155], v[200:203], v[96:99]
	v_mfma_f32_16x16x32_bf16 v[92:95], v[160:163], v[200:203], v[92:95]
	v_mfma_f32_16x16x32_bf16 v[80:83], v[152:155], v[208:211], v[80:83]
	v_mfma_f32_16x16x32_bf16 v[76:79], v[160:163], v[208:211], v[76:79]
	v_mfma_f32_16x16x32_bf16 v[116:119], v[164:167], v[180:183], v[116:119]
	v_mfma_f32_16x16x32_bf16 v[104:107], v[172:175], v[180:183], v[104:107]
	v_mfma_f32_16x16x32_bf16 v[100:103], v[164:167], v[188:191], v[100:103]
	v_mfma_f32_16x16x32_bf16 v[88:91], v[172:175], v[188:191], v[88:91]
	v_mfma_f32_16x16x32_bf16 v[84:87], v[164:167], v[196:199], v[84:87]
	v_mfma_f32_16x16x32_bf16 v[72:75], v[172:175], v[196:199], v[72:75]
	v_mfma_f32_16x16x32_bf16 v[68:71], v[164:167], v[204:207], v[68:71]
	v_mfma_f32_16x16x32_bf16 v[64:67], v[172:175], v[204:207], v[64:67]
	v_mfma_f32_16x16x32_bf16 v[116:119], v[168:171], v[184:187], v[116:119]
	v_mfma_f32_16x16x32_bf16 v[104:107], v[176:179], v[184:187], v[104:107]
	v_mfma_f32_16x16x32_bf16 v[100:103], v[168:171], v[192:195], v[100:103]
	v_mfma_f32_16x16x32_bf16 v[88:91], v[176:179], v[192:195], v[88:91]
	v_mfma_f32_16x16x32_bf16 v[84:87], v[168:171], v[200:203], v[84:87]
	v_mfma_f32_16x16x32_bf16 v[72:75], v[176:179], v[200:203], v[72:75]
	v_mfma_f32_16x16x32_bf16 v[68:71], v[168:171], v[208:211], v[68:71]
	v_mfma_f32_16x16x32_bf16 v[64:67], v[176:179], v[208:211], v[64:67]
	s_barrier
	s_add_i32 s26, s48, s37
	v_lshl_add_u64 v[140:141], s[30:31], 0, v[128:129]
	s_mov_b32 m0, s26
	ds_read_b128 v[180:183], v147 offset:16384
	ds_read_b128 v[184:187], v147 offset:17408
	ds_read_b128 v[188:191], v147 offset:18432
	ds_read_b128 v[192:195], v147 offset:19456
	ds_read_b128 v[196:199], v147 offset:20480
	ds_read_b128 v[200:203], v147 offset:21504
	ds_read_b128 v[204:207], v147 offset:22528
	ds_read_b128 v[208:211], v147 offset:23552
	global_load_lds_dwordx4 v[140:141], off
	s_add_i32 m0, s26, 0x2000
	s_add_u32 s26, s30, 0xb0000
	v_lshl_add_u64 v[212:213], s[30:31], 0, v[130:131]
	s_addc_u32 s27, s31, 0
	s_add_i32 s57, s49, s37
	global_load_lds_dwordx4 v[212:213], off
	v_lshl_add_u64 v[214:215], s[26:27], 0, v[128:129]
	s_mov_b32 m0, s57
	v_lshl_add_u64 v[216:217], s[34:35], 0, v[130:131]
	global_load_lds_dwordx4 v[214:215], off
	s_add_i32 m0, s57, 0x2000
	s_nop 0
	global_load_lds_dwordx4 v130, s[26:27]
	v_lshl_add_u64 v[214:215], s[34:35], 0, v[128:129]
	s_mov_b32 m0, s40
	s_nop 0
	global_load_lds_dwordx4 v[214:215], off
	s_mov_b32 m0, s41
	s_nop 0
	global_load_lds_dwordx4 v[216:217], off
	s_waitcnt vmcnt(8)
	s_waitcnt lgkmcnt(0)
	s_barrier
	s_waitcnt lgkmcnt(0)
	v_mfma_f32_16x16x32_bf16 v[60:63], v[148:151], v[180:183], v[60:63]
	v_mfma_f32_16x16x32_bf16 v[56:59], v[156:159], v[180:183], v[56:59]
	v_mfma_f32_16x16x32_bf16 v[48:51], v[148:151], v[188:191], v[48:51]
	v_mfma_f32_16x16x32_bf16 v[44:47], v[156:159], v[188:191], v[44:47]
	v_mfma_f32_16x16x32_bf16 v[32:35], v[148:151], v[196:199], v[32:35]
	v_mfma_f32_16x16x32_bf16 v[28:31], v[156:159], v[196:199], v[28:31]
	v_mfma_f32_16x16x32_bf16 v[16:19], v[148:151], v[204:207], v[16:19]
	v_mfma_f32_16x16x32_bf16 v[12:15], v[156:159], v[204:207], v[12:15]
	v_mfma_f32_16x16x32_bf16 v[60:63], v[152:155], v[184:187], v[60:63]
	v_mfma_f32_16x16x32_bf16 v[56:59], v[160:163], v[184:187], v[56:59]
	v_mfma_f32_16x16x32_bf16 v[48:51], v[152:155], v[192:195], v[48:51]
	v_mfma_f32_16x16x32_bf16 v[44:47], v[160:163], v[192:195], v[44:47]
	v_mfma_f32_16x16x32_bf16 v[32:35], v[152:155], v[200:203], v[32:35]
	v_mfma_f32_16x16x32_bf16 v[28:31], v[160:163], v[200:203], v[28:31]
	v_mfma_f32_16x16x32_bf16 v[16:19], v[152:155], v[208:211], v[16:19]
	v_mfma_f32_16x16x32_bf16 v[12:15], v[160:163], v[208:211], v[12:15]
	v_mfma_f32_16x16x32_bf16 v[52:55], v[164:167], v[180:183], v[52:55]
	v_mfma_f32_16x16x32_bf16 v[40:43], v[172:175], v[180:183], v[40:43]
	v_mfma_f32_16x16x32_bf16 v[36:39], v[164:167], v[188:191], v[36:39]
	v_mfma_f32_16x16x32_bf16 v[24:27], v[172:175], v[188:191], v[24:27]
	v_mfma_f32_16x16x32_bf16 v[20:23], v[164:167], v[196:199], v[20:23]
	v_mfma_f32_16x16x32_bf16 v[8:11], v[172:175], v[196:199], v[8:11]
	v_mfma_f32_16x16x32_bf16 v[4:7], v[164:167], v[204:207], v[4:7]
	v_mfma_f32_16x16x32_bf16 v[0:3], v[172:175], v[204:207], v[0:3]
	v_mfma_f32_16x16x32_bf16 v[52:55], v[168:171], v[184:187], v[52:55]
	v_mfma_f32_16x16x32_bf16 v[40:43], v[176:179], v[184:187], v[40:43]
	v_mfma_f32_16x16x32_bf16 v[36:39], v[168:171], v[192:195], v[36:39]
	v_mfma_f32_16x16x32_bf16 v[24:27], v[176:179], v[192:195], v[24:27]
	v_mfma_f32_16x16x32_bf16 v[20:23], v[168:171], v[200:203], v[20:23]
	v_mfma_f32_16x16x32_bf16 v[8:11], v[176:179], v[200:203], v[8:11]
	v_mfma_f32_16x16x32_bf16 v[4:7], v[168:171], v[208:211], v[4:7]
	v_mfma_f32_16x16x32_bf16 v[0:3], v[176:179], v[208:211], v[0:3]
	s_barrier
	s_add_i32 s57, 0, 0x18000
	s_add_i32 s58, 0, 0x1c000
	v_add_u32_e32 v160, s57, v143
	v_add_u32_e32 v176, s58, v143
	ds_read_b128 v[148:151], v160
	ds_read_b128 v[152:155], v160 offset:1024
	ds_read_b128 v[156:159], v160 offset:2048
	ds_read_b128 v[160:163], v160 offset:3072
	ds_read_b128 v[164:167], v176
	ds_read_b128 v[168:171], v176 offset:1024
	ds_read_b128 v[172:175], v176 offset:2048
	ds_read_b128 v[176:179], v176 offset:3072
	s_add_u32 s26, s34, 0xb0000
	s_addc_u32 s27, s35, 0
	s_mov_b32 m0, s42
	v_lshl_add_u64 v[218:219], s[26:27], 0, v[128:129]
	ds_read_b128 v[180:183], v147 offset:32768
	ds_read_b128 v[184:187], v147 offset:33792
	ds_read_b128 v[188:191], v147 offset:34816
	ds_read_b128 v[192:195], v147 offset:35840
	ds_read_b128 v[196:199], v147 offset:36864
	ds_read_b128 v[200:203], v147 offset:37888
	ds_read_b128 v[204:207], v147 offset:38912
	ds_read_b128 v[208:211], v147 offset:39936
	global_load_lds_dwordx4 v[218:219], off
	v_lshl_add_u64 v[218:219], s[26:27], 0, v[130:131]
	s_mov_b32 m0, s43
	s_nop 0
	global_load_lds_dwordx4 v[218:219], off
	s_waitcnt vmcnt(8)
	s_waitcnt lgkmcnt(0)
	s_barrier
	s_waitcnt lgkmcnt(0)
	v_mfma_f32_16x16x32_bf16 v[124:127], v[148:151], v[180:183], v[124:127]
	v_mfma_f32_16x16x32_bf16 v[120:123], v[156:159], v[180:183], v[120:123]
	v_mfma_f32_16x16x32_bf16 v[112:115], v[148:151], v[188:191], v[112:115]
	v_mfma_f32_16x16x32_bf16 v[108:111], v[156:159], v[188:191], v[108:111]
	v_mfma_f32_16x16x32_bf16 v[96:99], v[148:151], v[196:199], v[96:99]
	v_mfma_f32_16x16x32_bf16 v[92:95], v[156:159], v[196:199], v[92:95]
	v_mfma_f32_16x16x32_bf16 v[80:83], v[148:151], v[204:207], v[80:83]
	v_mfma_f32_16x16x32_bf16 v[76:79], v[156:159], v[204:207], v[76:79]
	v_mfma_f32_16x16x32_bf16 v[124:127], v[152:155], v[184:187], v[124:127]
	v_mfma_f32_16x16x32_bf16 v[120:123], v[160:163], v[184:187], v[120:123]
	v_mfma_f32_16x16x32_bf16 v[112:115], v[152:155], v[192:195], v[112:115]
	v_mfma_f32_16x16x32_bf16 v[108:111], v[160:163], v[192:195], v[108:111]
	v_mfma_f32_16x16x32_bf16 v[96:99], v[152:155], v[200:203], v[96:99]
	v_mfma_f32_16x16x32_bf16 v[92:95], v[160:163], v[200:203], v[92:95]
	v_mfma_f32_16x16x32_bf16 v[80:83], v[152:155], v[208:211], v[80:83]
	v_mfma_f32_16x16x32_bf16 v[76:79], v[160:163], v[208:211], v[76:79]
	v_mfma_f32_16x16x32_bf16 v[116:119], v[164:167], v[180:183], v[116:119]
	v_mfma_f32_16x16x32_bf16 v[104:107], v[172:175], v[180:183], v[104:107]
	v_mfma_f32_16x16x32_bf16 v[100:103], v[164:167], v[188:191], v[100:103]
	v_mfma_f32_16x16x32_bf16 v[88:91], v[172:175], v[188:191], v[88:91]
	v_mfma_f32_16x16x32_bf16 v[84:87], v[164:167], v[196:199], v[84:87]
	v_mfma_f32_16x16x32_bf16 v[72:75], v[172:175], v[196:199], v[72:75]
	v_mfma_f32_16x16x32_bf16 v[68:71], v[164:167], v[204:207], v[68:71]
	v_mfma_f32_16x16x32_bf16 v[64:67], v[172:175], v[204:207], v[64:67]
	v_mfma_f32_16x16x32_bf16 v[116:119], v[168:171], v[184:187], v[116:119]
	v_mfma_f32_16x16x32_bf16 v[104:107], v[176:179], v[184:187], v[104:107]
	v_mfma_f32_16x16x32_bf16 v[100:103], v[168:171], v[192:195], v[100:103]
	v_mfma_f32_16x16x32_bf16 v[88:91], v[176:179], v[192:195], v[88:91]
	v_mfma_f32_16x16x32_bf16 v[84:87], v[168:171], v[200:203], v[84:87]
	v_mfma_f32_16x16x32_bf16 v[72:75], v[176:179], v[200:203], v[72:75]
	v_mfma_f32_16x16x32_bf16 v[68:71], v[168:171], v[208:211], v[68:71]
	v_mfma_f32_16x16x32_bf16 v[64:67], v[176:179], v[208:211], v[64:67]
	s_barrier
	s_add_i32 s26, s57, s37
	v_lshl_add_u64 v[140:141], v[140:141], 0, s[14:15]
	s_mov_b32 m0, s26
	ds_read_b128 v[180:183], v147 offset:49152
	ds_read_b128 v[184:187], v147 offset:50176
	ds_read_b128 v[188:191], v147 offset:51200
	ds_read_b128 v[192:195], v147 offset:52224
	ds_read_b128 v[196:199], v147 offset:53248
	ds_read_b128 v[200:203], v147 offset:54272
	ds_read_b128 v[204:207], v147 offset:55296
	ds_read_b128 v[208:211], v147 offset:56320
	global_load_lds_dwordx4 v[140:141], off
	s_add_i32 m0, s26, 0x2000
	s_add_u32 s26, s30, 0xb0080
	v_lshl_add_u64 v[140:141], v[212:213], 0, s[14:15]
	s_addc_u32 s27, s31, 0
	s_add_i32 s30, s58, s37
	global_load_lds_dwordx4 v[140:141], off
	v_lshl_add_u64 v[140:141], s[26:27], 0, v[128:129]
	s_mov_b32 m0, s30
	s_nop 0
	global_load_lds_dwordx4 v[140:141], off
	s_add_i32 m0, s30, 0x2000
	s_nop 0
	global_load_lds_dwordx4 v130, s[26:27]
	v_lshl_add_u64 v[140:141], v[214:215], 0, s[14:15]
	s_mov_b32 m0, s45
	s_nop 0
	global_load_lds_dwordx4 v[140:141], off
	v_lshl_add_u64 v[140:141], v[216:217], 0, s[14:15]
	s_mov_b32 m0, s46
	s_nop 0
	global_load_lds_dwordx4 v[140:141], off
	s_waitcnt vmcnt(8)
	s_waitcnt lgkmcnt(0)
	s_barrier
	s_waitcnt lgkmcnt(0)
	v_mfma_f32_16x16x32_bf16 v[60:63], v[148:151], v[180:183], v[60:63]
	v_mfma_f32_16x16x32_bf16 v[56:59], v[156:159], v[180:183], v[56:59]
	v_mfma_f32_16x16x32_bf16 v[48:51], v[148:151], v[188:191], v[48:51]
	v_mfma_f32_16x16x32_bf16 v[44:47], v[156:159], v[188:191], v[44:47]
	v_mfma_f32_16x16x32_bf16 v[32:35], v[148:151], v[196:199], v[32:35]
	v_mfma_f32_16x16x32_bf16 v[28:31], v[156:159], v[196:199], v[28:31]
	v_mfma_f32_16x16x32_bf16 v[16:19], v[148:151], v[204:207], v[16:19]
	v_mfma_f32_16x16x32_bf16 v[12:15], v[156:159], v[204:207], v[12:15]
	v_mfma_f32_16x16x32_bf16 v[60:63], v[152:155], v[184:187], v[60:63]
	v_mfma_f32_16x16x32_bf16 v[56:59], v[160:163], v[184:187], v[56:59]
	v_mfma_f32_16x16x32_bf16 v[48:51], v[152:155], v[192:195], v[48:51]
	v_mfma_f32_16x16x32_bf16 v[44:47], v[160:163], v[192:195], v[44:47]
	v_mfma_f32_16x16x32_bf16 v[32:35], v[152:155], v[200:203], v[32:35]
	v_mfma_f32_16x16x32_bf16 v[28:31], v[160:163], v[200:203], v[28:31]
	v_mfma_f32_16x16x32_bf16 v[16:19], v[152:155], v[208:211], v[16:19]
	v_mfma_f32_16x16x32_bf16 v[12:15], v[160:163], v[208:211], v[12:15]
	v_mfma_f32_16x16x32_bf16 v[52:55], v[164:167], v[180:183], v[52:55]
	v_mfma_f32_16x16x32_bf16 v[40:43], v[172:175], v[180:183], v[40:43]
	v_mfma_f32_16x16x32_bf16 v[36:39], v[164:167], v[188:191], v[36:39]
	v_mfma_f32_16x16x32_bf16 v[24:27], v[172:175], v[188:191], v[24:27]
	v_mfma_f32_16x16x32_bf16 v[20:23], v[164:167], v[196:199], v[20:23]
	v_mfma_f32_16x16x32_bf16 v[8:11], v[172:175], v[196:199], v[8:11]
	v_mfma_f32_16x16x32_bf16 v[4:7], v[164:167], v[204:207], v[4:7]
	v_mfma_f32_16x16x32_bf16 v[0:3], v[172:175], v[204:207], v[0:3]
	v_mfma_f32_16x16x32_bf16 v[52:55], v[168:171], v[184:187], v[52:55]
	v_mfma_f32_16x16x32_bf16 v[40:43], v[176:179], v[184:187], v[40:43]
	v_mfma_f32_16x16x32_bf16 v[36:39], v[168:171], v[192:195], v[36:39]
	v_mfma_f32_16x16x32_bf16 v[24:27], v[176:179], v[192:195], v[24:27]
	v_mfma_f32_16x16x32_bf16 v[20:23], v[168:171], v[200:203], v[20:23]
	v_mfma_f32_16x16x32_bf16 v[8:11], v[176:179], v[200:203], v[8:11]
	v_mfma_f32_16x16x32_bf16 v[4:7], v[168:171], v[208:211], v[4:7]
	v_mfma_f32_16x16x32_bf16 v[0:3], v[176:179], v[208:211], v[0:3]
	s_add_i32 s56, s56, 2
	s_add_u32 s54, s54, 0x100
	s_addc_u32 s55, s55, 0
	s_cmp_gt_u32 s56, 41
	s_mov_b64 s[26:27], s[28:29]
	s_barrier
	s_cbranch_scc0 .LBB0_247
	s_and_b64 vcc, exec, s[16:17]
	s_cbranch_vccz .LBB0_250
	s_barrier

.LBB0_325:
	s_waitcnt lgkmcnt(0)
	s_cmp_lt_i32 s2, 5
	s_cselect_b64 s[4:5], -1, 0
	s_cmp_gt_i32 s3, 4
	s_cselect_b64 s[6:7], -1, 0
	s_and_b64 s[4:5], s[4:5], s[6:7]
	s_andn2_b64 vcc, exec, s[4:5]
	s_cbranch_vccnz .LBB0_367
	v_mbcnt_lo_u32_b32 v9, -1, 0
	v_mbcnt_hi_u32_b32 v9, -1, v9
	s_mov_b32 s2, 0xfffe0
	v_add_u32_e32 v0, s95, v9
	v_ashrrev_i32_e32 v2, 31, v0
	v_lshrrev_b32_e32 v2, 26, v2
	v_readfirstlane_b32 s12, v0
	v_lshlrev_b32_e32 v1, 4, v0
	v_add_u32_e32 v2, v0, v2
	v_bfe_i32 v0, v0, 27, 1
	v_lshrrev_b32_e32 v0, 22, v0
	v_add_u32_e32 v0, v1, v0
	v_and_b32_e32 v0, 0xfffffc00, v0
	v_sub_u32_e32 v0, v1, v0
	v_ashrrev_i32_e32 v8, 6, v2
	v_lshrrev_b32_e32 v2, 4, v0
	v_bitop3_b32 v0, v2, v0, 32 bitop3:0x6c
	v_ashrrev_i32_e32 v3, 31, v0
	v_lshrrev_b32_e32 v3, 26, v3
	v_add_u32_e32 v3, v0, v3
	v_lshlrev_b32_e32 v2, 3, v8
	v_ashrrev_i32_e32 v10, 6, v3
	v_and_b32_e32 v3, 0xc0, v3
	v_and_b32_e32 v2, -16, v2
	v_sub_u32_e32 v0, v0, v3
	v_mov_b32_e32 v3, 1
	v_add_u32_e32 v2, v10, v2
	v_ashrrev_i16_sdwa v0, v3, sext(v0) dst_sel:DWORD dst_unused:UNUSED_PAD src0_sel:DWORD src1_sel:BYTE_0
	v_lshlrev_b32_e32 v4, 5, v8
	v_bfe_i32 v11, v0, 0, 16
	v_lshlrev_b32_e32 v0, 1, v2
	v_lshrrev_b32_e32 v5, 2, v2
	v_and_b32_e32 v6, 3, v10
	v_and_b32_e32 v4, 32, v4
	v_and_b32_e32 v0, 24, v0
	v_and_b32_e32 v5, 4, v5
	v_and_or_b32 v6, v2, s2, v6
	v_or3_b32 v0, v6, v5, v0
	v_add_lshl_u32 v4, v4, v11, 1
	v_lshl_add_u32 v134, v0, 12, v4
	v_add_u32_e32 v0, 0x2000, v1
	v_ashrrev_i32_e32 v1, 31, v0
	v_lshrrev_b32_e32 v1, 22, v1
	v_add_u32_e32 v1, v0, v1
	v_ashrrev_i32_e32 v12, 10, v1
	v_mul_i32_i24_e32 v1, 0x400, v12
	v_sub_u32_e32 v0, v0, v1
	v_lshrrev_b32_e32 v1, 4, v0
	v_bitop3_b32 v0, v1, v0, 32 bitop3:0x6c
	v_lshl_add_u32 v132, v2, 12, v4
	v_ashrrev_i32_e32 v2, 31, v0
	v_lshrrev_b32_e32 v2, 26, v2
	v_add_u32_e32 v2, v0, v2
	v_lshlrev_b32_e32 v1, 3, v12
	v_ashrrev_i32_e32 v13, 6, v2
	v_and_b32_e32 v2, 0xc0, v2
	s_add_u32 s52, s70, 0x1f800000
	v_and_b32_e32 v1, -16, v1
	v_sub_u32_e32 v0, v0, v2
	s_addc_u32 s53, s71, 0
	s_ashr_i32 s10, s12, 6
	v_add_u32_e32 v1, v13, v1
	v_ashrrev_i16_sdwa v0, v3, sext(v0) dst_sel:DWORD dst_unused:UNUSED_PAD src0_sel:DWORD src1_sel:BYTE_0
	v_and_b32_e32 v3, 3, v13
	s_ashr_i32 s13, s12, 8
	v_and_or_b32 v3, v1, s2, v3
	s_cmpk_gt_i32 s33, 0x7f
	s_mul_i32 s2, s33, 3
	s_cselect_b64 s[4:5], -1, 0
	s_add_i32 s54, s2, 0xffffff00
	s_ashr_i32 s3, s54, 2
	s_lshl_b32 s55, s10, 10
	s_and_b32 s6, s2, 3
	s_cmpk_lt_i32 s33, 0x80
	s_cselect_b32 s2, s33, s3
	s_cselect_b32 s80, 4, s6
	s_ashr_i32 s3, s2, 31
	s_lshl_b64 s[6:7], s[2:3], 20
	s_lshl_b32 s3, s80, 20
	s_add_u32 s48, s52, s3
	v_lshlrev_b32_e32 v4, 5, v12
	v_bfe_i32 v14, v0, 0, 16
	v_lshlrev_b32_e32 v0, 1, v1
	v_lshrrev_b32_e32 v2, 2, v1
	s_addc_u32 s49, s53, 0
	s_add_i32 s56, s55, 0
	v_and_b32_e32 v4, 32, v4
	v_and_b32_e32 v0, 24, v0
	v_and_b32_e32 v2, 4, v2
	s_add_i32 m0, s56, 0x10000
	v_or3_b32 v0, v3, v2, v0
	v_add_lshl_u32 v2, v4, v14, 1
	global_load_lds_dwordx4 v134, s[48:49]
	s_add_i32 m0, s56, 0x12000
	v_lshl_add_u32 v138, v0, 12, v2
	s_add_u32 s8, s48, 0x80000
	global_load_lds_dwordx4 v138, s[48:49]
	s_addc_u32 s9, s49, 0
	s_add_i32 m0, s56, 0x14000
	v_lshl_add_u32 v136, v1, 12, v2
	global_load_lds_dwordx4 v134, s[8:9]
	s_add_i32 m0, s56, 0x16000
	s_add_u32 s46, s76, s6
	s_addc_u32 s47, s77, s7
	s_add_i32 s57, s56, 0x2000
	global_load_lds_dwordx4 v138, s[8:9]
	s_mov_b32 m0, s56
	s_add_u32 s6, s46, 0x80000
	global_load_lds_dwordx4 v132, s[46:47]
	s_mov_b32 m0, s57
	s_addc_u32 s7, s47, 0
	s_add_i32 s58, s56, 0x4000
	global_load_lds_dwordx4 v136, s[46:47]
	s_mov_b32 m0, s58
	s_add_i32 s59, s56, 0x6000
	global_load_lds_dwordx4 v132, s[6:7]
	s_mov_b32 m0, s59
	v_mov_b32_e32 v141, 0
	global_load_lds_dwordx4 v136, s[6:7]
	v_mov_b32_e32 v135, v141
	v_mov_b32_e32 v139, v141
	v_mov_b32_e32 v133, v141
	v_mov_b32_e32 v137, v141
	s_cmp_eq_u32 s13, 1
	s_mov_b32 s3, 0
	s_mov_b32 s60, 0x10000
	v_lshl_add_u64 v[4:5], s[48:49], 0, v[134:135]
	v_lshl_add_u64 v[0:1], s[48:49], 0, v[138:139]
	s_mov_b32 s61, 0x14000
	s_mov_b32 s62, 0x16000
	v_lshl_add_u64 v[2:3], s[46:47], 0, v[132:133]
	s_cselect_b64 s[6:7], -1, 0
	s_cmp_lg_u32 s13, 1
	v_lshl_add_u64 v[6:7], s[46:47], 0, v[136:137]
	s_setprio 1
	s_cbranch_scc1 .LBB0_328
	s_barrier
	s_setprio 0

.LBB0_340:
	ds_read_b128 v[128:131], v143
	ds_read_b128 v[150:153], v143 offset:1024
	ds_read_b128 v[154:157], v143 offset:2048
	ds_read_b128 v[164:167], v143 offset:3072
	ds_read_b128 v[168:171], v162
	ds_read_b128 v[172:175], v162 offset:1024
	ds_read_b128 v[176:179], v162 offset:2048
	ds_read_b128 v[180:183], v162 offset:3072
	s_add_i32 s86, s48, 2
	s_add_u32 s49, s46, 0xfff80080
	s_addc_u32 s50, s47, -1
	s_cmp_eq_u32 s83, s48
	s_cselect_b32 s48, s81, s84
	s_cselect_b32 s51, s3, s50
	s_cselect_b32 s50, s35, s49
	s_cselect_b32 s49, s37, s85
	s_add_i32 m0, s56, 0xc000
	ds_read_b128 v[184:187], v163
	ds_read_b128 v[188:191], v163 offset:1024
	ds_read_b128 v[192:195], v163 offset:2048
	ds_read_b128 v[196:199], v163 offset:3072
	ds_read_b128 v[200:203], v163 offset:4096
	ds_read_b128 v[204:207], v163 offset:5120
	ds_read_b128 v[208:211], v163 offset:6144
	ds_read_b128 v[212:215], v163 offset:7168
	global_load_lds_dwordx4 v146, s[46:47]
	s_add_i32 m0, s56, 0xe000
	s_nop 0
	global_load_lds_dwordx4 v148, s[46:47]
	s_waitcnt vmcnt(8)
	s_waitcnt lgkmcnt(0)
	s_barrier
	s_waitcnt lgkmcnt(0)
	v_mfma_f32_16x16x32_bf16 v[124:127], v[128:131], v[184:187], v[124:127]
	v_mfma_f32_16x16x32_bf16 v[120:123], v[154:157], v[184:187], v[120:123]
	v_mfma_f32_16x16x32_bf16 v[116:119], v[128:131], v[192:195], v[116:119]
	v_mfma_f32_16x16x32_bf16 v[108:111], v[154:157], v[192:195], v[108:111]
	v_mfma_f32_16x16x32_bf16 v[100:103], v[128:131], v[200:203], v[100:103]
	v_mfma_f32_16x16x32_bf16 v[92:95], v[154:157], v[200:203], v[92:95]
	v_mfma_f32_16x16x32_bf16 v[84:87], v[128:131], v[208:211], v[84:87]
	v_mfma_f32_16x16x32_bf16 v[76:79], v[154:157], v[208:211], v[76:79]
	v_mfma_f32_16x16x32_bf16 v[124:127], v[150:153], v[188:191], v[124:127]
	v_mfma_f32_16x16x32_bf16 v[120:123], v[164:167], v[188:191], v[120:123]
	v_mfma_f32_16x16x32_bf16 v[116:119], v[150:153], v[196:199], v[116:119]
	v_mfma_f32_16x16x32_bf16 v[108:111], v[164:167], v[196:199], v[108:111]
	v_mfma_f32_16x16x32_bf16 v[100:103], v[150:153], v[204:207], v[100:103]
	v_mfma_f32_16x16x32_bf16 v[92:95], v[164:167], v[204:207], v[92:95]
	v_mfma_f32_16x16x32_bf16 v[84:87], v[150:153], v[212:215], v[84:87]
	v_mfma_f32_16x16x32_bf16 v[76:79], v[164:167], v[212:215], v[76:79]
	v_mfma_f32_16x16x32_bf16 v[112:115], v[168:171], v[184:187], v[112:115]
	v_mfma_f32_16x16x32_bf16 v[104:107], v[176:179], v[184:187], v[104:107]
	v_mfma_f32_16x16x32_bf16 v[96:99], v[168:171], v[192:195], v[96:99]
	v_mfma_f32_16x16x32_bf16 v[88:91], v[176:179], v[192:195], v[88:91]
	v_mfma_f32_16x16x32_bf16 v[80:83], v[168:171], v[200:203], v[80:83]
	v_mfma_f32_16x16x32_bf16 v[72:75], v[176:179], v[200:203], v[72:75]
	v_mfma_f32_16x16x32_bf16 v[68:71], v[168:171], v[208:211], v[68:71]
	v_mfma_f32_16x16x32_bf16 v[64:67], v[176:179], v[208:211], v[64:67]
	v_mfma_f32_16x16x32_bf16 v[112:115], v[172:175], v[188:191], v[112:115]
	v_mfma_f32_16x16x32_bf16 v[104:107], v[180:183], v[188:191], v[104:107]
	v_mfma_f32_16x16x32_bf16 v[96:99], v[172:175], v[196:199], v[96:99]
	v_mfma_f32_16x16x32_bf16 v[88:91], v[180:183], v[196:199], v[88:91]
	v_mfma_f32_16x16x32_bf16 v[80:83], v[172:175], v[204:207], v[80:83]
	v_mfma_f32_16x16x32_bf16 v[72:75], v[180:183], v[204:207], v[72:75]
	v_mfma_f32_16x16x32_bf16 v[68:71], v[172:175], v[212:215], v[68:71]
	v_mfma_f32_16x16x32_bf16 v[64:67], v[180:183], v[212:215], v[64:67]
	s_barrier
	s_add_i32 s87, s65, s55
	v_lshl_add_u64 v[158:159], s[48:49], 0, v[134:135]
	s_mov_b32 m0, s87
	ds_read_b128 v[184:187], v163 offset:16384
	ds_read_b128 v[188:191], v163 offset:17408
	ds_read_b128 v[192:195], v163 offset:18432
	ds_read_b128 v[196:199], v163 offset:19456
	ds_read_b128 v[200:203], v163 offset:20480
	ds_read_b128 v[204:207], v163 offset:21504
	ds_read_b128 v[208:211], v163 offset:22528
	ds_read_b128 v[212:215], v163 offset:23552
	global_load_lds_dwordx4 v[158:159], off
	s_add_i32 m0, s87, 0x2000
	s_add_u32 s88, s48, 0x80000
	v_lshl_add_u64 v[216:217], s[48:49], 0, v[138:139]
	s_addc_u32 s89, s49, 0
	s_add_i32 s87, s66, s55
	global_load_lds_dwordx4 v[216:217], off
	s_mov_b32 m0, s87
	v_lshl_add_u64 v[220:221], s[50:51], 0, v[136:137]
	global_load_lds_dwordx4 v134, s[88:89]
	s_add_i32 m0, s87, 0x2000
	s_nop 0
	global_load_lds_dwordx4 v138, s[88:89]
	v_lshl_add_u64 v[218:219], s[50:51], 0, v[132:133]
	s_mov_b32 m0, s56
	s_nop 0
	global_load_lds_dwordx4 v[218:219], off
	s_mov_b32 m0, s57
	s_nop 0
	global_load_lds_dwordx4 v[220:221], off
	s_waitcnt vmcnt(8)
	s_waitcnt lgkmcnt(0)
	s_barrier
	s_waitcnt lgkmcnt(0)
	v_mfma_f32_16x16x32_bf16 v[60:63], v[128:131], v[184:187], v[60:63]
	v_mfma_f32_16x16x32_bf16 v[56:59], v[154:157], v[184:187], v[56:59]
	v_mfma_f32_16x16x32_bf16 v[52:55], v[128:131], v[192:195], v[52:55]
	v_mfma_f32_16x16x32_bf16 v[44:47], v[154:157], v[192:195], v[44:47]
	v_mfma_f32_16x16x32_bf16 v[36:39], v[128:131], v[200:203], v[36:39]
	v_mfma_f32_16x16x32_bf16 v[28:31], v[154:157], v[200:203], v[28:31]
	v_mfma_f32_16x16x32_bf16 v[20:23], v[128:131], v[208:211], v[20:23]
	v_mfma_f32_16x16x32_bf16 v[12:15], v[154:157], v[208:211], v[12:15]
	v_mfma_f32_16x16x32_bf16 v[60:63], v[150:153], v[188:191], v[60:63]
	v_mfma_f32_16x16x32_bf16 v[56:59], v[164:167], v[188:191], v[56:59]
	v_mfma_f32_16x16x32_bf16 v[52:55], v[150:153], v[196:199], v[52:55]
	v_mfma_f32_16x16x32_bf16 v[44:47], v[164:167], v[196:199], v[44:47]
	v_mfma_f32_16x16x32_bf16 v[36:39], v[150:153], v[204:207], v[36:39]
	v_mfma_f32_16x16x32_bf16 v[28:31], v[164:167], v[204:207], v[28:31]
	v_mfma_f32_16x16x32_bf16 v[20:23], v[150:153], v[212:215], v[20:23]
	v_mfma_f32_16x16x32_bf16 v[12:15], v[164:167], v[212:215], v[12:15]
	v_mfma_f32_16x16x32_bf16 v[48:51], v[168:171], v[184:187], v[48:51]
	v_mfma_f32_16x16x32_bf16 v[40:43], v[176:179], v[184:187], v[40:43]
	v_mfma_f32_16x16x32_bf16 v[32:35], v[168:171], v[192:195], v[32:35]
	v_mfma_f32_16x16x32_bf16 v[24:27], v[176:179], v[192:195], v[24:27]
	v_mfma_f32_16x16x32_bf16 v[16:19], v[168:171], v[200:203], v[16:19]
	v_mfma_f32_16x16x32_bf16 v[8:11], v[176:179], v[200:203], v[8:11]
	v_mfma_f32_16x16x32_bf16 v[4:7], v[168:171], v[208:211], v[4:7]
	v_mfma_f32_16x16x32_bf16 v[0:3], v[176:179], v[208:211], v[0:3]
	v_mfma_f32_16x16x32_bf16 v[48:51], v[172:175], v[188:191], v[48:51]
	v_mfma_f32_16x16x32_bf16 v[40:43], v[180:183], v[188:191], v[40:43]
	v_mfma_f32_16x16x32_bf16 v[32:35], v[172:175], v[196:199], v[32:35]
	v_mfma_f32_16x16x32_bf16 v[24:27], v[180:183], v[196:199], v[24:27]
	v_mfma_f32_16x16x32_bf16 v[16:19], v[172:175], v[204:207], v[16:19]
	v_mfma_f32_16x16x32_bf16 v[8:11], v[180:183], v[204:207], v[8:11]
	v_mfma_f32_16x16x32_bf16 v[4:7], v[172:175], v[212:215], v[4:7]
	v_mfma_f32_16x16x32_bf16 v[0:3], v[180:183], v[212:215], v[0:3]
	s_barrier
	s_add_i32 s87, 0, 0x18000
	v_add_u32_e32 v140, s87, v161
	s_add_i32 s88, 0, 0x1c000
	ds_read_b128 v[128:131], v140
	ds_read_b128 v[150:153], v140 offset:1024
	ds_read_b128 v[154:157], v140 offset:2048
	ds_read_b128 v[164:167], v140 offset:3072
	v_add_u32_e32 v140, s88, v161
	ds_read_b128 v[168:171], v140
	ds_read_b128 v[172:175], v140 offset:1024
	ds_read_b128 v[176:179], v140 offset:2048
	ds_read_b128 v[180:183], v140 offset:3072
	s_add_u32 s50, s50, 0x80000
	s_addc_u32 s51, s51, 0
	s_mov_b32 m0, s58
	ds_read_b128 v[184:187], v163 offset:32768
	ds_read_b128 v[188:191], v163 offset:33792
	ds_read_b128 v[192:195], v163 offset:34816
	ds_read_b128 v[196:199], v163 offset:35840
	ds_read_b128 v[200:203], v163 offset:36864
	ds_read_b128 v[204:207], v163 offset:37888
	ds_read_b128 v[208:211], v163 offset:38912
	ds_read_b128 v[212:215], v163 offset:39936
	global_load_lds_dwordx4 v132, s[50:51]
	v_lshl_add_u64 v[222:223], s[50:51], 0, v[136:137]
	s_mov_b32 m0, s59
	s_nop 0
	global_load_lds_dwordx4 v[222:223], off
	s_waitcnt vmcnt(8)
	s_waitcnt lgkmcnt(0)
	s_barrier
	s_waitcnt lgkmcnt(0)
	v_mfma_f32_16x16x32_bf16 v[124:127], v[128:131], v[184:187], v[124:127]
	v_mfma_f32_16x16x32_bf16 v[120:123], v[154:157], v[184:187], v[120:123]
	v_mfma_f32_16x16x32_bf16 v[116:119], v[128:131], v[192:195], v[116:119]
	v_mfma_f32_16x16x32_bf16 v[108:111], v[154:157], v[192:195], v[108:111]
	v_mfma_f32_16x16x32_bf16 v[100:103], v[128:131], v[200:203], v[100:103]
	v_mfma_f32_16x16x32_bf16 v[92:95], v[154:157], v[200:203], v[92:95]
	v_mfma_f32_16x16x32_bf16 v[84:87], v[128:131], v[208:211], v[84:87]
	v_mfma_f32_16x16x32_bf16 v[76:79], v[154:157], v[208:211], v[76:79]
	v_mfma_f32_16x16x32_bf16 v[124:127], v[150:153], v[188:191], v[124:127]
	v_mfma_f32_16x16x32_bf16 v[120:123], v[164:167], v[188:191], v[120:123]
	v_mfma_f32_16x16x32_bf16 v[116:119], v[150:153], v[196:199], v[116:119]
	v_mfma_f32_16x16x32_bf16 v[108:111], v[164:167], v[196:199], v[108:111]
	v_mfma_f32_16x16x32_bf16 v[100:103], v[150:153], v[204:207], v[100:103]
	v_mfma_f32_16x16x32_bf16 v[92:95], v[164:167], v[204:207], v[92:95]
	v_mfma_f32_16x16x32_bf16 v[84:87], v[150:153], v[212:215], v[84:87]
	v_mfma_f32_16x16x32_bf16 v[76:79], v[164:167], v[212:215], v[76:79]
	v_mfma_f32_16x16x32_bf16 v[112:115], v[168:171], v[184:187], v[112:115]
	v_mfma_f32_16x16x32_bf16 v[104:107], v[176:179], v[184:187], v[104:107]
	v_mfma_f32_16x16x32_bf16 v[96:99], v[168:171], v[192:195], v[96:99]
	v_mfma_f32_16x16x32_bf16 v[88:91], v[176:179], v[192:195], v[88:91]
	v_mfma_f32_16x16x32_bf16 v[80:83], v[168:171], v[200:203], v[80:83]
	v_mfma_f32_16x16x32_bf16 v[72:75], v[176:179], v[200:203], v[72:75]
	v_mfma_f32_16x16x32_bf16 v[68:71], v[168:171], v[208:211], v[68:71]
	v_mfma_f32_16x16x32_bf16 v[64:67], v[176:179], v[208:211], v[64:67]
	v_mfma_f32_16x16x32_bf16 v[112:115], v[172:175], v[188:191], v[112:115]
	v_mfma_f32_16x16x32_bf16 v[104:107], v[180:183], v[188:191], v[104:107]
	v_mfma_f32_16x16x32_bf16 v[96:99], v[172:175], v[196:199], v[96:99]
	v_mfma_f32_16x16x32_bf16 v[88:91], v[180:183], v[196:199], v[88:91]
	v_mfma_f32_16x16x32_bf16 v[80:83], v[172:175], v[204:207], v[80:83]
	v_mfma_f32_16x16x32_bf16 v[72:75], v[180:183], v[204:207], v[72:75]
	v_mfma_f32_16x16x32_bf16 v[68:71], v[172:175], v[212:215], v[68:71]
	v_mfma_f32_16x16x32_bf16 v[64:67], v[180:183], v[212:215], v[64:67]
	s_barrier
	s_add_i32 s50, s87, s55
	v_lshl_add_u64 v[158:159], v[158:159], 0, s[10:11]
	s_mov_b32 m0, s50
	ds_read_b128 v[184:187], v163 offset:49152
	ds_read_b128 v[188:191], v163 offset:50176
	ds_read_b128 v[192:195], v163 offset:51200
	ds_read_b128 v[196:199], v163 offset:52224
	ds_read_b128 v[200:203], v163 offset:53248
	ds_read_b128 v[204:207], v163 offset:54272
	ds_read_b128 v[208:211], v163 offset:55296
	ds_read_b128 v[212:215], v163 offset:56320
	global_load_lds_dwordx4 v[158:159], off
	s_add_i32 m0, s50, 0x2000
	s_add_u32 s48, s48, 0x80080
	v_lshl_add_u64 v[158:159], v[216:217], 0, s[10:11]
	s_addc_u32 s49, s49, 0
	s_add_i32 s50, s88, s55
	global_load_lds_dwordx4 v[158:159], off
	s_mov_b32 m0, s50
	s_nop 0
	global_load_lds_dwordx4 v134, s[48:49]
	s_add_i32 m0, s50, 0x2000
	s_nop 0
	global_load_lds_dwordx4 v138, s[48:49]
	v_lshl_add_u64 v[158:159], v[218:219], 0, s[10:11]
	s_mov_b32 m0, s63
	s_nop 0
	global_load_lds_dwordx4 v[158:159], off
	v_lshl_add_u64 v[158:159], v[220:221], 0, s[10:11]
	s_mov_b32 m0, s64
	s_nop 0
	global_load_lds_dwordx4 v[158:159], off
	s_waitcnt vmcnt(8)
	s_waitcnt lgkmcnt(0)
	s_barrier
	s_waitcnt lgkmcnt(0)
	v_mfma_f32_16x16x32_bf16 v[60:63], v[128:131], v[184:187], v[60:63]
	v_mfma_f32_16x16x32_bf16 v[56:59], v[154:157], v[184:187], v[56:59]
	v_mfma_f32_16x16x32_bf16 v[52:55], v[128:131], v[192:195], v[52:55]
	v_mfma_f32_16x16x32_bf16 v[44:47], v[154:157], v[192:195], v[44:47]
	v_mfma_f32_16x16x32_bf16 v[36:39], v[128:131], v[200:203], v[36:39]
	v_mfma_f32_16x16x32_bf16 v[28:31], v[154:157], v[200:203], v[28:31]
	v_mfma_f32_16x16x32_bf16 v[20:23], v[128:131], v[208:211], v[20:23]
	v_mfma_f32_16x16x32_bf16 v[12:15], v[154:157], v[208:211], v[12:15]
	v_mfma_f32_16x16x32_bf16 v[60:63], v[150:153], v[188:191], v[60:63]
	v_mfma_f32_16x16x32_bf16 v[56:59], v[164:167], v[188:191], v[56:59]
	v_mfma_f32_16x16x32_bf16 v[52:55], v[150:153], v[196:199], v[52:55]
	v_mfma_f32_16x16x32_bf16 v[44:47], v[164:167], v[196:199], v[44:47]
	v_mfma_f32_16x16x32_bf16 v[36:39], v[150:153], v[204:207], v[36:39]
	v_mfma_f32_16x16x32_bf16 v[28:31], v[164:167], v[204:207], v[28:31]
	v_mfma_f32_16x16x32_bf16 v[20:23], v[150:153], v[212:215], v[20:23]
	v_mfma_f32_16x16x32_bf16 v[12:15], v[164:167], v[212:215], v[12:15]
	v_mfma_f32_16x16x32_bf16 v[48:51], v[168:171], v[184:187], v[48:51]
	v_mfma_f32_16x16x32_bf16 v[40:43], v[176:179], v[184:187], v[40:43]
	v_mfma_f32_16x16x32_bf16 v[32:35], v[168:171], v[192:195], v[32:35]
	v_mfma_f32_16x16x32_bf16 v[24:27], v[176:179], v[192:195], v[24:27]
	v_mfma_f32_16x16x32_bf16 v[16:19], v[168:171], v[200:203], v[16:19]
	v_mfma_f32_16x16x32_bf16 v[8:11], v[176:179], v[200:203], v[8:11]
	v_mfma_f32_16x16x32_bf16 v[4:7], v[168:171], v[208:211], v[4:7]
	v_mfma_f32_16x16x32_bf16 v[0:3], v[176:179], v[208:211], v[0:3]
	v_mfma_f32_16x16x32_bf16 v[48:51], v[172:175], v[188:191], v[48:51]
	v_mfma_f32_16x16x32_bf16 v[40:43], v[180:183], v[188:191], v[40:43]
	v_mfma_f32_16x16x32_bf16 v[32:35], v[172:175], v[196:199], v[32:35]
	v_mfma_f32_16x16x32_bf16 v[24:27], v[180:183], v[196:199], v[24:27]
	v_mfma_f32_16x16x32_bf16 v[16:19], v[172:175], v[204:207], v[16:19]
	v_mfma_f32_16x16x32_bf16 v[8:11], v[180:183], v[204:207], v[8:11]
	v_mfma_f32_16x16x32_bf16 v[4:7], v[172:175], v[212:215], v[4:7]
	v_mfma_f32_16x16x32_bf16 v[0:3], v[180:183], v[212:215], v[0:3]
	s_add_u32 s46, s46, 0x100
	s_addc_u32 s47, s47, 0
	s_add_u32 s84, s84, 0x100
	s_addc_u32 s85, s85, 0
	s_cmp_ge_u32 s86, s82
	s_mov_b32 s48, s86
	s_barrier
	s_cbranch_scc0 .LBB0_340
	s_and_b64 vcc, exec, s[12:13]
	s_cbranch_vccz .LBB0_343
	s_barrier

.LBB0_404:
	v_ashrrev_i32_e32 v2, 31, v0
	v_lshrrev_b32_e32 v2, 26, v2
	v_lshlrev_b32_e32 v1, 4, v0
	v_add_u32_e32 v2, v0, v2
	v_bfe_i32 v0, v0, 27, 1
	v_lshrrev_b32_e32 v0, 22, v0
	v_add_u32_e32 v0, v1, v0
	v_and_b32_e32 v0, 0xfffffc00, v0
	v_sub_u32_e32 v0, v1, v0
	v_ashrrev_i32_e32 v9, 6, v2
	v_lshrrev_b32_e32 v2, 4, v0
	v_bitop3_b32 v0, v2, v0, 32 bitop3:0x6c
	v_ashrrev_i32_e32 v3, 31, v0
	v_lshrrev_b32_e32 v3, 26, v3
	v_add_u32_e32 v3, v0, v3
	v_lshlrev_b32_e32 v2, 3, v9
	v_ashrrev_i32_e32 v10, 6, v3
	v_and_b32_e32 v3, 0xc0, v3
	v_and_b32_e32 v2, -16, v2
	v_sub_u32_e32 v0, v0, v3
	v_mov_b32_e32 v3, 1
	v_add_u32_e32 v2, v10, v2
	v_ashrrev_i16_sdwa v0, v3, sext(v0) dst_sel:DWORD dst_unused:UNUSED_PAD src0_sel:DWORD src1_sel:BYTE_0
	s_ashr_i32 s2, s7, 3
	v_lshlrev_b32_e32 v4, 5, v9
	v_bfe_i32 v11, v0, 0, 16
	v_lshlrev_b32_e32 v0, 1, v2
	v_lshrrev_b32_e32 v5, 2, v2
	v_and_b32_e32 v6, 3, v10
	s_mov_b32 s7, 0x1fffe0
	v_and_b32_e32 v4, 32, v4
	v_and_b32_e32 v0, 24, v0
	v_and_b32_e32 v5, 4, v5
	v_and_or_b32 v6, v2, s7, v6
	v_or3_b32 v0, v6, v5, v0
	v_add_lshl_u32 v4, v4, v11, 1
	v_lshl_add_u32 v130, v0, 11, v4
	v_add_u32_e32 v0, 0x2000, v1
	v_ashrrev_i32_e32 v1, 31, v0
	v_lshrrev_b32_e32 v1, 22, v1
	v_add_u32_e32 v1, v0, v1
	v_ashrrev_i32_e32 v12, 10, v1
	v_mul_i32_i24_e32 v1, 0x400, v12
	v_sub_u32_e32 v0, v0, v1
	v_lshrrev_b32_e32 v1, 4, v0
	s_add_u32 s39, s70, 0xdc00000
	v_bitop3_b32 v0, v1, v0, 32 bitop3:0x6c
	s_addc_u32 s40, s71, 0
	v_lshl_add_u32 v128, v2, 11, v4
	v_ashrrev_i32_e32 v2, 31, v0
	s_add_u32 s41, s70, 0x4c00000
	v_lshrrev_b32_e32 v2, 26, v2
	s_addc_u32 s42, s71, 0
	v_add_u32_e32 v2, v0, v2
	s_add_i32 s2, s6, s2
	v_lshlrev_b32_e32 v1, 3, v12
	v_ashrrev_i32_e32 v13, 6, v2
	v_and_b32_e32 v2, 0xc0, v2
	s_ashr_i32 s6, s2, 31
	v_and_b32_e32 v1, -16, v1
	v_sub_u32_e32 v0, v0, v2
	s_lshr_b32 s6, s6, 27
	v_add_u32_e32 v1, v13, v1
	v_ashrrev_i16_sdwa v0, v3, sext(v0) dst_sel:DWORD dst_unused:UNUSED_PAD src0_sel:DWORD src1_sel:BYTE_0
	v_and_b32_e32 v3, 3, v13
	s_add_i32 s6, s2, s6
	v_and_or_b32 v3, v1, s7, v3
	s_ashr_i32 s7, s6, 5
	s_andn2_b32 s6, s6, 31
	s_sub_i32 s6, s2, s6
	s_bfe_i32 s2, s6, 0x80000
	s_bfe_u32 s2, s2, 0x3000c
	s_add_i32 s8, s6, s2
	s_bfe_i32 s2, s8, 0x80000
	s_and_b32 s8, s8, 0xf8
	s_sub_i32 s6, s6, s8
	s_lshl_b32 s7, s7, 3
	s_sext_i32_i16 s2, s2
	s_sext_i32_i8 s6, s6
	s_ashr_i32 s3, s12, 8
	s_lshr_b32 s2, s2, 3
	s_add_i32 s28, s7, s6
	s_ashr_i32 s10, s12, 6
	s_ashr_i32 s29, s28, 31
	s_bfe_i64 s[8:9], s[2:3], 0x100000
	s_lshl_b32 s43, s10, 10
	s_lshl_b64 s[6:7], s[28:29], 19
	s_lshl_b64 s[8:9], s[8:9], 19
	s_add_u32 s34, s41, s8
	v_lshlrev_b32_e32 v4, 5, v12
	v_bfe_i32 v14, v0, 0, 16
	v_lshlrev_b32_e32 v0, 1, v1
	v_lshrrev_b32_e32 v2, 2, v1
	s_addc_u32 s35, s42, s9
	s_add_i32 s29, s43, 0
	v_and_b32_e32 v4, 32, v4
	v_and_b32_e32 v0, 24, v0
	v_and_b32_e32 v2, 4, v2
	s_add_i32 m0, s29, 0x10000
	v_or3_b32 v0, v3, v2, v0
	v_add_lshl_u32 v2, v4, v14, 1
	global_load_lds_dwordx4 v130, s[34:35]
	s_add_i32 m0, s29, 0x12000
	v_lshl_add_u32 v134, v0, 11, v2
	s_add_u32 s8, s34, 0x40000
	global_load_lds_dwordx4 v134, s[34:35]
	s_addc_u32 s9, s35, 0
	s_add_i32 m0, s29, 0x14000
	v_lshl_add_u32 v132, v1, 11, v2
	global_load_lds_dwordx4 v130, s[8:9]
	s_add_i32 m0, s29, 0x16000
	s_add_u32 s30, s39, s6
	s_addc_u32 s31, s40, s7
	s_add_i32 s44, s29, 0x2000
	global_load_lds_dwordx4 v134, s[8:9]
	s_mov_b32 m0, s29
	s_add_u32 s6, s30, 0x40000
	global_load_lds_dwordx4 v128, s[30:31]
	s_mov_b32 m0, s44
	s_addc_u32 s7, s31, 0
	s_add_i32 s45, s29, 0x4000
	global_load_lds_dwordx4 v132, s[30:31]
	s_mov_b32 m0, s45
	s_add_i32 s46, s29, 0x6000
	global_load_lds_dwordx4 v128, s[6:7]
	s_mov_b32 m0, s46
	v_mov_b32_e32 v131, 0
	global_load_lds_dwordx4 v132, s[6:7]
	v_mov_b32_e32 v135, v131
	v_mov_b32_e32 v129, v131
	v_mov_b32_e32 v133, v131
	s_cmp_eq_u32 s3, 1
	s_mov_b32 s47, 0
	v_lshl_add_u64 v[6:7], s[34:35], 0, v[130:131]
	v_lshl_add_u64 v[2:3], s[34:35], 0, v[134:135]
	s_mov_b64 s[6:7], 0x40000
	v_lshl_add_u64 v[0:1], s[30:31], 0, v[128:129]
	s_cselect_b64 s[8:9], -1, 0
	s_cmp_lg_u32 s3, 1
	v_lshl_add_u64 v[4:5], s[30:31], 0, v[132:133]
	s_setprio 1
	s_cbranch_scc1 .LBB0_406
	s_barrier
	s_setprio 0

.LBB0_416:
	ds_read_b128 v[152:155], v149
	ds_read_b128 v[156:159], v149 offset:1024
	ds_read_b128 v[160:163], v149 offset:2048
	ds_read_b128 v[164:167], v149 offset:3072
	ds_read_b128 v[168:171], v150
	ds_read_b128 v[172:175], v150 offset:1024
	ds_read_b128 v[176:179], v150 offset:2048
	ds_read_b128 v[180:183], v150 offset:3072
	s_add_u32 s34, s30, 0xfffc0080
	s_addc_u32 s35, s31, -1
	s_cmp_eq_u32 s62, 12
	s_cselect_b32 s37, s23, s35
	s_cselect_b32 s36, s58, s34
	s_cselect_b32 s35, s21, s61
	s_cselect_b32 s34, s59, s60
	s_add_i32 m0, s29, 0xc000
	ds_read_b128 v[184:187], v151
	ds_read_b128 v[188:191], v151 offset:1024
	ds_read_b128 v[192:195], v151 offset:2048
	ds_read_b128 v[196:199], v151 offset:3072
	ds_read_b128 v[200:203], v151 offset:4096
	ds_read_b128 v[204:207], v151 offset:5120
	ds_read_b128 v[208:211], v151 offset:6144
	ds_read_b128 v[212:215], v151 offset:7168
	global_load_lds_dwordx4 v136, s[30:31]
	s_add_i32 m0, s29, 0xe000
	s_nop 0
	global_load_lds_dwordx4 v138, s[30:31]
	s_waitcnt vmcnt(8)
	s_waitcnt lgkmcnt(0)
	s_barrier
	s_waitcnt lgkmcnt(0)
	v_mfma_f32_16x16x32_bf16 v[124:127], v[152:155], v[184:187], v[124:127]
	v_mfma_f32_16x16x32_bf16 v[120:123], v[160:163], v[184:187], v[120:123]
	v_mfma_f32_16x16x32_bf16 v[116:119], v[152:155], v[192:195], v[116:119]
	v_mfma_f32_16x16x32_bf16 v[108:111], v[160:163], v[192:195], v[108:111]
	v_mfma_f32_16x16x32_bf16 v[100:103], v[152:155], v[200:203], v[100:103]
	v_mfma_f32_16x16x32_bf16 v[92:95], v[160:163], v[200:203], v[92:95]
	v_mfma_f32_16x16x32_bf16 v[84:87], v[152:155], v[208:211], v[84:87]
	v_mfma_f32_16x16x32_bf16 v[76:79], v[160:163], v[208:211], v[76:79]
	v_mfma_f32_16x16x32_bf16 v[124:127], v[156:159], v[188:191], v[124:127]
	v_mfma_f32_16x16x32_bf16 v[120:123], v[164:167], v[188:191], v[120:123]
	v_mfma_f32_16x16x32_bf16 v[116:119], v[156:159], v[196:199], v[116:119]
	v_mfma_f32_16x16x32_bf16 v[108:111], v[164:167], v[196:199], v[108:111]
	v_mfma_f32_16x16x32_bf16 v[100:103], v[156:159], v[204:207], v[100:103]
	v_mfma_f32_16x16x32_bf16 v[92:95], v[164:167], v[204:207], v[92:95]
	v_mfma_f32_16x16x32_bf16 v[84:87], v[156:159], v[212:215], v[84:87]
	v_mfma_f32_16x16x32_bf16 v[76:79], v[164:167], v[212:215], v[76:79]
	v_mfma_f32_16x16x32_bf16 v[112:115], v[168:171], v[184:187], v[112:115]
	v_mfma_f32_16x16x32_bf16 v[104:107], v[176:179], v[184:187], v[104:107]
	v_mfma_f32_16x16x32_bf16 v[96:99], v[168:171], v[192:195], v[96:99]
	v_mfma_f32_16x16x32_bf16 v[88:91], v[176:179], v[192:195], v[88:91]
	v_mfma_f32_16x16x32_bf16 v[80:83], v[168:171], v[200:203], v[80:83]
	v_mfma_f32_16x16x32_bf16 v[72:75], v[176:179], v[200:203], v[72:75]
	v_mfma_f32_16x16x32_bf16 v[68:71], v[168:171], v[208:211], v[68:71]
	v_mfma_f32_16x16x32_bf16 v[64:67], v[176:179], v[208:211], v[64:67]
	v_mfma_f32_16x16x32_bf16 v[112:115], v[172:175], v[188:191], v[112:115]
	v_mfma_f32_16x16x32_bf16 v[104:107], v[180:183], v[188:191], v[104:107]
	v_mfma_f32_16x16x32_bf16 v[96:99], v[172:175], v[196:199], v[96:99]
	v_mfma_f32_16x16x32_bf16 v[88:91], v[180:183], v[196:199], v[88:91]
	v_mfma_f32_16x16x32_bf16 v[80:83], v[172:175], v[204:207], v[80:83]
	v_mfma_f32_16x16x32_bf16 v[72:75], v[180:183], v[204:207], v[72:75]
	v_mfma_f32_16x16x32_bf16 v[68:71], v[172:175], v[212:215], v[68:71]
	v_mfma_f32_16x16x32_bf16 v[64:67], v[180:183], v[212:215], v[64:67]
	s_barrier
	s_add_i32 s63, s51, s43
	v_lshl_add_u64 v[144:145], s[34:35], 0, v[130:131]
	s_mov_b32 m0, s63
	ds_read_b128 v[184:187], v151 offset:16384
	ds_read_b128 v[188:191], v151 offset:17408
	ds_read_b128 v[192:195], v151 offset:18432
	ds_read_b128 v[196:199], v151 offset:19456
	ds_read_b128 v[200:203], v151 offset:20480
	ds_read_b128 v[204:207], v151 offset:21504
	ds_read_b128 v[208:211], v151 offset:22528
	ds_read_b128 v[212:215], v151 offset:23552
	global_load_lds_dwordx4 v[144:145], off
	s_add_i32 m0, s63, 0x2000
	s_add_u32 s64, s34, 0x40000
	v_lshl_add_u64 v[216:217], s[34:35], 0, v[134:135]
	s_addc_u32 s65, s35, 0
	s_add_i32 s63, s52, s43
	global_load_lds_dwordx4 v[216:217], off
	v_lshl_add_u64 v[218:219], s[64:65], 0, v[130:131]
	s_mov_b32 m0, s63
	v_lshl_add_u64 v[220:221], s[36:37], 0, v[132:133]
	global_load_lds_dwordx4 v[218:219], off
	s_add_i32 m0, s63, 0x2000
	s_nop 0
	global_load_lds_dwordx4 v134, s[64:65]
	v_lshl_add_u64 v[218:219], s[36:37], 0, v[128:129]
	s_mov_b32 m0, s29
	s_nop 0
	global_load_lds_dwordx4 v[218:219], off
	s_mov_b32 m0, s44
	s_nop 0
	global_load_lds_dwordx4 v[220:221], off
	s_waitcnt vmcnt(8)
	s_waitcnt lgkmcnt(0)
	s_barrier
	s_waitcnt lgkmcnt(0)
	v_mfma_f32_16x16x32_bf16 v[60:63], v[152:155], v[184:187], v[60:63]
	v_mfma_f32_16x16x32_bf16 v[56:59], v[160:163], v[184:187], v[56:59]
	v_mfma_f32_16x16x32_bf16 v[52:55], v[152:155], v[192:195], v[52:55]
	v_mfma_f32_16x16x32_bf16 v[44:47], v[160:163], v[192:195], v[44:47]
	v_mfma_f32_16x16x32_bf16 v[36:39], v[152:155], v[200:203], v[36:39]
	v_mfma_f32_16x16x32_bf16 v[28:31], v[160:163], v[200:203], v[28:31]
	v_mfma_f32_16x16x32_bf16 v[20:23], v[152:155], v[208:211], v[20:23]
	v_mfma_f32_16x16x32_bf16 v[12:15], v[160:163], v[208:211], v[12:15]
	v_mfma_f32_16x16x32_bf16 v[60:63], v[156:159], v[188:191], v[60:63]
	v_mfma_f32_16x16x32_bf16 v[56:59], v[164:167], v[188:191], v[56:59]
	v_mfma_f32_16x16x32_bf16 v[52:55], v[156:159], v[196:199], v[52:55]
	v_mfma_f32_16x16x32_bf16 v[44:47], v[164:167], v[196:199], v[44:47]
	v_mfma_f32_16x16x32_bf16 v[36:39], v[156:159], v[204:207], v[36:39]
	v_mfma_f32_16x16x32_bf16 v[28:31], v[164:167], v[204:207], v[28:31]
	v_mfma_f32_16x16x32_bf16 v[20:23], v[156:159], v[212:215], v[20:23]
	v_mfma_f32_16x16x32_bf16 v[12:15], v[164:167], v[212:215], v[12:15]
	v_mfma_f32_16x16x32_bf16 v[48:51], v[168:171], v[184:187], v[48:51]
	v_mfma_f32_16x16x32_bf16 v[40:43], v[176:179], v[184:187], v[40:43]
	v_mfma_f32_16x16x32_bf16 v[32:35], v[168:171], v[192:195], v[32:35]
	v_mfma_f32_16x16x32_bf16 v[24:27], v[176:179], v[192:195], v[24:27]
	v_mfma_f32_16x16x32_bf16 v[16:19], v[168:171], v[200:203], v[16:19]
	v_mfma_f32_16x16x32_bf16 v[8:11], v[176:179], v[200:203], v[8:11]
	v_mfma_f32_16x16x32_bf16 v[4:7], v[168:171], v[208:211], v[4:7]
	v_mfma_f32_16x16x32_bf16 v[0:3], v[176:179], v[208:211], v[0:3]
	v_mfma_f32_16x16x32_bf16 v[48:51], v[172:175], v[188:191], v[48:51]
	v_mfma_f32_16x16x32_bf16 v[40:43], v[180:183], v[188:191], v[40:43]
	v_mfma_f32_16x16x32_bf16 v[32:35], v[172:175], v[196:199], v[32:35]
	v_mfma_f32_16x16x32_bf16 v[24:27], v[180:183], v[196:199], v[24:27]
	v_mfma_f32_16x16x32_bf16 v[16:19], v[172:175], v[204:207], v[16:19]
	v_mfma_f32_16x16x32_bf16 v[8:11], v[180:183], v[204:207], v[8:11]
	v_mfma_f32_16x16x32_bf16 v[4:7], v[172:175], v[212:215], v[4:7]
	v_mfma_f32_16x16x32_bf16 v[0:3], v[180:183], v[212:215], v[0:3]
	s_barrier
	s_add_i32 s63, 0, 0x18000
	s_add_i32 s64, 0, 0x1c000
	v_add_u32_e32 v164, s63, v147
	v_add_u32_e32 v180, s64, v147
	ds_read_b128 v[152:155], v164
	ds_read_b128 v[156:159], v164 offset:1024
	ds_read_b128 v[160:163], v164 offset:2048
	ds_read_b128 v[164:167], v164 offset:3072
	ds_read_b128 v[168:171], v180
	ds_read_b128 v[172:175], v180 offset:1024
	ds_read_b128 v[176:179], v180 offset:2048
	ds_read_b128 v[180:183], v180 offset:3072
	s_add_u32 s36, s36, 0x40000
	s_addc_u32 s37, s37, 0
	s_mov_b32 m0, s45
	ds_read_b128 v[184:187], v151 offset:32768
	ds_read_b128 v[188:191], v151 offset:33792
	ds_read_b128 v[192:195], v151 offset:34816
	ds_read_b128 v[196:199], v151 offset:35840
	ds_read_b128 v[200:203], v151 offset:36864
	ds_read_b128 v[204:207], v151 offset:37888
	ds_read_b128 v[208:211], v151 offset:38912
	ds_read_b128 v[212:215], v151 offset:39936
	global_load_lds_dwordx4 v128, s[36:37]
	v_lshl_add_u64 v[222:223], s[36:37], 0, v[132:133]
	s_mov_b32 m0, s46
	s_nop 0
	global_load_lds_dwordx4 v[222:223], off
	s_waitcnt vmcnt(8)
	s_waitcnt lgkmcnt(0)
	s_barrier
	s_waitcnt lgkmcnt(0)
	v_mfma_f32_16x16x32_bf16 v[124:127], v[152:155], v[184:187], v[124:127]
	v_mfma_f32_16x16x32_bf16 v[120:123], v[160:163], v[184:187], v[120:123]
	v_mfma_f32_16x16x32_bf16 v[116:119], v[152:155], v[192:195], v[116:119]
	v_mfma_f32_16x16x32_bf16 v[108:111], v[160:163], v[192:195], v[108:111]
	v_mfma_f32_16x16x32_bf16 v[100:103], v[152:155], v[200:203], v[100:103]
	v_mfma_f32_16x16x32_bf16 v[92:95], v[160:163], v[200:203], v[92:95]
	v_mfma_f32_16x16x32_bf16 v[84:87], v[152:155], v[208:211], v[84:87]
	v_mfma_f32_16x16x32_bf16 v[76:79], v[160:163], v[208:211], v[76:79]
	v_mfma_f32_16x16x32_bf16 v[124:127], v[156:159], v[188:191], v[124:127]
	v_mfma_f32_16x16x32_bf16 v[120:123], v[164:167], v[188:191], v[120:123]
	v_mfma_f32_16x16x32_bf16 v[116:119], v[156:159], v[196:199], v[116:119]
	v_mfma_f32_16x16x32_bf16 v[108:111], v[164:167], v[196:199], v[108:111]
	v_mfma_f32_16x16x32_bf16 v[100:103], v[156:159], v[204:207], v[100:103]
	v_mfma_f32_16x16x32_bf16 v[92:95], v[164:167], v[204:207], v[92:95]
	v_mfma_f32_16x16x32_bf16 v[84:87], v[156:159], v[212:215], v[84:87]
	v_mfma_f32_16x16x32_bf16 v[76:79], v[164:167], v[212:215], v[76:79]
	v_mfma_f32_16x16x32_bf16 v[112:115], v[168:171], v[184:187], v[112:115]
	v_mfma_f32_16x16x32_bf16 v[104:107], v[176:179], v[184:187], v[104:107]
	v_mfma_f32_16x16x32_bf16 v[96:99], v[168:171], v[192:195], v[96:99]
	v_mfma_f32_16x16x32_bf16 v[88:91], v[176:179], v[192:195], v[88:91]
	v_mfma_f32_16x16x32_bf16 v[80:83], v[168:171], v[200:203], v[80:83]
	v_mfma_f32_16x16x32_bf16 v[72:75], v[176:179], v[200:203], v[72:75]
	v_mfma_f32_16x16x32_bf16 v[68:71], v[168:171], v[208:211], v[68:71]
	v_mfma_f32_16x16x32_bf16 v[64:67], v[176:179], v[208:211], v[64:67]
	v_mfma_f32_16x16x32_bf16 v[112:115], v[172:175], v[188:191], v[112:115]
	v_mfma_f32_16x16x32_bf16 v[104:107], v[180:183], v[188:191], v[104:107]
	v_mfma_f32_16x16x32_bf16 v[96:99], v[172:175], v[196:199], v[96:99]
	v_mfma_f32_16x16x32_bf16 v[88:91], v[180:183], v[196:199], v[88:91]
	v_mfma_f32_16x16x32_bf16 v[80:83], v[172:175], v[204:207], v[80:83]
	v_mfma_f32_16x16x32_bf16 v[72:75], v[180:183], v[204:207], v[72:75]
	v_mfma_f32_16x16x32_bf16 v[68:71], v[172:175], v[212:215], v[68:71]
	v_mfma_f32_16x16x32_bf16 v[64:67], v[180:183], v[212:215], v[64:67]
	s_barrier
	s_add_i32 s36, s63, s43
	v_lshl_add_u64 v[144:145], v[144:145], 0, s[10:11]
	s_mov_b32 m0, s36
	ds_read_b128 v[184:187], v151 offset:49152
	ds_read_b128 v[188:191], v151 offset:50176
	ds_read_b128 v[192:195], v151 offset:51200
	ds_read_b128 v[196:199], v151 offset:52224
	ds_read_b128 v[200:203], v151 offset:53248
	ds_read_b128 v[204:207], v151 offset:54272
	ds_read_b128 v[208:211], v151 offset:55296
	ds_read_b128 v[212:215], v151 offset:56320
	global_load_lds_dwordx4 v[144:145], off
	s_add_i32 m0, s36, 0x2000
	s_add_u32 s34, s34, 0x40080
	v_lshl_add_u64 v[144:145], v[216:217], 0, s[10:11]
	s_addc_u32 s35, s35, 0
	s_add_i32 s36, s64, s43
	global_load_lds_dwordx4 v[144:145], off
	v_lshl_add_u64 v[144:145], s[34:35], 0, v[130:131]
	s_mov_b32 m0, s36
	s_nop 0
	global_load_lds_dwordx4 v[144:145], off
	s_add_i32 m0, s36, 0x2000
	s_nop 0
	global_load_lds_dwordx4 v134, s[34:35]
	v_lshl_add_u64 v[144:145], v[218:219], 0, s[10:11]
	s_mov_b32 m0, s48
	s_nop 0
	global_load_lds_dwordx4 v[144:145], off
	v_lshl_add_u64 v[144:145], v[220:221], 0, s[10:11]
	s_mov_b32 m0, s49
	s_nop 0
	global_load_lds_dwordx4 v[144:145], off
	s_waitcnt vmcnt(8)
	s_waitcnt lgkmcnt(0)
	s_barrier
	s_waitcnt lgkmcnt(0)
	v_mfma_f32_16x16x32_bf16 v[60:63], v[152:155], v[184:187], v[60:63]
	v_mfma_f32_16x16x32_bf16 v[56:59], v[160:163], v[184:187], v[56:59]
	v_mfma_f32_16x16x32_bf16 v[52:55], v[152:155], v[192:195], v[52:55]
	v_mfma_f32_16x16x32_bf16 v[44:47], v[160:163], v[192:195], v[44:47]
	v_mfma_f32_16x16x32_bf16 v[36:39], v[152:155], v[200:203], v[36:39]
	v_mfma_f32_16x16x32_bf16 v[28:31], v[160:163], v[200:203], v[28:31]
	v_mfma_f32_16x16x32_bf16 v[20:23], v[152:155], v[208:211], v[20:23]
	v_mfma_f32_16x16x32_bf16 v[12:15], v[160:163], v[208:211], v[12:15]
	v_mfma_f32_16x16x32_bf16 v[60:63], v[156:159], v[188:191], v[60:63]
	v_mfma_f32_16x16x32_bf16 v[56:59], v[164:167], v[188:191], v[56:59]
	v_mfma_f32_16x16x32_bf16 v[52:55], v[156:159], v[196:199], v[52:55]
	v_mfma_f32_16x16x32_bf16 v[44:47], v[164:167], v[196:199], v[44:47]
	v_mfma_f32_16x16x32_bf16 v[36:39], v[156:159], v[204:207], v[36:39]
	v_mfma_f32_16x16x32_bf16 v[28:31], v[164:167], v[204:207], v[28:31]
	v_mfma_f32_16x16x32_bf16 v[20:23], v[156:159], v[212:215], v[20:23]
	v_mfma_f32_16x16x32_bf16 v[12:15], v[164:167], v[212:215], v[12:15]
	v_mfma_f32_16x16x32_bf16 v[48:51], v[168:171], v[184:187], v[48:51]
	v_mfma_f32_16x16x32_bf16 v[40:43], v[176:179], v[184:187], v[40:43]
	v_mfma_f32_16x16x32_bf16 v[32:35], v[168:171], v[192:195], v[32:35]
	v_mfma_f32_16x16x32_bf16 v[24:27], v[176:179], v[192:195], v[24:27]
	v_mfma_f32_16x16x32_bf16 v[16:19], v[168:171], v[200:203], v[16:19]
	v_mfma_f32_16x16x32_bf16 v[8:11], v[176:179], v[200:203], v[8:11]
	v_mfma_f32_16x16x32_bf16 v[4:7], v[168:171], v[208:211], v[4:7]
	v_mfma_f32_16x16x32_bf16 v[0:3], v[176:179], v[208:211], v[0:3]
	v_mfma_f32_16x16x32_bf16 v[48:51], v[172:175], v[188:191], v[48:51]
	v_mfma_f32_16x16x32_bf16 v[40:43], v[180:183], v[188:191], v[40:43]
	v_mfma_f32_16x16x32_bf16 v[32:35], v[172:175], v[196:199], v[32:35]
	v_mfma_f32_16x16x32_bf16 v[24:27], v[180:183], v[196:199], v[24:27]
	v_mfma_f32_16x16x32_bf16 v[16:19], v[172:175], v[204:207], v[16:19]
	v_mfma_f32_16x16x32_bf16 v[8:11], v[180:183], v[204:207], v[8:11]
	v_mfma_f32_16x16x32_bf16 v[4:7], v[172:175], v[212:215], v[4:7]
	v_mfma_f32_16x16x32_bf16 v[0:3], v[180:183], v[212:215], v[0:3]
	s_add_i32 s62, s62, 2
	s_add_u32 s30, s30, 0x100
	s_addc_u32 s31, s31, 0
	s_add_u32 s60, s60, 0x100
	s_addc_u32 s61, s61, 0
	s_cmp_gt_u32 s62, 13
	s_barrier
	s_cbranch_scc0 .LBB0_416
	s_and_b64 vcc, exec, s[12:13]
	s_cbranch_vccz .LBB0_419
	s_barrier

.LBB0_428:
	v_ashrrev_i32_e32 v2, 31, v0
	v_lshrrev_b32_e32 v2, 26, v2
	v_lshlrev_b32_e32 v1, 4, v0
	v_add_u32_e32 v2, v0, v2
	v_bfe_i32 v0, v0, 27, 1
	v_lshrrev_b32_e32 v0, 22, v0
	v_add_u32_e32 v0, v1, v0
	v_and_b32_e32 v0, 0xfffffc00, v0
	v_sub_u32_e32 v0, v1, v0
	v_ashrrev_i32_e32 v9, 6, v2
	v_lshrrev_b32_e32 v2, 4, v0
	v_bitop3_b32 v0, v2, v0, 32 bitop3:0x6c
	v_ashrrev_i32_e32 v3, 31, v0
	v_lshrrev_b32_e32 v3, 26, v3
	v_add_u32_e32 v3, v0, v3
	v_lshlrev_b32_e32 v2, 3, v9
	v_ashrrev_i32_e32 v10, 6, v3
	v_and_b32_e32 v3, 0xc0, v3
	v_and_b32_e32 v2, -16, v2
	v_sub_u32_e32 v0, v0, v3
	v_mov_b32_e32 v3, 1
	v_add_u32_e32 v2, v10, v2
	v_ashrrev_i16_sdwa v0, v3, sext(v0) dst_sel:DWORD dst_unused:UNUSED_PAD src0_sel:DWORD src1_sel:BYTE_0
	s_ashr_i32 s2, s5, 3
	v_lshlrev_b32_e32 v4, 5, v9
	v_bfe_i32 v11, v0, 0, 16
	v_lshlrev_b32_e32 v0, 1, v2
	v_lshrrev_b32_e32 v5, 2, v2
	v_and_b32_e32 v6, 3, v10
	s_mov_b32 s5, 0x1fffe0
	v_and_b32_e32 v4, 32, v4
	v_and_b32_e32 v0, 24, v0
	v_and_b32_e32 v5, 4, v5
	v_and_or_b32 v6, v2, s5, v6
	v_or3_b32 v0, v6, v5, v0
	v_add_lshl_u32 v4, v4, v11, 1
	v_lshl_add_u32 v130, v0, 11, v4
	v_add_u32_e32 v0, 0x2000, v1
	v_ashrrev_i32_e32 v1, 31, v0
	v_lshrrev_b32_e32 v1, 22, v1
	v_add_u32_e32 v1, v0, v1
	v_ashrrev_i32_e32 v12, 10, v1
	v_mul_i32_i24_e32 v1, 0x400, v12
	v_sub_u32_e32 v0, v0, v1
	v_lshrrev_b32_e32 v1, 4, v0
	s_add_u32 s37, s70, 0x11c00000
	v_bitop3_b32 v0, v1, v0, 32 bitop3:0x6c
	s_addc_u32 s38, s71, 0
	v_lshl_add_u32 v128, v2, 11, v4
	v_ashrrev_i32_e32 v2, 31, v0
	s_add_u32 s39, s70, 0x4e00000
	v_lshrrev_b32_e32 v2, 26, v2
	s_addc_u32 s40, s71, 0
	v_add_u32_e32 v2, v0, v2
	s_add_i32 s2, s4, s2
	v_lshlrev_b32_e32 v1, 3, v12
	v_ashrrev_i32_e32 v13, 6, v2
	v_and_b32_e32 v2, 0xc0, v2
	s_ashr_i32 s4, s2, 31
	v_and_b32_e32 v1, -16, v1
	v_sub_u32_e32 v0, v0, v2
	s_lshr_b32 s4, s4, 27
	v_add_u32_e32 v1, v13, v1
	v_ashrrev_i16_sdwa v0, v3, sext(v0) dst_sel:DWORD dst_unused:UNUSED_PAD src0_sel:DWORD src1_sel:BYTE_0
	v_and_b32_e32 v3, 3, v13
	s_add_i32 s4, s2, s4
	v_and_or_b32 v3, v1, s5, v3
	s_ashr_i32 s5, s4, 5
	s_andn2_b32 s4, s4, 31
	s_sub_i32 s4, s2, s4
	s_bfe_i32 s2, s4, 0x80000
	s_bfe_u32 s2, s2, 0x3000c
	s_add_i32 s6, s4, s2
	s_bfe_i32 s2, s6, 0x80000
	s_and_b32 s6, s6, 0xf8
	s_sub_i32 s4, s4, s6
	s_lshl_b32 s5, s5, 3
	s_sext_i32_i16 s2, s2
	s_sext_i32_i8 s4, s4
	s_ashr_i32 s3, s10, 8
	s_lshr_b32 s2, s2, 3
	s_add_i32 s26, s5, s4
	s_ashr_i32 s8, s10, 6
	s_ashr_i32 s27, s26, 31
	s_bfe_i64 s[6:7], s[2:3], 0x100000
	s_lshl_b32 s41, s8, 10
	s_lshl_b64 s[4:5], s[26:27], 19
	s_lshl_b64 s[6:7], s[6:7], 19
	s_add_u32 s30, s39, s6
	v_lshlrev_b32_e32 v4, 5, v12
	v_bfe_i32 v14, v0, 0, 16
	v_lshlrev_b32_e32 v0, 1, v1
	v_lshrrev_b32_e32 v2, 2, v1
	s_addc_u32 s31, s40, s7
	s_add_i32 s27, s41, 0
	v_and_b32_e32 v4, 32, v4
	v_and_b32_e32 v0, 24, v0
	v_and_b32_e32 v2, 4, v2
	s_add_i32 m0, s27, 0x10000
	v_or3_b32 v0, v3, v2, v0
	v_add_lshl_u32 v2, v4, v14, 1
	global_load_lds_dwordx4 v130, s[30:31]
	s_add_i32 m0, s27, 0x12000
	v_lshl_add_u32 v134, v0, 11, v2
	s_add_u32 s6, s30, 0x40000
	global_load_lds_dwordx4 v134, s[30:31]
	s_addc_u32 s7, s31, 0
	s_add_i32 m0, s27, 0x14000
	v_lshl_add_u32 v132, v1, 11, v2
	global_load_lds_dwordx4 v130, s[6:7]
	s_add_i32 m0, s27, 0x16000
	s_add_u32 s28, s37, s4
	s_addc_u32 s29, s38, s5
	s_add_i32 s42, s27, 0x2000
	global_load_lds_dwordx4 v134, s[6:7]
	s_mov_b32 m0, s27
	s_add_u32 s4, s28, 0x40000
	global_load_lds_dwordx4 v128, s[28:29]
	s_mov_b32 m0, s42
	s_addc_u32 s5, s29, 0
	s_add_i32 s43, s27, 0x4000
	global_load_lds_dwordx4 v132, s[28:29]
	s_mov_b32 m0, s43
	s_add_i32 s44, s27, 0x6000
	global_load_lds_dwordx4 v128, s[4:5]
	s_mov_b32 m0, s44
	v_mov_b32_e32 v131, 0
	global_load_lds_dwordx4 v132, s[4:5]
	v_mov_b32_e32 v135, v131
	v_mov_b32_e32 v129, v131
	v_mov_b32_e32 v133, v131
	s_cmp_eq_u32 s3, 1
	s_mov_b32 s45, 0
	v_lshl_add_u64 v[6:7], s[30:31], 0, v[130:131]
	v_lshl_add_u64 v[2:3], s[30:31], 0, v[134:135]
	s_mov_b64 s[4:5], 0x40000
	v_lshl_add_u64 v[0:1], s[28:29], 0, v[128:129]
	s_cselect_b64 s[6:7], -1, 0
	s_cmp_lg_u32 s3, 1
	v_lshl_add_u64 v[4:5], s[28:29], 0, v[132:133]
	s_setprio 1
	s_cbranch_scc1 .LBB0_430
	s_barrier
	s_setprio 0

.LBB0_440:
	ds_read_b128 v[152:155], v149
	ds_read_b128 v[156:159], v149 offset:1024
	ds_read_b128 v[160:163], v149 offset:2048
	ds_read_b128 v[164:167], v149 offset:3072
	ds_read_b128 v[168:171], v150
	ds_read_b128 v[172:175], v150 offset:1024
	ds_read_b128 v[176:179], v150 offset:2048
	ds_read_b128 v[180:183], v150 offset:3072
	s_add_u32 s30, s28, 0xfffc0080
	s_addc_u32 s31, s29, -1
	s_cmp_eq_u32 s60, 12
	s_cselect_b32 s35, s21, s31
	s_cselect_b32 s34, s56, s30
	s_cselect_b32 s31, s19, s59
	s_cselect_b32 s30, s57, s58
	s_add_i32 m0, s27, 0xc000
	ds_read_b128 v[184:187], v151
	ds_read_b128 v[188:191], v151 offset:1024
	ds_read_b128 v[192:195], v151 offset:2048
	ds_read_b128 v[196:199], v151 offset:3072
	ds_read_b128 v[200:203], v151 offset:4096
	ds_read_b128 v[204:207], v151 offset:5120
	ds_read_b128 v[208:211], v151 offset:6144
	ds_read_b128 v[212:215], v151 offset:7168
	global_load_lds_dwordx4 v136, s[28:29]
	s_add_i32 m0, s27, 0xe000
	s_nop 0
	global_load_lds_dwordx4 v138, s[28:29]
	s_waitcnt vmcnt(8)
	s_waitcnt lgkmcnt(0)
	s_barrier
	s_waitcnt lgkmcnt(0)
	v_mfma_f32_16x16x32_bf16 v[124:127], v[152:155], v[184:187], v[124:127]
	v_mfma_f32_16x16x32_bf16 v[120:123], v[160:163], v[184:187], v[120:123]
	v_mfma_f32_16x16x32_bf16 v[116:119], v[152:155], v[192:195], v[116:119]
	v_mfma_f32_16x16x32_bf16 v[108:111], v[160:163], v[192:195], v[108:111]
	v_mfma_f32_16x16x32_bf16 v[100:103], v[152:155], v[200:203], v[100:103]
	v_mfma_f32_16x16x32_bf16 v[92:95], v[160:163], v[200:203], v[92:95]
	v_mfma_f32_16x16x32_bf16 v[84:87], v[152:155], v[208:211], v[84:87]
	v_mfma_f32_16x16x32_bf16 v[76:79], v[160:163], v[208:211], v[76:79]
	v_mfma_f32_16x16x32_bf16 v[124:127], v[156:159], v[188:191], v[124:127]
	v_mfma_f32_16x16x32_bf16 v[120:123], v[164:167], v[188:191], v[120:123]
	v_mfma_f32_16x16x32_bf16 v[116:119], v[156:159], v[196:199], v[116:119]
	v_mfma_f32_16x16x32_bf16 v[108:111], v[164:167], v[196:199], v[108:111]
	v_mfma_f32_16x16x32_bf16 v[100:103], v[156:159], v[204:207], v[100:103]
	v_mfma_f32_16x16x32_bf16 v[92:95], v[164:167], v[204:207], v[92:95]
	v_mfma_f32_16x16x32_bf16 v[84:87], v[156:159], v[212:215], v[84:87]
	v_mfma_f32_16x16x32_bf16 v[76:79], v[164:167], v[212:215], v[76:79]
	v_mfma_f32_16x16x32_bf16 v[112:115], v[168:171], v[184:187], v[112:115]
	v_mfma_f32_16x16x32_bf16 v[104:107], v[176:179], v[184:187], v[104:107]
	v_mfma_f32_16x16x32_bf16 v[96:99], v[168:171], v[192:195], v[96:99]
	v_mfma_f32_16x16x32_bf16 v[88:91], v[176:179], v[192:195], v[88:91]
	v_mfma_f32_16x16x32_bf16 v[80:83], v[168:171], v[200:203], v[80:83]
	v_mfma_f32_16x16x32_bf16 v[72:75], v[176:179], v[200:203], v[72:75]
	v_mfma_f32_16x16x32_bf16 v[68:71], v[168:171], v[208:211], v[68:71]
	v_mfma_f32_16x16x32_bf16 v[64:67], v[176:179], v[208:211], v[64:67]
	v_mfma_f32_16x16x32_bf16 v[112:115], v[172:175], v[188:191], v[112:115]
	v_mfma_f32_16x16x32_bf16 v[104:107], v[180:183], v[188:191], v[104:107]
	v_mfma_f32_16x16x32_bf16 v[96:99], v[172:175], v[196:199], v[96:99]
	v_mfma_f32_16x16x32_bf16 v[88:91], v[180:183], v[196:199], v[88:91]
	v_mfma_f32_16x16x32_bf16 v[80:83], v[172:175], v[204:207], v[80:83]
	v_mfma_f32_16x16x32_bf16 v[72:75], v[180:183], v[204:207], v[72:75]
	v_mfma_f32_16x16x32_bf16 v[68:71], v[172:175], v[212:215], v[68:71]
	v_mfma_f32_16x16x32_bf16 v[64:67], v[180:183], v[212:215], v[64:67]
	s_barrier
	s_add_i32 s61, s49, s41
	v_lshl_add_u64 v[144:145], s[30:31], 0, v[130:131]
	s_mov_b32 m0, s61
	ds_read_b128 v[184:187], v151 offset:16384
	ds_read_b128 v[188:191], v151 offset:17408
	ds_read_b128 v[192:195], v151 offset:18432
	ds_read_b128 v[196:199], v151 offset:19456
	ds_read_b128 v[200:203], v151 offset:20480
	ds_read_b128 v[204:207], v151 offset:21504
	ds_read_b128 v[208:211], v151 offset:22528
	ds_read_b128 v[212:215], v151 offset:23552
	global_load_lds_dwordx4 v[144:145], off
	s_add_i32 m0, s61, 0x2000
	s_add_u32 s62, s30, 0x40000
	v_lshl_add_u64 v[216:217], s[30:31], 0, v[134:135]
	s_addc_u32 s63, s31, 0
	s_add_i32 s61, s50, s41
	global_load_lds_dwordx4 v[216:217], off
	v_lshl_add_u64 v[218:219], s[62:63], 0, v[130:131]
	s_mov_b32 m0, s61
	v_lshl_add_u64 v[220:221], s[34:35], 0, v[132:133]
	global_load_lds_dwordx4 v[218:219], off
	s_add_i32 m0, s61, 0x2000
	s_nop 0
	global_load_lds_dwordx4 v134, s[62:63]
	v_lshl_add_u64 v[218:219], s[34:35], 0, v[128:129]
	s_mov_b32 m0, s27
	s_nop 0
	global_load_lds_dwordx4 v[218:219], off
	s_mov_b32 m0, s42
	s_nop 0
	global_load_lds_dwordx4 v[220:221], off
	s_waitcnt vmcnt(8)
	s_waitcnt lgkmcnt(0)
	s_barrier
	s_waitcnt lgkmcnt(0)
	v_mfma_f32_16x16x32_bf16 v[60:63], v[152:155], v[184:187], v[60:63]
	v_mfma_f32_16x16x32_bf16 v[56:59], v[160:163], v[184:187], v[56:59]
	v_mfma_f32_16x16x32_bf16 v[52:55], v[152:155], v[192:195], v[52:55]
	v_mfma_f32_16x16x32_bf16 v[44:47], v[160:163], v[192:195], v[44:47]
	v_mfma_f32_16x16x32_bf16 v[36:39], v[152:155], v[200:203], v[36:39]
	v_mfma_f32_16x16x32_bf16 v[28:31], v[160:163], v[200:203], v[28:31]
	v_mfma_f32_16x16x32_bf16 v[20:23], v[152:155], v[208:211], v[20:23]
	v_mfma_f32_16x16x32_bf16 v[12:15], v[160:163], v[208:211], v[12:15]
	v_mfma_f32_16x16x32_bf16 v[60:63], v[156:159], v[188:191], v[60:63]
	v_mfma_f32_16x16x32_bf16 v[56:59], v[164:167], v[188:191], v[56:59]
	v_mfma_f32_16x16x32_bf16 v[52:55], v[156:159], v[196:199], v[52:55]
	v_mfma_f32_16x16x32_bf16 v[44:47], v[164:167], v[196:199], v[44:47]
	v_mfma_f32_16x16x32_bf16 v[36:39], v[156:159], v[204:207], v[36:39]
	v_mfma_f32_16x16x32_bf16 v[28:31], v[164:167], v[204:207], v[28:31]
	v_mfma_f32_16x16x32_bf16 v[20:23], v[156:159], v[212:215], v[20:23]
	v_mfma_f32_16x16x32_bf16 v[12:15], v[164:167], v[212:215], v[12:15]
	v_mfma_f32_16x16x32_bf16 v[48:51], v[168:171], v[184:187], v[48:51]
	v_mfma_f32_16x16x32_bf16 v[40:43], v[176:179], v[184:187], v[40:43]
	v_mfma_f32_16x16x32_bf16 v[32:35], v[168:171], v[192:195], v[32:35]
	v_mfma_f32_16x16x32_bf16 v[24:27], v[176:179], v[192:195], v[24:27]
	v_mfma_f32_16x16x32_bf16 v[16:19], v[168:171], v[200:203], v[16:19]
	v_mfma_f32_16x16x32_bf16 v[8:11], v[176:179], v[200:203], v[8:11]
	v_mfma_f32_16x16x32_bf16 v[4:7], v[168:171], v[208:211], v[4:7]
	v_mfma_f32_16x16x32_bf16 v[0:3], v[176:179], v[208:211], v[0:3]
	v_mfma_f32_16x16x32_bf16 v[48:51], v[172:175], v[188:191], v[48:51]
	v_mfma_f32_16x16x32_bf16 v[40:43], v[180:183], v[188:191], v[40:43]
	v_mfma_f32_16x16x32_bf16 v[32:35], v[172:175], v[196:199], v[32:35]
	v_mfma_f32_16x16x32_bf16 v[24:27], v[180:183], v[196:199], v[24:27]
	v_mfma_f32_16x16x32_bf16 v[16:19], v[172:175], v[204:207], v[16:19]
	v_mfma_f32_16x16x32_bf16 v[8:11], v[180:183], v[204:207], v[8:11]
	v_mfma_f32_16x16x32_bf16 v[4:7], v[172:175], v[212:215], v[4:7]
	v_mfma_f32_16x16x32_bf16 v[0:3], v[180:183], v[212:215], v[0:3]
	s_barrier
	s_add_i32 s61, 0, 0x18000
	s_add_i32 s62, 0, 0x1c000
	v_add_u32_e32 v164, s61, v147
	v_add_u32_e32 v180, s62, v147
	ds_read_b128 v[152:155], v164
	ds_read_b128 v[156:159], v164 offset:1024
	ds_read_b128 v[160:163], v164 offset:2048
	ds_read_b128 v[164:167], v164 offset:3072
	ds_read_b128 v[168:171], v180
	ds_read_b128 v[172:175], v180 offset:1024
	ds_read_b128 v[176:179], v180 offset:2048
	ds_read_b128 v[180:183], v180 offset:3072
	s_add_u32 s34, s34, 0x40000
	s_addc_u32 s35, s35, 0
	s_mov_b32 m0, s43
	ds_read_b128 v[184:187], v151 offset:32768
	ds_read_b128 v[188:191], v151 offset:33792
	ds_read_b128 v[192:195], v151 offset:34816
	ds_read_b128 v[196:199], v151 offset:35840
	ds_read_b128 v[200:203], v151 offset:36864
	ds_read_b128 v[204:207], v151 offset:37888
	ds_read_b128 v[208:211], v151 offset:38912
	ds_read_b128 v[212:215], v151 offset:39936
	global_load_lds_dwordx4 v128, s[34:35]
	v_lshl_add_u64 v[222:223], s[34:35], 0, v[132:133]
	s_mov_b32 m0, s44
	s_nop 0
	global_load_lds_dwordx4 v[222:223], off
	s_waitcnt vmcnt(8)
	s_waitcnt lgkmcnt(0)
	s_barrier
	s_waitcnt lgkmcnt(0)
	v_mfma_f32_16x16x32_bf16 v[124:127], v[152:155], v[184:187], v[124:127]
	v_mfma_f32_16x16x32_bf16 v[120:123], v[160:163], v[184:187], v[120:123]
	v_mfma_f32_16x16x32_bf16 v[116:119], v[152:155], v[192:195], v[116:119]
	v_mfma_f32_16x16x32_bf16 v[108:111], v[160:163], v[192:195], v[108:111]
	v_mfma_f32_16x16x32_bf16 v[100:103], v[152:155], v[200:203], v[100:103]
	v_mfma_f32_16x16x32_bf16 v[92:95], v[160:163], v[200:203], v[92:95]
	v_mfma_f32_16x16x32_bf16 v[84:87], v[152:155], v[208:211], v[84:87]
	v_mfma_f32_16x16x32_bf16 v[76:79], v[160:163], v[208:211], v[76:79]
	v_mfma_f32_16x16x32_bf16 v[124:127], v[156:159], v[188:191], v[124:127]
	v_mfma_f32_16x16x32_bf16 v[120:123], v[164:167], v[188:191], v[120:123]
	v_mfma_f32_16x16x32_bf16 v[116:119], v[156:159], v[196:199], v[116:119]
	v_mfma_f32_16x16x32_bf16 v[108:111], v[164:167], v[196:199], v[108:111]
	v_mfma_f32_16x16x32_bf16 v[100:103], v[156:159], v[204:207], v[100:103]
	v_mfma_f32_16x16x32_bf16 v[92:95], v[164:167], v[204:207], v[92:95]
	v_mfma_f32_16x16x32_bf16 v[84:87], v[156:159], v[212:215], v[84:87]
	v_mfma_f32_16x16x32_bf16 v[76:79], v[164:167], v[212:215], v[76:79]
	v_mfma_f32_16x16x32_bf16 v[112:115], v[168:171], v[184:187], v[112:115]
	v_mfma_f32_16x16x32_bf16 v[104:107], v[176:179], v[184:187], v[104:107]
	v_mfma_f32_16x16x32_bf16 v[96:99], v[168:171], v[192:195], v[96:99]
	v_mfma_f32_16x16x32_bf16 v[88:91], v[176:179], v[192:195], v[88:91]
	v_mfma_f32_16x16x32_bf16 v[80:83], v[168:171], v[200:203], v[80:83]
	v_mfma_f32_16x16x32_bf16 v[72:75], v[176:179], v[200:203], v[72:75]
	v_mfma_f32_16x16x32_bf16 v[68:71], v[168:171], v[208:211], v[68:71]
	v_mfma_f32_16x16x32_bf16 v[64:67], v[176:179], v[208:211], v[64:67]
	v_mfma_f32_16x16x32_bf16 v[112:115], v[172:175], v[188:191], v[112:115]
	v_mfma_f32_16x16x32_bf16 v[104:107], v[180:183], v[188:191], v[104:107]
	v_mfma_f32_16x16x32_bf16 v[96:99], v[172:175], v[196:199], v[96:99]
	v_mfma_f32_16x16x32_bf16 v[88:91], v[180:183], v[196:199], v[88:91]
	v_mfma_f32_16x16x32_bf16 v[80:83], v[172:175], v[204:207], v[80:83]
	v_mfma_f32_16x16x32_bf16 v[72:75], v[180:183], v[204:207], v[72:75]
	v_mfma_f32_16x16x32_bf16 v[68:71], v[172:175], v[212:215], v[68:71]
	v_mfma_f32_16x16x32_bf16 v[64:67], v[180:183], v[212:215], v[64:67]
	s_barrier
	s_add_i32 s34, s61, s41
	v_lshl_add_u64 v[144:145], v[144:145], 0, s[8:9]
	s_mov_b32 m0, s34
	ds_read_b128 v[184:187], v151 offset:49152
	ds_read_b128 v[188:191], v151 offset:50176
	ds_read_b128 v[192:195], v151 offset:51200
	ds_read_b128 v[196:199], v151 offset:52224
	ds_read_b128 v[200:203], v151 offset:53248
	ds_read_b128 v[204:207], v151 offset:54272
	ds_read_b128 v[208:211], v151 offset:55296
	ds_read_b128 v[212:215], v151 offset:56320
	global_load_lds_dwordx4 v[144:145], off
	s_add_i32 m0, s34, 0x2000
	s_add_u32 s30, s30, 0x40080
	v_lshl_add_u64 v[144:145], v[216:217], 0, s[8:9]
	s_addc_u32 s31, s31, 0
	s_add_i32 s34, s62, s41
	global_load_lds_dwordx4 v[144:145], off
	v_lshl_add_u64 v[144:145], s[30:31], 0, v[130:131]
	s_mov_b32 m0, s34
	s_nop 0
	global_load_lds_dwordx4 v[144:145], off
	s_add_i32 m0, s34, 0x2000
	s_nop 0
	global_load_lds_dwordx4 v134, s[30:31]
	v_lshl_add_u64 v[144:145], v[218:219], 0, s[8:9]
	s_mov_b32 m0, s46
	s_nop 0
	global_load_lds_dwordx4 v[144:145], off
	v_lshl_add_u64 v[144:145], v[220:221], 0, s[8:9]
	s_mov_b32 m0, s47
	s_nop 0
	global_load_lds_dwordx4 v[144:145], off
	s_waitcnt vmcnt(8)
	s_waitcnt lgkmcnt(0)
	s_barrier
	s_waitcnt lgkmcnt(0)
	v_mfma_f32_16x16x32_bf16 v[60:63], v[152:155], v[184:187], v[60:63]
	v_mfma_f32_16x16x32_bf16 v[56:59], v[160:163], v[184:187], v[56:59]
	v_mfma_f32_16x16x32_bf16 v[52:55], v[152:155], v[192:195], v[52:55]
	v_mfma_f32_16x16x32_bf16 v[44:47], v[160:163], v[192:195], v[44:47]
	v_mfma_f32_16x16x32_bf16 v[36:39], v[152:155], v[200:203], v[36:39]
	v_mfma_f32_16x16x32_bf16 v[28:31], v[160:163], v[200:203], v[28:31]
	v_mfma_f32_16x16x32_bf16 v[20:23], v[152:155], v[208:211], v[20:23]
	v_mfma_f32_16x16x32_bf16 v[12:15], v[160:163], v[208:211], v[12:15]
	v_mfma_f32_16x16x32_bf16 v[60:63], v[156:159], v[188:191], v[60:63]
	v_mfma_f32_16x16x32_bf16 v[56:59], v[164:167], v[188:191], v[56:59]
	v_mfma_f32_16x16x32_bf16 v[52:55], v[156:159], v[196:199], v[52:55]
	v_mfma_f32_16x16x32_bf16 v[44:47], v[164:167], v[196:199], v[44:47]
	v_mfma_f32_16x16x32_bf16 v[36:39], v[156:159], v[204:207], v[36:39]
	v_mfma_f32_16x16x32_bf16 v[28:31], v[164:167], v[204:207], v[28:31]
	v_mfma_f32_16x16x32_bf16 v[20:23], v[156:159], v[212:215], v[20:23]
	v_mfma_f32_16x16x32_bf16 v[12:15], v[164:167], v[212:215], v[12:15]
	v_mfma_f32_16x16x32_bf16 v[48:51], v[168:171], v[184:187], v[48:51]
	v_mfma_f32_16x16x32_bf16 v[40:43], v[176:179], v[184:187], v[40:43]
	v_mfma_f32_16x16x32_bf16 v[32:35], v[168:171], v[192:195], v[32:35]
	v_mfma_f32_16x16x32_bf16 v[24:27], v[176:179], v[192:195], v[24:27]
	v_mfma_f32_16x16x32_bf16 v[16:19], v[168:171], v[200:203], v[16:19]
	v_mfma_f32_16x16x32_bf16 v[8:11], v[176:179], v[200:203], v[8:11]
	v_mfma_f32_16x16x32_bf16 v[4:7], v[168:171], v[208:211], v[4:7]
	v_mfma_f32_16x16x32_bf16 v[0:3], v[176:179], v[208:211], v[0:3]
	v_mfma_f32_16x16x32_bf16 v[48:51], v[172:175], v[188:191], v[48:51]
	v_mfma_f32_16x16x32_bf16 v[40:43], v[180:183], v[188:191], v[40:43]
	v_mfma_f32_16x16x32_bf16 v[32:35], v[172:175], v[196:199], v[32:35]
	v_mfma_f32_16x16x32_bf16 v[24:27], v[180:183], v[196:199], v[24:27]
	v_mfma_f32_16x16x32_bf16 v[16:19], v[172:175], v[204:207], v[16:19]
	v_mfma_f32_16x16x32_bf16 v[8:11], v[180:183], v[204:207], v[8:11]
	v_mfma_f32_16x16x32_bf16 v[4:7], v[172:175], v[212:215], v[4:7]
	v_mfma_f32_16x16x32_bf16 v[0:3], v[180:183], v[212:215], v[0:3]
	s_add_i32 s60, s60, 2
	s_add_u32 s28, s28, 0x100
	s_addc_u32 s29, s29, 0
	s_add_u32 s58, s58, 0x100
	s_addc_u32 s59, s59, 0
	s_cmp_gt_u32 s60, 13
	s_barrier
	s_cbranch_scc0 .LBB0_440
	s_and_b64 vcc, exec, s[10:11]
	s_cbranch_vccz .LBB0_443
	s_barrier

.LBB0_453:
	s_andn2_b64 vcc, exec, s[2:3]
	s_cbranch_vccnz .LBB0_503
	v_ashrrev_i32_e32 v2, 31, v0
	v_lshrrev_b32_e32 v2, 26, v2
	v_lshlrev_b32_e32 v1, 4, v0
	v_add_u32_e32 v2, v0, v2
	v_bfe_i32 v0, v0, 27, 1
	v_lshrrev_b32_e32 v0, 22, v0
	v_add_u32_e32 v0, v1, v0
	v_and_b32_e32 v0, 0xfffffc00, v0
	v_sub_u32_e32 v0, v1, v0
	v_lshrrev_b32_e32 v3, 4, v0
	v_bitop3_b32 v0, v3, v0, 32 bitop3:0x6c
	v_ashrrev_i32_e32 v4, 31, v0
	v_ashrrev_i32_e32 v2, 6, v2
	v_lshrrev_b32_e32 v4, 26, v4
	v_lshlrev_b32_e32 v3, 3, v2
	v_add_u32_e32 v4, v0, v4
	v_and_b32_e32 v3, -16, v3
	v_ashrrev_i32_e32 v5, 6, v4
	v_and_b32_e32 v4, 0xc0, v4
	v_add_u32_e32 v3, v5, v3
	v_sub_u32_e32 v0, v0, v4
	v_mov_b32_e32 v4, 1
	v_lshlrev_b32_e32 v2, 5, v2
	v_ashrrev_i16_sdwa v0, v4, sext(v0) dst_sel:DWORD dst_unused:UNUSED_PAD src0_sel:DWORD src1_sel:BYTE_0
	v_lshlrev_b32_e32 v6, 1, v3
	v_lshrrev_b32_e32 v7, 2, v3
	v_and_b32_e32 v5, 3, v5
	s_mov_b32 s3, 0x7fffe0
	v_and_b32_e32 v2, 32, v2
	v_bfe_i32 v0, v0, 0, 16
	v_and_b32_e32 v6, 24, v6
	v_and_b32_e32 v7, 4, v7
	v_and_or_b32 v5, v3, s3, v5
	v_or3_b32 v5, v5, v7, v6
	v_add_lshl_u32 v0, v2, v0, 1
	v_lshl_add_u32 v128, v3, 9, v0
	v_lshl_add_u32 v130, v5, 9, v0
	v_add_u32_e32 v0, 0x2000, v1
	v_ashrrev_i32_e32 v1, 31, v0
	v_lshrrev_b32_e32 v1, 22, v1
	v_add_u32_e32 v1, v0, v1
	v_ashrrev_i32_e32 v1, 10, v1
	v_mul_i32_i24_e32 v2, 0x400, v1
	v_sub_u32_e32 v0, v0, v2
	v_lshrrev_b32_e32 v2, 4, v0
	v_bitop3_b32 v0, v2, v0, 32 bitop3:0x6c
	v_ashrrev_i32_e32 v3, 31, v0
	v_lshrrev_b32_e32 v3, 26, v3
	s_add_u32 s50, s70, 0x19c00000
	v_lshlrev_b32_e32 v2, 3, v1
	v_add_u32_e32 v3, v0, v3
	s_addc_u32 s51, s71, 0
	v_and_b32_e32 v2, -16, v2
	v_ashrrev_i32_e32 v5, 6, v3
	s_add_u32 s52, s70, 0x5300000
	v_add_u32_e32 v2, v5, v2
	v_and_b32_e32 v5, 3, v5
	s_addc_u32 s53, s71, 0
	v_and_or_b32 v5, v2, s3, v5
	s_ashr_i32 s3, s14, 6
	s_ashr_i32 s5, s4, 31
	s_ashr_i32 s41, s40, 31
	s_ashr_i32 s2, s14, 8
	v_and_b32_e32 v3, 0xc0, v3
	s_lshl_b32 s54, s3, 10
	s_lshl_b64 s[10:11], s[4:5], 17
	s_lshl_b64 s[12:13], s[40:41], 17
	v_sub_u32_e32 v0, v0, v3
	s_add_u32 s44, s52, s12
	v_lshlrev_b32_e32 v1, 5, v1
	v_ashrrev_i16_sdwa v0, v4, sext(v0) dst_sel:DWORD dst_unused:UNUSED_PAD src0_sel:DWORD src1_sel:BYTE_0
	v_lshlrev_b32_e32 v3, 1, v2
	v_lshrrev_b32_e32 v4, 2, v2
	s_addc_u32 s45, s53, s13
	s_add_i32 s55, s54, 0
	v_and_b32_e32 v1, 32, v1
	v_bfe_i32 v0, v0, 0, 16
	v_and_b32_e32 v3, 24, v3
	v_and_b32_e32 v4, 4, v4
	s_add_i32 m0, s55, 0x10000
	v_or3_b32 v3, v5, v4, v3
	v_add_lshl_u32 v0, v1, v0, 1
	global_load_lds_dwordx4 v130, s[44:45]
	s_add_i32 m0, s55, 0x12000
	v_lshl_add_u32 v134, v3, 9, v0
	s_add_u32 s12, s44, 0x10000
	global_load_lds_dwordx4 v134, s[44:45]
	s_addc_u32 s13, s45, 0
	s_add_i32 m0, s55, 0x14000
	v_lshl_add_u32 v132, v2, 9, v0
	global_load_lds_dwordx4 v130, s[12:13]
	s_add_i32 m0, s55, 0x16000
	s_add_u32 s42, s50, s10
	s_addc_u32 s43, s51, s11
	s_add_i32 s56, s55, 0x2000
	global_load_lds_dwordx4 v134, s[12:13]
	s_mov_b32 m0, s55
	s_add_u32 s10, s42, 0x10000
	global_load_lds_dwordx4 v128, s[42:43]
	s_mov_b32 m0, s56
	s_addc_u32 s11, s43, 0
	s_add_i32 s57, s55, 0x4000
	global_load_lds_dwordx4 v132, s[42:43]
	s_mov_b32 m0, s57
	s_add_i32 s58, s55, 0x6000
	global_load_lds_dwordx4 v128, s[10:11]
	s_mov_b32 m0, s58
	v_mov_b32_e32 v137, 0
	global_load_lds_dwordx4 v132, s[10:11]
	v_mov_b32_e32 v131, v137
	v_mov_b32_e32 v135, v137
	v_mov_b32_e32 v129, v137
	v_mov_b32_e32 v133, v137
	s_cmp_eq_u32 s2, 1
	v_lshl_add_u64 v[6:7], s[44:45], 0, v[130:131]
	v_lshl_add_u64 v[4:5], s[44:45], 0, v[134:135]
	v_lshl_add_u64 v[0:1], s[42:43], 0, v[128:129]
	s_cselect_b64 s[10:11], -1, 0
	s_cmp_lg_u32 s2, 1
	v_lshl_add_u64 v[2:3], s[42:43], 0, v[132:133]
	s_setprio 1
	s_cbranch_scc1 .LBB0_456
	s_barrier
	s_setprio 0

.LBB0_465:
	s_ashr_i32 s35, s34, 31
	s_lshl_b64 s[36:37], s[34:35], 17
	s_add_u32 s36, s50, s36
	s_addc_u32 s37, s51, s37
	s_and_b64 s[38:39], s[2:3], exec
	s_cselect_b32 s49, s37, s43
	s_cselect_b32 s48, s36, s42
	s_ashr_i32 s31, s30, 31
	s_lshl_b64 s[38:39], s[30:31], 17
	s_add_u32 s38, s52, s38
	s_addc_u32 s39, s53, s39
	s_and_b64 s[46:47], s[2:3], exec
	s_cselect_b32 s47, s39, s45
	s_cselect_b32 s46, s38, s44
	s_add_u32 s68, s42, 0x10080
	s_addc_u32 s69, s43, 0
	v_lshl_add_u64 v[64:65], s[68:69], 0, v[128:129]
	v_lshl_add_u64 v[64:65], s[68:69], 0, v[132:133]
	s_add_i32 s41, s62, s54
	v_lshl_add_u64 v[214:215], s[44:45], 0, v[130:131]
	s_add_i32 s5, s41, 0x2000
	v_lshl_add_u64 v[144:145], v[214:215], 0, s[18:19]
	v_lshl_add_u64 v[216:217], s[44:45], 0, v[134:135]
	s_add_u32 s68, s44, 0x10100
	v_lshl_add_u64 v[144:145], v[216:217], 0, s[18:19]
	s_addc_u32 s69, s45, 0
	s_add_i32 s31, s63, s54
	v_lshl_add_u64 v[144:145], s[68:69], 0, v[130:131]
	s_add_i32 s35, s31, 0x2000
	v_lshl_add_u64 v[144:145], s[68:69], 0, v[134:135]
	v_lshl_add_u64 v[218:219], s[42:43], 0, v[128:129]
	v_lshl_add_u64 v[144:145], v[218:219], 0, s[18:19]
	v_lshl_add_u64 v[220:221], s[42:43], 0, v[132:133]
	v_lshl_add_u64 v[144:145], v[220:221], 0, s[18:19]
	s_add_i32 s67, 0, 0x18000
	s_add_i32 s80, 0, 0x1c000
	v_add_u32_e32 v136, s67, v152
	v_add_u32_e32 v142, s80, v152
	s_add_u32 s68, s42, 0x10100
	s_addc_u32 s69, s43, 0
	v_lshl_add_u64 v[222:223], s[68:69], 0, v[128:129]
	v_lshl_add_u64 v[222:223], s[68:69], 0, v[132:133]
	s_add_i32 s68, s67, s54
	s_add_i32 s67, s68, 0x2000
	v_lshl_add_u64 v[214:215], v[214:215], 0, s[20:21]
	s_add_u32 s78, s44, 0x10180
	v_lshl_add_u64 v[214:215], v[216:217], 0, s[20:21]
	s_addc_u32 s79, s45, 0
	s_add_i32 s44, s80, s54
	v_lshl_add_u64 v[214:215], s[78:79], 0, v[130:131]
	s_add_i32 s45, s44, 0x2000
	v_lshl_add_u64 v[214:215], s[78:79], 0, v[134:135]
	v_lshl_add_u64 v[214:215], v[218:219], 0, s[20:21]
	v_lshl_add_u64 v[214:215], v[220:221], 0, s[20:21]
	ds_read_b128 v[104:107], v154
	ds_read_b128 v[108:111], v154 offset:1024
	ds_read_b128 v[112:115], v154 offset:2048
	ds_read_b128 v[116:119], v154 offset:3072
	ds_read_b128 v[120:123], v155
	ds_read_b128 v[124:127], v155 offset:1024
	ds_read_b128 v[174:177], v155 offset:2048
	ds_read_b128 v[178:181], v155 offset:3072
	s_add_u32 s42, s42, 0x10080
	s_addc_u32 s43, s43, 0
	s_mov_b32 m0, s64
	ds_read_b128 v[182:185], v156
	ds_read_b128 v[186:189], v156 offset:1024
	ds_read_b128 v[190:193], v156 offset:2048
	ds_read_b128 v[194:197], v156 offset:3072
	ds_read_b128 v[198:201], v156 offset:4096
	ds_read_b128 v[202:205], v156 offset:5120
	ds_read_b128 v[206:209], v156 offset:6144
	ds_read_b128 v[210:213], v156 offset:7168
	global_load_lds_dwordx4 v128, s[42:43]
	s_mov_b32 m0, s65
	s_nop 0
	global_load_lds_dwordx4 v132, s[42:43]
	s_waitcnt vmcnt(8)
	s_waitcnt lgkmcnt(0)
	s_barrier
	s_waitcnt lgkmcnt(0)
	v_mfma_f32_16x16x32_bf16 v[64:67], v[104:107], v[182:185], 0
	v_mfma_f32_16x16x32_bf16 v[68:71], v[112:115], v[182:185], 0
	v_mfma_f32_16x16x32_bf16 v[72:75], v[104:107], v[190:193], 0
	v_mfma_f32_16x16x32_bf16 v[76:79], v[112:115], v[190:193], 0
	v_mfma_f32_16x16x32_bf16 v[80:83], v[104:107], v[198:201], 0
	v_mfma_f32_16x16x32_bf16 v[84:87], v[112:115], v[198:201], 0
	v_mfma_f32_16x16x32_bf16 v[88:91], v[104:107], v[206:209], 0
	v_mfma_f32_16x16x32_bf16 v[64:67], v[108:111], v[186:189], v[64:67]
	v_mfma_f32_16x16x32_bf16 v[68:71], v[116:119], v[186:189], v[68:71]
	v_mfma_f32_16x16x32_bf16 v[72:75], v[108:111], v[194:197], v[72:75]
	v_mfma_f32_16x16x32_bf16 v[76:79], v[116:119], v[194:197], v[76:79]
	v_mfma_f32_16x16x32_bf16 v[80:83], v[108:111], v[202:205], v[80:83]
	v_mfma_f32_16x16x32_bf16 v[84:87], v[116:119], v[202:205], v[84:87]
	v_mfma_f32_16x16x32_bf16 v[214:217], v[108:111], v[210:213], v[88:91]
	v_mfma_f32_16x16x32_bf16 v[88:91], v[112:115], v[206:209], 0
	v_mfma_f32_16x16x32_bf16 v[218:221], v[116:119], v[210:213], v[88:91]
	v_mfma_f32_16x16x32_bf16 v[88:91], v[120:123], v[182:185], 0
	v_mfma_f32_16x16x32_bf16 v[32:35], v[174:177], v[182:185], 0
	v_mfma_f32_16x16x32_bf16 v[36:39], v[120:123], v[190:193], 0
	v_mfma_f32_16x16x32_bf16 v[40:43], v[174:177], v[190:193], 0
	v_mfma_f32_16x16x32_bf16 v[44:47], v[120:123], v[198:201], 0
	v_mfma_f32_16x16x32_bf16 v[48:51], v[174:177], v[198:201], 0
	v_mfma_f32_16x16x32_bf16 v[52:55], v[120:123], v[206:209], 0
	v_mfma_f32_16x16x32_bf16 v[56:59], v[174:177], v[206:209], 0
	v_mfma_f32_16x16x32_bf16 v[96:99], v[124:127], v[186:189], v[88:91]
	v_mfma_f32_16x16x32_bf16 v[32:35], v[178:181], v[186:189], v[32:35]
	v_mfma_f32_16x16x32_bf16 v[36:39], v[124:127], v[194:197], v[36:39]
	v_mfma_f32_16x16x32_bf16 v[40:43], v[178:181], v[194:197], v[40:43]
	v_mfma_f32_16x16x32_bf16 v[44:47], v[124:127], v[202:205], v[44:47]
	v_mfma_f32_16x16x32_bf16 v[48:51], v[178:181], v[202:205], v[48:51]
	v_mfma_f32_16x16x32_bf16 v[52:55], v[124:127], v[210:213], v[52:55]
	v_mfma_f32_16x16x32_bf16 v[56:59], v[178:181], v[210:213], v[56:59]
	s_barrier
	s_mov_b32 m0, s41
	v_lshl_add_u64 v[250:251], s[46:47], 0, v[130:131]
	s_add_u32 s42, s46, 0x10000
	ds_read_b128 v[88:91], v156 offset:16384
	ds_read_b128 v[92:95], v156 offset:17408
	ds_read_b128 v[182:185], v156 offset:18432
	ds_read_b128 v[186:189], v156 offset:19456
	ds_read_b128 v[190:193], v156 offset:20480
	ds_read_b128 v[194:197], v156 offset:21504
	ds_read_b128 v[198:201], v156 offset:22528
	ds_read_b128 v[202:205], v156 offset:23552
	global_load_lds_dwordx4 v[250:251], off
	v_lshl_add_u64 v[252:253], s[46:47], 0, v[134:135]
	s_mov_b32 m0, s5
	s_addc_u32 s43, s47, 0
	global_load_lds_dwordx4 v[252:253], off
	s_mov_b32 m0, s31
	v_lshl_add_u64 v[138:139], s[48:49], 0, v[128:129]
	global_load_lds_dwordx4 v130, s[42:43]
	s_mov_b32 m0, s35
	v_lshl_add_u64 v[140:141], s[48:49], 0, v[132:133]
	global_load_lds_dwordx4 v134, s[42:43]
	s_mov_b32 m0, s55
	s_nop 0
	global_load_lds_dwordx4 v[138:139], off
	s_mov_b32 m0, s56
	s_nop 0
	global_load_lds_dwordx4 v[140:141], off
	s_waitcnt vmcnt(8)
	s_waitcnt lgkmcnt(0)
	s_barrier
	s_waitcnt lgkmcnt(0)
	v_mfma_f32_16x16x32_bf16 v[0:3], v[104:107], v[198:201], 0
	v_mfma_f32_16x16x32_bf16 v[4:7], v[112:115], v[198:201], 0
	v_mfma_f32_16x16x32_bf16 v[144:147], v[104:107], v[88:91], 0
	v_mfma_f32_16x16x32_bf16 v[148:151], v[112:115], v[88:91], 0
	v_mfma_f32_16x16x32_bf16 v[158:161], v[104:107], v[182:185], 0
	v_mfma_f32_16x16x32_bf16 v[162:165], v[112:115], v[182:185], 0
	v_mfma_f32_16x16x32_bf16 v[166:169], v[104:107], v[190:193], 0
	v_mfma_f32_16x16x32_bf16 v[170:173], v[112:115], v[190:193], 0
	v_mfma_f32_16x16x32_bf16 v[0:3], v[108:111], v[202:205], v[0:3]
	v_mfma_f32_16x16x32_bf16 v[4:7], v[116:119], v[202:205], v[4:7]
	v_mfma_f32_16x16x32_bf16 v[144:147], v[108:111], v[92:95], v[144:147]
	v_mfma_f32_16x16x32_bf16 v[148:151], v[116:119], v[92:95], v[148:151]
	v_mfma_f32_16x16x32_bf16 v[158:161], v[108:111], v[186:189], v[158:161]
	v_mfma_f32_16x16x32_bf16 v[162:165], v[116:119], v[186:189], v[162:165]
	v_mfma_f32_16x16x32_bf16 v[166:169], v[108:111], v[194:197], v[166:169]
	v_mfma_f32_16x16x32_bf16 v[170:173], v[116:119], v[194:197], v[170:173]
	v_mfma_f32_16x16x32_bf16 v[8:11], v[120:123], v[88:91], 0
	v_mfma_f32_16x16x32_bf16 v[206:209], v[124:127], v[92:95], v[8:11]
	v_mfma_f32_16x16x32_bf16 v[8:11], v[174:177], v[88:91], 0
	v_mfma_f32_16x16x32_bf16 v[210:213], v[178:181], v[92:95], v[8:11]
	v_mfma_f32_16x16x32_bf16 v[8:11], v[120:123], v[182:185], 0
	v_mfma_f32_16x16x32_bf16 v[222:225], v[124:127], v[186:189], v[8:11]
	v_mfma_f32_16x16x32_bf16 v[8:11], v[174:177], v[182:185], 0
	v_mfma_f32_16x16x32_bf16 v[182:185], v[178:181], v[186:189], v[8:11]
	v_mfma_f32_16x16x32_bf16 v[8:11], v[120:123], v[190:193], 0
	v_mfma_f32_16x16x32_bf16 v[186:189], v[124:127], v[194:197], v[8:11]
	v_mfma_f32_16x16x32_bf16 v[8:11], v[174:177], v[190:193], 0
	v_mfma_f32_16x16x32_bf16 v[190:193], v[178:181], v[194:197], v[8:11]
	v_mfma_f32_16x16x32_bf16 v[8:11], v[120:123], v[198:201], 0
	v_mfma_f32_16x16x32_bf16 v[194:197], v[124:127], v[202:205], v[8:11]
	v_mfma_f32_16x16x32_bf16 v[8:11], v[174:177], v[198:201], 0
	v_mfma_f32_16x16x32_bf16 v[174:177], v[178:181], v[202:205], v[8:11]
	s_barrier
	s_nop 4
	ds_read_b128 v[8:11], v136
	ds_read_b128 v[12:15], v136 offset:1024
	ds_read_b128 v[16:19], v136 offset:2048
	ds_read_b128 v[20:23], v136 offset:3072
	ds_read_b128 v[178:181], v142
	ds_read_b128 v[198:201], v142 offset:1024
	ds_read_b128 v[202:205], v142 offset:2048
	ds_read_b128 v[226:229], v142 offset:3072
	s_add_u32 s42, s48, 0x10000
	s_addc_u32 s43, s49, 0
	s_mov_b32 m0, s57
	ds_read_b128 v[24:27], v156 offset:32768
	ds_read_b128 v[28:31], v156 offset:33792
	ds_read_b128 v[60:63], v156 offset:34816
	ds_read_b128 v[230:233], v156 offset:35840
	ds_read_b128 v[234:237], v156 offset:36864
	ds_read_b128 v[238:241], v156 offset:37888
	ds_read_b128 v[242:245], v156 offset:38912
	ds_read_b128 v[246:249], v156 offset:39936
	global_load_lds_dwordx4 v128, s[42:43]
	s_mov_b32 m0, s58
	s_nop 0
	global_load_lds_dwordx4 v132, s[42:43]
	s_waitcnt vmcnt(8)
	s_waitcnt lgkmcnt(0)
	s_barrier
	s_waitcnt lgkmcnt(0)
	v_mfma_f32_16x16x32_bf16 v[64:67], v[8:11], v[24:27], v[64:67]
	v_mfma_f32_16x16x32_bf16 v[124:127], v[12:15], v[28:31], v[64:67]
	v_mfma_f32_16x16x32_bf16 v[64:67], v[16:19], v[24:27], v[68:71]
	v_mfma_f32_16x16x32_bf16 v[120:123], v[20:23], v[28:31], v[64:67]
	v_mfma_f32_16x16x32_bf16 v[64:67], v[8:11], v[60:63], v[72:75]
	v_mfma_f32_16x16x32_bf16 v[108:111], v[12:15], v[230:233], v[64:67]
	v_mfma_f32_16x16x32_bf16 v[64:67], v[16:19], v[60:63], v[76:79]
	v_mfma_f32_16x16x32_bf16 v[104:107], v[20:23], v[230:233], v[64:67]
	v_mfma_f32_16x16x32_bf16 v[64:67], v[8:11], v[234:237], v[80:83]
	v_mfma_f32_16x16x32_bf16 v[92:95], v[12:15], v[238:241], v[64:67]
	v_mfma_f32_16x16x32_bf16 v[64:67], v[16:19], v[234:237], v[84:87]
	v_mfma_f32_16x16x32_bf16 v[88:91], v[20:23], v[238:241], v[64:67]
	v_mfma_f32_16x16x32_bf16 v[64:67], v[8:11], v[242:245], v[214:217]
	v_mfma_f32_16x16x32_bf16 v[76:79], v[12:15], v[246:249], v[64:67]
	v_mfma_f32_16x16x32_bf16 v[64:67], v[16:19], v[242:245], v[218:221]
	v_mfma_f32_16x16x32_bf16 v[72:75], v[20:23], v[246:249], v[64:67]
	v_mfma_f32_16x16x32_bf16 v[64:67], v[178:181], v[24:27], v[96:99]
	v_mfma_f32_16x16x32_bf16 v[24:27], v[202:205], v[24:27], v[32:35]
	v_mfma_f32_16x16x32_bf16 v[112:115], v[226:229], v[28:31], v[24:27]
	v_mfma_f32_16x16x32_bf16 v[24:27], v[178:181], v[60:63], v[36:39]
	v_mfma_f32_16x16x32_bf16 v[100:103], v[198:201], v[230:233], v[24:27]
	v_mfma_f32_16x16x32_bf16 v[24:27], v[202:205], v[60:63], v[40:43]
	v_mfma_f32_16x16x32_bf16 v[96:99], v[226:229], v[230:233], v[24:27]
	v_mfma_f32_16x16x32_bf16 v[24:27], v[178:181], v[234:237], v[44:47]
	v_mfma_f32_16x16x32_bf16 v[84:87], v[198:201], v[238:241], v[24:27]
	v_mfma_f32_16x16x32_bf16 v[24:27], v[202:205], v[234:237], v[48:51]
	v_mfma_f32_16x16x32_bf16 v[80:83], v[226:229], v[238:241], v[24:27]
	v_mfma_f32_16x16x32_bf16 v[24:27], v[178:181], v[242:245], v[52:55]
	v_mfma_f32_16x16x32_bf16 v[68:71], v[198:201], v[246:249], v[24:27]
	v_mfma_f32_16x16x32_bf16 v[24:27], v[202:205], v[242:245], v[56:59]
	v_mfma_f32_16x16x32_bf16 v[116:119], v[198:201], v[28:31], v[64:67]
	v_mfma_f32_16x16x32_bf16 v[64:67], v[226:229], v[246:249], v[24:27]
	s_barrier
	s_mov_b32 m0, s68
	s_nop 2
	v_lshl_add_u64 v[24:25], v[250:251], 0, s[12:13]
	s_add_u32 s42, s46, 0x10080
	ds_read_b128 v[32:35], v156 offset:49152
	ds_read_b128 v[36:39], v156 offset:50176
	ds_read_b128 v[214:217], v156 offset:51200
	ds_read_b128 v[218:221], v156 offset:52224
	ds_read_b128 v[230:233], v156 offset:53248
	ds_read_b128 v[234:237], v156 offset:54272
	ds_read_b128 v[238:241], v156 offset:55296
	ds_read_b128 v[242:245], v156 offset:56320
	global_load_lds_dwordx4 v[24:25], off
	v_lshl_add_u64 v[24:25], v[252:253], 0, s[12:13]
	s_mov_b32 m0, s67
	s_addc_u32 s43, s47, 0
	global_load_lds_dwordx4 v[24:25], off
	s_mov_b32 m0, s44
	s_nop 0
	global_load_lds_dwordx4 v130, s[42:43]
	s_mov_b32 m0, s45
	s_nop 0
	global_load_lds_dwordx4 v134, s[42:43]
	v_lshl_add_u64 v[24:25], v[138:139], 0, s[12:13]
	s_mov_b32 m0, s59
	s_nop 0
	global_load_lds_dwordx4 v[24:25], off
	v_lshl_add_u64 v[24:25], v[140:141], 0, s[12:13]
	s_mov_b32 m0, s60
	s_nop 0
	global_load_lds_dwordx4 v[24:25], off
	s_waitcnt vmcnt(8)
	s_waitcnt lgkmcnt(0)
	s_barrier
	s_waitcnt lgkmcnt(0)
	v_mfma_f32_16x16x32_bf16 v[24:27], v[8:11], v[32:35], v[144:147]
	v_mfma_f32_16x16x32_bf16 v[60:63], v[12:15], v[36:39], v[24:27]
	v_mfma_f32_16x16x32_bf16 v[24:27], v[16:19], v[32:35], v[148:151]
	v_mfma_f32_16x16x32_bf16 v[56:59], v[20:23], v[36:39], v[24:27]
	v_mfma_f32_16x16x32_bf16 v[24:27], v[8:11], v[214:217], v[158:161]
	v_mfma_f32_16x16x32_bf16 v[44:47], v[12:15], v[218:221], v[24:27]
	v_mfma_f32_16x16x32_bf16 v[24:27], v[16:19], v[214:217], v[162:165]
	v_mfma_f32_16x16x32_bf16 v[40:43], v[20:23], v[218:221], v[24:27]
	v_mfma_f32_16x16x32_bf16 v[24:27], v[8:11], v[230:233], v[166:169]
	v_mfma_f32_16x16x32_bf16 v[0:3], v[8:11], v[238:241], v[0:3]
	v_mfma_f32_16x16x32_bf16 v[28:31], v[12:15], v[234:237], v[24:27]
	v_mfma_f32_16x16x32_bf16 v[24:27], v[16:19], v[230:233], v[170:173]
	v_mfma_f32_16x16x32_bf16 v[12:15], v[12:15], v[242:245], v[0:3]
	v_mfma_f32_16x16x32_bf16 v[0:3], v[16:19], v[238:241], v[4:7]
	v_mfma_f32_16x16x32_bf16 v[24:27], v[20:23], v[234:237], v[24:27]
	v_mfma_f32_16x16x32_bf16 v[8:11], v[20:23], v[242:245], v[0:3]
	v_mfma_f32_16x16x32_bf16 v[0:3], v[178:181], v[32:35], v[206:209]
	v_mfma_f32_16x16x32_bf16 v[52:55], v[198:201], v[36:39], v[0:3]
	v_mfma_f32_16x16x32_bf16 v[0:3], v[202:205], v[32:35], v[210:213]
	v_mfma_f32_16x16x32_bf16 v[48:51], v[226:229], v[36:39], v[0:3]
	v_mfma_f32_16x16x32_bf16 v[0:3], v[178:181], v[214:217], v[222:225]
	v_mfma_f32_16x16x32_bf16 v[36:39], v[198:201], v[218:221], v[0:3]
	v_mfma_f32_16x16x32_bf16 v[0:3], v[202:205], v[214:217], v[182:185]
	v_mfma_f32_16x16x32_bf16 v[32:35], v[226:229], v[218:221], v[0:3]
	v_mfma_f32_16x16x32_bf16 v[0:3], v[178:181], v[230:233], v[186:189]
	v_mfma_f32_16x16x32_bf16 v[20:23], v[198:201], v[234:237], v[0:3]
	v_mfma_f32_16x16x32_bf16 v[0:3], v[202:205], v[230:233], v[190:193]
	v_mfma_f32_16x16x32_bf16 v[16:19], v[226:229], v[234:237], v[0:3]
	v_mfma_f32_16x16x32_bf16 v[0:3], v[178:181], v[238:241], v[194:197]
	v_mfma_f32_16x16x32_bf16 v[4:7], v[198:201], v[242:245], v[0:3]
	v_mfma_f32_16x16x32_bf16 v[0:3], v[202:205], v[238:241], v[174:177]
	v_mfma_f32_16x16x32_bf16 v[0:3], v[226:229], v[242:245], v[0:3]
	s_barrier
	s_andn2_b64 vcc, exec, s[14:15]
	s_cbranch_vccnz .LBB0_467
	s_barrier

.LBB0_773:
	s_andn2_b64 vcc, exec, s[10:11]
	s_cbranch_vccnz .LBB0_823
	v_ashrrev_i32_e32 v2, 31, v0
	v_lshrrev_b32_e32 v2, 26, v2
	v_lshlrev_b32_e32 v1, 4, v0
	v_add_u32_e32 v2, v0, v2
	v_bfe_i32 v0, v0, 27, 1
	v_lshrrev_b32_e32 v0, 22, v0
	v_add_u32_e32 v0, v1, v0
	v_and_b32_e32 v0, 0xfffffc00, v0
	v_sub_u32_e32 v0, v1, v0
	v_lshrrev_b32_e32 v3, 4, v0
	v_bitop3_b32 v0, v3, v0, 32 bitop3:0x6c
	v_ashrrev_i32_e32 v4, 31, v0
	v_ashrrev_i32_e32 v2, 6, v2
	v_lshrrev_b32_e32 v4, 26, v4
	v_lshlrev_b32_e32 v3, 3, v2
	v_add_u32_e32 v4, v0, v4
	v_and_b32_e32 v3, -16, v3
	v_ashrrev_i32_e32 v5, 6, v4
	v_and_b32_e32 v4, 0xc0, v4
	v_add_u32_e32 v3, v5, v3
	v_sub_u32_e32 v0, v0, v4
	v_mov_b32_e32 v4, 1
	v_lshlrev_b32_e32 v2, 5, v2
	v_ashrrev_i16_sdwa v0, v4, sext(v0) dst_sel:DWORD dst_unused:UNUSED_PAD src0_sel:DWORD src1_sel:BYTE_0
	v_lshlrev_b32_e32 v6, 1, v3
	v_lshrrev_b32_e32 v7, 2, v3
	v_and_b32_e32 v5, 3, v5
	s_mov_b32 s3, 0x7fffe0
	v_and_b32_e32 v2, 32, v2
	v_bfe_i32 v0, v0, 0, 16
	v_and_b32_e32 v6, 24, v6
	v_and_b32_e32 v7, 4, v7
	v_and_or_b32 v5, v3, s3, v5
	v_or3_b32 v5, v5, v7, v6
	v_add_lshl_u32 v0, v2, v0, 1
	v_lshl_add_u32 v128, v3, 9, v0
	v_lshl_add_u32 v130, v5, 9, v0
	v_add_u32_e32 v0, 0x2000, v1
	v_ashrrev_i32_e32 v1, 31, v0
	v_lshrrev_b32_e32 v1, 22, v1
	v_add_u32_e32 v1, v0, v1
	v_ashrrev_i32_e32 v1, 10, v1
	v_mul_i32_i24_e32 v2, 0x400, v1
	v_sub_u32_e32 v0, v0, v2
	v_lshrrev_b32_e32 v2, 4, v0
	v_bitop3_b32 v0, v2, v0, 32 bitop3:0x6c
	v_ashrrev_i32_e32 v3, 31, v0
	v_lshrrev_b32_e32 v3, 26, v3
	s_add_u32 s50, s70, 0x19c00100
	v_lshlrev_b32_e32 v2, 3, v1
	v_add_u32_e32 v3, v0, v3
	s_addc_u32 s51, s71, 0
	v_and_b32_e32 v2, -16, v2
	v_ashrrev_i32_e32 v5, 6, v3
	s_add_u32 s52, s70, 0x5400100
	v_add_u32_e32 v2, v5, v2
	v_and_b32_e32 v5, 3, v5
	s_addc_u32 s53, s71, 0
	v_and_or_b32 v5, v2, s3, v5
	s_ashr_i32 s3, s14, 6
	s_ashr_i32 s5, s4, 31
	s_ashr_i32 s41, s40, 31
	s_ashr_i32 s2, s14, 8
	v_and_b32_e32 v3, 0xc0, v3
	s_lshl_b32 s54, s3, 10
	s_lshl_b64 s[10:11], s[4:5], 17
	s_lshl_b64 s[12:13], s[40:41], 17
	v_sub_u32_e32 v0, v0, v3
	s_add_u32 s44, s52, s12
	v_lshlrev_b32_e32 v1, 5, v1
	v_ashrrev_i16_sdwa v0, v4, sext(v0) dst_sel:DWORD dst_unused:UNUSED_PAD src0_sel:DWORD src1_sel:BYTE_0
	v_lshlrev_b32_e32 v3, 1, v2
	v_lshrrev_b32_e32 v4, 2, v2
	s_addc_u32 s45, s53, s13
	s_add_i32 s55, s54, 0
	v_and_b32_e32 v1, 32, v1
	v_bfe_i32 v0, v0, 0, 16
	v_and_b32_e32 v3, 24, v3
	v_and_b32_e32 v4, 4, v4
	s_add_i32 m0, s55, 0x10000
	v_or3_b32 v3, v5, v4, v3
	v_add_lshl_u32 v0, v1, v0, 1
	global_load_lds_dwordx4 v130, s[44:45]
	s_add_i32 m0, s55, 0x12000
	v_lshl_add_u32 v134, v3, 9, v0
	s_add_u32 s12, s44, 0x10000
	global_load_lds_dwordx4 v134, s[44:45]
	s_addc_u32 s13, s45, 0
	s_add_i32 m0, s55, 0x14000
	v_lshl_add_u32 v132, v2, 9, v0
	global_load_lds_dwordx4 v130, s[12:13]
	s_add_i32 m0, s55, 0x16000
	s_add_u32 s42, s50, s10
	s_addc_u32 s43, s51, s11
	s_add_i32 s56, s55, 0x2000
	global_load_lds_dwordx4 v134, s[12:13]
	s_mov_b32 m0, s55
	s_add_u32 s10, s42, 0x10000
	global_load_lds_dwordx4 v128, s[42:43]
	s_mov_b32 m0, s56
	s_addc_u32 s11, s43, 0
	s_add_i32 s57, s55, 0x4000
	global_load_lds_dwordx4 v132, s[42:43]
	s_mov_b32 m0, s57
	s_add_i32 s58, s55, 0x6000
	global_load_lds_dwordx4 v128, s[10:11]
	s_mov_b32 m0, s58
	v_mov_b32_e32 v137, 0
	global_load_lds_dwordx4 v132, s[10:11]
	v_mov_b32_e32 v131, v137
	v_mov_b32_e32 v135, v137
	v_mov_b32_e32 v129, v137
	v_mov_b32_e32 v133, v137
	s_cmp_eq_u32 s2, 1
	v_lshl_add_u64 v[6:7], s[44:45], 0, v[130:131]
	v_lshl_add_u64 v[4:5], s[44:45], 0, v[134:135]
	v_lshl_add_u64 v[0:1], s[42:43], 0, v[128:129]
	s_cselect_b64 s[10:11], -1, 0
	s_cmp_lg_u32 s2, 1
	v_lshl_add_u64 v[2:3], s[42:43], 0, v[132:133]
	s_setprio 1
	s_cbranch_scc1 .LBB0_776
	s_barrier
	s_setprio 0

.LBB0_898:
	s_andn2_b64 vcc, exec, s[2:3]
	s_cbranch_vccnz .LBB0_934
	v_ashrrev_i32_e32 v1, 31, v2
	v_lshrrev_b32_e32 v1, 26, v1
	v_add_u32_e32 v1, v2, v1
	v_ashrrev_i32_e32 v9, 6, v1
	v_bfe_i32 v1, v2, 27, 1
	v_lshlrev_b32_e32 v0, 4, v2
	v_lshrrev_b32_e32 v1, 22, v1
	v_add_u32_e32 v1, v0, v1
	v_and_b32_e32 v1, 0xfffffc00, v1
	v_sub_u32_e32 v1, v0, v1
	v_lshrrev_b32_e32 v2, 4, v1
	v_bitop3_b32 v1, v2, v1, 32 bitop3:0x6c
	v_ashrrev_i32_e32 v3, 31, v1
	v_lshrrev_b32_e32 v3, 26, v3
	v_add_u32_e32 v3, v1, v3
	v_ashrrev_i32_e32 v10, 6, v3
	v_and_b32_e32 v3, 0xc0, v3
	v_sub_u32_e32 v1, v1, v3
	v_mov_b32_e32 v3, 1
	v_lshlrev_b32_e32 v2, 3, v9
	v_lshlrev_b32_e32 v4, 5, v9
	v_ashrrev_i16_sdwa v1, v3, sext(v1) dst_sel:DWORD dst_unused:UNUSED_PAD src0_sel:DWORD src1_sel:BYTE_0
	v_and_b32_e32 v2, 0x1ffff0, v2
	v_and_b32_e32 v4, 32, v4
	v_bfe_i32 v11, v1, 0, 16
	v_add_u32_e32 v1, v4, v11
	v_add_lshl_u32 v2, v10, v2, 11
	v_add_u32_e32 v0, 0x2000, v0
	v_lshl_add_u32 v128, v1, 1, v2
	v_ashrrev_i32_e32 v1, 31, v0
	v_lshrrev_b32_e32 v1, 22, v1
	v_add_u32_e32 v1, v0, v1
	v_ashrrev_i32_e32 v12, 10, v1
	v_mul_i32_i24_e32 v1, 0x400, v12
	v_sub_u32_e32 v0, v0, v1
	v_lshrrev_b32_e32 v1, 4, v0
	s_add_u32 s36, s70, 0x1ac00000
	v_bitop3_b32 v0, v1, v0, 32 bitop3:0x6c
	s_addc_u32 s37, s71, 0
	v_ashrrev_i32_e32 v2, 31, v0
	s_add_u32 s38, s70, 0x5000000
	v_lshrrev_b32_e32 v2, 26, v2
	s_addc_u32 s39, s71, 0
	s_ashr_i32 s2, s16, 6
	v_add_u32_e32 v2, v0, v2
	s_ashr_i32 s27, s26, 31
	s_ashr_i32 s11, s10, 31
	v_ashrrev_i32_e32 v13, 6, v2
	v_and_b32_e32 v2, 0xc0, v2
	s_ashr_i32 s3, s16, 8
	s_lshl_b32 s40, s2, 10
	s_lshl_b64 s[4:5], s[26:27], 19
	s_lshl_b64 s[12:13], s[10:11], 19
	v_sub_u32_e32 v0, v0, v2
	s_add_u32 s30, s38, s12
	v_lshlrev_b32_e32 v1, 3, v12
	v_lshlrev_b32_e32 v4, 5, v12
	v_ashrrev_i16_sdwa v0, v3, sext(v0) dst_sel:DWORD dst_unused:UNUSED_PAD src0_sel:DWORD src1_sel:BYTE_0
	s_addc_u32 s31, s39, s13
	s_add_i32 s41, s40, 0
	v_and_b32_e32 v1, 0x1ffff0, v1
	v_and_b32_e32 v4, 32, v4
	v_bfe_i32 v14, v0, 0, 16
	s_add_i32 m0, s41, 0x10000
	v_add_u32_e32 v0, v4, v14
	v_add_lshl_u32 v1, v13, v1, 11
	global_load_lds_dwordx4 v128, s[30:31]
	s_add_i32 m0, s41, 0x12000
	v_lshl_add_u32 v130, v0, 1, v1
	s_add_u32 s12, s30, 0x40000
	global_load_lds_dwordx4 v130, s[30:31]
	s_addc_u32 s13, s31, 0
	s_add_i32 m0, s41, 0x14000
	v_mov_b32_e32 v129, 0
	global_load_lds_dwordx4 v128, s[12:13]
	s_add_i32 m0, s41, 0x16000
	s_add_u32 s28, s36, s4
	s_addc_u32 s29, s37, s5
	s_add_i32 s42, s41, 0x2000
	global_load_lds_dwordx4 v130, s[12:13]
	s_mov_b32 m0, s41
	s_add_u32 s4, s28, 0x40000
	global_load_lds_dwordx4 v128, s[28:29]
	s_mov_b32 m0, s42
	s_addc_u32 s5, s29, 0
	s_add_i32 s43, s41, 0x4000
	global_load_lds_dwordx4 v130, s[28:29]
	s_mov_b32 m0, s43
	s_add_i32 s44, s41, 0x6000
	global_load_lds_dwordx4 v128, s[4:5]
	s_mov_b32 m0, s44
	v_mov_b32_e32 v131, v129
	global_load_lds_dwordx4 v130, s[4:5]
	s_cmp_eq_u32 s3, 1
	s_mov_b32 s11, 0
	v_lshl_add_u64 v[6:7], s[30:31], 0, v[128:129]
	v_lshl_add_u64 v[4:5], s[30:31], 0, v[130:131]
	v_lshl_add_u64 v[0:1], s[28:29], 0, v[128:129]
	s_cselect_b64 s[12:13], -1, 0
	s_cmp_lg_u32 s3, 1
	v_lshl_add_u64 v[2:3], s[28:29], 0, v[130:131]
	s_setprio 1
	s_cbranch_scc1 .LBB0_901
	s_barrier
	s_setprio 0

.LBB0_911:
	ds_read_b128 v[140:143], v147
	ds_read_b128 v[152:155], v147 offset:1024
	ds_read_b128 v[156:159], v147 offset:2048
	ds_read_b128 v[160:163], v147 offset:3072
	ds_read_b128 v[164:167], v148
	ds_read_b128 v[168:171], v148 offset:1024
	ds_read_b128 v[172:175], v148 offset:2048
	ds_read_b128 v[176:179], v148 offset:3072
	s_add_u32 s30, s28, 0xfffc0080
	s_addc_u32 s31, s29, -1
	s_cmp_eq_u32 s56, 12
	s_cselect_b32 s35, s21, s31
	s_cselect_b32 s34, s27, s30
	s_cselect_b32 s31, s19, s55
	s_cselect_b32 s30, s53, s54
	s_add_i32 m0, s41, 0xc000
	ds_read_b128 v[180:183], v149
	ds_read_b128 v[184:187], v149 offset:1024
	ds_read_b128 v[188:191], v149 offset:2048
	ds_read_b128 v[192:195], v149 offset:3072
	ds_read_b128 v[196:199], v149 offset:4096
	ds_read_b128 v[200:203], v149 offset:5120
	ds_read_b128 v[204:207], v149 offset:6144
	ds_read_b128 v[208:211], v149 offset:7168
	global_load_lds_dwordx4 v132, s[28:29]
	s_add_i32 m0, s41, 0xe000
	s_nop 0
	global_load_lds_dwordx4 v134, s[28:29]
	s_waitcnt vmcnt(8)
	s_waitcnt lgkmcnt(0)
	s_barrier
	s_waitcnt lgkmcnt(0)
	v_mfma_f32_16x16x32_bf16 v[124:127], v[140:143], v[180:183], v[124:127]
	v_mfma_f32_16x16x32_bf16 v[120:123], v[156:159], v[180:183], v[120:123]
	v_mfma_f32_16x16x32_bf16 v[108:111], v[140:143], v[188:191], v[108:111]
	v_mfma_f32_16x16x32_bf16 v[104:107], v[156:159], v[188:191], v[104:107]
	v_mfma_f32_16x16x32_bf16 v[92:95], v[140:143], v[196:199], v[92:95]
	v_mfma_f32_16x16x32_bf16 v[88:91], v[156:159], v[196:199], v[88:91]
	v_mfma_f32_16x16x32_bf16 v[76:79], v[140:143], v[204:207], v[76:79]
	v_mfma_f32_16x16x32_bf16 v[72:75], v[156:159], v[204:207], v[72:75]
	v_mfma_f32_16x16x32_bf16 v[124:127], v[152:155], v[184:187], v[124:127]
	v_mfma_f32_16x16x32_bf16 v[120:123], v[160:163], v[184:187], v[120:123]
	v_mfma_f32_16x16x32_bf16 v[108:111], v[152:155], v[192:195], v[108:111]
	v_mfma_f32_16x16x32_bf16 v[104:107], v[160:163], v[192:195], v[104:107]
	v_mfma_f32_16x16x32_bf16 v[92:95], v[152:155], v[200:203], v[92:95]
	v_mfma_f32_16x16x32_bf16 v[88:91], v[160:163], v[200:203], v[88:91]
	v_mfma_f32_16x16x32_bf16 v[76:79], v[152:155], v[208:211], v[76:79]
	v_mfma_f32_16x16x32_bf16 v[72:75], v[160:163], v[208:211], v[72:75]
	v_mfma_f32_16x16x32_bf16 v[116:119], v[164:167], v[180:183], v[116:119]
	v_mfma_f32_16x16x32_bf16 v[112:115], v[172:175], v[180:183], v[112:115]
	v_mfma_f32_16x16x32_bf16 v[100:103], v[164:167], v[188:191], v[100:103]
	v_mfma_f32_16x16x32_bf16 v[96:99], v[172:175], v[188:191], v[96:99]
	v_mfma_f32_16x16x32_bf16 v[84:87], v[164:167], v[196:199], v[84:87]
	v_mfma_f32_16x16x32_bf16 v[80:83], v[172:175], v[196:199], v[80:83]
	v_mfma_f32_16x16x32_bf16 v[68:71], v[164:167], v[204:207], v[68:71]
	v_mfma_f32_16x16x32_bf16 v[64:67], v[172:175], v[204:207], v[64:67]
	v_mfma_f32_16x16x32_bf16 v[116:119], v[168:171], v[184:187], v[116:119]
	v_mfma_f32_16x16x32_bf16 v[112:115], v[176:179], v[184:187], v[112:115]
	v_mfma_f32_16x16x32_bf16 v[100:103], v[168:171], v[192:195], v[100:103]
	v_mfma_f32_16x16x32_bf16 v[96:99], v[176:179], v[192:195], v[96:99]
	v_mfma_f32_16x16x32_bf16 v[84:87], v[168:171], v[200:203], v[84:87]
	v_mfma_f32_16x16x32_bf16 v[80:83], v[176:179], v[200:203], v[80:83]
	v_mfma_f32_16x16x32_bf16 v[68:71], v[168:171], v[208:211], v[68:71]
	v_mfma_f32_16x16x32_bf16 v[64:67], v[176:179], v[208:211], v[64:67]
	s_barrier
	s_add_i32 s57, s50, s40
	v_lshl_add_u64 v[212:213], s[30:31], 0, v[128:129]
	s_mov_b32 m0, s57
	ds_read_b128 v[180:183], v149 offset:16384
	ds_read_b128 v[184:187], v149 offset:17408
	ds_read_b128 v[188:191], v149 offset:18432
	ds_read_b128 v[192:195], v149 offset:19456
	ds_read_b128 v[196:199], v149 offset:20480
	ds_read_b128 v[200:203], v149 offset:21504
	ds_read_b128 v[204:207], v149 offset:22528
	ds_read_b128 v[208:211], v149 offset:23552
	global_load_lds_dwordx4 v[212:213], off
	s_add_i32 m0, s57, 0x2000
	s_add_u32 s58, s30, 0x40000
	v_lshl_add_u64 v[214:215], s[30:31], 0, v[130:131]
	s_addc_u32 s59, s31, 0
	s_add_i32 s57, s51, s40
	global_load_lds_dwordx4 v[214:215], off
	v_lshl_add_u64 v[216:217], s[58:59], 0, v[128:129]
	s_mov_b32 m0, s57
	v_lshl_add_u64 v[218:219], s[34:35], 0, v[130:131]
	global_load_lds_dwordx4 v[216:217], off
	s_add_i32 m0, s57, 0x2000
	s_nop 0
	global_load_lds_dwordx4 v130, s[58:59]
	v_lshl_add_u64 v[216:217], s[34:35], 0, v[128:129]
	s_mov_b32 m0, s41
	s_nop 0
	global_load_lds_dwordx4 v[216:217], off
	s_mov_b32 m0, s42
	s_nop 0
	global_load_lds_dwordx4 v[218:219], off
	s_waitcnt vmcnt(8)
	s_waitcnt lgkmcnt(0)
	s_barrier
	s_waitcnt lgkmcnt(0)
	v_mfma_f32_16x16x32_bf16 v[60:63], v[140:143], v[180:183], v[60:63]
	v_mfma_f32_16x16x32_bf16 v[56:59], v[156:159], v[180:183], v[56:59]
	v_mfma_f32_16x16x32_bf16 v[44:47], v[140:143], v[188:191], v[44:47]
	v_mfma_f32_16x16x32_bf16 v[40:43], v[156:159], v[188:191], v[40:43]
	v_mfma_f32_16x16x32_bf16 v[28:31], v[140:143], v[196:199], v[28:31]
	v_mfma_f32_16x16x32_bf16 v[24:27], v[156:159], v[196:199], v[24:27]
	v_mfma_f32_16x16x32_bf16 v[12:15], v[140:143], v[204:207], v[12:15]
	v_mfma_f32_16x16x32_bf16 v[8:11], v[156:159], v[204:207], v[8:11]
	v_mfma_f32_16x16x32_bf16 v[60:63], v[152:155], v[184:187], v[60:63]
	v_mfma_f32_16x16x32_bf16 v[56:59], v[160:163], v[184:187], v[56:59]
	v_mfma_f32_16x16x32_bf16 v[44:47], v[152:155], v[192:195], v[44:47]
	v_mfma_f32_16x16x32_bf16 v[40:43], v[160:163], v[192:195], v[40:43]
	v_mfma_f32_16x16x32_bf16 v[28:31], v[152:155], v[200:203], v[28:31]
	v_mfma_f32_16x16x32_bf16 v[24:27], v[160:163], v[200:203], v[24:27]
	v_mfma_f32_16x16x32_bf16 v[12:15], v[152:155], v[208:211], v[12:15]
	v_mfma_f32_16x16x32_bf16 v[8:11], v[160:163], v[208:211], v[8:11]
	v_mfma_f32_16x16x32_bf16 v[52:55], v[164:167], v[180:183], v[52:55]
	v_mfma_f32_16x16x32_bf16 v[48:51], v[172:175], v[180:183], v[48:51]
	v_mfma_f32_16x16x32_bf16 v[36:39], v[164:167], v[188:191], v[36:39]
	v_mfma_f32_16x16x32_bf16 v[32:35], v[172:175], v[188:191], v[32:35]
	v_mfma_f32_16x16x32_bf16 v[20:23], v[164:167], v[196:199], v[20:23]
	v_mfma_f32_16x16x32_bf16 v[16:19], v[172:175], v[196:199], v[16:19]
	v_mfma_f32_16x16x32_bf16 v[4:7], v[164:167], v[204:207], v[4:7]
	v_mfma_f32_16x16x32_bf16 v[0:3], v[172:175], v[204:207], v[0:3]
	v_mfma_f32_16x16x32_bf16 v[52:55], v[168:171], v[184:187], v[52:55]
	v_mfma_f32_16x16x32_bf16 v[48:51], v[176:179], v[184:187], v[48:51]
	v_mfma_f32_16x16x32_bf16 v[36:39], v[168:171], v[192:195], v[36:39]
	v_mfma_f32_16x16x32_bf16 v[32:35], v[176:179], v[192:195], v[32:35]
	v_mfma_f32_16x16x32_bf16 v[20:23], v[168:171], v[200:203], v[20:23]
	v_mfma_f32_16x16x32_bf16 v[16:19], v[176:179], v[200:203], v[16:19]
	v_mfma_f32_16x16x32_bf16 v[4:7], v[168:171], v[208:211], v[4:7]
	v_mfma_f32_16x16x32_bf16 v[0:3], v[176:179], v[208:211], v[0:3]
	s_barrier
	s_add_i32 s57, 0, 0x18000
	v_add_u32_e32 v151, s57, v145
	s_add_i32 s58, 0, 0x1c000
	ds_read_b128 v[140:143], v151
	ds_read_b128 v[152:155], v151 offset:1024
	ds_read_b128 v[156:159], v151 offset:2048
	ds_read_b128 v[160:163], v151 offset:3072
	v_add_u32_e32 v151, s58, v145
	ds_read_b128 v[164:167], v151
	ds_read_b128 v[168:171], v151 offset:1024
	ds_read_b128 v[172:175], v151 offset:2048
	ds_read_b128 v[176:179], v151 offset:3072
	s_add_u32 s34, s34, 0x40000
	s_addc_u32 s35, s35, 0
	s_mov_b32 m0, s43
	v_lshl_add_u64 v[220:221], s[34:35], 0, v[128:129]
	ds_read_b128 v[180:183], v149 offset:32768
	ds_read_b128 v[184:187], v149 offset:33792
	ds_read_b128 v[188:191], v149 offset:34816
	ds_read_b128 v[192:195], v149 offset:35840
	ds_read_b128 v[196:199], v149 offset:36864
	ds_read_b128 v[200:203], v149 offset:37888
	ds_read_b128 v[204:207], v149 offset:38912
	ds_read_b128 v[208:211], v149 offset:39936
	global_load_lds_dwordx4 v[220:221], off
	v_lshl_add_u64 v[220:221], s[34:35], 0, v[130:131]
	s_mov_b32 m0, s44
	s_nop 0
	global_load_lds_dwordx4 v[220:221], off
	s_waitcnt vmcnt(8)
	s_waitcnt lgkmcnt(0)
	s_barrier
	s_waitcnt lgkmcnt(0)
	v_mfma_f32_16x16x32_bf16 v[124:127], v[140:143], v[180:183], v[124:127]
	v_mfma_f32_16x16x32_bf16 v[120:123], v[156:159], v[180:183], v[120:123]
	v_mfma_f32_16x16x32_bf16 v[108:111], v[140:143], v[188:191], v[108:111]
	v_mfma_f32_16x16x32_bf16 v[104:107], v[156:159], v[188:191], v[104:107]
	v_mfma_f32_16x16x32_bf16 v[92:95], v[140:143], v[196:199], v[92:95]
	v_mfma_f32_16x16x32_bf16 v[88:91], v[156:159], v[196:199], v[88:91]
	v_mfma_f32_16x16x32_bf16 v[76:79], v[140:143], v[204:207], v[76:79]
	v_mfma_f32_16x16x32_bf16 v[72:75], v[156:159], v[204:207], v[72:75]
	v_mfma_f32_16x16x32_bf16 v[124:127], v[152:155], v[184:187], v[124:127]
	v_mfma_f32_16x16x32_bf16 v[120:123], v[160:163], v[184:187], v[120:123]
	v_mfma_f32_16x16x32_bf16 v[108:111], v[152:155], v[192:195], v[108:111]
	v_mfma_f32_16x16x32_bf16 v[104:107], v[160:163], v[192:195], v[104:107]
	v_mfma_f32_16x16x32_bf16 v[92:95], v[152:155], v[200:203], v[92:95]
	v_mfma_f32_16x16x32_bf16 v[88:91], v[160:163], v[200:203], v[88:91]
	v_mfma_f32_16x16x32_bf16 v[76:79], v[152:155], v[208:211], v[76:79]
	v_mfma_f32_16x16x32_bf16 v[72:75], v[160:163], v[208:211], v[72:75]
	v_mfma_f32_16x16x32_bf16 v[116:119], v[164:167], v[180:183], v[116:119]
	v_mfma_f32_16x16x32_bf16 v[112:115], v[172:175], v[180:183], v[112:115]
	v_mfma_f32_16x16x32_bf16 v[100:103], v[164:167], v[188:191], v[100:103]
	v_mfma_f32_16x16x32_bf16 v[96:99], v[172:175], v[188:191], v[96:99]
	v_mfma_f32_16x16x32_bf16 v[84:87], v[164:167], v[196:199], v[84:87]
	v_mfma_f32_16x16x32_bf16 v[80:83], v[172:175], v[196:199], v[80:83]
	v_mfma_f32_16x16x32_bf16 v[68:71], v[164:167], v[204:207], v[68:71]
	v_mfma_f32_16x16x32_bf16 v[64:67], v[172:175], v[204:207], v[64:67]
	v_mfma_f32_16x16x32_bf16 v[116:119], v[168:171], v[184:187], v[116:119]
	v_mfma_f32_16x16x32_bf16 v[112:115], v[176:179], v[184:187], v[112:115]
	v_mfma_f32_16x16x32_bf16 v[100:103], v[168:171], v[192:195], v[100:103]
	v_mfma_f32_16x16x32_bf16 v[96:99], v[176:179], v[192:195], v[96:99]
	v_mfma_f32_16x16x32_bf16 v[84:87], v[168:171], v[200:203], v[84:87]
	v_mfma_f32_16x16x32_bf16 v[80:83], v[176:179], v[200:203], v[80:83]
	v_mfma_f32_16x16x32_bf16 v[68:71], v[168:171], v[208:211], v[68:71]
	v_mfma_f32_16x16x32_bf16 v[64:67], v[176:179], v[208:211], v[64:67]
	s_barrier
	s_add_i32 s34, s57, s40
	v_lshl_add_u64 v[212:213], v[212:213], 0, s[14:15]
	s_mov_b32 m0, s34
	ds_read_b128 v[180:183], v149 offset:49152
	ds_read_b128 v[184:187], v149 offset:50176
	ds_read_b128 v[188:191], v149 offset:51200
	ds_read_b128 v[192:195], v149 offset:52224
	ds_read_b128 v[196:199], v149 offset:53248
	ds_read_b128 v[200:203], v149 offset:54272
	ds_read_b128 v[204:207], v149 offset:55296
	ds_read_b128 v[208:211], v149 offset:56320
	global_load_lds_dwordx4 v[212:213], off
	s_add_i32 m0, s34, 0x2000
	s_add_u32 s30, s30, 0x40080
	v_lshl_add_u64 v[212:213], v[214:215], 0, s[14:15]
	s_addc_u32 s31, s31, 0
	s_add_i32 s34, s58, s40
	global_load_lds_dwordx4 v[212:213], off
	v_lshl_add_u64 v[212:213], s[30:31], 0, v[128:129]
	s_mov_b32 m0, s34
	s_nop 0
	global_load_lds_dwordx4 v[212:213], off
	s_add_i32 m0, s34, 0x2000
	s_nop 0
	global_load_lds_dwordx4 v130, s[30:31]
	v_lshl_add_u64 v[212:213], v[216:217], 0, s[14:15]
	s_mov_b32 m0, s46
	s_nop 0
	global_load_lds_dwordx4 v[212:213], off
	v_lshl_add_u64 v[212:213], v[218:219], 0, s[14:15]
	s_mov_b32 m0, s47
	s_nop 0
	global_load_lds_dwordx4 v[212:213], off
	s_waitcnt vmcnt(8)
	s_waitcnt lgkmcnt(0)
	s_barrier
	s_waitcnt lgkmcnt(0)
	v_mfma_f32_16x16x32_bf16 v[60:63], v[140:143], v[180:183], v[60:63]
	v_mfma_f32_16x16x32_bf16 v[56:59], v[156:159], v[180:183], v[56:59]
	v_mfma_f32_16x16x32_bf16 v[44:47], v[140:143], v[188:191], v[44:47]
	v_mfma_f32_16x16x32_bf16 v[40:43], v[156:159], v[188:191], v[40:43]
	v_mfma_f32_16x16x32_bf16 v[28:31], v[140:143], v[196:199], v[28:31]
	v_mfma_f32_16x16x32_bf16 v[24:27], v[156:159], v[196:199], v[24:27]
	v_mfma_f32_16x16x32_bf16 v[12:15], v[140:143], v[204:207], v[12:15]
	v_mfma_f32_16x16x32_bf16 v[8:11], v[156:159], v[204:207], v[8:11]
	v_mfma_f32_16x16x32_bf16 v[60:63], v[152:155], v[184:187], v[60:63]
	v_mfma_f32_16x16x32_bf16 v[56:59], v[160:163], v[184:187], v[56:59]
	v_mfma_f32_16x16x32_bf16 v[44:47], v[152:155], v[192:195], v[44:47]
	v_mfma_f32_16x16x32_bf16 v[40:43], v[160:163], v[192:195], v[40:43]
	v_mfma_f32_16x16x32_bf16 v[28:31], v[152:155], v[200:203], v[28:31]
	v_mfma_f32_16x16x32_bf16 v[24:27], v[160:163], v[200:203], v[24:27]
	v_mfma_f32_16x16x32_bf16 v[12:15], v[152:155], v[208:211], v[12:15]
	v_mfma_f32_16x16x32_bf16 v[8:11], v[160:163], v[208:211], v[8:11]
	v_mfma_f32_16x16x32_bf16 v[52:55], v[164:167], v[180:183], v[52:55]
	v_mfma_f32_16x16x32_bf16 v[48:51], v[172:175], v[180:183], v[48:51]
	v_mfma_f32_16x16x32_bf16 v[36:39], v[164:167], v[188:191], v[36:39]
	v_mfma_f32_16x16x32_bf16 v[32:35], v[172:175], v[188:191], v[32:35]
	v_mfma_f32_16x16x32_bf16 v[20:23], v[164:167], v[196:199], v[20:23]
	v_mfma_f32_16x16x32_bf16 v[16:19], v[172:175], v[196:199], v[16:19]
	v_mfma_f32_16x16x32_bf16 v[4:7], v[164:167], v[204:207], v[4:7]
	v_mfma_f32_16x16x32_bf16 v[0:3], v[172:175], v[204:207], v[0:3]
	v_mfma_f32_16x16x32_bf16 v[52:55], v[168:171], v[184:187], v[52:55]
	v_mfma_f32_16x16x32_bf16 v[48:51], v[176:179], v[184:187], v[48:51]
	v_mfma_f32_16x16x32_bf16 v[36:39], v[168:171], v[192:195], v[36:39]
	v_mfma_f32_16x16x32_bf16 v[32:35], v[176:179], v[192:195], v[32:35]
	v_mfma_f32_16x16x32_bf16 v[20:23], v[168:171], v[200:203], v[20:23]
	v_mfma_f32_16x16x32_bf16 v[16:19], v[176:179], v[200:203], v[16:19]
	v_mfma_f32_16x16x32_bf16 v[4:7], v[168:171], v[208:211], v[4:7]
	v_mfma_f32_16x16x32_bf16 v[0:3], v[176:179], v[208:211], v[0:3]
	s_add_i32 s56, s56, 2
	s_add_u32 s28, s28, 0x100
	s_addc_u32 s29, s29, 0
	s_add_u32 s54, s54, 0x100
	s_addc_u32 s55, s55, 0
	s_cmp_gt_u32 s56, 13
	s_barrier
	s_cbranch_scc0 .LBB0_911
	s_and_b64 vcc, exec, s[16:17]
	s_cbranch_vccz .LBB0_914
	s_barrier

.LBB0_968:
	s_andn2_b64 vcc, exec, s[2:3]
	s_cbranch_vccnz .LBB0_1010
	v_ashrrev_i32_e32 v1, 31, v2
	v_lshrrev_b32_e32 v1, 26, v1
	v_add_u32_e32 v1, v2, v1
	v_ashrrev_i32_e32 v9, 6, v1
	v_bfe_i32 v1, v2, 27, 1
	v_lshlrev_b32_e32 v0, 4, v2
	v_lshrrev_b32_e32 v1, 22, v1
	v_add_u32_e32 v1, v0, v1
	v_and_b32_e32 v1, 0xfffffc00, v1
	v_sub_u32_e32 v1, v0, v1
	v_lshrrev_b32_e32 v2, 4, v1
	v_bitop3_b32 v1, v2, v1, 32 bitop3:0x6c
	v_ashrrev_i32_e32 v3, 31, v1
	v_lshrrev_b32_e32 v3, 26, v3
	v_add_u32_e32 v3, v1, v3
	v_lshlrev_b32_e32 v2, 3, v9
	v_ashrrev_i32_e32 v10, 6, v3
	v_and_b32_e32 v3, 0xc0, v3
	v_and_b32_e32 v2, -16, v2
	v_sub_u32_e32 v1, v1, v3
	v_mov_b32_e32 v3, 1
	v_add_u32_e32 v2, v10, v2
	v_ashrrev_i16_sdwa v1, v3, sext(v1) dst_sel:DWORD dst_unused:UNUSED_PAD src0_sel:DWORD src1_sel:BYTE_0
	v_lshlrev_b32_e32 v4, 5, v9
	v_bfe_i32 v11, v1, 0, 16
	v_lshlrev_b32_e32 v1, 1, v2
	v_lshrrev_b32_e32 v5, 2, v2
	v_and_b32_e32 v6, 3, v10
	s_mov_b32 s3, 0x1fffe0
	v_and_b32_e32 v4, 32, v4
	v_and_b32_e32 v1, 24, v1
	v_and_b32_e32 v5, 4, v5
	v_and_or_b32 v6, v2, s3, v6
	v_or3_b32 v1, v6, v5, v1
	v_add_lshl_u32 v4, v4, v11, 1
	v_add_u32_e32 v0, 0x2000, v0
	v_lshl_add_u32 v130, v1, 11, v4
	v_ashrrev_i32_e32 v1, 31, v0
	v_lshrrev_b32_e32 v1, 22, v1
	v_add_u32_e32 v1, v0, v1
	v_ashrrev_i32_e32 v12, 10, v1
	v_mul_i32_i24_e32 v1, 0x400, v12
	v_sub_u32_e32 v0, v0, v1
	v_lshrrev_b32_e32 v1, 4, v0
	v_bitop3_b32 v0, v1, v0, 32 bitop3:0x6c
	v_lshl_add_u32 v128, v2, 11, v4
	v_ashrrev_i32_e32 v2, 31, v0
	v_lshrrev_b32_e32 v2, 26, v2
	v_add_u32_e32 v2, v0, v2
	v_lshlrev_b32_e32 v1, 3, v12
	v_ashrrev_i32_e32 v13, 6, v2
	v_and_b32_e32 v2, 0xc0, v2
	s_add_u32 s38, s70, 0x1000000
	v_and_b32_e32 v1, -16, v1
	v_sub_u32_e32 v0, v0, v2
	s_addc_u32 s39, s71, 0
	s_ashr_i32 s2, s4, 6
	v_add_u32_e32 v1, v13, v1
	v_ashrrev_i16_sdwa v0, v3, sext(v0) dst_sel:DWORD dst_unused:UNUSED_PAD src0_sel:DWORD src1_sel:BYTE_0
	v_and_b32_e32 v3, 3, v13
	s_ashr_i32 s29, s28, 31
	s_ashr_i32 s27, s26, 31
	v_and_or_b32 v3, v1, s3, v3
	s_ashr_i32 s3, s4, 8
	s_lshl_b32 s40, s2, 10
	s_waitcnt lgkmcnt(0)
	s_lshl_b64 s[8:9], s[28:29], 19
	s_lshl_b64 s[10:11], s[26:27], 19
	s_add_u32 s34, s38, s10
	v_lshlrev_b32_e32 v4, 5, v12
	v_bfe_i32 v14, v0, 0, 16
	v_lshlrev_b32_e32 v0, 1, v1
	v_lshrrev_b32_e32 v2, 2, v1
	s_addc_u32 s35, s39, s11
	s_add_i32 s41, s40, 0
	v_and_b32_e32 v4, 32, v4
	v_and_b32_e32 v0, 24, v0
	v_and_b32_e32 v2, 4, v2
	s_add_i32 m0, s41, 0x10000
	v_or3_b32 v0, v3, v2, v0
	v_add_lshl_u32 v2, v4, v14, 1
	global_load_lds_dwordx4 v130, s[34:35]
	s_add_i32 m0, s41, 0x12000
	v_lshl_add_u32 v134, v0, 11, v2
	s_add_u32 s10, s34, 0x40000
	global_load_lds_dwordx4 v134, s[34:35]
	s_addc_u32 s11, s35, 0
	s_add_i32 m0, s41, 0x14000
	v_lshl_add_u32 v132, v1, 11, v2
	global_load_lds_dwordx4 v130, s[10:11]
	s_add_i32 m0, s41, 0x16000
	s_add_u32 s30, s76, s8
	s_addc_u32 s31, s77, s9
	s_add_i32 s42, s41, 0x2000
	global_load_lds_dwordx4 v134, s[10:11]
	s_mov_b32 m0, s41
	s_add_u32 s8, s30, 0x40000
	global_load_lds_dwordx4 v128, s[30:31]
	s_mov_b32 m0, s42
	s_addc_u32 s9, s31, 0
	s_add_i32 s43, s41, 0x4000
	global_load_lds_dwordx4 v132, s[30:31]
	s_mov_b32 m0, s43
	s_add_i32 s44, s41, 0x6000
	global_load_lds_dwordx4 v128, s[8:9]
	s_mov_b32 m0, s44
	v_mov_b32_e32 v137, 0
	global_load_lds_dwordx4 v132, s[8:9]
	v_mov_b32_e32 v131, v137
	v_mov_b32_e32 v135, v137
	v_mov_b32_e32 v129, v137
	v_mov_b32_e32 v133, v137
	s_cmp_eq_u32 s3, 1
	s_mov_b32 s9, 0
	v_lshl_add_u64 v[6:7], s[34:35], 0, v[130:131]
	v_lshl_add_u64 v[4:5], s[34:35], 0, v[134:135]
	v_lshl_add_u64 v[0:1], s[30:31], 0, v[128:129]
	s_cselect_b64 s[10:11], -1, 0
	s_cmp_lg_u32 s3, 1
	v_lshl_add_u64 v[2:3], s[30:31], 0, v[132:133]
	s_setprio 1
	s_cbranch_scc1 .LBB0_971
	s_barrier
	s_setprio 0

.LBB0_977:
	ds_read_b128 v[152:155], v143
	ds_read_b128 v[162:165], v143 offset:1024
	ds_read_b128 v[166:169], v143 offset:2048
	ds_read_b128 v[170:173], v143 offset:3072
	ds_read_b128 v[174:177], v158
	ds_read_b128 v[178:181], v158 offset:1024
	ds_read_b128 v[182:185], v158 offset:2048
	ds_read_b128 v[186:189], v158 offset:3072
	s_add_u32 s34, s30, 0xfffc0080
	s_addc_u32 s35, s31, -1
	s_cmp_eq_u32 s57, 12
	s_cselect_b32 s37, s21, s35
	s_cselect_b32 s36, s27, s34
	s_cselect_b32 s35, s19, s56
	s_cselect_b32 s34, s29, s55
	s_waitcnt lgkmcnt(0)
	s_add_i32 m0, s41, 0xc000
	ds_read_b128 v[190:193], v159
	ds_read_b128 v[194:197], v159 offset:1024
	ds_read_b128 v[198:201], v159 offset:2048
	ds_read_b128 v[202:205], v159 offset:3072
	ds_read_b128 v[206:209], v159 offset:4096
	ds_read_b128 v[210:213], v159 offset:5120
	ds_read_b128 v[214:217], v159 offset:6144
	ds_read_b128 v[218:221], v159 offset:7168
	global_load_lds_dwordx4 v144, s[30:31]
	s_add_i32 m0, s41, 0xe000
	s_nop 0
	global_load_lds_dwordx4 v146, s[30:31]
	s_waitcnt vmcnt(8)
	s_waitcnt lgkmcnt(0)
	s_barrier
	s_waitcnt lgkmcnt(0)
	v_mfma_f32_16x16x32_bf16 v[116:119], v[152:155], v[190:193], v[116:119]
	v_mfma_f32_16x16x32_bf16 v[112:115], v[166:169], v[190:193], v[112:115]
	v_mfma_f32_16x16x32_bf16 v[100:103], v[152:155], v[198:201], v[100:103]
	v_mfma_f32_16x16x32_bf16 v[96:99], v[166:169], v[198:201], v[96:99]
	v_mfma_f32_16x16x32_bf16 v[88:91], v[152:155], v[206:209], v[88:91]
	v_mfma_f32_16x16x32_bf16 v[84:87], v[166:169], v[206:209], v[84:87]
	v_mfma_f32_16x16x32_bf16 v[72:75], v[152:155], v[214:217], v[72:75]
	v_mfma_f32_16x16x32_bf16 v[68:71], v[166:169], v[214:217], v[68:71]
	v_mfma_f32_16x16x32_bf16 v[116:119], v[162:165], v[194:197], v[116:119]
	v_mfma_f32_16x16x32_bf16 v[112:115], v[170:173], v[194:197], v[112:115]
	v_mfma_f32_16x16x32_bf16 v[100:103], v[162:165], v[202:205], v[100:103]
	v_mfma_f32_16x16x32_bf16 v[96:99], v[170:173], v[202:205], v[96:99]
	v_mfma_f32_16x16x32_bf16 v[88:91], v[162:165], v[210:213], v[88:91]
	v_mfma_f32_16x16x32_bf16 v[84:87], v[170:173], v[210:213], v[84:87]
	v_mfma_f32_16x16x32_bf16 v[72:75], v[162:165], v[218:221], v[72:75]
	v_mfma_f32_16x16x32_bf16 v[68:71], v[170:173], v[218:221], v[68:71]
	v_mfma_f32_16x16x32_bf16 v[124:127], v[174:177], v[190:193], v[124:127]
	v_mfma_f32_16x16x32_bf16 v[120:123], v[182:185], v[190:193], v[120:123]
	v_mfma_f32_16x16x32_bf16 v[108:111], v[174:177], v[198:201], v[108:111]
	v_mfma_f32_16x16x32_bf16 v[104:107], v[182:185], v[198:201], v[104:107]
	v_mfma_f32_16x16x32_bf16 v[92:95], v[174:177], v[206:209], v[92:95]
	v_mfma_f32_16x16x32_bf16 v[80:83], v[182:185], v[206:209], v[80:83]
	v_mfma_f32_16x16x32_bf16 v[76:79], v[174:177], v[214:217], v[76:79]
	v_mfma_f32_16x16x32_bf16 v[64:67], v[182:185], v[214:217], v[64:67]
	v_mfma_f32_16x16x32_bf16 v[124:127], v[178:181], v[194:197], v[124:127]
	v_mfma_f32_16x16x32_bf16 v[120:123], v[186:189], v[194:197], v[120:123]
	v_mfma_f32_16x16x32_bf16 v[108:111], v[178:181], v[202:205], v[108:111]
	v_mfma_f32_16x16x32_bf16 v[104:107], v[186:189], v[202:205], v[104:107]
	v_mfma_f32_16x16x32_bf16 v[92:95], v[178:181], v[210:213], v[92:95]
	v_mfma_f32_16x16x32_bf16 v[80:83], v[186:189], v[210:213], v[80:83]
	v_mfma_f32_16x16x32_bf16 v[76:79], v[178:181], v[218:221], v[76:79]
	v_mfma_f32_16x16x32_bf16 v[64:67], v[186:189], v[218:221], v[64:67]
	s_barrier
	s_add_i32 s58, s51, s40
	v_lshl_add_u64 v[156:157], s[34:35], 0, v[130:131]
	s_mov_b32 m0, s58
	ds_read_b128 v[190:193], v159 offset:16384
	ds_read_b128 v[194:197], v159 offset:17408
	ds_read_b128 v[198:201], v159 offset:18432
	ds_read_b128 v[202:205], v159 offset:19456
	ds_read_b128 v[206:209], v159 offset:20480
	ds_read_b128 v[210:213], v159 offset:21504
	ds_read_b128 v[214:217], v159 offset:22528
	ds_read_b128 v[218:221], v159 offset:23552
	global_load_lds_dwordx4 v[156:157], off
	s_add_i32 m0, s58, 0x2000
	s_add_u32 s58, s34, 0x40000
	v_lshl_add_u64 v[222:223], s[34:35], 0, v[134:135]
	s_addc_u32 s59, s35, 0
	s_add_i32 s60, s52, s40
	global_load_lds_dwordx4 v[222:223], off
	s_mov_b32 m0, s60
	v_lshl_add_u64 v[226:227], s[36:37], 0, v[132:133]
	global_load_lds_dwordx4 v130, s[58:59]
	s_add_i32 m0, s60, 0x2000
	s_nop 0
	global_load_lds_dwordx4 v134, s[58:59]
	v_lshl_add_u64 v[224:225], s[36:37], 0, v[128:129]
	s_mov_b32 m0, s41
	s_nop 0
	global_load_lds_dwordx4 v[224:225], off
	s_mov_b32 m0, s42
	s_nop 0
	global_load_lds_dwordx4 v[226:227], off
	s_waitcnt vmcnt(8)
	s_waitcnt lgkmcnt(0)
	s_barrier
	s_waitcnt lgkmcnt(0)
	v_mfma_f32_16x16x32_bf16 v[56:59], v[152:155], v[190:193], v[56:59]
	v_mfma_f32_16x16x32_bf16 v[52:55], v[166:169], v[190:193], v[52:55]
	v_mfma_f32_16x16x32_bf16 v[40:43], v[152:155], v[198:201], v[40:43]
	v_mfma_f32_16x16x32_bf16 v[36:39], v[166:169], v[198:201], v[36:39]
	v_mfma_f32_16x16x32_bf16 v[24:27], v[152:155], v[206:209], v[24:27]
	v_mfma_f32_16x16x32_bf16 v[20:23], v[166:169], v[206:209], v[20:23]
	v_mfma_f32_16x16x32_bf16 v[8:11], v[152:155], v[214:217], v[8:11]
	v_mfma_f32_16x16x32_bf16 v[4:7], v[166:169], v[214:217], v[4:7]
	v_mfma_f32_16x16x32_bf16 v[56:59], v[162:165], v[194:197], v[56:59]
	v_mfma_f32_16x16x32_bf16 v[52:55], v[170:173], v[194:197], v[52:55]
	v_mfma_f32_16x16x32_bf16 v[40:43], v[162:165], v[202:205], v[40:43]
	v_mfma_f32_16x16x32_bf16 v[36:39], v[170:173], v[202:205], v[36:39]
	v_mfma_f32_16x16x32_bf16 v[24:27], v[162:165], v[210:213], v[24:27]
	v_mfma_f32_16x16x32_bf16 v[20:23], v[170:173], v[210:213], v[20:23]
	v_mfma_f32_16x16x32_bf16 v[8:11], v[162:165], v[218:221], v[8:11]
	v_mfma_f32_16x16x32_bf16 v[4:7], v[170:173], v[218:221], v[4:7]
	v_mfma_f32_16x16x32_bf16 v[60:63], v[174:177], v[190:193], v[60:63]
	v_mfma_f32_16x16x32_bf16 v[48:51], v[182:185], v[190:193], v[48:51]
	v_mfma_f32_16x16x32_bf16 v[44:47], v[174:177], v[198:201], v[44:47]
	v_mfma_f32_16x16x32_bf16 v[32:35], v[182:185], v[198:201], v[32:35]
	v_mfma_f32_16x16x32_bf16 v[28:31], v[174:177], v[206:209], v[28:31]
	v_mfma_f32_16x16x32_bf16 v[16:19], v[182:185], v[206:209], v[16:19]
	v_mfma_f32_16x16x32_bf16 v[12:15], v[174:177], v[214:217], v[12:15]
	v_mfma_f32_16x16x32_bf16 v[0:3], v[182:185], v[214:217], v[0:3]
	v_mfma_f32_16x16x32_bf16 v[60:63], v[178:181], v[194:197], v[60:63]
	v_mfma_f32_16x16x32_bf16 v[48:51], v[186:189], v[194:197], v[48:51]
	v_mfma_f32_16x16x32_bf16 v[44:47], v[178:181], v[202:205], v[44:47]
	v_mfma_f32_16x16x32_bf16 v[32:35], v[186:189], v[202:205], v[32:35]
	v_mfma_f32_16x16x32_bf16 v[28:31], v[178:181], v[210:213], v[28:31]
	v_mfma_f32_16x16x32_bf16 v[16:19], v[186:189], v[210:213], v[16:19]
	v_mfma_f32_16x16x32_bf16 v[12:15], v[178:181], v[218:221], v[12:15]
	v_mfma_f32_16x16x32_bf16 v[0:3], v[186:189], v[218:221], v[0:3]
	s_barrier
	s_add_i32 s58, 0, 0x18000
	s_add_i32 s59, 0, 0x1c000
	v_add_u32_e32 v170, s58, v141
	v_add_u32_e32 v186, s59, v141
	ds_read_b128 v[152:155], v170
	ds_read_b128 v[162:165], v170 offset:1024
	ds_read_b128 v[166:169], v170 offset:2048
	ds_read_b128 v[170:173], v170 offset:3072
	ds_read_b128 v[174:177], v186
	ds_read_b128 v[178:181], v186 offset:1024
	ds_read_b128 v[182:185], v186 offset:2048
	ds_read_b128 v[186:189], v186 offset:3072
	s_add_u32 s36, s36, 0x40000
	s_addc_u32 s37, s37, 0
	s_mov_b32 m0, s43
	ds_read_b128 v[190:193], v159 offset:32768
	ds_read_b128 v[194:197], v159 offset:33792
	ds_read_b128 v[198:201], v159 offset:34816
	ds_read_b128 v[202:205], v159 offset:35840
	ds_read_b128 v[206:209], v159 offset:36864
	ds_read_b128 v[210:213], v159 offset:37888
	ds_read_b128 v[214:217], v159 offset:38912
	ds_read_b128 v[218:221], v159 offset:39936
	global_load_lds_dwordx4 v128, s[36:37]
	v_lshl_add_u64 v[228:229], s[36:37], 0, v[132:133]
	s_mov_b32 m0, s44
	s_nop 0
	global_load_lds_dwordx4 v[228:229], off
	s_waitcnt vmcnt(8)
	s_waitcnt lgkmcnt(0)
	s_barrier
	s_waitcnt lgkmcnt(0)
	v_mfma_f32_16x16x32_bf16 v[116:119], v[152:155], v[190:193], v[116:119]
	v_mfma_f32_16x16x32_bf16 v[112:115], v[166:169], v[190:193], v[112:115]
	v_mfma_f32_16x16x32_bf16 v[100:103], v[152:155], v[198:201], v[100:103]
	v_mfma_f32_16x16x32_bf16 v[96:99], v[166:169], v[198:201], v[96:99]
	v_mfma_f32_16x16x32_bf16 v[88:91], v[152:155], v[206:209], v[88:91]
	v_mfma_f32_16x16x32_bf16 v[84:87], v[166:169], v[206:209], v[84:87]
	v_mfma_f32_16x16x32_bf16 v[72:75], v[152:155], v[214:217], v[72:75]
	v_mfma_f32_16x16x32_bf16 v[68:71], v[166:169], v[214:217], v[68:71]
	v_mfma_f32_16x16x32_bf16 v[116:119], v[162:165], v[194:197], v[116:119]
	v_mfma_f32_16x16x32_bf16 v[112:115], v[170:173], v[194:197], v[112:115]
	v_mfma_f32_16x16x32_bf16 v[100:103], v[162:165], v[202:205], v[100:103]
	v_mfma_f32_16x16x32_bf16 v[96:99], v[170:173], v[202:205], v[96:99]
	v_mfma_f32_16x16x32_bf16 v[88:91], v[162:165], v[210:213], v[88:91]
	v_mfma_f32_16x16x32_bf16 v[84:87], v[170:173], v[210:213], v[84:87]
	v_mfma_f32_16x16x32_bf16 v[72:75], v[162:165], v[218:221], v[72:75]
	v_mfma_f32_16x16x32_bf16 v[68:71], v[170:173], v[218:221], v[68:71]
	v_mfma_f32_16x16x32_bf16 v[124:127], v[174:177], v[190:193], v[124:127]
	v_mfma_f32_16x16x32_bf16 v[120:123], v[182:185], v[190:193], v[120:123]
	v_mfma_f32_16x16x32_bf16 v[108:111], v[174:177], v[198:201], v[108:111]
	v_mfma_f32_16x16x32_bf16 v[104:107], v[182:185], v[198:201], v[104:107]
	v_mfma_f32_16x16x32_bf16 v[92:95], v[174:177], v[206:209], v[92:95]
	v_mfma_f32_16x16x32_bf16 v[80:83], v[182:185], v[206:209], v[80:83]
	v_mfma_f32_16x16x32_bf16 v[76:79], v[174:177], v[214:217], v[76:79]
	v_mfma_f32_16x16x32_bf16 v[64:67], v[182:185], v[214:217], v[64:67]
	v_mfma_f32_16x16x32_bf16 v[124:127], v[178:181], v[194:197], v[124:127]
	v_mfma_f32_16x16x32_bf16 v[120:123], v[186:189], v[194:197], v[120:123]
	v_mfma_f32_16x16x32_bf16 v[108:111], v[178:181], v[202:205], v[108:111]
	v_mfma_f32_16x16x32_bf16 v[104:107], v[186:189], v[202:205], v[104:107]
	v_mfma_f32_16x16x32_bf16 v[92:95], v[178:181], v[210:213], v[92:95]
	v_mfma_f32_16x16x32_bf16 v[80:83], v[186:189], v[210:213], v[80:83]
	v_mfma_f32_16x16x32_bf16 v[76:79], v[178:181], v[218:221], v[76:79]
	v_mfma_f32_16x16x32_bf16 v[64:67], v[186:189], v[218:221], v[64:67]
	s_barrier
	s_add_i32 s36, s58, s40
	v_lshl_add_u64 v[156:157], v[156:157], 0, s[12:13]
	s_mov_b32 m0, s36
	ds_read_b128 v[190:193], v159 offset:49152
	ds_read_b128 v[194:197], v159 offset:50176
	ds_read_b128 v[198:201], v159 offset:51200
	ds_read_b128 v[202:205], v159 offset:52224
	ds_read_b128 v[206:209], v159 offset:53248
	ds_read_b128 v[210:213], v159 offset:54272
	ds_read_b128 v[214:217], v159 offset:55296
	ds_read_b128 v[218:221], v159 offset:56320
	global_load_lds_dwordx4 v[156:157], off
	s_add_i32 m0, s36, 0x2000
	s_add_u32 s34, s34, 0x40080
	v_lshl_add_u64 v[156:157], v[222:223], 0, s[12:13]
	s_addc_u32 s35, s35, 0
	s_add_i32 s36, s59, s40
	global_load_lds_dwordx4 v[156:157], off
	s_mov_b32 m0, s36
	s_nop 0
	global_load_lds_dwordx4 v130, s[34:35]
	s_add_i32 m0, s36, 0x2000
	s_nop 0
	global_load_lds_dwordx4 v134, s[34:35]
	v_lshl_add_u64 v[156:157], v[224:225], 0, s[12:13]
	s_mov_b32 m0, s45
	s_nop 0
	global_load_lds_dwordx4 v[156:157], off
	v_lshl_add_u64 v[156:157], v[226:227], 0, s[12:13]
	s_mov_b32 m0, s46
	s_nop 0
	global_load_lds_dwordx4 v[156:157], off
	s_waitcnt vmcnt(8)
	s_waitcnt lgkmcnt(0)
	s_barrier
	s_waitcnt lgkmcnt(0)
	v_mfma_f32_16x16x32_bf16 v[56:59], v[152:155], v[190:193], v[56:59]
	v_mfma_f32_16x16x32_bf16 v[52:55], v[166:169], v[190:193], v[52:55]
	v_mfma_f32_16x16x32_bf16 v[40:43], v[152:155], v[198:201], v[40:43]
	v_mfma_f32_16x16x32_bf16 v[36:39], v[166:169], v[198:201], v[36:39]
	v_mfma_f32_16x16x32_bf16 v[24:27], v[152:155], v[206:209], v[24:27]
	v_mfma_f32_16x16x32_bf16 v[20:23], v[166:169], v[206:209], v[20:23]
	v_mfma_f32_16x16x32_bf16 v[8:11], v[152:155], v[214:217], v[8:11]
	v_mfma_f32_16x16x32_bf16 v[4:7], v[166:169], v[214:217], v[4:7]
	v_mfma_f32_16x16x32_bf16 v[56:59], v[162:165], v[194:197], v[56:59]
	v_mfma_f32_16x16x32_bf16 v[52:55], v[170:173], v[194:197], v[52:55]
	v_mfma_f32_16x16x32_bf16 v[40:43], v[162:165], v[202:205], v[40:43]
	v_mfma_f32_16x16x32_bf16 v[36:39], v[170:173], v[202:205], v[36:39]
	v_mfma_f32_16x16x32_bf16 v[24:27], v[162:165], v[210:213], v[24:27]
	v_mfma_f32_16x16x32_bf16 v[20:23], v[170:173], v[210:213], v[20:23]
	v_mfma_f32_16x16x32_bf16 v[8:11], v[162:165], v[218:221], v[8:11]
	v_mfma_f32_16x16x32_bf16 v[4:7], v[170:173], v[218:221], v[4:7]
	v_mfma_f32_16x16x32_bf16 v[60:63], v[174:177], v[190:193], v[60:63]
	v_mfma_f32_16x16x32_bf16 v[48:51], v[182:185], v[190:193], v[48:51]
	v_mfma_f32_16x16x32_bf16 v[44:47], v[174:177], v[198:201], v[44:47]
	v_mfma_f32_16x16x32_bf16 v[32:35], v[182:185], v[198:201], v[32:35]
	v_mfma_f32_16x16x32_bf16 v[28:31], v[174:177], v[206:209], v[28:31]
	v_mfma_f32_16x16x32_bf16 v[16:19], v[182:185], v[206:209], v[16:19]
	v_mfma_f32_16x16x32_bf16 v[12:15], v[174:177], v[214:217], v[12:15]
	v_mfma_f32_16x16x32_bf16 v[0:3], v[182:185], v[214:217], v[0:3]
	v_mfma_f32_16x16x32_bf16 v[60:63], v[178:181], v[194:197], v[60:63]
	v_mfma_f32_16x16x32_bf16 v[48:51], v[186:189], v[194:197], v[48:51]
	v_mfma_f32_16x16x32_bf16 v[44:47], v[178:181], v[202:205], v[44:47]
	v_mfma_f32_16x16x32_bf16 v[32:35], v[186:189], v[202:205], v[32:35]
	v_mfma_f32_16x16x32_bf16 v[28:31], v[178:181], v[210:213], v[28:31]
	v_mfma_f32_16x16x32_bf16 v[16:19], v[186:189], v[210:213], v[16:19]
	v_mfma_f32_16x16x32_bf16 v[12:15], v[178:181], v[218:221], v[12:15]
	v_mfma_f32_16x16x32_bf16 v[0:3], v[186:189], v[218:221], v[0:3]
	s_add_i32 s57, s57, 2
	s_add_u32 s30, s30, 0x100
	s_addc_u32 s31, s31, 0
	s_add_u32 s55, s55, 0x100
	s_addc_u32 s56, s56, 0
	s_cmp_gt_u32 s57, 13
	s_barrier
	s_cbranch_scc0 .LBB0_977
	s_and_b64 vcc, exec, s[14:15]
	s_cbranch_vccz .LBB0_982
	s_barrier
	v_lshl_add_u32 v152, s28, 8, v139
	s_cmp_gt_i32 s26, 21
	s_mov_b64 s[28:29], -1
	s_cbranch_scc1 .LBB0_983

.LBB0_1048:
	s_andn2_b64 vcc, exec, s[2:3]
	s_cbranch_vccnz .LBB0_1088
	v_ashrrev_i32_e32 v1, 31, v2
	v_lshrrev_b32_e32 v1, 26, v1
	v_add_u32_e32 v1, v2, v1
	v_ashrrev_i32_e32 v9, 6, v1
	v_bfe_i32 v1, v2, 27, 1
	v_lshlrev_b32_e32 v0, 4, v2
	v_lshrrev_b32_e32 v1, 22, v1
	v_add_u32_e32 v1, v0, v1
	v_and_b32_e32 v1, 0xfffffc00, v1
	v_sub_u32_e32 v1, v0, v1
	v_lshrrev_b32_e32 v2, 4, v1
	v_bitop3_b32 v1, v2, v1, 32 bitop3:0x6c
	v_ashrrev_i32_e32 v3, 31, v1
	v_lshrrev_b32_e32 v3, 26, v3
	v_add_u32_e32 v3, v1, v3
	v_lshlrev_b32_e32 v2, 3, v9
	v_ashrrev_i32_e32 v11, 6, v3
	v_and_b32_e32 v3, 0xc0, v3
	v_and_b32_e32 v2, 0xfffff0, v2
	v_sub_u32_e32 v1, v1, v3
	v_mov_b32_e32 v3, 1
	v_add_u32_e32 v2, v11, v2
	v_lshlrev_b32_e32 v4, 5, v9
	v_ashrrev_i16_sdwa v1, v3, sext(v1) dst_sel:DWORD dst_unused:UNUSED_PAD src0_sel:DWORD src1_sel:BYTE_0
	s_movk_i32 s4, 0xb00
	v_and_b32_e32 v10, 32, v4
	v_bfe_i32 v12, v1, 0, 16
	v_mul_lo_u32 v1, v2, s4
	v_or_b32_e32 v1, v1, v10
	v_add_u32_e32 v0, 0x2000, v0
	v_add_lshl_u32 v128, v1, v12, 1
	v_ashrrev_i32_e32 v1, 31, v0
	v_lshrrev_b32_e32 v1, 22, v1
	v_add_u32_e32 v1, v0, v1
	v_ashrrev_i32_e32 v13, 10, v1
	v_mul_i32_i24_e32 v1, 0x400, v13
	v_sub_u32_e32 v0, v0, v1
	v_lshrrev_b32_e32 v1, 4, v0
	v_bitop3_b32 v0, v1, v0, 32 bitop3:0x6c
	v_ashrrev_i32_e32 v2, 31, v0
	s_add_u32 s30, s70, 0x3980000
	v_lshrrev_b32_e32 v2, 26, v2
	s_addc_u32 s31, s71, 0
	s_ashr_i32 s2, s6, 6
	v_add_u32_e32 v2, v0, v2
	v_lshlrev_b32_e32 v1, 3, v13
	v_ashrrev_i32_e32 v14, 6, v2
	v_and_b32_e32 v2, 0xc0, v2
	s_ashr_i32 s3, s6, 8
	s_lshl_b32 s34, s2, 10
	s_mul_i32 s14, s12, 0x160000
	v_and_b32_e32 v1, 0xfffff0, v1
	v_sub_u32_e32 v0, v0, v2
	s_mul_hi_i32 s13, s12, 0x160000
	s_add_u32 s24, s30, s14
	v_add_u32_e32 v1, v14, v1
	v_lshlrev_b32_e32 v4, 5, v13
	v_ashrrev_i16_sdwa v0, v3, sext(v0) dst_sel:DWORD dst_unused:UNUSED_PAD src0_sel:DWORD src1_sel:BYTE_0
	s_addc_u32 s25, s31, s13
	s_add_i32 s35, s34, 0
	v_and_b32_e32 v15, 32, v4
	v_bfe_i32 v16, v0, 0, 16
	v_mul_lo_u32 v0, v1, s4
	s_add_i32 m0, s35, 0x10000
	v_or_b32_e32 v0, v0, v15
	global_load_lds_dwordx4 v128, s[24:25]
	s_add_i32 m0, s35, 0x12000
	v_add_lshl_u32 v130, v0, v16, 1
	s_add_u32 s14, s24, 0xb0000
	global_load_lds_dwordx4 v130, s[24:25]
	s_addc_u32 s15, s25, 0
	s_add_i32 m0, s35, 0x14000
	s_mul_i32 s7, s49, 0x160000
	global_load_lds_dwordx4 v128, s[14:15]
	s_add_i32 m0, s35, 0x16000
	s_mul_hi_i32 s5, s49, 0x160000
	s_add_u32 s22, s72, s7
	s_addc_u32 s23, s73, s5
	s_add_i32 s36, s35, 0x2000
	global_load_lds_dwordx4 v130, s[14:15]
	s_mov_b32 m0, s35
	s_add_u32 s14, s22, 0xb0000
	global_load_lds_dwordx4 v128, s[22:23]
	s_mov_b32 m0, s36
	s_addc_u32 s15, s23, 0
	s_add_i32 s37, s35, 0x4000
	global_load_lds_dwordx4 v130, s[22:23]
	s_mov_b32 m0, s37
	s_add_i32 s38, s35, 0x6000
	global_load_lds_dwordx4 v128, s[14:15]
	s_mov_b32 m0, s38
	v_mov_b32_e32 v129, 0
	global_load_lds_dwordx4 v130, s[14:15]
	v_mov_b32_e32 v131, v129
	s_cmp_eq_u32 s3, 1
	s_mov_b32 s13, 0
	v_lshl_add_u64 v[6:7], s[24:25], 0, v[128:129]
	v_lshl_add_u64 v[4:5], s[24:25], 0, v[130:131]
	v_lshl_add_u64 v[0:1], s[22:23], 0, v[128:129]
	s_cselect_b64 s[14:15], -1, 0
	s_cmp_lg_u32 s3, 1
	v_lshl_add_u64 v[2:3], s[22:23], 0, v[130:131]
	s_setprio 1
	s_cbranch_scc1 .LBB0_1051
	s_barrier
	s_setprio 0

.LBB0_1065:
	ds_read_b128 v[140:143], v147
	ds_read_b128 v[152:155], v147 offset:1024
	ds_read_b128 v[156:159], v147 offset:2048
	ds_read_b128 v[160:163], v147 offset:3072
	ds_read_b128 v[164:167], v148
	ds_read_b128 v[168:171], v148 offset:1024
	ds_read_b128 v[172:175], v148 offset:2048
	ds_read_b128 v[176:179], v148 offset:3072
	s_add_u32 s24, s22, 0x100
	s_addc_u32 s25, s23, 0
	s_cmp_eq_u32 s52, 40
	s_cselect_b32 s29, s7, s25
	s_cselect_b32 s28, s6, s24
	s_cselect_b32 s27, s21, s51
	s_cselect_b32 s26, s20, s50
	v_lshl_add_u64 v[212:213], s[22:23], 0, v[132:133]
	s_add_i32 m0, s35, 0xc000
	ds_read_b128 v[180:183], v149
	ds_read_b128 v[184:187], v149 offset:1024
	ds_read_b128 v[188:191], v149 offset:2048
	ds_read_b128 v[192:195], v149 offset:3072
	ds_read_b128 v[196:199], v149 offset:4096
	ds_read_b128 v[200:203], v149 offset:5120
	ds_read_b128 v[204:207], v149 offset:6144
	ds_read_b128 v[208:211], v149 offset:7168
	global_load_lds_dwordx4 v[212:213], off
	v_lshl_add_u64 v[212:213], s[22:23], 0, v[134:135]
	s_add_i32 m0, s35, 0xe000
	s_nop 0
	global_load_lds_dwordx4 v[212:213], off
	s_waitcnt vmcnt(8)
	s_waitcnt lgkmcnt(0)
	s_barrier
	s_waitcnt lgkmcnt(0)
	v_mfma_f32_16x16x32_bf16 v[124:127], v[140:143], v[180:183], v[124:127]
	v_mfma_f32_16x16x32_bf16 v[120:123], v[156:159], v[180:183], v[120:123]
	v_mfma_f32_16x16x32_bf16 v[108:111], v[140:143], v[188:191], v[108:111]
	v_mfma_f32_16x16x32_bf16 v[104:107], v[156:159], v[188:191], v[104:107]
	v_mfma_f32_16x16x32_bf16 v[92:95], v[140:143], v[196:199], v[92:95]
	v_mfma_f32_16x16x32_bf16 v[88:91], v[156:159], v[196:199], v[88:91]
	v_mfma_f32_16x16x32_bf16 v[76:79], v[140:143], v[204:207], v[76:79]
	v_mfma_f32_16x16x32_bf16 v[72:75], v[156:159], v[204:207], v[72:75]
	v_mfma_f32_16x16x32_bf16 v[124:127], v[152:155], v[184:187], v[124:127]
	v_mfma_f32_16x16x32_bf16 v[120:123], v[160:163], v[184:187], v[120:123]
	v_mfma_f32_16x16x32_bf16 v[108:111], v[152:155], v[192:195], v[108:111]
	v_mfma_f32_16x16x32_bf16 v[104:107], v[160:163], v[192:195], v[104:107]
	v_mfma_f32_16x16x32_bf16 v[92:95], v[152:155], v[200:203], v[92:95]
	v_mfma_f32_16x16x32_bf16 v[88:91], v[160:163], v[200:203], v[88:91]
	v_mfma_f32_16x16x32_bf16 v[76:79], v[152:155], v[208:211], v[76:79]
	v_mfma_f32_16x16x32_bf16 v[72:75], v[160:163], v[208:211], v[72:75]
	v_mfma_f32_16x16x32_bf16 v[116:119], v[164:167], v[180:183], v[116:119]
	v_mfma_f32_16x16x32_bf16 v[112:115], v[172:175], v[180:183], v[112:115]
	v_mfma_f32_16x16x32_bf16 v[100:103], v[164:167], v[188:191], v[100:103]
	v_mfma_f32_16x16x32_bf16 v[96:99], v[172:175], v[188:191], v[96:99]
	v_mfma_f32_16x16x32_bf16 v[84:87], v[164:167], v[196:199], v[84:87]
	v_mfma_f32_16x16x32_bf16 v[80:83], v[172:175], v[196:199], v[80:83]
	v_mfma_f32_16x16x32_bf16 v[68:71], v[164:167], v[204:207], v[68:71]
	v_mfma_f32_16x16x32_bf16 v[64:67], v[172:175], v[204:207], v[64:67]
	v_mfma_f32_16x16x32_bf16 v[116:119], v[168:171], v[184:187], v[116:119]
	v_mfma_f32_16x16x32_bf16 v[112:115], v[176:179], v[184:187], v[112:115]
	v_mfma_f32_16x16x32_bf16 v[100:103], v[168:171], v[192:195], v[100:103]
	v_mfma_f32_16x16x32_bf16 v[96:99], v[176:179], v[192:195], v[96:99]
	v_mfma_f32_16x16x32_bf16 v[84:87], v[168:171], v[200:203], v[84:87]
	v_mfma_f32_16x16x32_bf16 v[80:83], v[176:179], v[200:203], v[80:83]
	v_mfma_f32_16x16x32_bf16 v[68:71], v[168:171], v[208:211], v[68:71]
	v_mfma_f32_16x16x32_bf16 v[64:67], v[176:179], v[208:211], v[64:67]
	s_barrier
	s_add_i32 s22, s44, s34
	v_lshl_add_u64 v[212:213], s[26:27], 0, v[128:129]
	s_mov_b32 m0, s22
	ds_read_b128 v[180:183], v149 offset:16384
	ds_read_b128 v[184:187], v149 offset:17408
	ds_read_b128 v[188:191], v149 offset:18432
	ds_read_b128 v[192:195], v149 offset:19456
	ds_read_b128 v[196:199], v149 offset:20480
	ds_read_b128 v[200:203], v149 offset:21504
	ds_read_b128 v[204:207], v149 offset:22528
	ds_read_b128 v[208:211], v149 offset:23552
	global_load_lds_dwordx4 v[212:213], off
	s_add_i32 m0, s22, 0x2000
	s_add_u32 s22, s26, 0xb0000
	v_lshl_add_u64 v[214:215], s[26:27], 0, v[130:131]
	s_addc_u32 s23, s27, 0
	s_add_i32 s53, s45, s34
	global_load_lds_dwordx4 v[214:215], off
	v_lshl_add_u64 v[216:217], s[22:23], 0, v[128:129]
	s_mov_b32 m0, s53
	v_lshl_add_u64 v[218:219], s[28:29], 0, v[130:131]
	global_load_lds_dwordx4 v[216:217], off
	s_add_i32 m0, s53, 0x2000
	s_nop 0
	global_load_lds_dwordx4 v130, s[22:23]
	v_lshl_add_u64 v[216:217], s[28:29], 0, v[128:129]
	s_mov_b32 m0, s35
	s_nop 0
	global_load_lds_dwordx4 v[216:217], off
	s_mov_b32 m0, s36
	s_nop 0
	global_load_lds_dwordx4 v[218:219], off
	s_waitcnt vmcnt(8)
	s_waitcnt lgkmcnt(0)
	s_barrier
	s_waitcnt lgkmcnt(0)
	v_mfma_f32_16x16x32_bf16 v[60:63], v[140:143], v[180:183], v[60:63]
	v_mfma_f32_16x16x32_bf16 v[56:59], v[156:159], v[180:183], v[56:59]
	v_mfma_f32_16x16x32_bf16 v[44:47], v[140:143], v[188:191], v[44:47]
	v_mfma_f32_16x16x32_bf16 v[40:43], v[156:159], v[188:191], v[40:43]
	v_mfma_f32_16x16x32_bf16 v[28:31], v[140:143], v[196:199], v[28:31]
	v_mfma_f32_16x16x32_bf16 v[24:27], v[156:159], v[196:199], v[24:27]
	v_mfma_f32_16x16x32_bf16 v[12:15], v[140:143], v[204:207], v[12:15]
	v_mfma_f32_16x16x32_bf16 v[8:11], v[156:159], v[204:207], v[8:11]
	v_mfma_f32_16x16x32_bf16 v[60:63], v[152:155], v[184:187], v[60:63]
	v_mfma_f32_16x16x32_bf16 v[56:59], v[160:163], v[184:187], v[56:59]
	v_mfma_f32_16x16x32_bf16 v[44:47], v[152:155], v[192:195], v[44:47]
	v_mfma_f32_16x16x32_bf16 v[40:43], v[160:163], v[192:195], v[40:43]
	v_mfma_f32_16x16x32_bf16 v[28:31], v[152:155], v[200:203], v[28:31]
	v_mfma_f32_16x16x32_bf16 v[24:27], v[160:163], v[200:203], v[24:27]
	v_mfma_f32_16x16x32_bf16 v[12:15], v[152:155], v[208:211], v[12:15]
	v_mfma_f32_16x16x32_bf16 v[8:11], v[160:163], v[208:211], v[8:11]
	v_mfma_f32_16x16x32_bf16 v[52:55], v[164:167], v[180:183], v[52:55]
	v_mfma_f32_16x16x32_bf16 v[48:51], v[172:175], v[180:183], v[48:51]
	v_mfma_f32_16x16x32_bf16 v[36:39], v[164:167], v[188:191], v[36:39]
	v_mfma_f32_16x16x32_bf16 v[32:35], v[172:175], v[188:191], v[32:35]
	v_mfma_f32_16x16x32_bf16 v[20:23], v[164:167], v[196:199], v[20:23]
	v_mfma_f32_16x16x32_bf16 v[16:19], v[172:175], v[196:199], v[16:19]
	v_mfma_f32_16x16x32_bf16 v[4:7], v[164:167], v[204:207], v[4:7]
	v_mfma_f32_16x16x32_bf16 v[0:3], v[172:175], v[204:207], v[0:3]
	v_mfma_f32_16x16x32_bf16 v[52:55], v[168:171], v[184:187], v[52:55]
	v_mfma_f32_16x16x32_bf16 v[48:51], v[176:179], v[184:187], v[48:51]
	v_mfma_f32_16x16x32_bf16 v[36:39], v[168:171], v[192:195], v[36:39]
	v_mfma_f32_16x16x32_bf16 v[32:35], v[176:179], v[192:195], v[32:35]
	v_mfma_f32_16x16x32_bf16 v[20:23], v[168:171], v[200:203], v[20:23]
	v_mfma_f32_16x16x32_bf16 v[16:19], v[176:179], v[200:203], v[16:19]
	v_mfma_f32_16x16x32_bf16 v[4:7], v[168:171], v[208:211], v[4:7]
	v_mfma_f32_16x16x32_bf16 v[0:3], v[176:179], v[208:211], v[0:3]
	s_barrier
	s_add_i32 s53, 0, 0x18000
	v_add_u32_e32 v151, s53, v145
	s_add_i32 s54, 0, 0x1c000
	ds_read_b128 v[140:143], v151
	ds_read_b128 v[152:155], v151 offset:1024
	ds_read_b128 v[156:159], v151 offset:2048
	ds_read_b128 v[160:163], v151 offset:3072
	v_add_u32_e32 v151, s54, v145
	ds_read_b128 v[164:167], v151
	ds_read_b128 v[168:171], v151 offset:1024
	ds_read_b128 v[172:175], v151 offset:2048
	ds_read_b128 v[176:179], v151 offset:3072
	s_add_u32 s22, s28, 0xb0000
	s_addc_u32 s23, s29, 0
	s_mov_b32 m0, s37
	v_lshl_add_u64 v[220:221], s[22:23], 0, v[128:129]
	ds_read_b128 v[180:183], v149 offset:32768
	ds_read_b128 v[184:187], v149 offset:33792
	ds_read_b128 v[188:191], v149 offset:34816
	ds_read_b128 v[192:195], v149 offset:35840
	ds_read_b128 v[196:199], v149 offset:36864
	ds_read_b128 v[200:203], v149 offset:37888
	ds_read_b128 v[204:207], v149 offset:38912
	ds_read_b128 v[208:211], v149 offset:39936
	global_load_lds_dwordx4 v[220:221], off
	v_lshl_add_u64 v[220:221], s[22:23], 0, v[130:131]
	s_mov_b32 m0, s38
	s_nop 0
	global_load_lds_dwordx4 v[220:221], off
	s_waitcnt vmcnt(8)
	s_waitcnt lgkmcnt(0)
	s_barrier
	s_waitcnt lgkmcnt(0)
	v_mfma_f32_16x16x32_bf16 v[124:127], v[140:143], v[180:183], v[124:127]
	v_mfma_f32_16x16x32_bf16 v[120:123], v[156:159], v[180:183], v[120:123]
	v_mfma_f32_16x16x32_bf16 v[108:111], v[140:143], v[188:191], v[108:111]
	v_mfma_f32_16x16x32_bf16 v[104:107], v[156:159], v[188:191], v[104:107]
	v_mfma_f32_16x16x32_bf16 v[92:95], v[140:143], v[196:199], v[92:95]
	v_mfma_f32_16x16x32_bf16 v[88:91], v[156:159], v[196:199], v[88:91]
	v_mfma_f32_16x16x32_bf16 v[76:79], v[140:143], v[204:207], v[76:79]
	v_mfma_f32_16x16x32_bf16 v[72:75], v[156:159], v[204:207], v[72:75]
	v_mfma_f32_16x16x32_bf16 v[124:127], v[152:155], v[184:187], v[124:127]
	v_mfma_f32_16x16x32_bf16 v[120:123], v[160:163], v[184:187], v[120:123]
	v_mfma_f32_16x16x32_bf16 v[108:111], v[152:155], v[192:195], v[108:111]
	v_mfma_f32_16x16x32_bf16 v[104:107], v[160:163], v[192:195], v[104:107]
	v_mfma_f32_16x16x32_bf16 v[92:95], v[152:155], v[200:203], v[92:95]
	v_mfma_f32_16x16x32_bf16 v[88:91], v[160:163], v[200:203], v[88:91]
	v_mfma_f32_16x16x32_bf16 v[76:79], v[152:155], v[208:211], v[76:79]
	v_mfma_f32_16x16x32_bf16 v[72:75], v[160:163], v[208:211], v[72:75]
	v_mfma_f32_16x16x32_bf16 v[116:119], v[164:167], v[180:183], v[116:119]
	v_mfma_f32_16x16x32_bf16 v[112:115], v[172:175], v[180:183], v[112:115]
	v_mfma_f32_16x16x32_bf16 v[100:103], v[164:167], v[188:191], v[100:103]
	v_mfma_f32_16x16x32_bf16 v[96:99], v[172:175], v[188:191], v[96:99]
	v_mfma_f32_16x16x32_bf16 v[84:87], v[164:167], v[196:199], v[84:87]
	v_mfma_f32_16x16x32_bf16 v[80:83], v[172:175], v[196:199], v[80:83]
	v_mfma_f32_16x16x32_bf16 v[68:71], v[164:167], v[204:207], v[68:71]
	v_mfma_f32_16x16x32_bf16 v[64:67], v[172:175], v[204:207], v[64:67]
	v_mfma_f32_16x16x32_bf16 v[116:119], v[168:171], v[184:187], v[116:119]
	v_mfma_f32_16x16x32_bf16 v[112:115], v[176:179], v[184:187], v[112:115]
	v_mfma_f32_16x16x32_bf16 v[100:103], v[168:171], v[192:195], v[100:103]
	v_mfma_f32_16x16x32_bf16 v[96:99], v[176:179], v[192:195], v[96:99]
	v_mfma_f32_16x16x32_bf16 v[84:87], v[168:171], v[200:203], v[84:87]
	v_mfma_f32_16x16x32_bf16 v[80:83], v[176:179], v[200:203], v[80:83]
	v_mfma_f32_16x16x32_bf16 v[68:71], v[168:171], v[208:211], v[68:71]
	v_mfma_f32_16x16x32_bf16 v[64:67], v[176:179], v[208:211], v[64:67]
	s_barrier
	s_add_i32 s22, s53, s34
	v_lshl_add_u64 v[212:213], v[212:213], 0, s[16:17]
	s_mov_b32 m0, s22
	ds_read_b128 v[180:183], v149 offset:49152
	ds_read_b128 v[184:187], v149 offset:50176
	ds_read_b128 v[188:191], v149 offset:51200
	ds_read_b128 v[192:195], v149 offset:52224
	ds_read_b128 v[196:199], v149 offset:53248
	ds_read_b128 v[200:203], v149 offset:54272
	ds_read_b128 v[204:207], v149 offset:55296
	ds_read_b128 v[208:211], v149 offset:56320
	global_load_lds_dwordx4 v[212:213], off
	s_add_i32 m0, s22, 0x2000
	s_add_u32 s22, s26, 0xb0080
	v_lshl_add_u64 v[212:213], v[214:215], 0, s[16:17]
	s_addc_u32 s23, s27, 0
	s_add_i32 s26, s54, s34
	global_load_lds_dwordx4 v[212:213], off
	v_lshl_add_u64 v[212:213], s[22:23], 0, v[128:129]
	s_mov_b32 m0, s26
	s_nop 0
	global_load_lds_dwordx4 v[212:213], off
	s_add_i32 m0, s26, 0x2000
	s_nop 0
	global_load_lds_dwordx4 v130, s[22:23]
	v_lshl_add_u64 v[212:213], v[216:217], 0, s[16:17]
	s_mov_b32 m0, s40
	s_nop 0
	global_load_lds_dwordx4 v[212:213], off
	v_lshl_add_u64 v[212:213], v[218:219], 0, s[16:17]
	s_mov_b32 m0, s41
	s_nop 0
	global_load_lds_dwordx4 v[212:213], off
	s_waitcnt vmcnt(8)
	s_waitcnt lgkmcnt(0)
	s_barrier
	s_waitcnt lgkmcnt(0)
	v_mfma_f32_16x16x32_bf16 v[60:63], v[140:143], v[180:183], v[60:63]
	v_mfma_f32_16x16x32_bf16 v[56:59], v[156:159], v[180:183], v[56:59]
	v_mfma_f32_16x16x32_bf16 v[44:47], v[140:143], v[188:191], v[44:47]
	v_mfma_f32_16x16x32_bf16 v[40:43], v[156:159], v[188:191], v[40:43]
	v_mfma_f32_16x16x32_bf16 v[28:31], v[140:143], v[196:199], v[28:31]
	v_mfma_f32_16x16x32_bf16 v[24:27], v[156:159], v[196:199], v[24:27]
	v_mfma_f32_16x16x32_bf16 v[12:15], v[140:143], v[204:207], v[12:15]
	v_mfma_f32_16x16x32_bf16 v[8:11], v[156:159], v[204:207], v[8:11]
	v_mfma_f32_16x16x32_bf16 v[60:63], v[152:155], v[184:187], v[60:63]
	v_mfma_f32_16x16x32_bf16 v[56:59], v[160:163], v[184:187], v[56:59]
	v_mfma_f32_16x16x32_bf16 v[44:47], v[152:155], v[192:195], v[44:47]
	v_mfma_f32_16x16x32_bf16 v[40:43], v[160:163], v[192:195], v[40:43]
	v_mfma_f32_16x16x32_bf16 v[28:31], v[152:155], v[200:203], v[28:31]
	v_mfma_f32_16x16x32_bf16 v[24:27], v[160:163], v[200:203], v[24:27]
	v_mfma_f32_16x16x32_bf16 v[12:15], v[152:155], v[208:211], v[12:15]
	v_mfma_f32_16x16x32_bf16 v[8:11], v[160:163], v[208:211], v[8:11]
	v_mfma_f32_16x16x32_bf16 v[52:55], v[164:167], v[180:183], v[52:55]
	v_mfma_f32_16x16x32_bf16 v[48:51], v[172:175], v[180:183], v[48:51]
	v_mfma_f32_16x16x32_bf16 v[36:39], v[164:167], v[188:191], v[36:39]
	v_mfma_f32_16x16x32_bf16 v[32:35], v[172:175], v[188:191], v[32:35]
	v_mfma_f32_16x16x32_bf16 v[20:23], v[164:167], v[196:199], v[20:23]
	v_mfma_f32_16x16x32_bf16 v[16:19], v[172:175], v[196:199], v[16:19]
	v_mfma_f32_16x16x32_bf16 v[4:7], v[164:167], v[204:207], v[4:7]
	v_mfma_f32_16x16x32_bf16 v[0:3], v[172:175], v[204:207], v[0:3]
	v_mfma_f32_16x16x32_bf16 v[52:55], v[168:171], v[184:187], v[52:55]
	v_mfma_f32_16x16x32_bf16 v[48:51], v[176:179], v[184:187], v[48:51]
	v_mfma_f32_16x16x32_bf16 v[36:39], v[168:171], v[192:195], v[36:39]
	v_mfma_f32_16x16x32_bf16 v[32:35], v[176:179], v[192:195], v[32:35]
	v_mfma_f32_16x16x32_bf16 v[20:23], v[168:171], v[200:203], v[20:23]
	v_mfma_f32_16x16x32_bf16 v[16:19], v[176:179], v[200:203], v[16:19]
	v_mfma_f32_16x16x32_bf16 v[4:7], v[168:171], v[208:211], v[4:7]
	v_mfma_f32_16x16x32_bf16 v[0:3], v[176:179], v[208:211], v[0:3]
	s_add_i32 s52, s52, 2
	s_add_u32 s50, s50, 0x100
	s_addc_u32 s51, s51, 0
	s_cmp_gt_u32 s52, 41
	s_mov_b64 s[22:23], s[24:25]
	s_barrier
	s_cbranch_scc0 .LBB0_1065
	s_and_b64 vcc, exec, s[18:19]
	s_cbranch_vccz .LBB0_1068
	s_barrier

.LBB0_1122:
	s_andn2_b64 vcc, exec, s[2:3]
	s_cbranch_vccnz .LBB0_1164
	v_ashrrev_i32_e32 v1, 31, v2
	v_lshrrev_b32_e32 v1, 26, v1
	v_add_u32_e32 v1, v2, v1
	v_ashrrev_i32_e32 v9, 6, v1
	v_bfe_i32 v1, v2, 27, 1
	v_lshlrev_b32_e32 v0, 4, v2
	v_lshrrev_b32_e32 v1, 22, v1
	v_add_u32_e32 v1, v0, v1
	v_and_b32_e32 v1, 0xfffffc00, v1
	v_sub_u32_e32 v1, v0, v1
	v_lshrrev_b32_e32 v2, 4, v1
	v_bitop3_b32 v1, v2, v1, 32 bitop3:0x6c
	v_ashrrev_i32_e32 v3, 31, v1
	v_lshrrev_b32_e32 v3, 26, v3
	v_add_u32_e32 v3, v1, v3
	v_lshlrev_b32_e32 v2, 3, v9
	v_ashrrev_i32_e32 v10, 6, v3
	v_and_b32_e32 v3, 0xc0, v3
	v_and_b32_e32 v2, -16, v2
	v_sub_u32_e32 v1, v1, v3
	v_mov_b32_e32 v3, 1
	v_add_u32_e32 v2, v10, v2
	v_ashrrev_i16_sdwa v1, v3, sext(v1) dst_sel:DWORD dst_unused:UNUSED_PAD src0_sel:DWORD src1_sel:BYTE_0
	v_lshlrev_b32_e32 v4, 5, v9
	v_bfe_i32 v11, v1, 0, 16
	v_lshlrev_b32_e32 v1, 1, v2
	v_lshrrev_b32_e32 v5, 2, v2
	v_and_b32_e32 v6, 3, v10
	s_mov_b32 s3, 0x1fffe0
	v_and_b32_e32 v4, 32, v4
	v_and_b32_e32 v1, 24, v1
	v_and_b32_e32 v5, 4, v5
	v_and_or_b32 v6, v2, s3, v6
	v_or3_b32 v1, v6, v5, v1
	v_add_lshl_u32 v4, v4, v11, 1
	v_add_u32_e32 v0, 0x2000, v0
	v_lshl_add_u32 v130, v1, 11, v4
	v_ashrrev_i32_e32 v1, 31, v0
	v_lshrrev_b32_e32 v1, 22, v1
	v_add_u32_e32 v1, v0, v1
	v_ashrrev_i32_e32 v12, 10, v1
	v_mul_i32_i24_e32 v1, 0x400, v12
	v_sub_u32_e32 v0, v0, v1
	v_lshrrev_b32_e32 v1, 4, v0
	v_bitop3_b32 v0, v1, v0, 32 bitop3:0x6c
	v_lshl_add_u32 v128, v2, 11, v4
	v_ashrrev_i32_e32 v2, 31, v0
	v_lshrrev_b32_e32 v2, 26, v2
	v_add_u32_e32 v2, v0, v2
	v_lshlrev_b32_e32 v1, 3, v12
	v_ashrrev_i32_e32 v13, 6, v2
	v_and_b32_e32 v2, 0xc0, v2
	s_add_u32 s40, s70, 0x1c00000
	v_and_b32_e32 v1, -16, v1
	v_sub_u32_e32 v0, v0, v2
	s_addc_u32 s41, s71, 0
	s_ashr_i32 s2, s4, 6
	v_add_u32_e32 v1, v13, v1
	v_ashrrev_i16_sdwa v0, v3, sext(v0) dst_sel:DWORD dst_unused:UNUSED_PAD src0_sel:DWORD src1_sel:BYTE_0
	v_and_b32_e32 v3, 3, v13
	s_ashr_i32 s31, s30, 31
	s_ashr_i32 s29, s28, 31
	v_and_or_b32 v3, v1, s3, v3
	s_ashr_i32 s3, s4, 8
	s_lshl_b32 s42, s2, 10
	s_lshl_b64 s[8:9], s[30:31], 19
	s_waitcnt lgkmcnt(0)
	s_lshl_b64 s[10:11], s[28:29], 19
	s_add_u32 s36, s40, s10
	v_lshlrev_b32_e32 v4, 5, v12
	v_bfe_i32 v14, v0, 0, 16
	v_lshlrev_b32_e32 v0, 1, v1
	v_lshrrev_b32_e32 v2, 2, v1
	s_addc_u32 s37, s41, s11
	s_add_i32 s43, s42, 0
	v_and_b32_e32 v4, 32, v4
	v_and_b32_e32 v0, 24, v0
	v_and_b32_e32 v2, 4, v2
	s_add_i32 m0, s43, 0x10000
	v_or3_b32 v0, v3, v2, v0
	v_add_lshl_u32 v2, v4, v14, 1
	global_load_lds_dwordx4 v130, s[36:37]
	s_add_i32 m0, s43, 0x12000
	v_lshl_add_u32 v134, v0, 11, v2
	s_add_u32 s10, s36, 0x40000
	global_load_lds_dwordx4 v134, s[36:37]
	s_addc_u32 s11, s37, 0
	s_add_i32 m0, s43, 0x14000
	v_lshl_add_u32 v132, v1, 11, v2
	global_load_lds_dwordx4 v130, s[10:11]
	s_add_i32 m0, s43, 0x16000
	s_add_u32 s34, s76, s8
	s_addc_u32 s35, s77, s9
	s_add_i32 s44, s43, 0x2000
	global_load_lds_dwordx4 v134, s[10:11]
	s_mov_b32 m0, s43
	s_add_u32 s8, s34, 0x40000
	global_load_lds_dwordx4 v128, s[34:35]
	s_mov_b32 m0, s44
	s_addc_u32 s9, s35, 0
	s_add_i32 s45, s43, 0x4000
	global_load_lds_dwordx4 v132, s[34:35]
	s_mov_b32 m0, s45
	s_add_i32 s46, s43, 0x6000
	global_load_lds_dwordx4 v128, s[8:9]
	s_mov_b32 m0, s46
	v_mov_b32_e32 v137, 0
	global_load_lds_dwordx4 v132, s[8:9]
	v_mov_b32_e32 v131, v137
	v_mov_b32_e32 v135, v137
	v_mov_b32_e32 v129, v137
	v_mov_b32_e32 v133, v137
	s_cmp_eq_u32 s3, 1
	s_mov_b32 s9, 0
	v_lshl_add_u64 v[6:7], s[36:37], 0, v[130:131]
	v_lshl_add_u64 v[4:5], s[36:37], 0, v[134:135]
	v_lshl_add_u64 v[0:1], s[34:35], 0, v[128:129]
	s_cselect_b64 s[10:11], -1, 0
	s_cmp_lg_u32 s3, 1
	v_lshl_add_u64 v[2:3], s[34:35], 0, v[132:133]
	s_setprio 1
	s_cbranch_scc1 .LBB0_1125
	s_barrier
	s_setprio 0

.LBB0_1131:
	ds_read_b128 v[154:157], v160
	ds_read_b128 v[166:169], v160 offset:1024
	ds_read_b128 v[170:173], v160 offset:2048
	ds_read_b128 v[174:177], v160 offset:3072
	ds_read_b128 v[178:181], v161
	ds_read_b128 v[182:185], v161 offset:1024
	ds_read_b128 v[186:189], v161 offset:2048
	ds_read_b128 v[190:193], v161 offset:3072
	s_add_u32 s36, s34, 0xfffc0080
	s_addc_u32 s37, s35, -1
	s_cmp_eq_u32 s58, 12
	s_cselect_b32 s39, s23, s37
	s_cselect_b32 s38, s29, s36
	s_cselect_b32 s37, s21, s57
	s_cselect_b32 s36, s31, s56
	s_add_i32 m0, s43, 0xc000
	ds_read_b128 v[194:197], v162
	ds_read_b128 v[198:201], v162 offset:1024
	ds_read_b128 v[202:205], v162 offset:2048
	ds_read_b128 v[206:209], v162 offset:3072
	ds_read_b128 v[210:213], v162 offset:4096
	ds_read_b128 v[214:217], v162 offset:5120
	ds_read_b128 v[218:221], v162 offset:6144
	ds_read_b128 v[222:225], v162 offset:7168
	global_load_lds_dwordx4 v146, s[34:35]
	s_add_i32 m0, s43, 0xe000
	s_nop 0
	global_load_lds_dwordx4 v148, s[34:35]
	s_waitcnt vmcnt(8)
	s_waitcnt lgkmcnt(0)
	s_barrier
	s_waitcnt lgkmcnt(0)
	v_mfma_f32_16x16x32_bf16 v[116:119], v[154:157], v[194:197], v[116:119]
	v_mfma_f32_16x16x32_bf16 v[112:115], v[170:173], v[194:197], v[112:115]
	v_mfma_f32_16x16x32_bf16 v[100:103], v[154:157], v[202:205], v[100:103]
	v_mfma_f32_16x16x32_bf16 v[96:99], v[170:173], v[202:205], v[96:99]
	v_mfma_f32_16x16x32_bf16 v[88:91], v[154:157], v[210:213], v[88:91]
	v_mfma_f32_16x16x32_bf16 v[84:87], v[170:173], v[210:213], v[84:87]
	v_mfma_f32_16x16x32_bf16 v[72:75], v[154:157], v[218:221], v[72:75]
	v_mfma_f32_16x16x32_bf16 v[68:71], v[170:173], v[218:221], v[68:71]
	v_mfma_f32_16x16x32_bf16 v[116:119], v[166:169], v[198:201], v[116:119]
	v_mfma_f32_16x16x32_bf16 v[112:115], v[174:177], v[198:201], v[112:115]
	v_mfma_f32_16x16x32_bf16 v[100:103], v[166:169], v[206:209], v[100:103]
	v_mfma_f32_16x16x32_bf16 v[96:99], v[174:177], v[206:209], v[96:99]
	v_mfma_f32_16x16x32_bf16 v[88:91], v[166:169], v[214:217], v[88:91]
	v_mfma_f32_16x16x32_bf16 v[84:87], v[174:177], v[214:217], v[84:87]
	v_mfma_f32_16x16x32_bf16 v[72:75], v[166:169], v[222:225], v[72:75]
	v_mfma_f32_16x16x32_bf16 v[68:71], v[174:177], v[222:225], v[68:71]
	v_mfma_f32_16x16x32_bf16 v[124:127], v[178:181], v[194:197], v[124:127]
	v_mfma_f32_16x16x32_bf16 v[120:123], v[186:189], v[194:197], v[120:123]
	v_mfma_f32_16x16x32_bf16 v[108:111], v[178:181], v[202:205], v[108:111]
	v_mfma_f32_16x16x32_bf16 v[104:107], v[186:189], v[202:205], v[104:107]
	v_mfma_f32_16x16x32_bf16 v[92:95], v[178:181], v[210:213], v[92:95]
	v_mfma_f32_16x16x32_bf16 v[80:83], v[186:189], v[210:213], v[80:83]
	v_mfma_f32_16x16x32_bf16 v[76:79], v[178:181], v[218:221], v[76:79]
	v_mfma_f32_16x16x32_bf16 v[64:67], v[186:189], v[218:221], v[64:67]
	v_mfma_f32_16x16x32_bf16 v[124:127], v[182:185], v[198:201], v[124:127]
	v_mfma_f32_16x16x32_bf16 v[120:123], v[190:193], v[198:201], v[120:123]
	v_mfma_f32_16x16x32_bf16 v[108:111], v[182:185], v[206:209], v[108:111]
	v_mfma_f32_16x16x32_bf16 v[104:107], v[190:193], v[206:209], v[104:107]
	v_mfma_f32_16x16x32_bf16 v[92:95], v[182:185], v[214:217], v[92:95]
	v_mfma_f32_16x16x32_bf16 v[80:83], v[190:193], v[214:217], v[80:83]
	v_mfma_f32_16x16x32_bf16 v[76:79], v[182:185], v[222:225], v[76:79]
	v_mfma_f32_16x16x32_bf16 v[64:67], v[190:193], v[222:225], v[64:67]
	s_barrier
	s_add_i32 s59, s52, s42
	v_lshl_add_u64 v[226:227], s[36:37], 0, v[130:131]
	s_mov_b32 m0, s59
	ds_read_b128 v[194:197], v162 offset:16384
	ds_read_b128 v[198:201], v162 offset:17408
	ds_read_b128 v[202:205], v162 offset:18432
	ds_read_b128 v[206:209], v162 offset:19456
	ds_read_b128 v[210:213], v162 offset:20480
	ds_read_b128 v[214:217], v162 offset:21504
	ds_read_b128 v[218:221], v162 offset:22528
	ds_read_b128 v[222:225], v162 offset:23552
	global_load_lds_dwordx4 v[226:227], off
	s_add_i32 m0, s59, 0x2000
	s_add_u32 s60, s36, 0x40000
	v_lshl_add_u64 v[228:229], s[36:37], 0, v[134:135]
	s_addc_u32 s61, s37, 0
	s_add_i32 s59, s53, s42
	global_load_lds_dwordx4 v[228:229], off
	s_mov_b32 m0, s59
	v_lshl_add_u64 v[232:233], s[38:39], 0, v[132:133]
	global_load_lds_dwordx4 v130, s[60:61]
	s_add_i32 m0, s59, 0x2000
	s_nop 0
	global_load_lds_dwordx4 v134, s[60:61]
	v_lshl_add_u64 v[230:231], s[38:39], 0, v[128:129]
	s_mov_b32 m0, s43
	s_nop 0
	global_load_lds_dwordx4 v[230:231], off
	s_mov_b32 m0, s44
	s_nop 0
	global_load_lds_dwordx4 v[232:233], off
	s_waitcnt vmcnt(8)
	s_waitcnt lgkmcnt(0)
	s_barrier
	s_waitcnt lgkmcnt(0)
	v_mfma_f32_16x16x32_bf16 v[56:59], v[154:157], v[194:197], v[56:59]
	v_mfma_f32_16x16x32_bf16 v[52:55], v[170:173], v[194:197], v[52:55]
	v_mfma_f32_16x16x32_bf16 v[40:43], v[154:157], v[202:205], v[40:43]
	v_mfma_f32_16x16x32_bf16 v[36:39], v[170:173], v[202:205], v[36:39]
	v_mfma_f32_16x16x32_bf16 v[24:27], v[154:157], v[210:213], v[24:27]
	v_mfma_f32_16x16x32_bf16 v[20:23], v[170:173], v[210:213], v[20:23]
	v_mfma_f32_16x16x32_bf16 v[8:11], v[154:157], v[218:221], v[8:11]
	v_mfma_f32_16x16x32_bf16 v[4:7], v[170:173], v[218:221], v[4:7]
	v_mfma_f32_16x16x32_bf16 v[56:59], v[166:169], v[198:201], v[56:59]
	v_mfma_f32_16x16x32_bf16 v[52:55], v[174:177], v[198:201], v[52:55]
	v_mfma_f32_16x16x32_bf16 v[40:43], v[166:169], v[206:209], v[40:43]
	v_mfma_f32_16x16x32_bf16 v[36:39], v[174:177], v[206:209], v[36:39]
	v_mfma_f32_16x16x32_bf16 v[24:27], v[166:169], v[214:217], v[24:27]
	v_mfma_f32_16x16x32_bf16 v[20:23], v[174:177], v[214:217], v[20:23]
	v_mfma_f32_16x16x32_bf16 v[8:11], v[166:169], v[222:225], v[8:11]
	v_mfma_f32_16x16x32_bf16 v[4:7], v[174:177], v[222:225], v[4:7]
	v_mfma_f32_16x16x32_bf16 v[60:63], v[178:181], v[194:197], v[60:63]
	v_mfma_f32_16x16x32_bf16 v[48:51], v[186:189], v[194:197], v[48:51]
	v_mfma_f32_16x16x32_bf16 v[44:47], v[178:181], v[202:205], v[44:47]
	v_mfma_f32_16x16x32_bf16 v[32:35], v[186:189], v[202:205], v[32:35]
	v_mfma_f32_16x16x32_bf16 v[28:31], v[178:181], v[210:213], v[28:31]
	v_mfma_f32_16x16x32_bf16 v[16:19], v[186:189], v[210:213], v[16:19]
	v_mfma_f32_16x16x32_bf16 v[12:15], v[178:181], v[218:221], v[12:15]
	v_mfma_f32_16x16x32_bf16 v[0:3], v[186:189], v[218:221], v[0:3]
	v_mfma_f32_16x16x32_bf16 v[60:63], v[182:185], v[198:201], v[60:63]
	v_mfma_f32_16x16x32_bf16 v[48:51], v[190:193], v[198:201], v[48:51]
	v_mfma_f32_16x16x32_bf16 v[44:47], v[182:185], v[206:209], v[44:47]
	v_mfma_f32_16x16x32_bf16 v[32:35], v[190:193], v[206:209], v[32:35]
	v_mfma_f32_16x16x32_bf16 v[28:31], v[182:185], v[214:217], v[28:31]
	v_mfma_f32_16x16x32_bf16 v[16:19], v[190:193], v[214:217], v[16:19]
	v_mfma_f32_16x16x32_bf16 v[12:15], v[182:185], v[222:225], v[12:15]
	v_mfma_f32_16x16x32_bf16 v[0:3], v[190:193], v[222:225], v[0:3]
	s_barrier
	s_add_i32 s59, 0, 0x18000
	v_add_u32_e32 v165, s59, v159
	s_add_i32 s60, 0, 0x1c000
	ds_read_b128 v[154:157], v165
	ds_read_b128 v[166:169], v165 offset:1024
	ds_read_b128 v[170:173], v165 offset:2048
	ds_read_b128 v[174:177], v165 offset:3072
	v_add_u32_e32 v165, s60, v159
	ds_read_b128 v[178:181], v165
	ds_read_b128 v[182:185], v165 offset:1024
	ds_read_b128 v[186:189], v165 offset:2048
	ds_read_b128 v[190:193], v165 offset:3072
	s_add_u32 s38, s38, 0x40000
	s_addc_u32 s39, s39, 0
	s_mov_b32 m0, s45
	ds_read_b128 v[194:197], v162 offset:32768
	ds_read_b128 v[198:201], v162 offset:33792
	ds_read_b128 v[202:205], v162 offset:34816
	ds_read_b128 v[206:209], v162 offset:35840
	ds_read_b128 v[210:213], v162 offset:36864
	ds_read_b128 v[214:217], v162 offset:37888
	ds_read_b128 v[218:221], v162 offset:38912
	ds_read_b128 v[222:225], v162 offset:39936
	global_load_lds_dwordx4 v128, s[38:39]
	v_lshl_add_u64 v[234:235], s[38:39], 0, v[132:133]
	s_mov_b32 m0, s46
	s_nop 0
	global_load_lds_dwordx4 v[234:235], off
	s_waitcnt vmcnt(8)
	s_waitcnt lgkmcnt(0)
	s_barrier
	s_waitcnt lgkmcnt(0)
	v_mfma_f32_16x16x32_bf16 v[116:119], v[154:157], v[194:197], v[116:119]
	v_mfma_f32_16x16x32_bf16 v[112:115], v[170:173], v[194:197], v[112:115]
	v_mfma_f32_16x16x32_bf16 v[100:103], v[154:157], v[202:205], v[100:103]
	v_mfma_f32_16x16x32_bf16 v[96:99], v[170:173], v[202:205], v[96:99]
	v_mfma_f32_16x16x32_bf16 v[88:91], v[154:157], v[210:213], v[88:91]
	v_mfma_f32_16x16x32_bf16 v[84:87], v[170:173], v[210:213], v[84:87]
	v_mfma_f32_16x16x32_bf16 v[72:75], v[154:157], v[218:221], v[72:75]
	v_mfma_f32_16x16x32_bf16 v[68:71], v[170:173], v[218:221], v[68:71]
	v_mfma_f32_16x16x32_bf16 v[116:119], v[166:169], v[198:201], v[116:119]
	v_mfma_f32_16x16x32_bf16 v[112:115], v[174:177], v[198:201], v[112:115]
	v_mfma_f32_16x16x32_bf16 v[100:103], v[166:169], v[206:209], v[100:103]
	v_mfma_f32_16x16x32_bf16 v[96:99], v[174:177], v[206:209], v[96:99]
	v_mfma_f32_16x16x32_bf16 v[88:91], v[166:169], v[214:217], v[88:91]
	v_mfma_f32_16x16x32_bf16 v[84:87], v[174:177], v[214:217], v[84:87]
	v_mfma_f32_16x16x32_bf16 v[72:75], v[166:169], v[222:225], v[72:75]
	v_mfma_f32_16x16x32_bf16 v[68:71], v[174:177], v[222:225], v[68:71]
	v_mfma_f32_16x16x32_bf16 v[124:127], v[178:181], v[194:197], v[124:127]
	v_mfma_f32_16x16x32_bf16 v[120:123], v[186:189], v[194:197], v[120:123]
	v_mfma_f32_16x16x32_bf16 v[108:111], v[178:181], v[202:205], v[108:111]
	v_mfma_f32_16x16x32_bf16 v[104:107], v[186:189], v[202:205], v[104:107]
	v_mfma_f32_16x16x32_bf16 v[92:95], v[178:181], v[210:213], v[92:95]
	v_mfma_f32_16x16x32_bf16 v[80:83], v[186:189], v[210:213], v[80:83]
	v_mfma_f32_16x16x32_bf16 v[76:79], v[178:181], v[218:221], v[76:79]
	v_mfma_f32_16x16x32_bf16 v[64:67], v[186:189], v[218:221], v[64:67]
	v_mfma_f32_16x16x32_bf16 v[124:127], v[182:185], v[198:201], v[124:127]
	v_mfma_f32_16x16x32_bf16 v[120:123], v[190:193], v[198:201], v[120:123]
	v_mfma_f32_16x16x32_bf16 v[108:111], v[182:185], v[206:209], v[108:111]
	v_mfma_f32_16x16x32_bf16 v[104:107], v[190:193], v[206:209], v[104:107]
	v_mfma_f32_16x16x32_bf16 v[92:95], v[182:185], v[214:217], v[92:95]
	v_mfma_f32_16x16x32_bf16 v[80:83], v[190:193], v[214:217], v[80:83]
	v_mfma_f32_16x16x32_bf16 v[76:79], v[182:185], v[222:225], v[76:79]
	v_mfma_f32_16x16x32_bf16 v[64:67], v[190:193], v[222:225], v[64:67]
	s_barrier
	s_add_i32 s38, s59, s42
	v_lshl_add_u64 v[226:227], v[226:227], 0, s[12:13]
	s_mov_b32 m0, s38
	ds_read_b128 v[194:197], v162 offset:49152
	ds_read_b128 v[198:201], v162 offset:50176
	ds_read_b128 v[202:205], v162 offset:51200
	ds_read_b128 v[206:209], v162 offset:52224
	ds_read_b128 v[210:213], v162 offset:53248
	ds_read_b128 v[214:217], v162 offset:54272
	ds_read_b128 v[218:221], v162 offset:55296
	ds_read_b128 v[222:225], v162 offset:56320
	global_load_lds_dwordx4 v[226:227], off
	s_add_i32 m0, s38, 0x2000
	s_add_u32 s36, s36, 0x40080
	v_lshl_add_u64 v[226:227], v[228:229], 0, s[12:13]
	s_addc_u32 s37, s37, 0
	s_add_i32 s38, s60, s42
	global_load_lds_dwordx4 v[226:227], off
	s_mov_b32 m0, s38
	s_nop 0
	global_load_lds_dwordx4 v130, s[36:37]
	s_add_i32 m0, s38, 0x2000
	s_nop 0
	global_load_lds_dwordx4 v134, s[36:37]
	v_lshl_add_u64 v[226:227], v[230:231], 0, s[12:13]
	s_mov_b32 m0, s47
	s_nop 0
	global_load_lds_dwordx4 v[226:227], off
	v_lshl_add_u64 v[226:227], v[232:233], 0, s[12:13]
	s_mov_b32 m0, s48
	s_nop 0
	global_load_lds_dwordx4 v[226:227], off
	s_waitcnt vmcnt(8)
	s_waitcnt lgkmcnt(0)
	s_barrier
	s_waitcnt lgkmcnt(0)
	v_mfma_f32_16x16x32_bf16 v[56:59], v[154:157], v[194:197], v[56:59]
	v_mfma_f32_16x16x32_bf16 v[52:55], v[170:173], v[194:197], v[52:55]
	v_mfma_f32_16x16x32_bf16 v[40:43], v[154:157], v[202:205], v[40:43]
	v_mfma_f32_16x16x32_bf16 v[36:39], v[170:173], v[202:205], v[36:39]
	v_mfma_f32_16x16x32_bf16 v[24:27], v[154:157], v[210:213], v[24:27]
	v_mfma_f32_16x16x32_bf16 v[20:23], v[170:173], v[210:213], v[20:23]
	v_mfma_f32_16x16x32_bf16 v[8:11], v[154:157], v[218:221], v[8:11]
	v_mfma_f32_16x16x32_bf16 v[4:7], v[170:173], v[218:221], v[4:7]
	v_mfma_f32_16x16x32_bf16 v[56:59], v[166:169], v[198:201], v[56:59]
	v_mfma_f32_16x16x32_bf16 v[52:55], v[174:177], v[198:201], v[52:55]
	v_mfma_f32_16x16x32_bf16 v[40:43], v[166:169], v[206:209], v[40:43]
	v_mfma_f32_16x16x32_bf16 v[36:39], v[174:177], v[206:209], v[36:39]
	v_mfma_f32_16x16x32_bf16 v[24:27], v[166:169], v[214:217], v[24:27]
	v_mfma_f32_16x16x32_bf16 v[20:23], v[174:177], v[214:217], v[20:23]
	v_mfma_f32_16x16x32_bf16 v[8:11], v[166:169], v[222:225], v[8:11]
	v_mfma_f32_16x16x32_bf16 v[4:7], v[174:177], v[222:225], v[4:7]
	v_mfma_f32_16x16x32_bf16 v[60:63], v[178:181], v[194:197], v[60:63]
	v_mfma_f32_16x16x32_bf16 v[48:51], v[186:189], v[194:197], v[48:51]
	v_mfma_f32_16x16x32_bf16 v[44:47], v[178:181], v[202:205], v[44:47]
	v_mfma_f32_16x16x32_bf16 v[32:35], v[186:189], v[202:205], v[32:35]
	v_mfma_f32_16x16x32_bf16 v[28:31], v[178:181], v[210:213], v[28:31]
	v_mfma_f32_16x16x32_bf16 v[16:19], v[186:189], v[210:213], v[16:19]
	v_mfma_f32_16x16x32_bf16 v[12:15], v[178:181], v[218:221], v[12:15]
	v_mfma_f32_16x16x32_bf16 v[0:3], v[186:189], v[218:221], v[0:3]
	v_mfma_f32_16x16x32_bf16 v[60:63], v[182:185], v[198:201], v[60:63]
	v_mfma_f32_16x16x32_bf16 v[48:51], v[190:193], v[198:201], v[48:51]
	v_mfma_f32_16x16x32_bf16 v[44:47], v[182:185], v[206:209], v[44:47]
	v_mfma_f32_16x16x32_bf16 v[32:35], v[190:193], v[206:209], v[32:35]
	v_mfma_f32_16x16x32_bf16 v[28:31], v[182:185], v[214:217], v[28:31]
	v_mfma_f32_16x16x32_bf16 v[16:19], v[190:193], v[214:217], v[16:19]
	v_mfma_f32_16x16x32_bf16 v[12:15], v[182:185], v[222:225], v[12:15]
	v_mfma_f32_16x16x32_bf16 v[0:3], v[190:193], v[222:225], v[0:3]
	s_add_i32 s58, s58, 2
	s_add_u32 s34, s34, 0x100
	s_addc_u32 s35, s35, 0
	s_add_u32 s56, s56, 0x100
	s_addc_u32 s57, s57, 0
	s_cmp_gt_u32 s58, 13
	s_barrier
	s_cbranch_scc0 .LBB0_1131
	s_and_b64 vcc, exec, s[14:15]
	s_cbranch_vccz .LBB0_1136
	s_barrier
	v_lshl_add_u32 v154, s30, 8, v158
	s_cmp_gt_i32 s28, 21
	s_mov_b64 s[30:31], -1
	s_cbranch_scc1 .LBB0_1137

.LBB0_1202:
	v_cndmask_b32_e64 v1, 0, 1, s[4:5]
	v_cmp_ne_u32_e64 s[2:3], 1, v1
	s_andn2_b64 vcc, exec, s[4:5]
	s_cbranch_vccnz .LBB0_1242
	v_ashrrev_i32_e32 v2, 31, v0
	v_lshrrev_b32_e32 v2, 26, v2
	v_lshlrev_b32_e32 v1, 4, v0
	v_add_u32_e32 v2, v0, v2
	v_bfe_i32 v0, v0, 27, 1
	v_lshrrev_b32_e32 v0, 22, v0
	v_add_u32_e32 v0, v1, v0
	v_and_b32_e32 v0, 0xfffffc00, v0
	v_sub_u32_e32 v0, v1, v0
	v_ashrrev_i32_e32 v9, 6, v2
	v_lshrrev_b32_e32 v2, 4, v0
	v_bitop3_b32 v0, v2, v0, 32 bitop3:0x6c
	v_ashrrev_i32_e32 v3, 31, v0
	v_lshrrev_b32_e32 v3, 26, v3
	v_add_u32_e32 v3, v0, v3
	v_lshlrev_b32_e32 v2, 3, v9
	v_ashrrev_i32_e32 v11, 6, v3
	v_and_b32_e32 v3, 0xc0, v3
	v_and_b32_e32 v2, 0xfffff0, v2
	v_sub_u32_e32 v0, v0, v3
	v_mov_b32_e32 v3, 1
	v_add_u32_e32 v2, v11, v2
	v_lshlrev_b32_e32 v4, 5, v9
	v_ashrrev_i16_sdwa v0, v3, sext(v0) dst_sel:DWORD dst_unused:UNUSED_PAD src0_sel:DWORD src1_sel:BYTE_0
	s_movk_i32 s7, 0xb00
	v_and_b32_e32 v10, 32, v4
	v_bfe_i32 v12, v0, 0, 16
	v_mul_lo_u32 v0, v2, s7
	v_or_b32_e32 v0, v0, v10
	v_add_lshl_u32 v128, v0, v12, 1
	v_add_u32_e32 v0, 0x2000, v1
	v_ashrrev_i32_e32 v1, 31, v0
	v_lshrrev_b32_e32 v1, 22, v1
	v_add_u32_e32 v1, v0, v1
	v_ashrrev_i32_e32 v13, 10, v1
	v_mul_i32_i24_e32 v1, 0x400, v13
	v_sub_u32_e32 v0, v0, v1
	v_lshrrev_b32_e32 v1, 4, v0
	v_bitop3_b32 v0, v1, v0, 32 bitop3:0x6c
	v_ashrrev_i32_e32 v2, 31, v0
	s_add_u32 s34, s70, 0x3f00000
	v_lshrrev_b32_e32 v2, 26, v2
	s_addc_u32 s35, s71, 0
	s_ashr_i32 s4, s6, 6
	v_add_u32_e32 v2, v0, v2
	v_lshlrev_b32_e32 v1, 3, v13
	v_ashrrev_i32_e32 v14, 6, v2
	v_and_b32_e32 v2, 0xc0, v2
	s_ashr_i32 s5, s6, 8
	s_lshl_b32 s36, s4, 10
	s_mul_i32 s9, s14, 0x160000
	v_and_b32_e32 v1, 0xfffff0, v1
	v_sub_u32_e32 v0, v0, v2
	s_mul_hi_i32 s8, s14, 0x160000
	s_add_u32 s26, s34, s9
	v_add_u32_e32 v1, v14, v1
	v_lshlrev_b32_e32 v4, 5, v13
	v_ashrrev_i16_sdwa v0, v3, sext(v0) dst_sel:DWORD dst_unused:UNUSED_PAD src0_sel:DWORD src1_sel:BYTE_0
	s_addc_u32 s27, s35, s8
	s_add_i32 s37, s36, 0
	v_and_b32_e32 v15, 32, v4
	v_bfe_i32 v16, v0, 0, 16
	v_mul_lo_u32 v0, v1, s7
	s_add_i32 m0, s37, 0x10000
	v_or_b32_e32 v0, v0, v15
	global_load_lds_dwordx4 v128, s[26:27]
	s_add_i32 m0, s37, 0x12000
	v_add_lshl_u32 v130, v0, v16, 1
	s_add_u32 s8, s26, 0xb0000
	global_load_lds_dwordx4 v130, s[26:27]
	s_addc_u32 s9, s27, 0
	s_add_i32 m0, s37, 0x14000
	s_mul_i32 s16, s51, 0x160000
	global_load_lds_dwordx4 v128, s[8:9]
	s_add_i32 m0, s37, 0x16000
	s_mul_hi_i32 s15, s51, 0x160000
	s_add_u32 s24, s72, s16
	s_addc_u32 s25, s73, s15
	s_add_i32 s38, s37, 0x2000
	global_load_lds_dwordx4 v130, s[8:9]
	s_mov_b32 m0, s37
	s_add_u32 s8, s24, 0xb0000
	global_load_lds_dwordx4 v128, s[24:25]
	s_mov_b32 m0, s38
	s_addc_u32 s9, s25, 0
	s_add_i32 s39, s37, 0x4000
	global_load_lds_dwordx4 v130, s[24:25]
	s_mov_b32 m0, s39
	s_add_i32 s40, s37, 0x6000
	global_load_lds_dwordx4 v128, s[8:9]
	s_mov_b32 m0, s40
	v_mov_b32_e32 v129, 0
	global_load_lds_dwordx4 v130, s[8:9]
	v_mov_b32_e32 v131, v129
	s_cmp_eq_u32 s5, 1
	s_mov_b32 s15, 0
	v_lshl_add_u64 v[6:7], s[26:27], 0, v[128:129]
	v_lshl_add_u64 v[4:5], s[26:27], 0, v[130:131]
	v_lshl_add_u64 v[0:1], s[24:25], 0, v[128:129]
	s_cselect_b64 s[16:17], -1, 0
	s_cmp_lg_u32 s5, 1
	v_lshl_add_u64 v[2:3], s[24:25], 0, v[130:131]
	s_setprio 1
	s_cbranch_scc1 .LBB0_1205
	s_barrier
	s_setprio 0

.LBB0_1219:
	ds_read_b128 v[140:143], v147
	ds_read_b128 v[152:155], v147 offset:1024
	ds_read_b128 v[156:159], v147 offset:2048
	ds_read_b128 v[160:163], v147 offset:3072
	ds_read_b128 v[164:167], v148
	ds_read_b128 v[168:171], v148 offset:1024
	ds_read_b128 v[172:175], v148 offset:2048
	ds_read_b128 v[176:179], v148 offset:3072
	s_add_u32 s26, s24, 0x100
	s_addc_u32 s27, s25, 0
	s_cmp_eq_u32 s54, 40
	s_cselect_b32 s31, s9, s27
	s_cselect_b32 s30, s8, s26
	s_cselect_b32 s29, s23, s53
	s_cselect_b32 s28, s22, s52
	v_lshl_add_u64 v[212:213], s[24:25], 0, v[132:133]
	s_add_i32 m0, s37, 0xc000
	ds_read_b128 v[180:183], v149
	ds_read_b128 v[184:187], v149 offset:1024
	ds_read_b128 v[188:191], v149 offset:2048
	ds_read_b128 v[192:195], v149 offset:3072
	ds_read_b128 v[196:199], v149 offset:4096
	ds_read_b128 v[200:203], v149 offset:5120
	ds_read_b128 v[204:207], v149 offset:6144
	ds_read_b128 v[208:211], v149 offset:7168
	global_load_lds_dwordx4 v[212:213], off
	v_lshl_add_u64 v[212:213], s[24:25], 0, v[134:135]
	s_add_i32 m0, s37, 0xe000
	s_nop 0
	global_load_lds_dwordx4 v[212:213], off
	s_waitcnt vmcnt(8)
	s_waitcnt lgkmcnt(0)
	s_barrier
	s_waitcnt lgkmcnt(0)
	v_mfma_f32_16x16x32_bf16 v[124:127], v[140:143], v[180:183], v[124:127]
	v_mfma_f32_16x16x32_bf16 v[120:123], v[156:159], v[180:183], v[120:123]
	v_mfma_f32_16x16x32_bf16 v[108:111], v[140:143], v[188:191], v[108:111]
	v_mfma_f32_16x16x32_bf16 v[104:107], v[156:159], v[188:191], v[104:107]
	v_mfma_f32_16x16x32_bf16 v[92:95], v[140:143], v[196:199], v[92:95]
	v_mfma_f32_16x16x32_bf16 v[88:91], v[156:159], v[196:199], v[88:91]
	v_mfma_f32_16x16x32_bf16 v[76:79], v[140:143], v[204:207], v[76:79]
	v_mfma_f32_16x16x32_bf16 v[72:75], v[156:159], v[204:207], v[72:75]
	v_mfma_f32_16x16x32_bf16 v[124:127], v[152:155], v[184:187], v[124:127]
	v_mfma_f32_16x16x32_bf16 v[120:123], v[160:163], v[184:187], v[120:123]
	v_mfma_f32_16x16x32_bf16 v[108:111], v[152:155], v[192:195], v[108:111]
	v_mfma_f32_16x16x32_bf16 v[104:107], v[160:163], v[192:195], v[104:107]
	v_mfma_f32_16x16x32_bf16 v[92:95], v[152:155], v[200:203], v[92:95]
	v_mfma_f32_16x16x32_bf16 v[88:91], v[160:163], v[200:203], v[88:91]
	v_mfma_f32_16x16x32_bf16 v[76:79], v[152:155], v[208:211], v[76:79]
	v_mfma_f32_16x16x32_bf16 v[72:75], v[160:163], v[208:211], v[72:75]
	v_mfma_f32_16x16x32_bf16 v[116:119], v[164:167], v[180:183], v[116:119]
	v_mfma_f32_16x16x32_bf16 v[112:115], v[172:175], v[180:183], v[112:115]
	v_mfma_f32_16x16x32_bf16 v[100:103], v[164:167], v[188:191], v[100:103]
	v_mfma_f32_16x16x32_bf16 v[96:99], v[172:175], v[188:191], v[96:99]
	v_mfma_f32_16x16x32_bf16 v[84:87], v[164:167], v[196:199], v[84:87]
	v_mfma_f32_16x16x32_bf16 v[80:83], v[172:175], v[196:199], v[80:83]
	v_mfma_f32_16x16x32_bf16 v[68:71], v[164:167], v[204:207], v[68:71]
	v_mfma_f32_16x16x32_bf16 v[64:67], v[172:175], v[204:207], v[64:67]
	v_mfma_f32_16x16x32_bf16 v[116:119], v[168:171], v[184:187], v[116:119]
	v_mfma_f32_16x16x32_bf16 v[112:115], v[176:179], v[184:187], v[112:115]
	v_mfma_f32_16x16x32_bf16 v[100:103], v[168:171], v[192:195], v[100:103]
	v_mfma_f32_16x16x32_bf16 v[96:99], v[176:179], v[192:195], v[96:99]
	v_mfma_f32_16x16x32_bf16 v[84:87], v[168:171], v[200:203], v[84:87]
	v_mfma_f32_16x16x32_bf16 v[80:83], v[176:179], v[200:203], v[80:83]
	v_mfma_f32_16x16x32_bf16 v[68:71], v[168:171], v[208:211], v[68:71]
	v_mfma_f32_16x16x32_bf16 v[64:67], v[176:179], v[208:211], v[64:67]
	s_barrier
	s_add_i32 s24, s46, s36
	v_lshl_add_u64 v[212:213], s[28:29], 0, v[128:129]
	s_mov_b32 m0, s24
	ds_read_b128 v[180:183], v149 offset:16384
	ds_read_b128 v[184:187], v149 offset:17408
	ds_read_b128 v[188:191], v149 offset:18432
	ds_read_b128 v[192:195], v149 offset:19456
	ds_read_b128 v[196:199], v149 offset:20480
	ds_read_b128 v[200:203], v149 offset:21504
	ds_read_b128 v[204:207], v149 offset:22528
	ds_read_b128 v[208:211], v149 offset:23552
	global_load_lds_dwordx4 v[212:213], off
	s_add_i32 m0, s24, 0x2000
	s_add_u32 s24, s28, 0xb0000
	v_lshl_add_u64 v[214:215], s[28:29], 0, v[130:131]
	s_addc_u32 s25, s29, 0
	s_add_i32 s55, s47, s36
	global_load_lds_dwordx4 v[214:215], off
	v_lshl_add_u64 v[216:217], s[24:25], 0, v[128:129]
	s_mov_b32 m0, s55
	v_lshl_add_u64 v[218:219], s[30:31], 0, v[130:131]
	global_load_lds_dwordx4 v[216:217], off
	s_add_i32 m0, s55, 0x2000
	s_nop 0
	global_load_lds_dwordx4 v130, s[24:25]
	v_lshl_add_u64 v[216:217], s[30:31], 0, v[128:129]
	s_mov_b32 m0, s37
	s_nop 0
	global_load_lds_dwordx4 v[216:217], off
	s_mov_b32 m0, s38
	s_nop 0
	global_load_lds_dwordx4 v[218:219], off
	s_waitcnt vmcnt(8)
	s_waitcnt lgkmcnt(0)
	s_barrier
	s_waitcnt lgkmcnt(0)
	v_mfma_f32_16x16x32_bf16 v[60:63], v[140:143], v[180:183], v[60:63]
	v_mfma_f32_16x16x32_bf16 v[56:59], v[156:159], v[180:183], v[56:59]
	v_mfma_f32_16x16x32_bf16 v[44:47], v[140:143], v[188:191], v[44:47]
	v_mfma_f32_16x16x32_bf16 v[40:43], v[156:159], v[188:191], v[40:43]
	v_mfma_f32_16x16x32_bf16 v[28:31], v[140:143], v[196:199], v[28:31]
	v_mfma_f32_16x16x32_bf16 v[24:27], v[156:159], v[196:199], v[24:27]
	v_mfma_f32_16x16x32_bf16 v[12:15], v[140:143], v[204:207], v[12:15]
	v_mfma_f32_16x16x32_bf16 v[8:11], v[156:159], v[204:207], v[8:11]
	v_mfma_f32_16x16x32_bf16 v[60:63], v[152:155], v[184:187], v[60:63]
	v_mfma_f32_16x16x32_bf16 v[56:59], v[160:163], v[184:187], v[56:59]
	v_mfma_f32_16x16x32_bf16 v[44:47], v[152:155], v[192:195], v[44:47]
	v_mfma_f32_16x16x32_bf16 v[40:43], v[160:163], v[192:195], v[40:43]
	v_mfma_f32_16x16x32_bf16 v[28:31], v[152:155], v[200:203], v[28:31]
	v_mfma_f32_16x16x32_bf16 v[24:27], v[160:163], v[200:203], v[24:27]
	v_mfma_f32_16x16x32_bf16 v[12:15], v[152:155], v[208:211], v[12:15]
	v_mfma_f32_16x16x32_bf16 v[8:11], v[160:163], v[208:211], v[8:11]
	v_mfma_f32_16x16x32_bf16 v[52:55], v[164:167], v[180:183], v[52:55]
	v_mfma_f32_16x16x32_bf16 v[48:51], v[172:175], v[180:183], v[48:51]
	v_mfma_f32_16x16x32_bf16 v[36:39], v[164:167], v[188:191], v[36:39]
	v_mfma_f32_16x16x32_bf16 v[32:35], v[172:175], v[188:191], v[32:35]
	v_mfma_f32_16x16x32_bf16 v[20:23], v[164:167], v[196:199], v[20:23]
	v_mfma_f32_16x16x32_bf16 v[16:19], v[172:175], v[196:199], v[16:19]
	v_mfma_f32_16x16x32_bf16 v[4:7], v[164:167], v[204:207], v[4:7]
	v_mfma_f32_16x16x32_bf16 v[0:3], v[172:175], v[204:207], v[0:3]
	v_mfma_f32_16x16x32_bf16 v[52:55], v[168:171], v[184:187], v[52:55]
	v_mfma_f32_16x16x32_bf16 v[48:51], v[176:179], v[184:187], v[48:51]
	v_mfma_f32_16x16x32_bf16 v[36:39], v[168:171], v[192:195], v[36:39]
	v_mfma_f32_16x16x32_bf16 v[32:35], v[176:179], v[192:195], v[32:35]
	v_mfma_f32_16x16x32_bf16 v[20:23], v[168:171], v[200:203], v[20:23]
	v_mfma_f32_16x16x32_bf16 v[16:19], v[176:179], v[200:203], v[16:19]
	v_mfma_f32_16x16x32_bf16 v[4:7], v[168:171], v[208:211], v[4:7]
	v_mfma_f32_16x16x32_bf16 v[0:3], v[176:179], v[208:211], v[0:3]
	s_barrier
	s_add_i32 s55, 0, 0x18000
	v_add_u32_e32 v151, s55, v145
	s_add_i32 s56, 0, 0x1c000
	ds_read_b128 v[140:143], v151
	ds_read_b128 v[152:155], v151 offset:1024
	ds_read_b128 v[156:159], v151 offset:2048
	ds_read_b128 v[160:163], v151 offset:3072
	v_add_u32_e32 v151, s56, v145
	ds_read_b128 v[164:167], v151
	ds_read_b128 v[168:171], v151 offset:1024
	ds_read_b128 v[172:175], v151 offset:2048
	ds_read_b128 v[176:179], v151 offset:3072
	s_add_u32 s24, s30, 0xb0000
	s_addc_u32 s25, s31, 0
	s_mov_b32 m0, s39
	v_lshl_add_u64 v[220:221], s[24:25], 0, v[128:129]
	ds_read_b128 v[180:183], v149 offset:32768
	ds_read_b128 v[184:187], v149 offset:33792
	ds_read_b128 v[188:191], v149 offset:34816
	ds_read_b128 v[192:195], v149 offset:35840
	ds_read_b128 v[196:199], v149 offset:36864
	ds_read_b128 v[200:203], v149 offset:37888
	ds_read_b128 v[204:207], v149 offset:38912
	ds_read_b128 v[208:211], v149 offset:39936
	global_load_lds_dwordx4 v[220:221], off
	v_lshl_add_u64 v[220:221], s[24:25], 0, v[130:131]
	s_mov_b32 m0, s40
	s_nop 0
	global_load_lds_dwordx4 v[220:221], off
	s_waitcnt vmcnt(8)
	s_waitcnt lgkmcnt(0)
	s_barrier
	s_waitcnt lgkmcnt(0)
	v_mfma_f32_16x16x32_bf16 v[124:127], v[140:143], v[180:183], v[124:127]
	v_mfma_f32_16x16x32_bf16 v[120:123], v[156:159], v[180:183], v[120:123]
	v_mfma_f32_16x16x32_bf16 v[108:111], v[140:143], v[188:191], v[108:111]
	v_mfma_f32_16x16x32_bf16 v[104:107], v[156:159], v[188:191], v[104:107]
	v_mfma_f32_16x16x32_bf16 v[92:95], v[140:143], v[196:199], v[92:95]
	v_mfma_f32_16x16x32_bf16 v[88:91], v[156:159], v[196:199], v[88:91]
	v_mfma_f32_16x16x32_bf16 v[76:79], v[140:143], v[204:207], v[76:79]
	v_mfma_f32_16x16x32_bf16 v[72:75], v[156:159], v[204:207], v[72:75]
	v_mfma_f32_16x16x32_bf16 v[124:127], v[152:155], v[184:187], v[124:127]
	v_mfma_f32_16x16x32_bf16 v[120:123], v[160:163], v[184:187], v[120:123]
	v_mfma_f32_16x16x32_bf16 v[108:111], v[152:155], v[192:195], v[108:111]
	v_mfma_f32_16x16x32_bf16 v[104:107], v[160:163], v[192:195], v[104:107]
	v_mfma_f32_16x16x32_bf16 v[92:95], v[152:155], v[200:203], v[92:95]
	v_mfma_f32_16x16x32_bf16 v[88:91], v[160:163], v[200:203], v[88:91]
	v_mfma_f32_16x16x32_bf16 v[76:79], v[152:155], v[208:211], v[76:79]
	v_mfma_f32_16x16x32_bf16 v[72:75], v[160:163], v[208:211], v[72:75]
	v_mfma_f32_16x16x32_bf16 v[116:119], v[164:167], v[180:183], v[116:119]
	v_mfma_f32_16x16x32_bf16 v[112:115], v[172:175], v[180:183], v[112:115]
	v_mfma_f32_16x16x32_bf16 v[100:103], v[164:167], v[188:191], v[100:103]
	v_mfma_f32_16x16x32_bf16 v[96:99], v[172:175], v[188:191], v[96:99]
	v_mfma_f32_16x16x32_bf16 v[84:87], v[164:167], v[196:199], v[84:87]
	v_mfma_f32_16x16x32_bf16 v[80:83], v[172:175], v[196:199], v[80:83]
	v_mfma_f32_16x16x32_bf16 v[68:71], v[164:167], v[204:207], v[68:71]
	v_mfma_f32_16x16x32_bf16 v[64:67], v[172:175], v[204:207], v[64:67]
	v_mfma_f32_16x16x32_bf16 v[116:119], v[168:171], v[184:187], v[116:119]
	v_mfma_f32_16x16x32_bf16 v[112:115], v[176:179], v[184:187], v[112:115]
	v_mfma_f32_16x16x32_bf16 v[100:103], v[168:171], v[192:195], v[100:103]
	v_mfma_f32_16x16x32_bf16 v[96:99], v[176:179], v[192:195], v[96:99]
	v_mfma_f32_16x16x32_bf16 v[84:87], v[168:171], v[200:203], v[84:87]
	v_mfma_f32_16x16x32_bf16 v[80:83], v[176:179], v[200:203], v[80:83]
	v_mfma_f32_16x16x32_bf16 v[68:71], v[168:171], v[208:211], v[68:71]
	v_mfma_f32_16x16x32_bf16 v[64:67], v[176:179], v[208:211], v[64:67]
	s_barrier
	s_add_i32 s24, s55, s36
	v_lshl_add_u64 v[212:213], v[212:213], 0, s[18:19]
	s_mov_b32 m0, s24
	ds_read_b128 v[180:183], v149 offset:49152
	ds_read_b128 v[184:187], v149 offset:50176
	ds_read_b128 v[188:191], v149 offset:51200
	ds_read_b128 v[192:195], v149 offset:52224
	ds_read_b128 v[196:199], v149 offset:53248
	ds_read_b128 v[200:203], v149 offset:54272
	ds_read_b128 v[204:207], v149 offset:55296
	ds_read_b128 v[208:211], v149 offset:56320
	global_load_lds_dwordx4 v[212:213], off
	s_add_i32 m0, s24, 0x2000
	s_add_u32 s24, s28, 0xb0080
	v_lshl_add_u64 v[212:213], v[214:215], 0, s[18:19]
	s_addc_u32 s25, s29, 0
	s_add_i32 s28, s56, s36
	global_load_lds_dwordx4 v[212:213], off
	v_lshl_add_u64 v[212:213], s[24:25], 0, v[128:129]
	s_mov_b32 m0, s28
	s_nop 0
	global_load_lds_dwordx4 v[212:213], off
	s_add_i32 m0, s28, 0x2000
	s_nop 0
	global_load_lds_dwordx4 v130, s[24:25]
	v_lshl_add_u64 v[212:213], v[216:217], 0, s[18:19]
	s_mov_b32 m0, s42
	s_nop 0
	global_load_lds_dwordx4 v[212:213], off
	v_lshl_add_u64 v[212:213], v[218:219], 0, s[18:19]
	s_mov_b32 m0, s43
	s_nop 0
	global_load_lds_dwordx4 v[212:213], off
	s_waitcnt vmcnt(8)
	s_waitcnt lgkmcnt(0)
	s_barrier
	s_waitcnt lgkmcnt(0)
	v_mfma_f32_16x16x32_bf16 v[60:63], v[140:143], v[180:183], v[60:63]
	v_mfma_f32_16x16x32_bf16 v[56:59], v[156:159], v[180:183], v[56:59]
	v_mfma_f32_16x16x32_bf16 v[44:47], v[140:143], v[188:191], v[44:47]
	v_mfma_f32_16x16x32_bf16 v[40:43], v[156:159], v[188:191], v[40:43]
	v_mfma_f32_16x16x32_bf16 v[28:31], v[140:143], v[196:199], v[28:31]
	v_mfma_f32_16x16x32_bf16 v[24:27], v[156:159], v[196:199], v[24:27]
	v_mfma_f32_16x16x32_bf16 v[12:15], v[140:143], v[204:207], v[12:15]
	v_mfma_f32_16x16x32_bf16 v[8:11], v[156:159], v[204:207], v[8:11]
	v_mfma_f32_16x16x32_bf16 v[60:63], v[152:155], v[184:187], v[60:63]
	v_mfma_f32_16x16x32_bf16 v[56:59], v[160:163], v[184:187], v[56:59]
	v_mfma_f32_16x16x32_bf16 v[44:47], v[152:155], v[192:195], v[44:47]
	v_mfma_f32_16x16x32_bf16 v[40:43], v[160:163], v[192:195], v[40:43]
	v_mfma_f32_16x16x32_bf16 v[28:31], v[152:155], v[200:203], v[28:31]
	v_mfma_f32_16x16x32_bf16 v[24:27], v[160:163], v[200:203], v[24:27]
	v_mfma_f32_16x16x32_bf16 v[12:15], v[152:155], v[208:211], v[12:15]
	v_mfma_f32_16x16x32_bf16 v[8:11], v[160:163], v[208:211], v[8:11]
	v_mfma_f32_16x16x32_bf16 v[52:55], v[164:167], v[180:183], v[52:55]
	v_mfma_f32_16x16x32_bf16 v[48:51], v[172:175], v[180:183], v[48:51]
	v_mfma_f32_16x16x32_bf16 v[36:39], v[164:167], v[188:191], v[36:39]
	v_mfma_f32_16x16x32_bf16 v[32:35], v[172:175], v[188:191], v[32:35]
	v_mfma_f32_16x16x32_bf16 v[20:23], v[164:167], v[196:199], v[20:23]
	v_mfma_f32_16x16x32_bf16 v[16:19], v[172:175], v[196:199], v[16:19]
	v_mfma_f32_16x16x32_bf16 v[4:7], v[164:167], v[204:207], v[4:7]
	v_mfma_f32_16x16x32_bf16 v[0:3], v[172:175], v[204:207], v[0:3]
	v_mfma_f32_16x16x32_bf16 v[52:55], v[168:171], v[184:187], v[52:55]
	v_mfma_f32_16x16x32_bf16 v[48:51], v[176:179], v[184:187], v[48:51]
	v_mfma_f32_16x16x32_bf16 v[36:39], v[168:171], v[192:195], v[36:39]
	v_mfma_f32_16x16x32_bf16 v[32:35], v[176:179], v[192:195], v[32:35]
	v_mfma_f32_16x16x32_bf16 v[20:23], v[168:171], v[200:203], v[20:23]
	v_mfma_f32_16x16x32_bf16 v[16:19], v[176:179], v[200:203], v[16:19]
	v_mfma_f32_16x16x32_bf16 v[4:7], v[168:171], v[208:211], v[4:7]
	v_mfma_f32_16x16x32_bf16 v[0:3], v[176:179], v[208:211], v[0:3]
	s_add_i32 s54, s54, 2
	s_add_u32 s52, s52, 0x100
	s_addc_u32 s53, s53, 0
	s_cmp_gt_u32 s54, 41
	s_mov_b64 s[24:25], s[26:27]
	s_barrier
	s_cbranch_scc0 .LBB0_1219
	s_and_b64 vcc, exec, s[20:21]
	s_cbranch_vccz .LBB0_1222
	s_barrier

.LBB0_1247:
	v_ashrrev_i32_e32 v2, 31, v0
	v_lshrrev_b32_e32 v2, 26, v2
	s_waitcnt lgkmcnt(0)
	v_lshlrev_b32_e32 v1, 4, v0
	v_add_u32_e32 v2, v0, v2
	v_bfe_i32 v0, v0, 27, 1
	v_lshrrev_b32_e32 v0, 22, v0
	v_add_u32_e32 v0, v1, v0
	v_and_b32_e32 v0, 0xfffffc00, v0
	v_sub_u32_e32 v0, v1, v0
	v_lshrrev_b32_e32 v3, 4, v0
	v_bitop3_b32 v0, v3, v0, 32 bitop3:0x6c
	v_ashrrev_i32_e32 v4, 31, v0
	v_ashrrev_i32_e32 v2, 6, v2
	v_lshrrev_b32_e32 v4, 26, v4
	v_lshlrev_b32_e32 v3, 3, v2
	v_add_u32_e32 v4, v0, v4
	v_and_b32_e32 v3, -16, v3
	v_ashrrev_i32_e32 v5, 6, v4
	v_and_b32_e32 v4, 0xc0, v4
	v_add_u32_e32 v3, v5, v3
	v_sub_u32_e32 v0, v0, v4
	v_mov_b32_e32 v4, 1
	s_ashr_i32 s4, s7, 3
	v_lshlrev_b32_e32 v2, 5, v2
	v_ashrrev_i16_sdwa v0, v4, sext(v0) dst_sel:DWORD dst_unused:UNUSED_PAD src0_sel:DWORD src1_sel:BYTE_0
	v_lshlrev_b32_e32 v6, 1, v3
	v_lshrrev_b32_e32 v7, 2, v3
	v_and_b32_e32 v5, 3, v5
	s_mov_b32 s7, 0x7fffe0
	v_and_b32_e32 v2, 32, v2
	v_bfe_i32 v0, v0, 0, 16
	v_and_b32_e32 v6, 24, v6
	v_and_b32_e32 v7, 4, v7
	v_and_or_b32 v5, v3, s7, v5
	v_or3_b32 v5, v5, v7, v6
	v_add_lshl_u32 v0, v2, v0, 1
	v_lshl_add_u32 v128, v3, 9, v0
	v_lshl_add_u32 v130, v5, 9, v0
	v_add_u32_e32 v0, 0x2000, v1
	v_ashrrev_i32_e32 v1, 31, v0
	v_lshrrev_b32_e32 v1, 22, v1
	v_add_u32_e32 v1, v0, v1
	v_ashrrev_i32_e32 v1, 10, v1
	v_mul_i32_i24_e32 v2, 0x400, v1
	v_sub_u32_e32 v0, v0, v2
	v_lshrrev_b32_e32 v2, 4, v0
	v_bitop3_b32 v0, v2, v0, 32 bitop3:0x6c
	s_add_u32 s42, s70, 0x5500000
	v_ashrrev_i32_e32 v3, 31, v0
	s_addc_u32 s43, s71, 0
	v_lshrrev_b32_e32 v3, 26, v3
	s_add_i32 s4, s6, s4
	v_lshlrev_b32_e32 v2, 3, v1
	v_add_u32_e32 v3, v0, v3
	s_ashr_i32 s6, s4, 31
	v_and_b32_e32 v2, -16, v2
	v_ashrrev_i32_e32 v5, 6, v3
	s_lshr_b32 s6, s6, 27
	v_add_u32_e32 v2, v5, v2
	v_and_b32_e32 v5, 3, v5
	s_add_i32 s6, s4, s6
	v_and_or_b32 v5, v2, s7, v5
	s_ashr_i32 s7, s6, 5
	s_andn2_b32 s6, s6, 31
	s_sub_i32 s6, s4, s6
	s_bfe_i32 s4, s6, 0x80000
	s_bfe_u32 s4, s4, 0x3000c
	s_add_i32 s8, s6, s4
	s_bfe_i32 s4, s8, 0x80000
	s_and_b32 s8, s8, 0xf8
	s_sub_i32 s6, s6, s8
	s_lshl_b32 s7, s7, 3
	s_sext_i32_i16 s4, s4
	s_sext_i32_i8 s6, s6
	s_ashr_i32 s5, s14, 8
	s_lshr_b32 s4, s4, 3
	s_add_i32 s30, s7, s6
	s_ashr_i32 s12, s14, 6
	s_ashr_i32 s31, s30, 31
	s_bfe_i64 s[8:9], s[4:5], 0x100000
	v_and_b32_e32 v3, 0xc0, v3
	s_lshl_b32 s44, s12, 10
	s_lshl_b64 s[6:7], s[30:31], 17
	s_lshl_b64 s[8:9], s[8:9], 17
	v_sub_u32_e32 v0, v0, v3
	s_add_u32 s36, s42, s8
	v_lshlrev_b32_e32 v1, 5, v1
	v_ashrrev_i16_sdwa v0, v4, sext(v0) dst_sel:DWORD dst_unused:UNUSED_PAD src0_sel:DWORD src1_sel:BYTE_0
	v_lshlrev_b32_e32 v3, 1, v2
	v_lshrrev_b32_e32 v4, 2, v2
	s_addc_u32 s37, s43, s9
	s_add_i32 s31, s44, 0
	v_and_b32_e32 v1, 32, v1
	v_bfe_i32 v0, v0, 0, 16
	v_and_b32_e32 v3, 24, v3
	v_and_b32_e32 v4, 4, v4
	s_add_i32 m0, s31, 0x10000
	v_or3_b32 v3, v5, v4, v3
	v_add_lshl_u32 v0, v1, v0, 1
	global_load_lds_dwordx4 v130, s[36:37]
	s_add_i32 m0, s31, 0x12000
	v_lshl_add_u32 v134, v3, 9, v0
	s_add_u32 s8, s36, 0x10000
	global_load_lds_dwordx4 v134, s[36:37]
	s_addc_u32 s9, s37, 0
	s_add_i32 m0, s31, 0x14000
	v_lshl_add_u32 v132, v2, 9, v0
	global_load_lds_dwordx4 v130, s[8:9]
	s_add_i32 m0, s31, 0x16000
	s_add_u32 s34, s48, s6
	s_addc_u32 s35, s49, s7
	s_add_i32 s45, s31, 0x2000
	global_load_lds_dwordx4 v134, s[8:9]
	s_mov_b32 m0, s31
	s_add_u32 s6, s34, 0x10000
	global_load_lds_dwordx4 v128, s[34:35]
	s_mov_b32 m0, s45
	s_addc_u32 s7, s35, 0
	s_add_i32 s46, s31, 0x4000
	global_load_lds_dwordx4 v132, s[34:35]
	s_mov_b32 m0, s46
	s_add_i32 s47, s31, 0x6000
	global_load_lds_dwordx4 v128, s[6:7]
	s_mov_b32 m0, s47
	v_mov_b32_e32 v131, 0
	global_load_lds_dwordx4 v132, s[6:7]
	v_mov_b32_e32 v135, v131
	v_mov_b32_e32 v129, v131
	v_mov_b32_e32 v133, v131
	s_cmp_eq_u32 s5, 1
	v_lshl_add_u64 v[6:7], s[36:37], 0, v[130:131]
	v_lshl_add_u64 v[4:5], s[36:37], 0, v[134:135]
	v_lshl_add_u64 v[0:1], s[34:35], 0, v[128:129]
	s_cselect_b64 s[6:7], -1, 0
	s_cmp_lg_u32 s5, 1
	v_lshl_add_u64 v[2:3], s[34:35], 0, v[132:133]
	s_setprio 1
	s_cbranch_scc1 .LBB0_1249
	s_barrier
	s_setprio 0

.LBB0_1258:
	ds_read_b128 v[0:3], v147
	ds_read_b128 v[4:7], v147 offset:1024
	ds_read_b128 v[8:11], v147 offset:2048
	ds_read_b128 v[12:15], v147 offset:3072
	ds_read_b128 v[16:19], v148
	ds_read_b128 v[20:23], v148 offset:1024
	ds_read_b128 v[24:27], v148 offset:2048
	ds_read_b128 v[28:31], v148 offset:3072
	s_ashr_i32 s25, s24, 31
	s_lshl_b64 s[26:27], s[24:25], 17
	s_add_u32 s26, s48, s26
	s_addc_u32 s27, s49, s27
	s_and_b64 s[28:29], s[4:5], exec
	s_cselect_b32 s41, s27, s35
	s_cselect_b32 s40, s26, s34
	s_ashr_i32 s23, s22, 31
	s_lshl_b64 s[28:29], s[22:23], 17
	s_add_u32 s28, s42, s28
	s_addc_u32 s29, s43, s29
	s_and_b64 s[38:39], s[4:5], exec
	s_cselect_b32 s39, s29, s37
	s_cselect_b32 s38, s28, s36
	s_add_u32 s58, s34, 0x10080
	s_addc_u32 s59, s35, 0
	s_mov_b32 m0, s55
	ds_read_b128 v[32:35], v149
	ds_read_b128 v[36:39], v149 offset:1024
	ds_read_b128 v[40:43], v149 offset:2048
	ds_read_b128 v[44:47], v149 offset:3072
	ds_read_b128 v[48:51], v149 offset:4096
	ds_read_b128 v[52:55], v149 offset:5120
	ds_read_b128 v[56:59], v149 offset:6144
	ds_read_b128 v[60:63], v149 offset:7168
	global_load_lds_dwordx4 v128, s[58:59]
	s_mov_b32 m0, s56
	s_nop 0
	global_load_lds_dwordx4 v132, s[58:59]
	s_waitcnt vmcnt(8)
	s_waitcnt lgkmcnt(0)
	s_barrier
	s_waitcnt lgkmcnt(0)
	v_mfma_f32_16x16x32_bf16 v[64:67], v[0:3], v[32:35], 0
	v_mfma_f32_16x16x32_bf16 v[68:71], v[8:11], v[32:35], 0
	v_mfma_f32_16x16x32_bf16 v[72:75], v[0:3], v[40:43], 0
	v_mfma_f32_16x16x32_bf16 v[76:79], v[8:11], v[40:43], 0
	v_mfma_f32_16x16x32_bf16 v[80:83], v[0:3], v[48:51], 0
	v_mfma_f32_16x16x32_bf16 v[84:87], v[8:11], v[48:51], 0
	v_mfma_f32_16x16x32_bf16 v[88:91], v[0:3], v[56:59], 0
	v_mfma_f32_16x16x32_bf16 v[92:95], v[8:11], v[56:59], 0
	v_mfma_f32_16x16x32_bf16 v[64:67], v[4:7], v[36:39], v[64:67]
	v_mfma_f32_16x16x32_bf16 v[68:71], v[12:15], v[36:39], v[68:71]
	v_mfma_f32_16x16x32_bf16 v[72:75], v[4:7], v[44:47], v[72:75]
	v_mfma_f32_16x16x32_bf16 v[76:79], v[12:15], v[44:47], v[76:79]
	v_mfma_f32_16x16x32_bf16 v[80:83], v[4:7], v[52:55], v[80:83]
	v_mfma_f32_16x16x32_bf16 v[84:87], v[12:15], v[52:55], v[84:87]
	v_mfma_f32_16x16x32_bf16 v[88:91], v[4:7], v[60:63], v[88:91]
	v_mfma_f32_16x16x32_bf16 v[92:95], v[12:15], v[60:63], v[92:95]
	v_mfma_f32_16x16x32_bf16 v[96:99], v[16:19], v[32:35], 0
	v_mfma_f32_16x16x32_bf16 v[32:35], v[24:27], v[32:35], 0
	v_mfma_f32_16x16x32_bf16 v[96:99], v[20:23], v[36:39], v[96:99]
	v_mfma_f32_16x16x32_bf16 v[32:35], v[28:31], v[36:39], v[32:35]
	v_mfma_f32_16x16x32_bf16 v[36:39], v[16:19], v[40:43], 0
	v_mfma_f32_16x16x32_bf16 v[40:43], v[24:27], v[40:43], 0
	v_mfma_f32_16x16x32_bf16 v[36:39], v[20:23], v[44:47], v[36:39]
	v_mfma_f32_16x16x32_bf16 v[40:43], v[28:31], v[44:47], v[40:43]
	v_mfma_f32_16x16x32_bf16 v[44:47], v[16:19], v[48:51], 0
	v_mfma_f32_16x16x32_bf16 v[48:51], v[24:27], v[48:51], 0
	v_mfma_f32_16x16x32_bf16 v[44:47], v[20:23], v[52:55], v[44:47]
	v_mfma_f32_16x16x32_bf16 v[48:51], v[28:31], v[52:55], v[48:51]
	v_mfma_f32_16x16x32_bf16 v[52:55], v[16:19], v[56:59], 0
	v_mfma_f32_16x16x32_bf16 v[56:59], v[24:27], v[56:59], 0
	v_mfma_f32_16x16x32_bf16 v[52:55], v[20:23], v[60:63], v[52:55]
	v_mfma_f32_16x16x32_bf16 v[56:59], v[28:31], v[60:63], v[56:59]
	s_barrier
	s_add_i32 s59, s53, s44
	v_lshl_add_u64 v[212:213], s[36:37], 0, v[130:131]
	s_add_i32 s23, s59, 0x2000
	v_lshl_add_u64 v[140:141], v[212:213], 0, s[18:19]
	s_mov_b32 m0, s59
	v_lshl_add_u64 v[214:215], s[36:37], 0, v[134:135]
	s_add_u32 s60, s36, 0x10100
	ds_read_b128 v[60:63], v149 offset:16384
	ds_read_b128 v[100:103], v149 offset:17408
	ds_read_b128 v[104:107], v149 offset:18432
	ds_read_b128 v[108:111], v149 offset:19456
	ds_read_b128 v[112:115], v149 offset:20480
	ds_read_b128 v[116:119], v149 offset:21504
	ds_read_b128 v[120:123], v149 offset:22528
	ds_read_b128 v[124:127], v149 offset:23552
	global_load_lds_dwordx4 v[140:141], off
	v_lshl_add_u64 v[140:141], v[214:215], 0, s[18:19]
	s_mov_b32 m0, s23
	s_addc_u32 s61, s37, 0
	s_add_i32 s25, s54, s44
	global_load_lds_dwordx4 v[140:141], off
	v_lshl_add_u64 v[140:141], s[60:61], 0, v[130:131]
	s_mov_b32 m0, s25
	s_add_i32 s58, s25, 0x2000
	global_load_lds_dwordx4 v[140:141], off
	s_mov_b32 m0, s58
	v_lshl_add_u64 v[216:217], s[34:35], 0, v[128:129]
	global_load_lds_dwordx4 v134, s[60:61]
	v_lshl_add_u64 v[140:141], v[216:217], 0, s[18:19]
	s_mov_b32 m0, s31
	v_lshl_add_u64 v[218:219], s[34:35], 0, v[132:133]
	global_load_lds_dwordx4 v[140:141], off
	v_lshl_add_u64 v[140:141], v[218:219], 0, s[18:19]
	s_mov_b32 m0, s45
	s_nop 0
	global_load_lds_dwordx4 v[140:141], off
	s_waitcnt vmcnt(8)
	s_waitcnt lgkmcnt(0)
	s_barrier
	s_waitcnt lgkmcnt(0)
	v_mfma_f32_16x16x32_bf16 v[140:143], v[0:3], v[60:63], 0
	v_mfma_f32_16x16x32_bf16 v[156:159], v[0:3], v[104:107], 0
	v_mfma_f32_16x16x32_bf16 v[164:167], v[0:3], v[112:115], 0
	v_mfma_f32_16x16x32_bf16 v[0:3], v[0:3], v[120:123], 0
	v_mfma_f32_16x16x32_bf16 v[140:143], v[4:7], v[100:103], v[140:143]
	v_mfma_f32_16x16x32_bf16 v[156:159], v[4:7], v[108:111], v[156:159]
	v_mfma_f32_16x16x32_bf16 v[164:167], v[4:7], v[116:119], v[164:167]
	v_mfma_f32_16x16x32_bf16 v[0:3], v[4:7], v[124:127], v[0:3]
	v_mfma_f32_16x16x32_bf16 v[4:7], v[8:11], v[120:123], 0
	v_mfma_f32_16x16x32_bf16 v[152:155], v[8:11], v[60:63], 0
	v_mfma_f32_16x16x32_bf16 v[160:163], v[8:11], v[104:107], 0
	v_mfma_f32_16x16x32_bf16 v[168:171], v[8:11], v[112:115], 0
	v_mfma_f32_16x16x32_bf16 v[4:7], v[12:15], v[124:127], v[4:7]
	v_mfma_f32_16x16x32_bf16 v[152:155], v[12:15], v[100:103], v[152:155]
	v_mfma_f32_16x16x32_bf16 v[160:163], v[12:15], v[108:111], v[160:163]
	v_mfma_f32_16x16x32_bf16 v[168:171], v[12:15], v[116:119], v[168:171]
	v_mfma_f32_16x16x32_bf16 v[8:11], v[16:19], v[60:63], 0
	v_mfma_f32_16x16x32_bf16 v[12:15], v[24:27], v[60:63], 0
	v_mfma_f32_16x16x32_bf16 v[8:11], v[20:23], v[100:103], v[8:11]
	v_mfma_f32_16x16x32_bf16 v[12:15], v[28:31], v[100:103], v[12:15]
	v_mfma_f32_16x16x32_bf16 v[60:63], v[16:19], v[104:107], 0
	v_mfma_f32_16x16x32_bf16 v[100:103], v[24:27], v[104:107], 0
	v_mfma_f32_16x16x32_bf16 v[104:107], v[16:19], v[112:115], 0
	v_mfma_f32_16x16x32_bf16 v[16:19], v[16:19], v[120:123], 0
	v_mfma_f32_16x16x32_bf16 v[60:63], v[20:23], v[108:111], v[60:63]
	v_mfma_f32_16x16x32_bf16 v[100:103], v[28:31], v[108:111], v[100:103]
	v_mfma_f32_16x16x32_bf16 v[104:107], v[20:23], v[116:119], v[104:107]
	v_mfma_f32_16x16x32_bf16 v[108:111], v[24:27], v[112:115], 0
	v_mfma_f32_16x16x32_bf16 v[16:19], v[20:23], v[124:127], v[16:19]
	v_mfma_f32_16x16x32_bf16 v[20:23], v[24:27], v[120:123], 0
	v_mfma_f32_16x16x32_bf16 v[108:111], v[28:31], v[116:119], v[108:111]
	v_mfma_f32_16x16x32_bf16 v[20:23], v[28:31], v[124:127], v[20:23]
	s_barrier
	s_add_i32 s62, 0, 0x18000
	s_add_i32 s64, 0, 0x1c000
	v_add_u32_e32 v151, s62, v145
	v_add_u32_e32 v222, s64, v145
	ds_read_b128 v[24:27], v151
	ds_read_b128 v[28:31], v151 offset:1024
	ds_read_b128 v[112:115], v151 offset:2048
	ds_read_b128 v[116:119], v151 offset:3072
	ds_read_b128 v[120:123], v222
	ds_read_b128 v[124:127], v222 offset:1024
	ds_read_b128 v[172:175], v222 offset:2048
	ds_read_b128 v[176:179], v222 offset:3072
	s_add_u32 s60, s34, 0x10100
	s_addc_u32 s61, s35, 0
	s_mov_b32 m0, s46
	ds_read_b128 v[180:183], v149 offset:32768
	ds_read_b128 v[184:187], v149 offset:33792
	ds_read_b128 v[188:191], v149 offset:34816
	ds_read_b128 v[192:195], v149 offset:35840
	ds_read_b128 v[196:199], v149 offset:36864
	ds_read_b128 v[200:203], v149 offset:37888
	ds_read_b128 v[204:207], v149 offset:38912
	ds_read_b128 v[208:211], v149 offset:39936
	global_load_lds_dwordx4 v128, s[60:61]
	s_mov_b32 m0, s47
	s_nop 0
	global_load_lds_dwordx4 v132, s[60:61]
	s_waitcnt vmcnt(8)
	s_waitcnt lgkmcnt(0)
	s_barrier
	s_waitcnt lgkmcnt(0)
	v_mfma_f32_16x16x32_bf16 v[64:67], v[24:27], v[180:183], v[64:67]
	v_mfma_f32_16x16x32_bf16 v[68:71], v[112:115], v[180:183], v[68:71]
	v_mfma_f32_16x16x32_bf16 v[72:75], v[24:27], v[188:191], v[72:75]
	v_mfma_f32_16x16x32_bf16 v[76:79], v[112:115], v[188:191], v[76:79]
	v_mfma_f32_16x16x32_bf16 v[80:83], v[24:27], v[196:199], v[80:83]
	v_mfma_f32_16x16x32_bf16 v[84:87], v[112:115], v[196:199], v[84:87]
	v_mfma_f32_16x16x32_bf16 v[88:91], v[24:27], v[204:207], v[88:91]
	v_mfma_f32_16x16x32_bf16 v[92:95], v[112:115], v[204:207], v[92:95]
	v_mfma_f32_16x16x32_bf16 v[64:67], v[28:31], v[184:187], v[64:67]
	v_mfma_f32_16x16x32_bf16 v[68:71], v[116:119], v[184:187], v[68:71]
	v_mfma_f32_16x16x32_bf16 v[72:75], v[28:31], v[192:195], v[72:75]
	v_mfma_f32_16x16x32_bf16 v[76:79], v[116:119], v[192:195], v[76:79]
	v_mfma_f32_16x16x32_bf16 v[80:83], v[28:31], v[200:203], v[80:83]
	v_mfma_f32_16x16x32_bf16 v[84:87], v[116:119], v[200:203], v[84:87]
	v_mfma_f32_16x16x32_bf16 v[88:91], v[28:31], v[208:211], v[88:91]
	v_mfma_f32_16x16x32_bf16 v[92:95], v[116:119], v[208:211], v[92:95]
	v_mfma_f32_16x16x32_bf16 v[96:99], v[120:123], v[180:183], v[96:99]
	v_mfma_f32_16x16x32_bf16 v[32:35], v[172:175], v[180:183], v[32:35]
	v_mfma_f32_16x16x32_bf16 v[36:39], v[120:123], v[188:191], v[36:39]
	v_mfma_f32_16x16x32_bf16 v[40:43], v[172:175], v[188:191], v[40:43]
	v_mfma_f32_16x16x32_bf16 v[44:47], v[120:123], v[196:199], v[44:47]
	v_mfma_f32_16x16x32_bf16 v[48:51], v[172:175], v[196:199], v[48:51]
	v_mfma_f32_16x16x32_bf16 v[52:55], v[120:123], v[204:207], v[52:55]
	v_mfma_f32_16x16x32_bf16 v[56:59], v[172:175], v[204:207], v[56:59]
	v_mfma_f32_16x16x32_bf16 v[96:99], v[124:127], v[184:187], v[96:99]
	v_mfma_f32_16x16x32_bf16 v[32:35], v[176:179], v[184:187], v[32:35]
	v_mfma_f32_16x16x32_bf16 v[36:39], v[124:127], v[192:195], v[36:39]
	v_mfma_f32_16x16x32_bf16 v[40:43], v[176:179], v[192:195], v[40:43]
	v_mfma_f32_16x16x32_bf16 v[44:47], v[124:127], v[200:203], v[44:47]
	v_mfma_f32_16x16x32_bf16 v[48:51], v[176:179], v[200:203], v[48:51]
	v_mfma_f32_16x16x32_bf16 v[52:55], v[124:127], v[208:211], v[52:55]
	v_mfma_f32_16x16x32_bf16 v[56:59], v[176:179], v[208:211], v[56:59]
	s_barrier
	s_add_i32 s61, s62, s44
	s_add_i32 s60, s61, 0x2000
	v_lshl_add_u64 v[212:213], v[212:213], 0, s[20:21]
	s_mov_b32 m0, s61
	s_add_u32 s62, s36, 0x10180
	ds_read_b128 v[180:183], v149 offset:49152
	ds_read_b128 v[184:187], v149 offset:50176
	ds_read_b128 v[188:191], v149 offset:51200
	ds_read_b128 v[192:195], v149 offset:52224
	ds_read_b128 v[196:199], v149 offset:53248
	ds_read_b128 v[200:203], v149 offset:54272
	ds_read_b128 v[204:207], v149 offset:55296
	ds_read_b128 v[208:211], v149 offset:56320
	global_load_lds_dwordx4 v[212:213], off
	v_lshl_add_u64 v[212:213], v[214:215], 0, s[20:21]
	s_mov_b32 m0, s60
	s_addc_u32 s63, s37, 0
	s_add_i32 s36, s64, s44
	global_load_lds_dwordx4 v[212:213], off
	v_lshl_add_u64 v[212:213], s[62:63], 0, v[130:131]
	s_mov_b32 m0, s36
	s_add_i32 s37, s36, 0x2000
	global_load_lds_dwordx4 v[212:213], off
	s_mov_b32 m0, s37
	s_nop 0
	global_load_lds_dwordx4 v134, s[62:63]
	v_lshl_add_u64 v[212:213], v[216:217], 0, s[20:21]
	s_mov_b32 m0, s50
	s_nop 0
	global_load_lds_dwordx4 v[212:213], off
	v_lshl_add_u64 v[212:213], v[218:219], 0, s[20:21]
	s_mov_b32 m0, s51
	s_nop 0
	global_load_lds_dwordx4 v[212:213], off
	s_waitcnt vmcnt(8)
	s_waitcnt lgkmcnt(0)
	s_barrier
	s_waitcnt lgkmcnt(0)
	v_mfma_f32_16x16x32_bf16 v[0:3], v[24:27], v[204:207], v[0:3]
	v_mfma_f32_16x16x32_bf16 v[4:7], v[112:115], v[204:207], v[4:7]
	v_mfma_f32_16x16x32_bf16 v[140:143], v[24:27], v[180:183], v[140:143]
	v_mfma_f32_16x16x32_bf16 v[152:155], v[112:115], v[180:183], v[152:155]
	v_mfma_f32_16x16x32_bf16 v[156:159], v[24:27], v[188:191], v[156:159]
	v_mfma_f32_16x16x32_bf16 v[160:163], v[112:115], v[188:191], v[160:163]
	v_mfma_f32_16x16x32_bf16 v[164:167], v[24:27], v[196:199], v[164:167]
	v_mfma_f32_16x16x32_bf16 v[168:171], v[112:115], v[196:199], v[168:171]
	v_mfma_f32_16x16x32_bf16 v[0:3], v[28:31], v[208:211], v[0:3]
	v_mfma_f32_16x16x32_bf16 v[4:7], v[116:119], v[208:211], v[4:7]
	v_mfma_f32_16x16x32_bf16 v[140:143], v[28:31], v[184:187], v[140:143]
	v_mfma_f32_16x16x32_bf16 v[152:155], v[116:119], v[184:187], v[152:155]
	v_mfma_f32_16x16x32_bf16 v[156:159], v[28:31], v[192:195], v[156:159]
	v_mfma_f32_16x16x32_bf16 v[160:163], v[116:119], v[192:195], v[160:163]
	v_mfma_f32_16x16x32_bf16 v[164:167], v[28:31], v[200:203], v[164:167]
	v_mfma_f32_16x16x32_bf16 v[168:171], v[116:119], v[200:203], v[168:171]
	v_mfma_f32_16x16x32_bf16 v[8:11], v[120:123], v[180:183], v[8:11]
	v_mfma_f32_16x16x32_bf16 v[12:15], v[172:175], v[180:183], v[12:15]
	v_mfma_f32_16x16x32_bf16 v[24:27], v[120:123], v[188:191], v[60:63]
	v_mfma_f32_16x16x32_bf16 v[28:31], v[172:175], v[188:191], v[100:103]
	v_mfma_f32_16x16x32_bf16 v[60:63], v[120:123], v[196:199], v[104:107]
	v_mfma_f32_16x16x32_bf16 v[100:103], v[172:175], v[196:199], v[108:111]
	v_mfma_f32_16x16x32_bf16 v[16:19], v[120:123], v[204:207], v[16:19]
	v_mfma_f32_16x16x32_bf16 v[20:23], v[172:175], v[204:207], v[20:23]
	v_mfma_f32_16x16x32_bf16 v[8:11], v[124:127], v[184:187], v[8:11]
	v_mfma_f32_16x16x32_bf16 v[12:15], v[176:179], v[184:187], v[12:15]
	v_mfma_f32_16x16x32_bf16 v[24:27], v[124:127], v[192:195], v[24:27]
	v_mfma_f32_16x16x32_bf16 v[28:31], v[176:179], v[192:195], v[28:31]
	v_mfma_f32_16x16x32_bf16 v[60:63], v[124:127], v[200:203], v[60:63]
	v_mfma_f32_16x16x32_bf16 v[100:103], v[176:179], v[200:203], v[100:103]
	v_mfma_f32_16x16x32_bf16 v[16:19], v[124:127], v[208:211], v[16:19]
	v_mfma_f32_16x16x32_bf16 v[20:23], v[176:179], v[208:211], v[20:23]
	s_barrier
	ds_read_b128 v[104:107], v147
	ds_read_b128 v[108:111], v147 offset:1024
	ds_read_b128 v[112:115], v147 offset:2048
	ds_read_b128 v[116:119], v147 offset:3072
	ds_read_b128 v[120:123], v148
	ds_read_b128 v[124:127], v148 offset:1024
	ds_read_b128 v[172:175], v148 offset:2048
	ds_read_b128 v[176:179], v148 offset:3072
	s_add_u32 s34, s34, 0x10180
	s_addc_u32 s35, s35, 0
	s_mov_b32 m0, s55
	ds_read_b128 v[180:183], v149
	ds_read_b128 v[184:187], v149 offset:1024
	ds_read_b128 v[188:191], v149 offset:2048
	ds_read_b128 v[192:195], v149 offset:3072
	ds_read_b128 v[196:199], v149 offset:4096
	ds_read_b128 v[200:203], v149 offset:5120
	ds_read_b128 v[204:207], v149 offset:6144
	ds_read_b128 v[208:211], v149 offset:7168
	global_load_lds_dwordx4 v128, s[34:35]
	s_mov_b32 m0, s56
	s_nop 0
	global_load_lds_dwordx4 v132, s[34:35]
	s_waitcnt vmcnt(8)
	s_waitcnt lgkmcnt(0)
	s_barrier
	s_waitcnt lgkmcnt(0)
	v_mfma_f32_16x16x32_bf16 v[64:67], v[104:107], v[180:183], v[64:67]
	v_mfma_f32_16x16x32_bf16 v[68:71], v[112:115], v[180:183], v[68:71]
	v_mfma_f32_16x16x32_bf16 v[72:75], v[104:107], v[188:191], v[72:75]
	v_mfma_f32_16x16x32_bf16 v[76:79], v[112:115], v[188:191], v[76:79]
	v_mfma_f32_16x16x32_bf16 v[80:83], v[104:107], v[196:199], v[80:83]
	v_mfma_f32_16x16x32_bf16 v[84:87], v[112:115], v[196:199], v[84:87]
	v_mfma_f32_16x16x32_bf16 v[88:91], v[104:107], v[204:207], v[88:91]
	v_mfma_f32_16x16x32_bf16 v[92:95], v[112:115], v[204:207], v[92:95]
	v_mfma_f32_16x16x32_bf16 v[64:67], v[108:111], v[184:187], v[64:67]
	v_mfma_f32_16x16x32_bf16 v[68:71], v[116:119], v[184:187], v[68:71]
	v_mfma_f32_16x16x32_bf16 v[72:75], v[108:111], v[192:195], v[72:75]
	v_mfma_f32_16x16x32_bf16 v[76:79], v[116:119], v[192:195], v[76:79]
	v_mfma_f32_16x16x32_bf16 v[80:83], v[108:111], v[200:203], v[80:83]
	v_mfma_f32_16x16x32_bf16 v[84:87], v[116:119], v[200:203], v[84:87]
	v_mfma_f32_16x16x32_bf16 v[88:91], v[108:111], v[208:211], v[88:91]
	v_mfma_f32_16x16x32_bf16 v[92:95], v[116:119], v[208:211], v[92:95]
	v_mfma_f32_16x16x32_bf16 v[32:35], v[172:175], v[180:183], v[32:35]
	v_mfma_f32_16x16x32_bf16 v[36:39], v[120:123], v[188:191], v[36:39]
	v_mfma_f32_16x16x32_bf16 v[40:43], v[172:175], v[188:191], v[40:43]
	v_mfma_f32_16x16x32_bf16 v[44:47], v[120:123], v[196:199], v[44:47]
	v_mfma_f32_16x16x32_bf16 v[48:51], v[172:175], v[196:199], v[48:51]
	v_mfma_f32_16x16x32_bf16 v[52:55], v[120:123], v[204:207], v[52:55]
	v_mfma_f32_16x16x32_bf16 v[56:59], v[172:175], v[204:207], v[56:59]
	v_mfma_f32_16x16x32_bf16 v[96:99], v[120:123], v[180:183], v[96:99]
	v_mfma_f32_16x16x32_bf16 v[32:35], v[176:179], v[184:187], v[32:35]
	v_mfma_f32_16x16x32_bf16 v[36:39], v[124:127], v[192:195], v[36:39]
	v_mfma_f32_16x16x32_bf16 v[40:43], v[176:179], v[192:195], v[40:43]
	v_mfma_f32_16x16x32_bf16 v[44:47], v[124:127], v[200:203], v[44:47]
	v_mfma_f32_16x16x32_bf16 v[48:51], v[176:179], v[200:203], v[48:51]
	v_mfma_f32_16x16x32_bf16 v[52:55], v[124:127], v[208:211], v[52:55]
	v_mfma_f32_16x16x32_bf16 v[56:59], v[176:179], v[208:211], v[56:59]
	v_mfma_f32_16x16x32_bf16 v[212:215], v[124:127], v[184:187], v[96:99]
	s_barrier
	s_mov_b32 m0, s59
	v_lshl_add_u64 v[240:241], s[38:39], 0, v[130:131]
	s_add_u32 s34, s38, 0x10000
	ds_read_b128 v[96:99], v149 offset:16384
	ds_read_b128 v[180:183], v149 offset:17408
	ds_read_b128 v[184:187], v149 offset:18432
	ds_read_b128 v[188:191], v149 offset:19456
	ds_read_b128 v[192:195], v149 offset:20480
	ds_read_b128 v[196:199], v149 offset:21504
	ds_read_b128 v[200:203], v149 offset:22528
	ds_read_b128 v[204:207], v149 offset:23552
	global_load_lds_dwordx4 v[240:241], off
	v_lshl_add_u64 v[242:243], s[38:39], 0, v[134:135]
	s_mov_b32 m0, s23
	s_addc_u32 s35, s39, 0
	global_load_lds_dwordx4 v[242:243], off
	v_lshl_add_u64 v[208:209], s[34:35], 0, v[130:131]
	s_mov_b32 m0, s25
	v_lshl_add_u64 v[244:245], s[40:41], 0, v[128:129]
	global_load_lds_dwordx4 v[208:209], off
	s_mov_b32 m0, s58
	v_lshl_add_u64 v[246:247], s[40:41], 0, v[132:133]
	global_load_lds_dwordx4 v134, s[34:35]
	s_mov_b32 m0, s31
	s_nop 0
	global_load_lds_dwordx4 v[244:245], off
	s_mov_b32 m0, s45
	s_nop 0
	global_load_lds_dwordx4 v[246:247], off
	s_waitcnt vmcnt(8)
	s_waitcnt lgkmcnt(0)
	s_barrier
	s_waitcnt lgkmcnt(0)
	v_mfma_f32_16x16x32_bf16 v[0:3], v[104:107], v[200:203], v[0:3]
	v_mfma_f32_16x16x32_bf16 v[4:7], v[112:115], v[200:203], v[4:7]
	v_mfma_f32_16x16x32_bf16 v[140:143], v[104:107], v[96:99], v[140:143]
	v_mfma_f32_16x16x32_bf16 v[152:155], v[112:115], v[96:99], v[152:155]
	v_mfma_f32_16x16x32_bf16 v[156:159], v[104:107], v[184:187], v[156:159]
	v_mfma_f32_16x16x32_bf16 v[160:163], v[112:115], v[184:187], v[160:163]
	v_mfma_f32_16x16x32_bf16 v[164:167], v[104:107], v[192:195], v[164:167]
	v_mfma_f32_16x16x32_bf16 v[168:171], v[112:115], v[192:195], v[168:171]
	v_mfma_f32_16x16x32_bf16 v[0:3], v[108:111], v[204:207], v[0:3]
	v_mfma_f32_16x16x32_bf16 v[4:7], v[116:119], v[204:207], v[4:7]
	v_mfma_f32_16x16x32_bf16 v[140:143], v[108:111], v[180:183], v[140:143]
	v_mfma_f32_16x16x32_bf16 v[152:155], v[116:119], v[180:183], v[152:155]
	v_mfma_f32_16x16x32_bf16 v[156:159], v[108:111], v[188:191], v[156:159]
	v_mfma_f32_16x16x32_bf16 v[160:163], v[116:119], v[188:191], v[160:163]
	v_mfma_f32_16x16x32_bf16 v[164:167], v[108:111], v[196:199], v[164:167]
	v_mfma_f32_16x16x32_bf16 v[168:171], v[116:119], v[196:199], v[168:171]
	v_mfma_f32_16x16x32_bf16 v[8:11], v[120:123], v[96:99], v[8:11]
	v_mfma_f32_16x16x32_bf16 v[12:15], v[172:175], v[96:99], v[12:15]
	v_mfma_f32_16x16x32_bf16 v[24:27], v[120:123], v[184:187], v[24:27]
	v_mfma_f32_16x16x32_bf16 v[28:31], v[172:175], v[184:187], v[28:31]
	v_mfma_f32_16x16x32_bf16 v[60:63], v[120:123], v[192:195], v[60:63]
	v_mfma_f32_16x16x32_bf16 v[16:19], v[120:123], v[200:203], v[16:19]
	v_mfma_f32_16x16x32_bf16 v[8:11], v[124:127], v[180:183], v[8:11]
	v_mfma_f32_16x16x32_bf16 v[12:15], v[176:179], v[180:183], v[12:15]
	v_mfma_f32_16x16x32_bf16 v[24:27], v[124:127], v[188:191], v[24:27]
	v_mfma_f32_16x16x32_bf16 v[28:31], v[176:179], v[188:191], v[28:31]
	v_mfma_f32_16x16x32_bf16 v[180:183], v[124:127], v[196:199], v[60:63]
	v_mfma_f32_16x16x32_bf16 v[60:63], v[172:175], v[192:195], v[100:103]
	v_mfma_f32_16x16x32_bf16 v[188:191], v[124:127], v[204:207], v[16:19]
	v_mfma_f32_16x16x32_bf16 v[16:19], v[172:175], v[200:203], v[20:23]
	v_mfma_f32_16x16x32_bf16 v[184:187], v[176:179], v[196:199], v[60:63]
	v_mfma_f32_16x16x32_bf16 v[172:175], v[176:179], v[204:207], v[16:19]
	s_barrier
	s_nop 1
	ds_read_b128 v[60:63], v151
	ds_read_b128 v[176:179], v151 offset:1024
	ds_read_b128 v[192:195], v151 offset:2048
	ds_read_b128 v[196:199], v151 offset:3072
	ds_read_b128 v[200:203], v222
	ds_read_b128 v[204:207], v222 offset:1024
	ds_read_b128 v[208:211], v222 offset:2048
	ds_read_b128 v[216:219], v222 offset:3072
	s_add_u32 s34, s40, 0x10000
	s_addc_u32 s35, s41, 0
	s_mov_b32 m0, s46
	ds_read_b128 v[16:19], v149 offset:32768
	ds_read_b128 v[20:23], v149 offset:33792
	ds_read_b128 v[108:111], v149 offset:34816
	ds_read_b128 v[220:223], v149 offset:35840
	ds_read_b128 v[224:227], v149 offset:36864
	ds_read_b128 v[228:231], v149 offset:37888
	ds_read_b128 v[232:235], v149 offset:38912
	ds_read_b128 v[236:239], v149 offset:39936
	global_load_lds_dwordx4 v128, s[34:35]
	s_mov_b32 m0, s47
	s_nop 0
	global_load_lds_dwordx4 v132, s[34:35]
	s_waitcnt vmcnt(8)
	s_waitcnt lgkmcnt(0)
	s_barrier
	s_waitcnt lgkmcnt(0)
	v_mfma_f32_16x16x32_bf16 v[64:67], v[60:63], v[16:19], v[64:67]
	v_mfma_f32_16x16x32_bf16 v[112:115], v[176:179], v[20:23], v[64:67]
	v_mfma_f32_16x16x32_bf16 v[64:67], v[192:195], v[16:19], v[68:71]
	v_mfma_f32_16x16x32_bf16 v[116:119], v[196:199], v[20:23], v[64:67]
	v_mfma_f32_16x16x32_bf16 v[64:67], v[60:63], v[108:111], v[72:75]
	v_mfma_f32_16x16x32_bf16 v[96:99], v[176:179], v[220:223], v[64:67]
	v_mfma_f32_16x16x32_bf16 v[64:67], v[192:195], v[108:111], v[76:79]
	v_mfma_f32_16x16x32_bf16 v[100:103], v[196:199], v[220:223], v[64:67]
	v_mfma_f32_16x16x32_bf16 v[64:67], v[60:63], v[224:227], v[80:83]
	v_mfma_f32_16x16x32_bf16 v[80:83], v[176:179], v[228:231], v[64:67]
	v_mfma_f32_16x16x32_bf16 v[64:67], v[192:195], v[224:227], v[84:87]
	v_mfma_f32_16x16x32_bf16 v[84:87], v[196:199], v[228:231], v[64:67]
	v_mfma_f32_16x16x32_bf16 v[64:67], v[60:63], v[232:235], v[88:91]
	v_mfma_f32_16x16x32_bf16 v[68:71], v[192:195], v[232:235], v[92:95]
	v_mfma_f32_16x16x32_bf16 v[64:67], v[176:179], v[236:239], v[64:67]
	v_mfma_f32_16x16x32_bf16 v[68:71], v[196:199], v[236:239], v[68:71]
	v_mfma_f32_16x16x32_bf16 v[72:75], v[200:203], v[16:19], v[212:215]
	v_mfma_f32_16x16x32_bf16 v[16:19], v[208:211], v[16:19], v[32:35]
	v_mfma_f32_16x16x32_bf16 v[124:127], v[216:219], v[20:23], v[16:19]
	v_mfma_f32_16x16x32_bf16 v[16:19], v[200:203], v[108:111], v[36:39]
	v_mfma_f32_16x16x32_bf16 v[104:107], v[204:207], v[220:223], v[16:19]
	v_mfma_f32_16x16x32_bf16 v[16:19], v[208:211], v[108:111], v[40:43]
	v_mfma_f32_16x16x32_bf16 v[108:111], v[216:219], v[220:223], v[16:19]
	v_mfma_f32_16x16x32_bf16 v[16:19], v[200:203], v[224:227], v[44:47]
	v_mfma_f32_16x16x32_bf16 v[88:91], v[204:207], v[228:231], v[16:19]
	v_mfma_f32_16x16x32_bf16 v[16:19], v[208:211], v[224:227], v[48:51]
	v_mfma_f32_16x16x32_bf16 v[92:95], v[216:219], v[228:231], v[16:19]
	v_mfma_f32_16x16x32_bf16 v[16:19], v[200:203], v[232:235], v[52:55]
	v_mfma_f32_16x16x32_bf16 v[120:123], v[204:207], v[20:23], v[72:75]
	v_mfma_f32_16x16x32_bf16 v[72:75], v[204:207], v[236:239], v[16:19]
	v_mfma_f32_16x16x32_bf16 v[16:19], v[208:211], v[232:235], v[56:59]
	v_mfma_f32_16x16x32_bf16 v[76:79], v[216:219], v[236:239], v[16:19]
	s_barrier
	s_mov_b32 m0, s61
	s_nop 3
	v_lshl_add_u64 v[16:17], v[240:241], 0, s[12:13]
	s_add_u32 s34, s38, 0x10080
	ds_read_b128 v[40:43], v149 offset:49152
	ds_read_b128 v[44:47], v149 offset:50176
	ds_read_b128 v[212:215], v149 offset:51200
	ds_read_b128 v[220:223], v149 offset:52224
	ds_read_b128 v[224:227], v149 offset:53248
	ds_read_b128 v[228:231], v149 offset:54272
	ds_read_b128 v[232:235], v149 offset:55296
	ds_read_b128 v[236:239], v149 offset:56320
	global_load_lds_dwordx4 v[16:17], off
	v_lshl_add_u64 v[16:17], v[242:243], 0, s[12:13]
	s_mov_b32 m0, s60
	s_addc_u32 s35, s39, 0
	global_load_lds_dwordx4 v[16:17], off
	v_lshl_add_u64 v[16:17], s[34:35], 0, v[130:131]
	s_mov_b32 m0, s36
	s_nop 0
	global_load_lds_dwordx4 v[16:17], off
	s_mov_b32 m0, s37
	s_nop 0
	global_load_lds_dwordx4 v134, s[34:35]
	v_lshl_add_u64 v[16:17], v[244:245], 0, s[12:13]
	s_mov_b32 m0, s50
	s_nop 0
	global_load_lds_dwordx4 v[16:17], off
	v_lshl_add_u64 v[16:17], v[246:247], 0, s[12:13]
	s_mov_b32 m0, s51
	s_nop 0
	global_load_lds_dwordx4 v[16:17], off
	s_waitcnt vmcnt(8)
	s_waitcnt lgkmcnt(0)
	s_barrier
	s_waitcnt lgkmcnt(0)
	v_mfma_f32_16x16x32_bf16 v[16:19], v[60:63], v[40:43], v[140:143]
	v_mfma_f32_16x16x32_bf16 v[48:51], v[176:179], v[44:47], v[16:19]
	v_mfma_f32_16x16x32_bf16 v[16:19], v[192:195], v[40:43], v[152:155]
	v_mfma_f32_16x16x32_bf16 v[52:55], v[196:199], v[44:47], v[16:19]
	v_mfma_f32_16x16x32_bf16 v[16:19], v[60:63], v[212:215], v[156:159]
	v_mfma_f32_16x16x32_bf16 v[32:35], v[176:179], v[220:223], v[16:19]
	v_mfma_f32_16x16x32_bf16 v[16:19], v[192:195], v[212:215], v[160:163]
	v_mfma_f32_16x16x32_bf16 v[36:39], v[196:199], v[220:223], v[16:19]
	v_mfma_f32_16x16x32_bf16 v[16:19], v[60:63], v[224:227], v[164:167]
	v_mfma_f32_16x16x32_bf16 v[20:23], v[192:195], v[224:227], v[168:171]
	v_mfma_f32_16x16x32_bf16 v[0:3], v[60:63], v[232:235], v[0:3]
	v_mfma_f32_16x16x32_bf16 v[4:7], v[192:195], v[232:235], v[4:7]
	v_mfma_f32_16x16x32_bf16 v[16:19], v[176:179], v[228:231], v[16:19]
	v_mfma_f32_16x16x32_bf16 v[20:23], v[196:199], v[228:231], v[20:23]
	v_mfma_f32_16x16x32_bf16 v[0:3], v[176:179], v[236:239], v[0:3]
	v_mfma_f32_16x16x32_bf16 v[4:7], v[196:199], v[236:239], v[4:7]
	v_mfma_f32_16x16x32_bf16 v[8:11], v[200:203], v[40:43], v[8:11]
	v_mfma_f32_16x16x32_bf16 v[56:59], v[204:207], v[44:47], v[8:11]
	v_mfma_f32_16x16x32_bf16 v[8:11], v[208:211], v[40:43], v[12:15]
	v_mfma_f32_16x16x32_bf16 v[60:63], v[216:219], v[44:47], v[8:11]
	v_mfma_f32_16x16x32_bf16 v[8:11], v[200:203], v[212:215], v[24:27]
	v_mfma_f32_16x16x32_bf16 v[40:43], v[204:207], v[220:223], v[8:11]
	v_mfma_f32_16x16x32_bf16 v[8:11], v[208:211], v[212:215], v[28:31]
	v_mfma_f32_16x16x32_bf16 v[44:47], v[216:219], v[220:223], v[8:11]
	v_mfma_f32_16x16x32_bf16 v[8:11], v[200:203], v[224:227], v[180:183]
	v_mfma_f32_16x16x32_bf16 v[24:27], v[204:207], v[228:231], v[8:11]
	v_mfma_f32_16x16x32_bf16 v[8:11], v[208:211], v[224:227], v[184:187]
	v_mfma_f32_16x16x32_bf16 v[28:31], v[216:219], v[228:231], v[8:11]
	v_mfma_f32_16x16x32_bf16 v[8:11], v[200:203], v[232:235], v[188:191]
	v_mfma_f32_16x16x32_bf16 v[12:15], v[208:211], v[232:235], v[172:175]
	v_mfma_f32_16x16x32_bf16 v[8:11], v[204:207], v[236:239], v[8:11]
	v_mfma_f32_16x16x32_bf16 v[12:15], v[216:219], v[236:239], v[12:15]
	s_barrier
	s_andn2_b64 vcc, exec, s[14:15]
	s_cbranch_vccnz .LBB0_1260
	s_barrier

.LBB0_1269:
	v_ashrrev_i32_e32 v2, 31, v0
	v_lshrrev_b32_e32 v2, 26, v2
	v_lshlrev_b32_e32 v1, 4, v0
	v_add_u32_e32 v2, v0, v2
	v_bfe_i32 v0, v0, 27, 1
	v_lshrrev_b32_e32 v0, 22, v0
	v_add_u32_e32 v0, v1, v0
	v_and_b32_e32 v0, 0xfffffc00, v0
	v_sub_u32_e32 v0, v1, v0
	v_lshrrev_b32_e32 v3, 4, v0
	v_bitop3_b32 v0, v3, v0, 32 bitop3:0x6c
	v_ashrrev_i32_e32 v4, 31, v0
	v_ashrrev_i32_e32 v2, 6, v2
	v_lshrrev_b32_e32 v4, 26, v4
	v_lshlrev_b32_e32 v3, 3, v2
	v_add_u32_e32 v4, v0, v4
	v_and_b32_e32 v3, -16, v3
	v_ashrrev_i32_e32 v5, 6, v4
	v_and_b32_e32 v4, 0xc0, v4
	v_add_u32_e32 v3, v5, v3
	v_sub_u32_e32 v0, v0, v4
	v_mov_b32_e32 v4, 1
	s_ashr_i32 s2, s5, 3
	v_lshlrev_b32_e32 v2, 5, v2
	v_ashrrev_i16_sdwa v0, v4, sext(v0) dst_sel:DWORD dst_unused:UNUSED_PAD src0_sel:DWORD src1_sel:BYTE_0
	v_lshlrev_b32_e32 v6, 1, v3
	v_lshrrev_b32_e32 v7, 2, v3
	v_and_b32_e32 v5, 3, v5
	s_mov_b32 s5, 0x7fffe0
	v_and_b32_e32 v2, 32, v2
	v_bfe_i32 v0, v0, 0, 16
	v_and_b32_e32 v6, 24, v6
	v_and_b32_e32 v7, 4, v7
	v_and_or_b32 v5, v3, s5, v5
	v_or3_b32 v5, v5, v7, v6
	v_add_lshl_u32 v0, v2, v0, 1
	v_lshl_add_u32 v128, v3, 9, v0
	v_lshl_add_u32 v130, v5, 9, v0
	v_add_u32_e32 v0, 0x2000, v1
	v_ashrrev_i32_e32 v1, 31, v0
	v_lshrrev_b32_e32 v1, 22, v1
	v_add_u32_e32 v1, v0, v1
	v_ashrrev_i32_e32 v1, 10, v1
	v_mul_i32_i24_e32 v2, 0x400, v1
	v_sub_u32_e32 v0, v0, v2
	s_add_u32 s50, s70, 0x5580000
	v_lshrrev_b32_e32 v2, 4, v0
	s_addc_u32 s51, s71, 0
	v_bitop3_b32 v0, v2, v0, 32 bitop3:0x6c
	s_add_i32 s2, s4, s2
	v_ashrrev_i32_e32 v3, 31, v0
	s_ashr_i32 s4, s2, 31
	v_lshrrev_b32_e32 v3, 26, v3
	s_lshr_b32 s4, s4, 22
	v_lshlrev_b32_e32 v2, 3, v1
	v_add_u32_e32 v3, v0, v3
	s_add_i32 s4, s2, s4
	v_and_b32_e32 v2, -16, v2
	v_ashrrev_i32_e32 v5, 6, v3
	v_and_b32_e32 v3, 0xc0, v3
	s_ashr_i32 s4, s4, 10
	v_add_u32_e32 v2, v5, v2
	v_sub_u32_e32 v0, v0, v3
	v_and_b32_e32 v5, 3, v5
	s_lshl_b32 s6, s4, 3
	v_lshlrev_b32_e32 v1, 5, v1
	v_ashrrev_i16_sdwa v0, v4, sext(v0) dst_sel:DWORD dst_unused:UNUSED_PAD src0_sel:DWORD src1_sel:BYTE_0
	v_lshlrev_b32_e32 v3, 1, v2
	v_lshrrev_b32_e32 v4, 2, v2
	v_and_or_b32 v5, v2, s5, v5
	s_sub_i32 s5, 4, s6
	s_lshl_b32 s4, s4, 10
	v_and_b32_e32 v1, 32, v1
	v_bfe_i32 v0, v0, 0, 16
	v_and_b32_e32 v3, 24, v3
	v_and_b32_e32 v4, 4, v4
	s_min_u32 s7, s5, 8
	s_sub_i32 s9, s2, s4
	v_or3_b32 v3, v5, v4, v3
	v_add_lshl_u32 v0, v1, v0, 1
	s_sext_i32_i16 s2, s9
	v_cvt_f32_ubyte0_e32 v1, s7
	v_lshl_add_u32 v132, v2, 9, v0
	v_lshl_add_u32 v134, v3, 9, v0
	v_cvt_f32_i32_e32 v0, s2
	v_rcp_iflag_f32_e32 v2, v1
	s_ashr_i32 s8, s12, 6
	s_ashr_i32 s2, s2, 30
	s_ashr_i32 s3, s12, 8
	v_mul_f32_e32 v2, v0, v2
	v_trunc_f32_e32 v2, v2
	v_fma_f32 v0, -v2, v1, v0
	v_cvt_i32_f32_e32 v2, v2
	s_lshl_b32 s52, s8, 10
	s_or_b32 s2, s2, 1
	v_cmp_ge_f32_e64 s[4:5], |v0|, v1
	s_and_b64 s[4:5], s[4:5], exec
	s_cselect_b32 s2, s2, 0
	v_readfirstlane_b32 s4, v2
	s_add_i32 s2, s4, s2
	s_mul_i32 s4, s2, s7
	s_sub_i32 s4, s9, s4
	s_sext_i32_i16 s4, s4
	s_add_i32 s38, s6, s4
	s_ashr_i32 s39, s38, 31
	s_bfe_i64 s[6:7], s[2:3], 0x100000
	s_lshl_b64 s[4:5], s[38:39], 17
	s_lshl_b64 s[6:7], s[6:7], 17
	s_add_u32 s42, s48, s6
	s_addc_u32 s43, s49, s7
	s_add_i32 s39, s52, 0
	s_add_i32 m0, s39, 0x10000
	v_mov_b32_e32 v131, 0
	global_load_lds_dwordx4 v130, s[42:43]
	s_add_i32 m0, s39, 0x12000
	s_add_u32 s6, s42, 0x10000
	global_load_lds_dwordx4 v134, s[42:43]
	s_addc_u32 s7, s43, 0
	s_add_i32 m0, s39, 0x14000
	v_mov_b32_e32 v135, v131
	global_load_lds_dwordx4 v130, s[6:7]
	s_add_i32 m0, s39, 0x16000
	s_add_u32 s40, s50, s4
	s_addc_u32 s41, s51, s5
	s_add_i32 s53, s39, 0x2000
	global_load_lds_dwordx4 v134, s[6:7]
	s_mov_b32 m0, s39
	s_add_u32 s4, s40, 0x10000
	global_load_lds_dwordx4 v128, s[40:41]
	s_mov_b32 m0, s53
	s_addc_u32 s5, s41, 0
	s_add_i32 s54, s39, 0x4000
	global_load_lds_dwordx4 v132, s[40:41]
	s_mov_b32 m0, s54
	s_add_i32 s55, s39, 0x6000
	global_load_lds_dwordx4 v128, s[4:5]
	s_mov_b32 m0, s55
	v_mov_b32_e32 v129, v131
	global_load_lds_dwordx4 v132, s[4:5]
	v_mov_b32_e32 v133, v131
	s_cmp_eq_u32 s3, 1
	v_lshl_add_u64 v[6:7], s[42:43], 0, v[130:131]
	v_lshl_add_u64 v[4:5], s[42:43], 0, v[134:135]
	v_lshl_add_u64 v[0:1], s[40:41], 0, v[128:129]
	s_cselect_b64 s[4:5], -1, 0
	s_cmp_lg_u32 s3, 1
	v_lshl_add_u64 v[2:3], s[40:41], 0, v[132:133]
	s_setprio 1
	s_cbranch_scc1 .LBB0_1271
	s_barrier
	s_setprio 0

.LBB0_1280:
	ds_read_b128 v[0:3], v161
	ds_read_b128 v[4:7], v161 offset:1024
	ds_read_b128 v[8:11], v161 offset:2048
	ds_read_b128 v[12:15], v161 offset:3072
	ds_read_b128 v[16:19], v162
	ds_read_b128 v[20:23], v162 offset:1024
	ds_read_b128 v[24:27], v162 offset:2048
	ds_read_b128 v[28:31], v162 offset:3072
	s_ashr_i32 s31, s30, 31
	s_lshl_b64 s[34:35], s[30:31], 17
	s_add_u32 s34, s50, s34
	s_addc_u32 s35, s51, s35
	s_and_b64 s[36:37], s[2:3], exec
	s_cselect_b32 s47, s35, s41
	s_cselect_b32 s46, s34, s40
	s_ashr_i32 s29, s28, 31
	s_lshl_b64 s[36:37], s[28:29], 17
	s_add_u32 s36, s48, s36
	s_addc_u32 s37, s49, s37
	s_and_b64 s[44:45], s[2:3], exec
	s_cselect_b32 s45, s37, s43
	s_cselect_b32 s44, s36, s42
	s_add_u32 s66, s40, 0x10080
	s_addc_u32 s67, s41, 0
	s_add_i32 s84, s39, 0xc000
	s_mov_b32 m0, s84
	s_add_i32 s29, s39, 0xe000
	ds_read_b128 v[32:35], v163
	ds_read_b128 v[36:39], v163 offset:1024
	ds_read_b128 v[40:43], v163 offset:2048
	ds_read_b128 v[44:47], v163 offset:3072
	ds_read_b128 v[48:51], v163 offset:4096
	ds_read_b128 v[52:55], v163 offset:5120
	ds_read_b128 v[56:59], v163 offset:6144
	ds_read_b128 v[60:63], v163 offset:7168
	global_load_lds_dwordx4 v128, s[66:67]
	s_mov_b32 m0, s29
	s_nop 0
	global_load_lds_dwordx4 v132, s[66:67]
	s_waitcnt vmcnt(8)
	s_waitcnt lgkmcnt(0)
	s_barrier
	s_waitcnt lgkmcnt(0)
	v_mfma_f32_16x16x32_bf16 v[64:67], v[0:3], v[32:35], 0
	v_mfma_f32_16x16x32_bf16 v[68:71], v[8:11], v[32:35], 0
	v_mfma_f32_16x16x32_bf16 v[72:75], v[0:3], v[40:43], 0
	v_mfma_f32_16x16x32_bf16 v[76:79], v[8:11], v[40:43], 0
	v_mfma_f32_16x16x32_bf16 v[80:83], v[0:3], v[48:51], 0
	v_mfma_f32_16x16x32_bf16 v[84:87], v[8:11], v[48:51], 0
	v_mfma_f32_16x16x32_bf16 v[88:91], v[0:3], v[56:59], 0
	v_mfma_f32_16x16x32_bf16 v[92:95], v[8:11], v[56:59], 0
	v_mfma_f32_16x16x32_bf16 v[64:67], v[4:7], v[36:39], v[64:67]
	v_mfma_f32_16x16x32_bf16 v[68:71], v[12:15], v[36:39], v[68:71]
	v_mfma_f32_16x16x32_bf16 v[72:75], v[4:7], v[44:47], v[72:75]
	v_mfma_f32_16x16x32_bf16 v[76:79], v[12:15], v[44:47], v[76:79]
	v_mfma_f32_16x16x32_bf16 v[80:83], v[4:7], v[52:55], v[80:83]
	v_mfma_f32_16x16x32_bf16 v[84:87], v[12:15], v[52:55], v[84:87]
	v_mfma_f32_16x16x32_bf16 v[88:91], v[4:7], v[60:63], v[88:91]
	v_mfma_f32_16x16x32_bf16 v[92:95], v[12:15], v[60:63], v[92:95]
	v_mfma_f32_16x16x32_bf16 v[96:99], v[16:19], v[32:35], 0
	v_mfma_f32_16x16x32_bf16 v[32:35], v[24:27], v[32:35], 0
	v_mfma_f32_16x16x32_bf16 v[96:99], v[20:23], v[36:39], v[96:99]
	v_mfma_f32_16x16x32_bf16 v[32:35], v[28:31], v[36:39], v[32:35]
	v_mfma_f32_16x16x32_bf16 v[36:39], v[16:19], v[40:43], 0
	v_mfma_f32_16x16x32_bf16 v[40:43], v[24:27], v[40:43], 0
	v_mfma_f32_16x16x32_bf16 v[36:39], v[20:23], v[44:47], v[36:39]
	v_mfma_f32_16x16x32_bf16 v[40:43], v[28:31], v[44:47], v[40:43]
	v_mfma_f32_16x16x32_bf16 v[44:47], v[16:19], v[48:51], 0
	v_mfma_f32_16x16x32_bf16 v[48:51], v[24:27], v[48:51], 0
	v_mfma_f32_16x16x32_bf16 v[44:47], v[20:23], v[52:55], v[44:47]
	v_mfma_f32_16x16x32_bf16 v[48:51], v[28:31], v[52:55], v[48:51]
	v_mfma_f32_16x16x32_bf16 v[52:55], v[16:19], v[56:59], 0
	v_mfma_f32_16x16x32_bf16 v[56:59], v[24:27], v[56:59], 0
	v_mfma_f32_16x16x32_bf16 v[52:55], v[20:23], v[60:63], v[52:55]
	v_mfma_f32_16x16x32_bf16 v[56:59], v[28:31], v[60:63], v[56:59]
	s_barrier
	s_add_i32 s68, s59, s52
	v_lshl_add_u64 v[156:157], s[42:43], 0, v[130:131]
	s_add_i32 s31, s68, 0x2000
	v_lshl_add_u64 v[140:141], v[156:157], 0, s[16:17]
	s_mov_b32 m0, s68
	v_lshl_add_u64 v[214:215], s[42:43], 0, v[134:135]
	s_add_u32 s86, s42, 0x10100
	ds_read_b128 v[60:63], v163 offset:16384
	ds_read_b128 v[100:103], v163 offset:17408
	ds_read_b128 v[104:107], v163 offset:18432
	ds_read_b128 v[108:111], v163 offset:19456
	ds_read_b128 v[112:115], v163 offset:20480
	ds_read_b128 v[116:119], v163 offset:21504
	ds_read_b128 v[120:123], v163 offset:22528
	ds_read_b128 v[124:127], v163 offset:23552
	global_load_lds_dwordx4 v[140:141], off
	v_lshl_add_u64 v[140:141], v[214:215], 0, s[16:17]
	s_mov_b32 m0, s31
	s_addc_u32 s87, s43, 0
	s_add_i32 s66, s60, s52
	global_load_lds_dwordx4 v[140:141], off
	v_lshl_add_u64 v[140:141], s[86:87], 0, v[130:131]
	s_mov_b32 m0, s66
	s_add_i32 s67, s66, 0x2000
	global_load_lds_dwordx4 v[140:141], off
	s_mov_b32 m0, s67
	v_lshl_add_u64 v[216:217], s[40:41], 0, v[128:129]
	global_load_lds_dwordx4 v134, s[86:87]
	v_lshl_add_u64 v[140:141], v[216:217], 0, s[16:17]
	s_mov_b32 m0, s39
	v_lshl_add_u64 v[218:219], s[40:41], 0, v[132:133]
	global_load_lds_dwordx4 v[140:141], off
	v_lshl_add_u64 v[140:141], v[218:219], 0, s[16:17]
	s_mov_b32 m0, s53
	s_nop 0
	global_load_lds_dwordx4 v[140:141], off
	s_waitcnt vmcnt(8)
	s_waitcnt lgkmcnt(0)
	s_barrier
	s_waitcnt lgkmcnt(0)
	v_mfma_f32_16x16x32_bf16 v[140:143], v[0:3], v[60:63], 0
	v_mfma_f32_16x16x32_bf16 v[148:151], v[0:3], v[104:107], 0
	v_mfma_f32_16x16x32_bf16 v[166:169], v[0:3], v[112:115], 0
	v_mfma_f32_16x16x32_bf16 v[0:3], v[0:3], v[120:123], 0
	v_mfma_f32_16x16x32_bf16 v[140:143], v[4:7], v[100:103], v[140:143]
	v_mfma_f32_16x16x32_bf16 v[148:151], v[4:7], v[108:111], v[148:151]
	v_mfma_f32_16x16x32_bf16 v[166:169], v[4:7], v[116:119], v[166:169]
	v_mfma_f32_16x16x32_bf16 v[0:3], v[4:7], v[124:127], v[0:3]
	v_mfma_f32_16x16x32_bf16 v[4:7], v[8:11], v[120:123], 0
	v_mfma_f32_16x16x32_bf16 v[144:147], v[8:11], v[60:63], 0
	v_mfma_f32_16x16x32_bf16 v[152:155], v[8:11], v[104:107], 0
	v_mfma_f32_16x16x32_bf16 v[170:173], v[8:11], v[112:115], 0
	v_mfma_f32_16x16x32_bf16 v[4:7], v[12:15], v[124:127], v[4:7]
	v_mfma_f32_16x16x32_bf16 v[144:147], v[12:15], v[100:103], v[144:147]
	v_mfma_f32_16x16x32_bf16 v[152:155], v[12:15], v[108:111], v[152:155]
	v_mfma_f32_16x16x32_bf16 v[170:173], v[12:15], v[116:119], v[170:173]
	v_mfma_f32_16x16x32_bf16 v[8:11], v[16:19], v[60:63], 0
	v_mfma_f32_16x16x32_bf16 v[12:15], v[24:27], v[60:63], 0
	v_mfma_f32_16x16x32_bf16 v[8:11], v[20:23], v[100:103], v[8:11]
	v_mfma_f32_16x16x32_bf16 v[12:15], v[28:31], v[100:103], v[12:15]
	v_mfma_f32_16x16x32_bf16 v[60:63], v[16:19], v[104:107], 0
	v_mfma_f32_16x16x32_bf16 v[100:103], v[24:27], v[104:107], 0
	v_mfma_f32_16x16x32_bf16 v[104:107], v[16:19], v[112:115], 0
	v_mfma_f32_16x16x32_bf16 v[16:19], v[16:19], v[120:123], 0
	v_mfma_f32_16x16x32_bf16 v[60:63], v[20:23], v[108:111], v[60:63]
	v_mfma_f32_16x16x32_bf16 v[100:103], v[28:31], v[108:111], v[100:103]
	v_mfma_f32_16x16x32_bf16 v[104:107], v[20:23], v[116:119], v[104:107]
	v_mfma_f32_16x16x32_bf16 v[108:111], v[24:27], v[112:115], 0
	v_mfma_f32_16x16x32_bf16 v[16:19], v[20:23], v[124:127], v[16:19]
	v_mfma_f32_16x16x32_bf16 v[20:23], v[24:27], v[120:123], 0
	v_mfma_f32_16x16x32_bf16 v[108:111], v[28:31], v[116:119], v[108:111]
	v_mfma_f32_16x16x32_bf16 v[20:23], v[28:31], v[124:127], v[20:23]
	s_barrier
	s_add_i32 s85, 0, 0x18000
	s_add_i32 s88, 0, 0x1c000
	v_add_u32_e32 v165, s85, v159
	v_add_u32_e32 v226, s88, v159
	ds_read_b128 v[24:27], v165
	ds_read_b128 v[28:31], v165 offset:1024
	ds_read_b128 v[112:115], v165 offset:2048
	ds_read_b128 v[116:119], v165 offset:3072
	ds_read_b128 v[120:123], v226
	ds_read_b128 v[124:127], v226 offset:1024
	ds_read_b128 v[174:177], v226 offset:2048
	ds_read_b128 v[178:181], v226 offset:3072
	s_add_u32 s86, s40, 0x10100
	s_addc_u32 s87, s41, 0
	s_mov_b32 m0, s54
	ds_read_b128 v[182:185], v163 offset:32768
	ds_read_b128 v[186:189], v163 offset:33792
	ds_read_b128 v[190:193], v163 offset:34816
	ds_read_b128 v[194:197], v163 offset:35840
	ds_read_b128 v[198:201], v163 offset:36864
	ds_read_b128 v[202:205], v163 offset:37888
	ds_read_b128 v[206:209], v163 offset:38912
	ds_read_b128 v[210:213], v163 offset:39936
	global_load_lds_dwordx4 v128, s[86:87]
	s_mov_b32 m0, s55
	s_nop 0
	global_load_lds_dwordx4 v132, s[86:87]
	s_waitcnt vmcnt(8)
	s_waitcnt lgkmcnt(0)
	s_barrier
	s_waitcnt lgkmcnt(0)
	v_mfma_f32_16x16x32_bf16 v[64:67], v[24:27], v[182:185], v[64:67]
	v_mfma_f32_16x16x32_bf16 v[68:71], v[112:115], v[182:185], v[68:71]
	v_mfma_f32_16x16x32_bf16 v[72:75], v[24:27], v[190:193], v[72:75]
	v_mfma_f32_16x16x32_bf16 v[76:79], v[112:115], v[190:193], v[76:79]
	v_mfma_f32_16x16x32_bf16 v[80:83], v[24:27], v[198:201], v[80:83]
	v_mfma_f32_16x16x32_bf16 v[84:87], v[112:115], v[198:201], v[84:87]
	v_mfma_f32_16x16x32_bf16 v[88:91], v[24:27], v[206:209], v[88:91]
	v_mfma_f32_16x16x32_bf16 v[92:95], v[112:115], v[206:209], v[92:95]
	v_mfma_f32_16x16x32_bf16 v[64:67], v[28:31], v[186:189], v[64:67]
	v_mfma_f32_16x16x32_bf16 v[68:71], v[116:119], v[186:189], v[68:71]
	v_mfma_f32_16x16x32_bf16 v[72:75], v[28:31], v[194:197], v[72:75]
	v_mfma_f32_16x16x32_bf16 v[76:79], v[116:119], v[194:197], v[76:79]
	v_mfma_f32_16x16x32_bf16 v[80:83], v[28:31], v[202:205], v[80:83]
	v_mfma_f32_16x16x32_bf16 v[84:87], v[116:119], v[202:205], v[84:87]
	v_mfma_f32_16x16x32_bf16 v[88:91], v[28:31], v[210:213], v[88:91]
	v_mfma_f32_16x16x32_bf16 v[92:95], v[116:119], v[210:213], v[92:95]
	v_mfma_f32_16x16x32_bf16 v[96:99], v[120:123], v[182:185], v[96:99]
	v_mfma_f32_16x16x32_bf16 v[32:35], v[174:177], v[182:185], v[32:35]
	v_mfma_f32_16x16x32_bf16 v[36:39], v[120:123], v[190:193], v[36:39]
	v_mfma_f32_16x16x32_bf16 v[40:43], v[174:177], v[190:193], v[40:43]
	v_mfma_f32_16x16x32_bf16 v[44:47], v[120:123], v[198:201], v[44:47]
	v_mfma_f32_16x16x32_bf16 v[48:51], v[174:177], v[198:201], v[48:51]
	v_mfma_f32_16x16x32_bf16 v[52:55], v[120:123], v[206:209], v[52:55]
	v_mfma_f32_16x16x32_bf16 v[56:59], v[174:177], v[206:209], v[56:59]
	v_mfma_f32_16x16x32_bf16 v[96:99], v[124:127], v[186:189], v[96:99]
	v_mfma_f32_16x16x32_bf16 v[32:35], v[178:181], v[186:189], v[32:35]
	v_mfma_f32_16x16x32_bf16 v[36:39], v[124:127], v[194:197], v[36:39]
	v_mfma_f32_16x16x32_bf16 v[40:43], v[178:181], v[194:197], v[40:43]
	v_mfma_f32_16x16x32_bf16 v[44:47], v[124:127], v[202:205], v[44:47]
	v_mfma_f32_16x16x32_bf16 v[48:51], v[178:181], v[202:205], v[48:51]
	v_mfma_f32_16x16x32_bf16 v[52:55], v[124:127], v[210:213], v[52:55]
	v_mfma_f32_16x16x32_bf16 v[56:59], v[178:181], v[210:213], v[56:59]
	s_barrier
	s_add_i32 s85, s85, s52
	s_add_i32 s69, s85, 0x2000
	v_lshl_add_u64 v[156:157], v[156:157], 0, s[18:19]
	s_mov_b32 m0, s85
	s_add_u32 s86, s42, 0x10180
	ds_read_b128 v[182:185], v163 offset:49152
	ds_read_b128 v[186:189], v163 offset:50176
	ds_read_b128 v[190:193], v163 offset:51200
	ds_read_b128 v[194:197], v163 offset:52224
	ds_read_b128 v[198:201], v163 offset:53248
	ds_read_b128 v[202:205], v163 offset:54272
	ds_read_b128 v[206:209], v163 offset:55296
	ds_read_b128 v[210:213], v163 offset:56320
	global_load_lds_dwordx4 v[156:157], off
	v_lshl_add_u64 v[156:157], v[214:215], 0, s[18:19]
	s_mov_b32 m0, s69
	s_addc_u32 s87, s43, 0
	s_add_i32 s42, s88, s52
	global_load_lds_dwordx4 v[156:157], off
	v_lshl_add_u64 v[156:157], s[86:87], 0, v[130:131]
	s_mov_b32 m0, s42
	s_add_i32 s43, s42, 0x2000
	global_load_lds_dwordx4 v[156:157], off
	s_mov_b32 m0, s43
	s_nop 0
	global_load_lds_dwordx4 v134, s[86:87]
	v_lshl_add_u64 v[156:157], v[216:217], 0, s[18:19]
	s_mov_b32 m0, s56
	s_nop 0
	global_load_lds_dwordx4 v[156:157], off
	v_lshl_add_u64 v[156:157], v[218:219], 0, s[18:19]
	s_mov_b32 m0, s57
	s_nop 0
	global_load_lds_dwordx4 v[156:157], off
	s_waitcnt vmcnt(8)
	s_waitcnt lgkmcnt(0)
	s_barrier
	s_waitcnt lgkmcnt(0)
	v_mfma_f32_16x16x32_bf16 v[0:3], v[24:27], v[206:209], v[0:3]
	v_mfma_f32_16x16x32_bf16 v[4:7], v[112:115], v[206:209], v[4:7]
	v_mfma_f32_16x16x32_bf16 v[140:143], v[24:27], v[182:185], v[140:143]
	v_mfma_f32_16x16x32_bf16 v[144:147], v[112:115], v[182:185], v[144:147]
	v_mfma_f32_16x16x32_bf16 v[148:151], v[24:27], v[190:193], v[148:151]
	v_mfma_f32_16x16x32_bf16 v[152:155], v[112:115], v[190:193], v[152:155]
	v_mfma_f32_16x16x32_bf16 v[166:169], v[24:27], v[198:201], v[166:169]
	v_mfma_f32_16x16x32_bf16 v[170:173], v[112:115], v[198:201], v[170:173]
	v_mfma_f32_16x16x32_bf16 v[0:3], v[28:31], v[210:213], v[0:3]
	v_mfma_f32_16x16x32_bf16 v[4:7], v[116:119], v[210:213], v[4:7]
	v_mfma_f32_16x16x32_bf16 v[140:143], v[28:31], v[186:189], v[140:143]
	v_mfma_f32_16x16x32_bf16 v[144:147], v[116:119], v[186:189], v[144:147]
	v_mfma_f32_16x16x32_bf16 v[148:151], v[28:31], v[194:197], v[148:151]
	v_mfma_f32_16x16x32_bf16 v[152:155], v[116:119], v[194:197], v[152:155]
	v_mfma_f32_16x16x32_bf16 v[166:169], v[28:31], v[202:205], v[166:169]
	v_mfma_f32_16x16x32_bf16 v[170:173], v[116:119], v[202:205], v[170:173]
	v_mfma_f32_16x16x32_bf16 v[8:11], v[120:123], v[182:185], v[8:11]
	v_mfma_f32_16x16x32_bf16 v[12:15], v[174:177], v[182:185], v[12:15]
	v_mfma_f32_16x16x32_bf16 v[24:27], v[120:123], v[190:193], v[60:63]
	v_mfma_f32_16x16x32_bf16 v[28:31], v[174:177], v[190:193], v[100:103]
	v_mfma_f32_16x16x32_bf16 v[60:63], v[120:123], v[198:201], v[104:107]
	v_mfma_f32_16x16x32_bf16 v[100:103], v[174:177], v[198:201], v[108:111]
	v_mfma_f32_16x16x32_bf16 v[16:19], v[120:123], v[206:209], v[16:19]
	v_mfma_f32_16x16x32_bf16 v[20:23], v[174:177], v[206:209], v[20:23]
	v_mfma_f32_16x16x32_bf16 v[8:11], v[124:127], v[186:189], v[8:11]
	v_mfma_f32_16x16x32_bf16 v[12:15], v[178:181], v[186:189], v[12:15]
	v_mfma_f32_16x16x32_bf16 v[24:27], v[124:127], v[194:197], v[24:27]
	v_mfma_f32_16x16x32_bf16 v[28:31], v[178:181], v[194:197], v[28:31]
	v_mfma_f32_16x16x32_bf16 v[60:63], v[124:127], v[202:205], v[60:63]
	v_mfma_f32_16x16x32_bf16 v[100:103], v[178:181], v[202:205], v[100:103]
	v_mfma_f32_16x16x32_bf16 v[16:19], v[124:127], v[210:213], v[16:19]
	v_mfma_f32_16x16x32_bf16 v[20:23], v[178:181], v[210:213], v[20:23]
	s_barrier
	ds_read_b128 v[104:107], v161
	ds_read_b128 v[108:111], v161 offset:1024
	ds_read_b128 v[112:115], v161 offset:2048
	ds_read_b128 v[116:119], v161 offset:3072
	ds_read_b128 v[120:123], v162
	ds_read_b128 v[124:127], v162 offset:1024
	ds_read_b128 v[174:177], v162 offset:2048
	ds_read_b128 v[178:181], v162 offset:3072
	s_add_u32 s40, s40, 0x10180
	s_addc_u32 s41, s41, 0
	s_mov_b32 m0, s84
	ds_read_b128 v[182:185], v163
	ds_read_b128 v[186:189], v163 offset:1024
	ds_read_b128 v[190:193], v163 offset:2048
	ds_read_b128 v[194:197], v163 offset:3072
	ds_read_b128 v[198:201], v163 offset:4096
	ds_read_b128 v[202:205], v163 offset:5120
	ds_read_b128 v[206:209], v163 offset:6144
	ds_read_b128 v[210:213], v163 offset:7168
	global_load_lds_dwordx4 v128, s[40:41]
	s_mov_b32 m0, s29
	s_nop 0
	global_load_lds_dwordx4 v132, s[40:41]
	s_waitcnt vmcnt(8)
	s_waitcnt lgkmcnt(0)
	s_barrier
	s_waitcnt lgkmcnt(0)
	v_mfma_f32_16x16x32_bf16 v[64:67], v[104:107], v[182:185], v[64:67]
	v_mfma_f32_16x16x32_bf16 v[68:71], v[112:115], v[182:185], v[68:71]
	v_mfma_f32_16x16x32_bf16 v[72:75], v[104:107], v[190:193], v[72:75]
	v_mfma_f32_16x16x32_bf16 v[76:79], v[112:115], v[190:193], v[76:79]
	v_mfma_f32_16x16x32_bf16 v[80:83], v[104:107], v[198:201], v[80:83]
	v_mfma_f32_16x16x32_bf16 v[84:87], v[112:115], v[198:201], v[84:87]
	v_mfma_f32_16x16x32_bf16 v[88:91], v[104:107], v[206:209], v[88:91]
	v_mfma_f32_16x16x32_bf16 v[64:67], v[108:111], v[186:189], v[64:67]
	v_mfma_f32_16x16x32_bf16 v[68:71], v[116:119], v[186:189], v[68:71]
	v_mfma_f32_16x16x32_bf16 v[72:75], v[108:111], v[194:197], v[72:75]
	v_mfma_f32_16x16x32_bf16 v[76:79], v[116:119], v[194:197], v[76:79]
	v_mfma_f32_16x16x32_bf16 v[80:83], v[108:111], v[202:205], v[80:83]
	v_mfma_f32_16x16x32_bf16 v[84:87], v[116:119], v[202:205], v[84:87]
	v_mfma_f32_16x16x32_bf16 v[214:217], v[108:111], v[210:213], v[88:91]
	v_mfma_f32_16x16x32_bf16 v[88:91], v[112:115], v[206:209], v[92:95]
	v_mfma_f32_16x16x32_bf16 v[218:221], v[116:119], v[210:213], v[88:91]
	v_mfma_f32_16x16x32_bf16 v[88:91], v[120:123], v[182:185], v[96:99]
	v_mfma_f32_16x16x32_bf16 v[32:35], v[174:177], v[182:185], v[32:35]
	v_mfma_f32_16x16x32_bf16 v[36:39], v[120:123], v[190:193], v[36:39]
	v_mfma_f32_16x16x32_bf16 v[40:43], v[174:177], v[190:193], v[40:43]
	v_mfma_f32_16x16x32_bf16 v[44:47], v[120:123], v[198:201], v[44:47]
	v_mfma_f32_16x16x32_bf16 v[48:51], v[174:177], v[198:201], v[48:51]
	v_mfma_f32_16x16x32_bf16 v[52:55], v[120:123], v[206:209], v[52:55]
	v_mfma_f32_16x16x32_bf16 v[56:59], v[174:177], v[206:209], v[56:59]
	v_mfma_f32_16x16x32_bf16 v[96:99], v[124:127], v[186:189], v[88:91]
	v_mfma_f32_16x16x32_bf16 v[32:35], v[178:181], v[186:189], v[32:35]
	v_mfma_f32_16x16x32_bf16 v[36:39], v[124:127], v[194:197], v[36:39]
	v_mfma_f32_16x16x32_bf16 v[40:43], v[178:181], v[194:197], v[40:43]
	v_mfma_f32_16x16x32_bf16 v[44:47], v[124:127], v[202:205], v[44:47]
	v_mfma_f32_16x16x32_bf16 v[48:51], v[178:181], v[202:205], v[48:51]
	v_mfma_f32_16x16x32_bf16 v[52:55], v[124:127], v[210:213], v[52:55]
	v_mfma_f32_16x16x32_bf16 v[56:59], v[178:181], v[210:213], v[56:59]
	s_barrier
	s_mov_b32 m0, s68
	v_lshl_add_u64 v[156:157], s[44:45], 0, v[130:131]
	s_add_u32 s40, s44, 0x10000
	ds_read_b128 v[88:91], v163 offset:16384
	ds_read_b128 v[92:95], v163 offset:17408
	ds_read_b128 v[182:185], v163 offset:18432
	ds_read_b128 v[186:189], v163 offset:19456
	ds_read_b128 v[190:193], v163 offset:20480
	ds_read_b128 v[194:197], v163 offset:21504
	ds_read_b128 v[198:201], v163 offset:22528
	ds_read_b128 v[202:205], v163 offset:23552
	global_load_lds_dwordx4 v[156:157], off
	v_lshl_add_u64 v[250:251], s[44:45], 0, v[134:135]
	s_mov_b32 m0, s31
	s_addc_u32 s41, s45, 0
	global_load_lds_dwordx4 v[250:251], off
	v_lshl_add_u64 v[206:207], s[40:41], 0, v[130:131]
	s_mov_b32 m0, s66
	v_lshl_add_u64 v[252:253], s[46:47], 0, v[128:129]
	global_load_lds_dwordx4 v[206:207], off
	s_mov_b32 m0, s67
	v_lshl_add_u64 v[136:137], s[46:47], 0, v[132:133]
	global_load_lds_dwordx4 v134, s[40:41]
	s_mov_b32 m0, s39
	s_nop 0
	global_load_lds_dwordx4 v[252:253], off
	s_mov_b32 m0, s53
	s_nop 0
	global_load_lds_dwordx4 v[136:137], off
	s_waitcnt vmcnt(8)
	s_waitcnt lgkmcnt(0)
	s_barrier
	s_waitcnt lgkmcnt(0)
	v_mfma_f32_16x16x32_bf16 v[0:3], v[104:107], v[198:201], v[0:3]
	v_mfma_f32_16x16x32_bf16 v[4:7], v[112:115], v[198:201], v[4:7]
	v_mfma_f32_16x16x32_bf16 v[140:143], v[104:107], v[88:91], v[140:143]
	v_mfma_f32_16x16x32_bf16 v[144:147], v[112:115], v[88:91], v[144:147]
	v_mfma_f32_16x16x32_bf16 v[148:151], v[104:107], v[182:185], v[148:151]
	v_mfma_f32_16x16x32_bf16 v[152:155], v[112:115], v[182:185], v[152:155]
	v_mfma_f32_16x16x32_bf16 v[166:169], v[104:107], v[190:193], v[166:169]
	v_mfma_f32_16x16x32_bf16 v[170:173], v[112:115], v[190:193], v[170:173]
	v_mfma_f32_16x16x32_bf16 v[0:3], v[108:111], v[202:205], v[0:3]
	v_mfma_f32_16x16x32_bf16 v[4:7], v[116:119], v[202:205], v[4:7]
	v_mfma_f32_16x16x32_bf16 v[140:143], v[108:111], v[92:95], v[140:143]
	v_mfma_f32_16x16x32_bf16 v[144:147], v[116:119], v[92:95], v[144:147]
	v_mfma_f32_16x16x32_bf16 v[148:151], v[108:111], v[186:189], v[148:151]
	v_mfma_f32_16x16x32_bf16 v[152:155], v[116:119], v[186:189], v[152:155]
	v_mfma_f32_16x16x32_bf16 v[166:169], v[108:111], v[194:197], v[166:169]
	v_mfma_f32_16x16x32_bf16 v[170:173], v[116:119], v[194:197], v[170:173]
	v_mfma_f32_16x16x32_bf16 v[8:11], v[120:123], v[88:91], v[8:11]
	v_mfma_f32_16x16x32_bf16 v[206:209], v[124:127], v[92:95], v[8:11]
	v_mfma_f32_16x16x32_bf16 v[8:11], v[174:177], v[88:91], v[12:15]
	v_mfma_f32_16x16x32_bf16 v[210:213], v[178:181], v[92:95], v[8:11]
	v_mfma_f32_16x16x32_bf16 v[8:11], v[120:123], v[182:185], v[24:27]
	v_mfma_f32_16x16x32_bf16 v[222:225], v[124:127], v[186:189], v[8:11]
	v_mfma_f32_16x16x32_bf16 v[8:11], v[174:177], v[182:185], v[28:31]
	v_mfma_f32_16x16x32_bf16 v[182:185], v[178:181], v[186:189], v[8:11]
	v_mfma_f32_16x16x32_bf16 v[8:11], v[120:123], v[190:193], v[60:63]
	v_mfma_f32_16x16x32_bf16 v[186:189], v[124:127], v[194:197], v[8:11]
	v_mfma_f32_16x16x32_bf16 v[8:11], v[174:177], v[190:193], v[100:103]
	v_mfma_f32_16x16x32_bf16 v[190:193], v[178:181], v[194:197], v[8:11]
	v_mfma_f32_16x16x32_bf16 v[8:11], v[120:123], v[198:201], v[16:19]
	v_mfma_f32_16x16x32_bf16 v[194:197], v[124:127], v[202:205], v[8:11]
	v_mfma_f32_16x16x32_bf16 v[8:11], v[174:177], v[198:201], v[20:23]
	v_mfma_f32_16x16x32_bf16 v[174:177], v[178:181], v[202:205], v[8:11]
	s_barrier
	s_nop 4
	ds_read_b128 v[8:11], v165
	ds_read_b128 v[12:15], v165 offset:1024
	ds_read_b128 v[16:19], v165 offset:2048
	ds_read_b128 v[20:23], v165 offset:3072
	ds_read_b128 v[178:181], v226
	ds_read_b128 v[198:201], v226 offset:1024
	ds_read_b128 v[202:205], v226 offset:2048
	ds_read_b128 v[226:229], v226 offset:3072
	s_add_u32 s40, s46, 0x10000
	s_addc_u32 s41, s47, 0
	s_mov_b32 m0, s54
	ds_read_b128 v[24:27], v163 offset:32768
	ds_read_b128 v[28:31], v163 offset:33792
	ds_read_b128 v[60:63], v163 offset:34816
	ds_read_b128 v[230:233], v163 offset:35840
	ds_read_b128 v[234:237], v163 offset:36864
	ds_read_b128 v[238:241], v163 offset:37888
	ds_read_b128 v[242:245], v163 offset:38912
	ds_read_b128 v[246:249], v163 offset:39936
	global_load_lds_dwordx4 v128, s[40:41]
	s_mov_b32 m0, s55
	s_nop 0
	global_load_lds_dwordx4 v132, s[40:41]
	s_waitcnt vmcnt(8)
	s_waitcnt lgkmcnt(0)
	s_barrier
	s_waitcnt lgkmcnt(0)
	v_mfma_f32_16x16x32_bf16 v[64:67], v[8:11], v[24:27], v[64:67]
	v_mfma_f32_16x16x32_bf16 v[124:127], v[12:15], v[28:31], v[64:67]
	v_mfma_f32_16x16x32_bf16 v[64:67], v[16:19], v[24:27], v[68:71]
	v_mfma_f32_16x16x32_bf16 v[120:123], v[20:23], v[28:31], v[64:67]
	v_mfma_f32_16x16x32_bf16 v[64:67], v[8:11], v[60:63], v[72:75]
	v_mfma_f32_16x16x32_bf16 v[108:111], v[12:15], v[230:233], v[64:67]
	v_mfma_f32_16x16x32_bf16 v[64:67], v[16:19], v[60:63], v[76:79]
	v_mfma_f32_16x16x32_bf16 v[104:107], v[20:23], v[230:233], v[64:67]
	v_mfma_f32_16x16x32_bf16 v[64:67], v[8:11], v[234:237], v[80:83]
	v_mfma_f32_16x16x32_bf16 v[92:95], v[12:15], v[238:241], v[64:67]
	v_mfma_f32_16x16x32_bf16 v[64:67], v[16:19], v[234:237], v[84:87]
	v_mfma_f32_16x16x32_bf16 v[88:91], v[20:23], v[238:241], v[64:67]
	v_mfma_f32_16x16x32_bf16 v[64:67], v[8:11], v[242:245], v[214:217]
	v_mfma_f32_16x16x32_bf16 v[68:71], v[12:15], v[246:249], v[64:67]
	v_mfma_f32_16x16x32_bf16 v[64:67], v[16:19], v[242:245], v[218:221]
	v_mfma_f32_16x16x32_bf16 v[64:67], v[20:23], v[246:249], v[64:67]
	v_mfma_f32_16x16x32_bf16 v[72:75], v[178:181], v[24:27], v[96:99]
	v_mfma_f32_16x16x32_bf16 v[24:27], v[202:205], v[24:27], v[32:35]
	v_mfma_f32_16x16x32_bf16 v[112:115], v[226:229], v[28:31], v[24:27]
	v_mfma_f32_16x16x32_bf16 v[24:27], v[178:181], v[60:63], v[36:39]
	v_mfma_f32_16x16x32_bf16 v[100:103], v[198:201], v[230:233], v[24:27]
	v_mfma_f32_16x16x32_bf16 v[24:27], v[202:205], v[60:63], v[40:43]
	v_mfma_f32_16x16x32_bf16 v[96:99], v[226:229], v[230:233], v[24:27]
	v_mfma_f32_16x16x32_bf16 v[24:27], v[178:181], v[234:237], v[44:47]
	v_mfma_f32_16x16x32_bf16 v[84:87], v[198:201], v[238:241], v[24:27]
	v_mfma_f32_16x16x32_bf16 v[24:27], v[202:205], v[234:237], v[48:51]
	v_mfma_f32_16x16x32_bf16 v[80:83], v[226:229], v[238:241], v[24:27]
	v_mfma_f32_16x16x32_bf16 v[24:27], v[178:181], v[242:245], v[52:55]
	v_mfma_f32_16x16x32_bf16 v[52:55], v[198:201], v[246:249], v[24:27]
	v_mfma_f32_16x16x32_bf16 v[24:27], v[202:205], v[242:245], v[56:59]
	v_mfma_f32_16x16x32_bf16 v[116:119], v[198:201], v[28:31], v[72:75]
	v_mfma_f32_16x16x32_bf16 v[48:51], v[226:229], v[246:249], v[24:27]
	s_barrier
	s_mov_b32 m0, s85
	s_nop 2
	v_lshl_add_u64 v[24:25], v[156:157], 0, s[8:9]
	s_add_u32 s40, s44, 0x10080
	ds_read_b128 v[32:35], v163 offset:49152
	ds_read_b128 v[36:39], v163 offset:50176
	ds_read_b128 v[214:217], v163 offset:51200
	ds_read_b128 v[218:221], v163 offset:52224
	ds_read_b128 v[230:233], v163 offset:53248
	ds_read_b128 v[234:237], v163 offset:54272
	ds_read_b128 v[238:241], v163 offset:55296
	ds_read_b128 v[242:245], v163 offset:56320
	global_load_lds_dwordx4 v[24:25], off
	v_lshl_add_u64 v[24:25], v[250:251], 0, s[8:9]
	s_mov_b32 m0, s69
	s_addc_u32 s41, s45, 0
	global_load_lds_dwordx4 v[24:25], off
	v_lshl_add_u64 v[24:25], s[40:41], 0, v[130:131]
	s_mov_b32 m0, s42
	s_nop 0
	global_load_lds_dwordx4 v[24:25], off
	s_mov_b32 m0, s43
	s_nop 0
	global_load_lds_dwordx4 v134, s[40:41]
	v_lshl_add_u64 v[24:25], v[252:253], 0, s[8:9]
	s_mov_b32 m0, s56
	s_nop 0
	global_load_lds_dwordx4 v[24:25], off
	v_lshl_add_u64 v[24:25], v[136:137], 0, s[8:9]
	s_mov_b32 m0, s57
	s_nop 0
	global_load_lds_dwordx4 v[24:25], off
	s_waitcnt vmcnt(8)
	s_waitcnt lgkmcnt(0)
	s_barrier
	s_waitcnt lgkmcnt(0)
	v_mfma_f32_16x16x32_bf16 v[24:27], v[8:11], v[32:35], v[140:143]
	v_mfma_f32_16x16x32_bf16 v[76:79], v[12:15], v[36:39], v[24:27]
	v_mfma_f32_16x16x32_bf16 v[24:27], v[16:19], v[32:35], v[144:147]
	v_mfma_f32_16x16x32_bf16 v[72:75], v[20:23], v[36:39], v[24:27]
	v_mfma_f32_16x16x32_bf16 v[24:27], v[8:11], v[214:217], v[148:151]
	v_mfma_f32_16x16x32_bf16 v[44:47], v[12:15], v[218:221], v[24:27]
	v_mfma_f32_16x16x32_bf16 v[24:27], v[16:19], v[214:217], v[152:155]
	v_mfma_f32_16x16x32_bf16 v[40:43], v[20:23], v[218:221], v[24:27]
	v_mfma_f32_16x16x32_bf16 v[24:27], v[8:11], v[230:233], v[166:169]
	v_mfma_f32_16x16x32_bf16 v[0:3], v[8:11], v[238:241], v[0:3]
	v_mfma_f32_16x16x32_bf16 v[28:31], v[12:15], v[234:237], v[24:27]
	v_mfma_f32_16x16x32_bf16 v[24:27], v[16:19], v[230:233], v[170:173]
	v_mfma_f32_16x16x32_bf16 v[12:15], v[12:15], v[242:245], v[0:3]
	v_mfma_f32_16x16x32_bf16 v[0:3], v[16:19], v[238:241], v[4:7]
	v_mfma_f32_16x16x32_bf16 v[24:27], v[20:23], v[234:237], v[24:27]
	v_mfma_f32_16x16x32_bf16 v[8:11], v[20:23], v[242:245], v[0:3]
	v_mfma_f32_16x16x32_bf16 v[0:3], v[178:181], v[32:35], v[206:209]
	v_mfma_f32_16x16x32_bf16 v[60:63], v[198:201], v[36:39], v[0:3]
	v_mfma_f32_16x16x32_bf16 v[0:3], v[202:205], v[32:35], v[210:213]
	v_mfma_f32_16x16x32_bf16 v[56:59], v[226:229], v[36:39], v[0:3]
	v_mfma_f32_16x16x32_bf16 v[0:3], v[178:181], v[214:217], v[222:225]
	v_mfma_f32_16x16x32_bf16 v[36:39], v[198:201], v[218:221], v[0:3]
	v_mfma_f32_16x16x32_bf16 v[0:3], v[202:205], v[214:217], v[182:185]
	v_mfma_f32_16x16x32_bf16 v[32:35], v[226:229], v[218:221], v[0:3]
	v_mfma_f32_16x16x32_bf16 v[0:3], v[178:181], v[230:233], v[186:189]
	v_mfma_f32_16x16x32_bf16 v[20:23], v[198:201], v[234:237], v[0:3]
	v_mfma_f32_16x16x32_bf16 v[0:3], v[202:205], v[230:233], v[190:193]
	v_mfma_f32_16x16x32_bf16 v[16:19], v[226:229], v[234:237], v[0:3]
	v_mfma_f32_16x16x32_bf16 v[0:3], v[178:181], v[238:241], v[194:197]
	v_mfma_f32_16x16x32_bf16 v[4:7], v[198:201], v[242:245], v[0:3]
	v_mfma_f32_16x16x32_bf16 v[0:3], v[202:205], v[238:241], v[174:177]
	v_mfma_f32_16x16x32_bf16 v[0:3], v[226:229], v[242:245], v[0:3]
	s_barrier
	s_andn2_b64 vcc, exec, s[12:13]
	s_cbranch_vccnz .LBB0_1282
	s_barrier

.LBB0_1324:
	s_andn2_b64 vcc, exec, s[4:5]
	s_cbranch_vccnz .LBB0_1360
	v_ashrrev_i32_e32 v2, 31, v0
	v_lshrrev_b32_e32 v2, 26, v2
	v_lshlrev_b32_e32 v1, 4, v0
	v_add_u32_e32 v2, v0, v2
	v_bfe_i32 v0, v0, 27, 1
	v_lshrrev_b32_e32 v0, 22, v0
	v_add_u32_e32 v0, v1, v0
	v_and_b32_e32 v0, 0xfffffc00, v0
	v_sub_u32_e32 v0, v1, v0
	v_ashrrev_i32_e32 v9, 6, v2
	v_lshrrev_b32_e32 v2, 4, v0
	v_bitop3_b32 v0, v2, v0, 32 bitop3:0x6c
	v_ashrrev_i32_e32 v3, 31, v0
	v_lshrrev_b32_e32 v3, 26, v3
	v_add_u32_e32 v3, v0, v3
	v_lshlrev_b32_e32 v2, 3, v9
	v_ashrrev_i32_e32 v10, 6, v3
	v_and_b32_e32 v3, 0xc0, v3
	v_and_b32_e32 v2, -16, v2
	v_sub_u32_e32 v0, v0, v3
	v_mov_b32_e32 v3, 1
	v_add_u32_e32 v2, v10, v2
	v_ashrrev_i16_sdwa v0, v3, sext(v0) dst_sel:DWORD dst_unused:UNUSED_PAD src0_sel:DWORD src1_sel:BYTE_0
	v_lshlrev_b32_e32 v4, 5, v9
	v_bfe_i32 v11, v0, 0, 16
	v_lshlrev_b32_e32 v0, 1, v2
	v_lshrrev_b32_e32 v5, 2, v2
	v_and_b32_e32 v6, 3, v10
	s_mov_b32 s3, 0x1fffe0
	v_and_b32_e32 v4, 32, v4
	v_and_b32_e32 v0, 24, v0
	v_and_b32_e32 v5, 4, v5
	v_and_or_b32 v6, v2, s3, v6
	v_or3_b32 v0, v6, v5, v0
	v_add_lshl_u32 v4, v4, v11, 1
	v_lshl_add_u32 v130, v0, 11, v4
	v_add_u32_e32 v0, 0x2000, v1
	v_ashrrev_i32_e32 v1, 31, v0
	v_lshrrev_b32_e32 v1, 22, v1
	v_add_u32_e32 v1, v0, v1
	v_ashrrev_i32_e32 v12, 10, v1
	v_mul_i32_i24_e32 v1, 0x400, v12
	v_sub_u32_e32 v0, v0, v1
	v_lshrrev_b32_e32 v1, 4, v0
	v_bitop3_b32 v0, v1, v0, 32 bitop3:0x6c
	v_lshl_add_u32 v128, v2, 11, v4
	v_ashrrev_i32_e32 v2, 31, v0
	v_lshrrev_b32_e32 v2, 26, v2
	v_add_u32_e32 v2, v0, v2
	v_lshlrev_b32_e32 v1, 3, v12
	v_ashrrev_i32_e32 v13, 6, v2
	v_and_b32_e32 v2, 0xc0, v2
	s_add_u32 s30, s70, 0x5600000
	v_and_b32_e32 v1, -16, v1
	v_sub_u32_e32 v0, v0, v2
	s_addc_u32 s31, s71, 0
	s_ashr_i32 s2, s12, 6
	v_add_u32_e32 v1, v13, v1
	v_ashrrev_i16_sdwa v0, v3, sext(v0) dst_sel:DWORD dst_unused:UNUSED_PAD src0_sel:DWORD src1_sel:BYTE_0
	v_and_b32_e32 v3, 3, v13
	s_ashr_i32 s23, s22, 31
	s_ashr_i32 s7, s6, 31
	v_and_or_b32 v3, v1, s3, v3
	s_ashr_i32 s3, s12, 8
	s_lshl_b32 s34, s2, 10
	s_lshl_b64 s[4:5], s[22:23], 19
	s_lshl_b64 s[8:9], s[6:7], 19
	s_add_u32 s26, s30, s8
	v_lshlrev_b32_e32 v4, 5, v12
	v_bfe_i32 v14, v0, 0, 16
	v_lshlrev_b32_e32 v0, 1, v1
	v_lshrrev_b32_e32 v2, 2, v1
	s_addc_u32 s27, s31, s9
	s_add_i32 s35, s34, 0
	v_and_b32_e32 v4, 32, v4
	v_and_b32_e32 v0, 24, v0
	v_and_b32_e32 v2, 4, v2
	s_add_i32 m0, s35, 0x10000
	v_or3_b32 v0, v3, v2, v0
	v_add_lshl_u32 v2, v4, v14, 1
	global_load_lds_dwordx4 v130, s[26:27]
	s_add_i32 m0, s35, 0x12000
	v_lshl_add_u32 v134, v0, 11, v2
	s_add_u32 s8, s26, 0x40000
	global_load_lds_dwordx4 v134, s[26:27]
	s_addc_u32 s9, s27, 0
	s_add_i32 m0, s35, 0x14000
	v_lshl_add_u32 v132, v1, 11, v2
	global_load_lds_dwordx4 v130, s[8:9]
	s_add_i32 m0, s35, 0x16000
	s_add_u32 s24, s76, s4
	s_addc_u32 s25, s77, s5
	s_add_i32 s36, s35, 0x2000
	global_load_lds_dwordx4 v134, s[8:9]
	s_mov_b32 m0, s35
	s_add_u32 s4, s24, 0x40000
	global_load_lds_dwordx4 v128, s[24:25]
	s_mov_b32 m0, s36
	s_addc_u32 s5, s25, 0
	s_add_i32 s37, s35, 0x4000
	global_load_lds_dwordx4 v132, s[24:25]
	s_mov_b32 m0, s37
	s_add_i32 s38, s35, 0x6000
	global_load_lds_dwordx4 v128, s[4:5]
	s_mov_b32 m0, s38
	v_mov_b32_e32 v131, 0
	global_load_lds_dwordx4 v132, s[4:5]
	v_mov_b32_e32 v135, v131
	v_mov_b32_e32 v129, v131
	v_mov_b32_e32 v133, v131
	s_cmp_eq_u32 s3, 1
	s_mov_b32 s7, 0
	v_lshl_add_u64 v[6:7], s[26:27], 0, v[130:131]
	v_lshl_add_u64 v[4:5], s[26:27], 0, v[134:135]
	v_lshl_add_u64 v[0:1], s[24:25], 0, v[128:129]
	s_cselect_b64 s[8:9], -1, 0
	s_cmp_lg_u32 s3, 1
	v_lshl_add_u64 v[2:3], s[24:25], 0, v[132:133]
	s_setprio 1
	s_cbranch_scc1 .LBB0_1327
	s_barrier
	s_setprio 0

.LBB0_1337:
	ds_read_b128 v[144:147], v151
	ds_read_b128 v[156:159], v151 offset:1024
	ds_read_b128 v[160:163], v151 offset:2048
	ds_read_b128 v[164:167], v151 offset:3072
	ds_read_b128 v[168:171], v152
	ds_read_b128 v[172:175], v152 offset:1024
	ds_read_b128 v[176:179], v152 offset:2048
	ds_read_b128 v[180:183], v152 offset:3072
	s_add_u32 s26, s24, 0xfffc0080
	s_addc_u32 s27, s25, -1
	s_cmp_eq_u32 s50, 12
	s_cselect_b32 s29, s17, s27
	s_cselect_b32 s28, s23, s26
	s_cselect_b32 s27, s15, s49
	s_cselect_b32 s26, s47, s48
	s_add_i32 m0, s35, 0xc000
	ds_read_b128 v[184:187], v153
	ds_read_b128 v[188:191], v153 offset:1024
	ds_read_b128 v[192:195], v153 offset:2048
	ds_read_b128 v[196:199], v153 offset:3072
	ds_read_b128 v[200:203], v153 offset:4096
	ds_read_b128 v[204:207], v153 offset:5120
	ds_read_b128 v[208:211], v153 offset:6144
	ds_read_b128 v[212:215], v153 offset:7168
	global_load_lds_dwordx4 v136, s[24:25]
	s_add_i32 m0, s35, 0xe000
	s_nop 0
	global_load_lds_dwordx4 v138, s[24:25]
	s_waitcnt vmcnt(8)
	s_waitcnt lgkmcnt(0)
	s_barrier
	s_waitcnt lgkmcnt(0)
	v_mfma_f32_16x16x32_bf16 v[124:127], v[144:147], v[184:187], v[124:127]
	v_mfma_f32_16x16x32_bf16 v[120:123], v[160:163], v[184:187], v[120:123]
	v_mfma_f32_16x16x32_bf16 v[108:111], v[144:147], v[192:195], v[108:111]
	v_mfma_f32_16x16x32_bf16 v[104:107], v[160:163], v[192:195], v[104:107]
	v_mfma_f32_16x16x32_bf16 v[92:95], v[144:147], v[200:203], v[92:95]
	v_mfma_f32_16x16x32_bf16 v[88:91], v[160:163], v[200:203], v[88:91]
	v_mfma_f32_16x16x32_bf16 v[76:79], v[144:147], v[208:211], v[76:79]
	v_mfma_f32_16x16x32_bf16 v[72:75], v[160:163], v[208:211], v[72:75]
	v_mfma_f32_16x16x32_bf16 v[124:127], v[156:159], v[188:191], v[124:127]
	v_mfma_f32_16x16x32_bf16 v[120:123], v[164:167], v[188:191], v[120:123]
	v_mfma_f32_16x16x32_bf16 v[108:111], v[156:159], v[196:199], v[108:111]
	v_mfma_f32_16x16x32_bf16 v[104:107], v[164:167], v[196:199], v[104:107]
	v_mfma_f32_16x16x32_bf16 v[92:95], v[156:159], v[204:207], v[92:95]
	v_mfma_f32_16x16x32_bf16 v[88:91], v[164:167], v[204:207], v[88:91]
	v_mfma_f32_16x16x32_bf16 v[76:79], v[156:159], v[212:215], v[76:79]
	v_mfma_f32_16x16x32_bf16 v[72:75], v[164:167], v[212:215], v[72:75]
	v_mfma_f32_16x16x32_bf16 v[116:119], v[168:171], v[184:187], v[116:119]
	v_mfma_f32_16x16x32_bf16 v[112:115], v[176:179], v[184:187], v[112:115]
	v_mfma_f32_16x16x32_bf16 v[100:103], v[168:171], v[192:195], v[100:103]
	v_mfma_f32_16x16x32_bf16 v[96:99], v[176:179], v[192:195], v[96:99]
	v_mfma_f32_16x16x32_bf16 v[84:87], v[168:171], v[200:203], v[84:87]
	v_mfma_f32_16x16x32_bf16 v[80:83], v[176:179], v[200:203], v[80:83]
	v_mfma_f32_16x16x32_bf16 v[68:71], v[168:171], v[208:211], v[68:71]
	v_mfma_f32_16x16x32_bf16 v[64:67], v[176:179], v[208:211], v[64:67]
	v_mfma_f32_16x16x32_bf16 v[116:119], v[172:175], v[188:191], v[116:119]
	v_mfma_f32_16x16x32_bf16 v[112:115], v[180:183], v[188:191], v[112:115]
	v_mfma_f32_16x16x32_bf16 v[100:103], v[172:175], v[196:199], v[100:103]
	v_mfma_f32_16x16x32_bf16 v[96:99], v[180:183], v[196:199], v[96:99]
	v_mfma_f32_16x16x32_bf16 v[84:87], v[172:175], v[204:207], v[84:87]
	v_mfma_f32_16x16x32_bf16 v[80:83], v[180:183], v[204:207], v[80:83]
	v_mfma_f32_16x16x32_bf16 v[68:71], v[172:175], v[212:215], v[68:71]
	v_mfma_f32_16x16x32_bf16 v[64:67], v[180:183], v[212:215], v[64:67]
	s_barrier
	s_add_i32 s51, s44, s34
	v_lshl_add_u64 v[216:217], s[26:27], 0, v[130:131]
	s_mov_b32 m0, s51
	ds_read_b128 v[184:187], v153 offset:16384
	ds_read_b128 v[188:191], v153 offset:17408
	ds_read_b128 v[192:195], v153 offset:18432
	ds_read_b128 v[196:199], v153 offset:19456
	ds_read_b128 v[200:203], v153 offset:20480
	ds_read_b128 v[204:207], v153 offset:21504
	ds_read_b128 v[208:211], v153 offset:22528
	ds_read_b128 v[212:215], v153 offset:23552
	global_load_lds_dwordx4 v[216:217], off
	s_add_i32 m0, s51, 0x2000
	s_add_u32 s52, s26, 0x40000
	v_lshl_add_u64 v[218:219], s[26:27], 0, v[134:135]
	s_addc_u32 s53, s27, 0
	s_add_i32 s51, s45, s34
	global_load_lds_dwordx4 v[218:219], off
	v_lshl_add_u64 v[220:221], s[52:53], 0, v[130:131]
	s_mov_b32 m0, s51
	v_lshl_add_u64 v[222:223], s[28:29], 0, v[132:133]
	global_load_lds_dwordx4 v[220:221], off
	s_add_i32 m0, s51, 0x2000
	s_nop 0
	global_load_lds_dwordx4 v134, s[52:53]
	v_lshl_add_u64 v[220:221], s[28:29], 0, v[128:129]
	s_mov_b32 m0, s35
	s_nop 0
	global_load_lds_dwordx4 v[220:221], off
	s_mov_b32 m0, s36
	s_nop 0
	global_load_lds_dwordx4 v[222:223], off
	s_waitcnt vmcnt(8)
	s_waitcnt lgkmcnt(0)
	s_barrier
	s_waitcnt lgkmcnt(0)
	v_mfma_f32_16x16x32_bf16 v[60:63], v[144:147], v[184:187], v[60:63]
	v_mfma_f32_16x16x32_bf16 v[56:59], v[160:163], v[184:187], v[56:59]
	v_mfma_f32_16x16x32_bf16 v[44:47], v[144:147], v[192:195], v[44:47]
	v_mfma_f32_16x16x32_bf16 v[40:43], v[160:163], v[192:195], v[40:43]
	v_mfma_f32_16x16x32_bf16 v[28:31], v[144:147], v[200:203], v[28:31]
	v_mfma_f32_16x16x32_bf16 v[24:27], v[160:163], v[200:203], v[24:27]
	v_mfma_f32_16x16x32_bf16 v[12:15], v[144:147], v[208:211], v[12:15]
	v_mfma_f32_16x16x32_bf16 v[8:11], v[160:163], v[208:211], v[8:11]
	v_mfma_f32_16x16x32_bf16 v[60:63], v[156:159], v[188:191], v[60:63]
	v_mfma_f32_16x16x32_bf16 v[56:59], v[164:167], v[188:191], v[56:59]
	v_mfma_f32_16x16x32_bf16 v[44:47], v[156:159], v[196:199], v[44:47]
	v_mfma_f32_16x16x32_bf16 v[40:43], v[164:167], v[196:199], v[40:43]
	v_mfma_f32_16x16x32_bf16 v[28:31], v[156:159], v[204:207], v[28:31]
	v_mfma_f32_16x16x32_bf16 v[24:27], v[164:167], v[204:207], v[24:27]
	v_mfma_f32_16x16x32_bf16 v[12:15], v[156:159], v[212:215], v[12:15]
	v_mfma_f32_16x16x32_bf16 v[8:11], v[164:167], v[212:215], v[8:11]
	v_mfma_f32_16x16x32_bf16 v[52:55], v[168:171], v[184:187], v[52:55]
	v_mfma_f32_16x16x32_bf16 v[48:51], v[176:179], v[184:187], v[48:51]
	v_mfma_f32_16x16x32_bf16 v[36:39], v[168:171], v[192:195], v[36:39]
	v_mfma_f32_16x16x32_bf16 v[32:35], v[176:179], v[192:195], v[32:35]
	v_mfma_f32_16x16x32_bf16 v[20:23], v[168:171], v[200:203], v[20:23]
	v_mfma_f32_16x16x32_bf16 v[16:19], v[176:179], v[200:203], v[16:19]
	v_mfma_f32_16x16x32_bf16 v[4:7], v[168:171], v[208:211], v[4:7]
	v_mfma_f32_16x16x32_bf16 v[0:3], v[176:179], v[208:211], v[0:3]
	v_mfma_f32_16x16x32_bf16 v[52:55], v[172:175], v[188:191], v[52:55]
	v_mfma_f32_16x16x32_bf16 v[48:51], v[180:183], v[188:191], v[48:51]
	v_mfma_f32_16x16x32_bf16 v[36:39], v[172:175], v[196:199], v[36:39]
	v_mfma_f32_16x16x32_bf16 v[32:35], v[180:183], v[196:199], v[32:35]
	v_mfma_f32_16x16x32_bf16 v[20:23], v[172:175], v[204:207], v[20:23]
	v_mfma_f32_16x16x32_bf16 v[16:19], v[180:183], v[204:207], v[16:19]
	v_mfma_f32_16x16x32_bf16 v[4:7], v[172:175], v[212:215], v[4:7]
	v_mfma_f32_16x16x32_bf16 v[0:3], v[180:183], v[212:215], v[0:3]
	s_barrier
	s_add_i32 s51, 0, 0x18000
	s_add_i32 s52, 0, 0x1c000
	v_add_u32_e32 v164, s51, v149
	v_add_u32_e32 v180, s52, v149
	ds_read_b128 v[144:147], v164
	ds_read_b128 v[156:159], v164 offset:1024
	ds_read_b128 v[160:163], v164 offset:2048
	ds_read_b128 v[164:167], v164 offset:3072
	ds_read_b128 v[168:171], v180
	ds_read_b128 v[172:175], v180 offset:1024
	ds_read_b128 v[176:179], v180 offset:2048
	ds_read_b128 v[180:183], v180 offset:3072
	s_add_u32 s28, s28, 0x40000
	s_addc_u32 s29, s29, 0
	s_mov_b32 m0, s37
	ds_read_b128 v[184:187], v153 offset:32768
	ds_read_b128 v[188:191], v153 offset:33792
	ds_read_b128 v[192:195], v153 offset:34816
	ds_read_b128 v[196:199], v153 offset:35840
	ds_read_b128 v[200:203], v153 offset:36864
	ds_read_b128 v[204:207], v153 offset:37888
	ds_read_b128 v[208:211], v153 offset:38912
	ds_read_b128 v[212:215], v153 offset:39936
	global_load_lds_dwordx4 v128, s[28:29]
	v_lshl_add_u64 v[224:225], s[28:29], 0, v[132:133]
	s_mov_b32 m0, s38
	s_nop 0
	global_load_lds_dwordx4 v[224:225], off
	s_waitcnt vmcnt(8)
	s_waitcnt lgkmcnt(0)
	s_barrier
	s_waitcnt lgkmcnt(0)
	v_mfma_f32_16x16x32_bf16 v[124:127], v[144:147], v[184:187], v[124:127]
	v_mfma_f32_16x16x32_bf16 v[120:123], v[160:163], v[184:187], v[120:123]
	v_mfma_f32_16x16x32_bf16 v[108:111], v[144:147], v[192:195], v[108:111]
	v_mfma_f32_16x16x32_bf16 v[104:107], v[160:163], v[192:195], v[104:107]
	v_mfma_f32_16x16x32_bf16 v[92:95], v[144:147], v[200:203], v[92:95]
	v_mfma_f32_16x16x32_bf16 v[88:91], v[160:163], v[200:203], v[88:91]
	v_mfma_f32_16x16x32_bf16 v[76:79], v[144:147], v[208:211], v[76:79]
	v_mfma_f32_16x16x32_bf16 v[72:75], v[160:163], v[208:211], v[72:75]
	v_mfma_f32_16x16x32_bf16 v[124:127], v[156:159], v[188:191], v[124:127]
	v_mfma_f32_16x16x32_bf16 v[120:123], v[164:167], v[188:191], v[120:123]
	v_mfma_f32_16x16x32_bf16 v[108:111], v[156:159], v[196:199], v[108:111]
	v_mfma_f32_16x16x32_bf16 v[104:107], v[164:167], v[196:199], v[104:107]
	v_mfma_f32_16x16x32_bf16 v[92:95], v[156:159], v[204:207], v[92:95]
	v_mfma_f32_16x16x32_bf16 v[88:91], v[164:167], v[204:207], v[88:91]
	v_mfma_f32_16x16x32_bf16 v[76:79], v[156:159], v[212:215], v[76:79]
	v_mfma_f32_16x16x32_bf16 v[72:75], v[164:167], v[212:215], v[72:75]
	v_mfma_f32_16x16x32_bf16 v[116:119], v[168:171], v[184:187], v[116:119]
	v_mfma_f32_16x16x32_bf16 v[112:115], v[176:179], v[184:187], v[112:115]
	v_mfma_f32_16x16x32_bf16 v[100:103], v[168:171], v[192:195], v[100:103]
	v_mfma_f32_16x16x32_bf16 v[96:99], v[176:179], v[192:195], v[96:99]
	v_mfma_f32_16x16x32_bf16 v[84:87], v[168:171], v[200:203], v[84:87]
	v_mfma_f32_16x16x32_bf16 v[80:83], v[176:179], v[200:203], v[80:83]
	v_mfma_f32_16x16x32_bf16 v[68:71], v[168:171], v[208:211], v[68:71]
	v_mfma_f32_16x16x32_bf16 v[64:67], v[176:179], v[208:211], v[64:67]
	v_mfma_f32_16x16x32_bf16 v[116:119], v[172:175], v[188:191], v[116:119]
	v_mfma_f32_16x16x32_bf16 v[112:115], v[180:183], v[188:191], v[112:115]
	v_mfma_f32_16x16x32_bf16 v[100:103], v[172:175], v[196:199], v[100:103]
	v_mfma_f32_16x16x32_bf16 v[96:99], v[180:183], v[196:199], v[96:99]
	v_mfma_f32_16x16x32_bf16 v[84:87], v[172:175], v[204:207], v[84:87]
	v_mfma_f32_16x16x32_bf16 v[80:83], v[180:183], v[204:207], v[80:83]
	v_mfma_f32_16x16x32_bf16 v[68:71], v[172:175], v[212:215], v[68:71]
	v_mfma_f32_16x16x32_bf16 v[64:67], v[180:183], v[212:215], v[64:67]
	s_barrier
	s_add_i32 s28, s51, s34
	v_lshl_add_u64 v[216:217], v[216:217], 0, s[10:11]
	s_mov_b32 m0, s28
	ds_read_b128 v[184:187], v153 offset:49152
	ds_read_b128 v[188:191], v153 offset:50176
	ds_read_b128 v[192:195], v153 offset:51200
	ds_read_b128 v[196:199], v153 offset:52224
	ds_read_b128 v[200:203], v153 offset:53248
	ds_read_b128 v[204:207], v153 offset:54272
	ds_read_b128 v[208:211], v153 offset:55296
	ds_read_b128 v[212:215], v153 offset:56320
	global_load_lds_dwordx4 v[216:217], off
	s_add_i32 m0, s28, 0x2000
	s_add_u32 s26, s26, 0x40080
	v_lshl_add_u64 v[216:217], v[218:219], 0, s[10:11]
	s_addc_u32 s27, s27, 0
	s_add_i32 s28, s52, s34
	global_load_lds_dwordx4 v[216:217], off
	v_lshl_add_u64 v[216:217], s[26:27], 0, v[130:131]
	s_mov_b32 m0, s28
	s_nop 0
	global_load_lds_dwordx4 v[216:217], off
	s_add_i32 m0, s28, 0x2000
	s_nop 0
	global_load_lds_dwordx4 v134, s[26:27]
	v_lshl_add_u64 v[216:217], v[220:221], 0, s[10:11]
	s_mov_b32 m0, s40
	s_nop 0
	global_load_lds_dwordx4 v[216:217], off
	v_lshl_add_u64 v[216:217], v[222:223], 0, s[10:11]
	s_mov_b32 m0, s41
	s_nop 0
	global_load_lds_dwordx4 v[216:217], off
	s_waitcnt vmcnt(8)
	s_waitcnt lgkmcnt(0)
	s_barrier
	s_waitcnt lgkmcnt(0)
	v_mfma_f32_16x16x32_bf16 v[60:63], v[144:147], v[184:187], v[60:63]
	v_mfma_f32_16x16x32_bf16 v[56:59], v[160:163], v[184:187], v[56:59]
	v_mfma_f32_16x16x32_bf16 v[44:47], v[144:147], v[192:195], v[44:47]
	v_mfma_f32_16x16x32_bf16 v[40:43], v[160:163], v[192:195], v[40:43]
	v_mfma_f32_16x16x32_bf16 v[28:31], v[144:147], v[200:203], v[28:31]
	v_mfma_f32_16x16x32_bf16 v[24:27], v[160:163], v[200:203], v[24:27]
	v_mfma_f32_16x16x32_bf16 v[12:15], v[144:147], v[208:211], v[12:15]
	v_mfma_f32_16x16x32_bf16 v[8:11], v[160:163], v[208:211], v[8:11]
	v_mfma_f32_16x16x32_bf16 v[60:63], v[156:159], v[188:191], v[60:63]
	v_mfma_f32_16x16x32_bf16 v[56:59], v[164:167], v[188:191], v[56:59]
	v_mfma_f32_16x16x32_bf16 v[44:47], v[156:159], v[196:199], v[44:47]
	v_mfma_f32_16x16x32_bf16 v[40:43], v[164:167], v[196:199], v[40:43]
	v_mfma_f32_16x16x32_bf16 v[28:31], v[156:159], v[204:207], v[28:31]
	v_mfma_f32_16x16x32_bf16 v[24:27], v[164:167], v[204:207], v[24:27]
	v_mfma_f32_16x16x32_bf16 v[12:15], v[156:159], v[212:215], v[12:15]
	v_mfma_f32_16x16x32_bf16 v[8:11], v[164:167], v[212:215], v[8:11]
	v_mfma_f32_16x16x32_bf16 v[52:55], v[168:171], v[184:187], v[52:55]
	v_mfma_f32_16x16x32_bf16 v[48:51], v[176:179], v[184:187], v[48:51]
	v_mfma_f32_16x16x32_bf16 v[36:39], v[168:171], v[192:195], v[36:39]
	v_mfma_f32_16x16x32_bf16 v[32:35], v[176:179], v[192:195], v[32:35]
	v_mfma_f32_16x16x32_bf16 v[20:23], v[168:171], v[200:203], v[20:23]
	v_mfma_f32_16x16x32_bf16 v[16:19], v[176:179], v[200:203], v[16:19]
	v_mfma_f32_16x16x32_bf16 v[4:7], v[168:171], v[208:211], v[4:7]
	v_mfma_f32_16x16x32_bf16 v[0:3], v[176:179], v[208:211], v[0:3]
	v_mfma_f32_16x16x32_bf16 v[52:55], v[172:175], v[188:191], v[52:55]
	v_mfma_f32_16x16x32_bf16 v[48:51], v[180:183], v[188:191], v[48:51]
	v_mfma_f32_16x16x32_bf16 v[36:39], v[172:175], v[196:199], v[36:39]
	v_mfma_f32_16x16x32_bf16 v[32:35], v[180:183], v[196:199], v[32:35]
	v_mfma_f32_16x16x32_bf16 v[20:23], v[172:175], v[204:207], v[20:23]
	v_mfma_f32_16x16x32_bf16 v[16:19], v[180:183], v[204:207], v[16:19]
	v_mfma_f32_16x16x32_bf16 v[4:7], v[172:175], v[212:215], v[4:7]
	v_mfma_f32_16x16x32_bf16 v[0:3], v[180:183], v[212:215], v[0:3]
	s_add_i32 s50, s50, 2
	s_add_u32 s24, s24, 0x100
	s_addc_u32 s25, s25, 0
	s_add_u32 s48, s48, 0x100
	s_addc_u32 s49, s49, 0
	s_cmp_gt_u32 s50, 13
	s_barrier
	s_cbranch_scc0 .LBB0_1337
	s_and_b64 vcc, exec, s[12:13]
	s_cbranch_vccz .LBB0_1340
	s_barrier

.LBB0_1394:
	s_andn2_b64 vcc, exec, s[8:9]
	s_cbranch_vccnz .LBB0_1442
	v_ashrrev_i32_e32 v2, 31, v0
	v_lshrrev_b32_e32 v2, 26, v2
	v_lshlrev_b32_e32 v1, 4, v0
	v_add_u32_e32 v2, v0, v2
	v_bfe_i32 v0, v0, 27, 1
	v_lshrrev_b32_e32 v0, 22, v0
	v_add_u32_e32 v0, v1, v0
	v_and_b32_e32 v0, 0xfffffc00, v0
	v_sub_u32_e32 v0, v1, v0
	v_ashrrev_i32_e32 v9, 6, v2
	v_lshrrev_b32_e32 v2, 4, v0
	v_bitop3_b32 v0, v2, v0, 32 bitop3:0x6c
	v_ashrrev_i32_e32 v3, 31, v0
	v_lshrrev_b32_e32 v3, 26, v3
	v_add_u32_e32 v3, v0, v3
	v_lshlrev_b32_e32 v2, 3, v9
	v_ashrrev_i32_e32 v10, 6, v3
	v_and_b32_e32 v3, 0xc0, v3
	v_and_b32_e32 v2, -16, v2
	v_sub_u32_e32 v0, v0, v3
	v_mov_b32_e32 v3, 1
	v_add_u32_e32 v2, v10, v2
	v_ashrrev_i16_sdwa v0, v3, sext(v0) dst_sel:DWORD dst_unused:UNUSED_PAD src0_sel:DWORD src1_sel:BYTE_0
	v_lshlrev_b32_e32 v4, 5, v9
	v_bfe_i32 v11, v0, 0, 16
	v_lshlrev_b32_e32 v0, 1, v2
	v_lshrrev_b32_e32 v5, 2, v2
	v_and_b32_e32 v6, 3, v10
	s_mov_b32 s3, 0x3fffe0
	v_and_b32_e32 v4, 32, v4
	v_and_b32_e32 v0, 24, v0
	v_and_b32_e32 v5, 4, v5
	v_and_or_b32 v6, v2, s3, v6
	v_or3_b32 v0, v6, v5, v0
	v_add_lshl_u32 v4, v4, v11, 1
	v_lshl_add_u32 v134, v0, 10, v4
	v_add_u32_e32 v0, 0x2000, v1
	v_ashrrev_i32_e32 v1, 31, v0
	v_lshrrev_b32_e32 v1, 22, v1
	v_add_u32_e32 v1, v0, v1
	v_ashrrev_i32_e32 v12, 10, v1
	v_mul_i32_i24_e32 v1, 0x400, v12
	v_sub_u32_e32 v0, v0, v1
	v_lshrrev_b32_e32 v1, 4, v0
	v_bitop3_b32 v0, v1, v0, 32 bitop3:0x6c
	v_lshl_add_u32 v132, v2, 10, v4
	v_ashrrev_i32_e32 v2, 31, v0
	v_lshrrev_b32_e32 v2, 26, v2
	v_add_u32_e32 v2, v0, v2
	v_lshlrev_b32_e32 v1, 3, v12
	v_ashrrev_i32_e32 v13, 6, v2
	v_and_b32_e32 v2, 0xc0, v2
	s_add_u32 s36, s70, 0x5700000
	v_and_b32_e32 v1, -16, v1
	v_sub_u32_e32 v0, v0, v2
	s_addc_u32 s37, s71, 0
	s_ashr_i32 s2, s16, 6
	v_add_u32_e32 v1, v13, v1
	v_ashrrev_i16_sdwa v0, v3, sext(v0) dst_sel:DWORD dst_unused:UNUSED_PAD src0_sel:DWORD src1_sel:BYTE_0
	v_and_b32_e32 v3, 3, v13
	s_ashr_i32 s7, s6, 31
	s_ashr_i32 s5, s4, 31
	v_and_or_b32 v3, v1, s3, v3
	s_ashr_i32 s3, s16, 8
	s_lshl_b32 s38, s2, 10
	s_lshl_b64 s[8:9], s[6:7], 18
	s_lshl_b64 s[10:11], s[4:5], 18
	s_add_u32 s30, s36, s10
	v_lshlrev_b32_e32 v4, 5, v12
	v_bfe_i32 v14, v0, 0, 16
	v_lshlrev_b32_e32 v0, 1, v1
	v_lshrrev_b32_e32 v2, 2, v1
	s_addc_u32 s31, s37, s11
	s_add_i32 s39, s38, 0
	v_and_b32_e32 v4, 32, v4
	v_and_b32_e32 v0, 24, v0
	v_and_b32_e32 v2, 4, v2
	s_add_i32 m0, s39, 0x10000
	v_or3_b32 v0, v3, v2, v0
	v_add_lshl_u32 v2, v4, v14, 1
	global_load_lds_dwordx4 v134, s[30:31]
	s_add_i32 m0, s39, 0x12000
	v_lshl_add_u32 v138, v0, 10, v2
	s_add_u32 s10, s30, 0x20000
	global_load_lds_dwordx4 v138, s[30:31]
	s_addc_u32 s11, s31, 0
	s_add_i32 m0, s39, 0x14000
	v_lshl_add_u32 v136, v1, 10, v2
	global_load_lds_dwordx4 v134, s[10:11]
	s_add_i32 m0, s39, 0x16000
	s_add_u32 s28, s72, s8
	s_addc_u32 s29, s73, s9
	s_add_i32 s40, s39, 0x2000
	global_load_lds_dwordx4 v138, s[10:11]
	s_mov_b32 m0, s39
	s_add_u32 s8, s28, 0x20000
	global_load_lds_dwordx4 v132, s[28:29]
	s_mov_b32 m0, s40
	s_addc_u32 s9, s29, 0
	s_add_i32 s41, s39, 0x4000
	global_load_lds_dwordx4 v136, s[28:29]
	s_mov_b32 m0, s41
	s_add_i32 s42, s39, 0x6000
	global_load_lds_dwordx4 v132, s[8:9]
	s_mov_b32 m0, s42
	v_mov_b32_e32 v141, 0
	global_load_lds_dwordx4 v136, s[8:9]
	v_mov_b32_e32 v135, v141
	v_mov_b32_e32 v139, v141
	v_mov_b32_e32 v133, v141
	v_mov_b32_e32 v137, v141
	s_cmp_eq_u32 s3, 1
	s_mov_b32 s7, 0
	v_lshl_add_u64 v[6:7], s[30:31], 0, v[134:135]
	v_lshl_add_u64 v[4:5], s[30:31], 0, v[138:139]
	v_lshl_add_u64 v[0:1], s[28:29], 0, v[132:133]
	s_cselect_b64 s[8:9], -1, 0
	s_cmp_lg_u32 s3, 1
	v_lshl_add_u64 v[2:3], s[28:29], 0, v[136:137]
	s_setprio 1
	s_cbranch_scc1 .LBB0_1397
	s_barrier
	s_setprio 0

.LBB0_1403:
	ds_read_b128 v[128:131], v164
	ds_read_b128 v[160:163], v164 offset:1024
	ds_read_b128 v[168:171], v164 offset:2048
	ds_read_b128 v[172:175], v164 offset:3072
	ds_read_b128 v[176:179], v165
	ds_read_b128 v[180:183], v165 offset:1024
	ds_read_b128 v[184:187], v165 offset:2048
	ds_read_b128 v[188:191], v165 offset:3072
	s_add_u32 s30, s28, 0xfffe0080
	s_addc_u32 s31, s29, -1
	s_cmp_eq_u32 s56, 4
	s_cselect_b32 s35, s5, s31
	s_cselect_b32 s34, s23, s30
	s_cselect_b32 s31, s21, s55
	s_cselect_b32 s30, s53, s54
	s_add_i32 m0, s39, 0xc000
	ds_read_b128 v[192:195], v166
	ds_read_b128 v[196:199], v166 offset:1024
	ds_read_b128 v[200:203], v166 offset:2048
	ds_read_b128 v[204:207], v166 offset:3072
	ds_read_b128 v[208:211], v166 offset:4096
	ds_read_b128 v[212:215], v166 offset:5120
	ds_read_b128 v[216:219], v166 offset:6144
	ds_read_b128 v[220:223], v166 offset:7168
	global_load_lds_dwordx4 v148, s[28:29]
	s_add_i32 m0, s39, 0xe000
	s_nop 0
	global_load_lds_dwordx4 v150, s[28:29]
	s_waitcnt vmcnt(8)
	s_waitcnt lgkmcnt(0)
	s_barrier
	s_waitcnt lgkmcnt(0)
	v_mfma_f32_16x16x32_bf16 v[124:127], v[128:131], v[192:195], v[124:127]
	v_mfma_f32_16x16x32_bf16 v[120:123], v[168:171], v[192:195], v[120:123]
	v_mfma_f32_16x16x32_bf16 v[108:111], v[128:131], v[200:203], v[108:111]
	v_mfma_f32_16x16x32_bf16 v[104:107], v[168:171], v[200:203], v[104:107]
	v_mfma_f32_16x16x32_bf16 v[92:95], v[128:131], v[208:211], v[92:95]
	v_mfma_f32_16x16x32_bf16 v[88:91], v[168:171], v[208:211], v[88:91]
	v_mfma_f32_16x16x32_bf16 v[76:79], v[128:131], v[216:219], v[76:79]
	v_mfma_f32_16x16x32_bf16 v[72:75], v[168:171], v[216:219], v[72:75]
	v_mfma_f32_16x16x32_bf16 v[124:127], v[160:163], v[196:199], v[124:127]
	v_mfma_f32_16x16x32_bf16 v[120:123], v[172:175], v[196:199], v[120:123]
	v_mfma_f32_16x16x32_bf16 v[108:111], v[160:163], v[204:207], v[108:111]
	v_mfma_f32_16x16x32_bf16 v[104:107], v[172:175], v[204:207], v[104:107]
	v_mfma_f32_16x16x32_bf16 v[92:95], v[160:163], v[212:215], v[92:95]
	v_mfma_f32_16x16x32_bf16 v[88:91], v[172:175], v[212:215], v[88:91]
	v_mfma_f32_16x16x32_bf16 v[76:79], v[160:163], v[220:223], v[76:79]
	v_mfma_f32_16x16x32_bf16 v[72:75], v[172:175], v[220:223], v[72:75]
	v_mfma_f32_16x16x32_bf16 v[116:119], v[176:179], v[192:195], v[116:119]
	v_mfma_f32_16x16x32_bf16 v[112:115], v[184:187], v[192:195], v[112:115]
	v_mfma_f32_16x16x32_bf16 v[100:103], v[176:179], v[200:203], v[100:103]
	v_mfma_f32_16x16x32_bf16 v[96:99], v[184:187], v[200:203], v[96:99]
	v_mfma_f32_16x16x32_bf16 v[84:87], v[176:179], v[208:211], v[84:87]
	v_mfma_f32_16x16x32_bf16 v[80:83], v[184:187], v[208:211], v[80:83]
	v_mfma_f32_16x16x32_bf16 v[68:71], v[176:179], v[216:219], v[68:71]
	v_mfma_f32_16x16x32_bf16 v[64:67], v[184:187], v[216:219], v[64:67]
	v_mfma_f32_16x16x32_bf16 v[116:119], v[180:183], v[196:199], v[116:119]
	v_mfma_f32_16x16x32_bf16 v[112:115], v[188:191], v[196:199], v[112:115]
	v_mfma_f32_16x16x32_bf16 v[100:103], v[180:183], v[204:207], v[100:103]
	v_mfma_f32_16x16x32_bf16 v[96:99], v[188:191], v[204:207], v[96:99]
	v_mfma_f32_16x16x32_bf16 v[84:87], v[180:183], v[212:215], v[84:87]
	v_mfma_f32_16x16x32_bf16 v[80:83], v[188:191], v[212:215], v[80:83]
	v_mfma_f32_16x16x32_bf16 v[68:71], v[180:183], v[220:223], v[68:71]
	v_mfma_f32_16x16x32_bf16 v[64:67], v[188:191], v[220:223], v[64:67]
	s_barrier
	s_add_i32 s57, s50, s38
	v_lshl_add_u64 v[156:157], s[30:31], 0, v[134:135]
	s_mov_b32 m0, s57
	ds_read_b128 v[192:195], v166 offset:16384
	ds_read_b128 v[196:199], v166 offset:17408
	ds_read_b128 v[200:203], v166 offset:18432
	ds_read_b128 v[204:207], v166 offset:19456
	ds_read_b128 v[208:211], v166 offset:20480
	ds_read_b128 v[212:215], v166 offset:21504
	ds_read_b128 v[216:219], v166 offset:22528
	ds_read_b128 v[220:223], v166 offset:23552
	global_load_lds_dwordx4 v[156:157], off
	s_add_i32 m0, s57, 0x2000
	s_add_u32 s58, s30, 0x20000
	v_lshl_add_u64 v[224:225], s[30:31], 0, v[138:139]
	s_addc_u32 s59, s31, 0
	s_add_i32 s57, s51, s38
	global_load_lds_dwordx4 v[224:225], off
	s_mov_b32 m0, s57
	v_lshl_add_u64 v[228:229], s[34:35], 0, v[136:137]
	global_load_lds_dwordx4 v134, s[58:59]
	s_add_i32 m0, s57, 0x2000
	s_nop 0
	global_load_lds_dwordx4 v138, s[58:59]
	v_lshl_add_u64 v[226:227], s[34:35], 0, v[132:133]
	s_mov_b32 m0, s39
	s_nop 0
	global_load_lds_dwordx4 v[226:227], off
	s_mov_b32 m0, s40
	s_nop 0
	global_load_lds_dwordx4 v[228:229], off
	s_waitcnt vmcnt(8)
	s_waitcnt lgkmcnt(0)
	s_barrier
	s_waitcnt lgkmcnt(0)
	v_mfma_f32_16x16x32_bf16 v[60:63], v[128:131], v[192:195], v[60:63]
	v_mfma_f32_16x16x32_bf16 v[56:59], v[168:171], v[192:195], v[56:59]
	v_mfma_f32_16x16x32_bf16 v[44:47], v[128:131], v[200:203], v[44:47]
	v_mfma_f32_16x16x32_bf16 v[40:43], v[168:171], v[200:203], v[40:43]
	v_mfma_f32_16x16x32_bf16 v[28:31], v[128:131], v[208:211], v[28:31]
	v_mfma_f32_16x16x32_bf16 v[24:27], v[168:171], v[208:211], v[24:27]
	v_mfma_f32_16x16x32_bf16 v[12:15], v[128:131], v[216:219], v[12:15]
	v_mfma_f32_16x16x32_bf16 v[8:11], v[168:171], v[216:219], v[8:11]
	v_mfma_f32_16x16x32_bf16 v[60:63], v[160:163], v[196:199], v[60:63]
	v_mfma_f32_16x16x32_bf16 v[56:59], v[172:175], v[196:199], v[56:59]
	v_mfma_f32_16x16x32_bf16 v[44:47], v[160:163], v[204:207], v[44:47]
	v_mfma_f32_16x16x32_bf16 v[40:43], v[172:175], v[204:207], v[40:43]
	v_mfma_f32_16x16x32_bf16 v[28:31], v[160:163], v[212:215], v[28:31]
	v_mfma_f32_16x16x32_bf16 v[24:27], v[172:175], v[212:215], v[24:27]
	v_mfma_f32_16x16x32_bf16 v[12:15], v[160:163], v[220:223], v[12:15]
	v_mfma_f32_16x16x32_bf16 v[8:11], v[172:175], v[220:223], v[8:11]
	v_mfma_f32_16x16x32_bf16 v[52:55], v[176:179], v[192:195], v[52:55]
	v_mfma_f32_16x16x32_bf16 v[48:51], v[184:187], v[192:195], v[48:51]
	v_mfma_f32_16x16x32_bf16 v[36:39], v[176:179], v[200:203], v[36:39]
	v_mfma_f32_16x16x32_bf16 v[32:35], v[184:187], v[200:203], v[32:35]
	v_mfma_f32_16x16x32_bf16 v[20:23], v[176:179], v[208:211], v[20:23]
	v_mfma_f32_16x16x32_bf16 v[16:19], v[184:187], v[208:211], v[16:19]
	v_mfma_f32_16x16x32_bf16 v[4:7], v[176:179], v[216:219], v[4:7]
	v_mfma_f32_16x16x32_bf16 v[0:3], v[184:187], v[216:219], v[0:3]
	v_mfma_f32_16x16x32_bf16 v[52:55], v[180:183], v[196:199], v[52:55]
	v_mfma_f32_16x16x32_bf16 v[48:51], v[188:191], v[196:199], v[48:51]
	v_mfma_f32_16x16x32_bf16 v[36:39], v[180:183], v[204:207], v[36:39]
	v_mfma_f32_16x16x32_bf16 v[32:35], v[188:191], v[204:207], v[32:35]
	v_mfma_f32_16x16x32_bf16 v[20:23], v[180:183], v[212:215], v[20:23]
	v_mfma_f32_16x16x32_bf16 v[16:19], v[188:191], v[212:215], v[16:19]
	v_mfma_f32_16x16x32_bf16 v[4:7], v[180:183], v[220:223], v[4:7]
	v_mfma_f32_16x16x32_bf16 v[0:3], v[188:191], v[220:223], v[0:3]
	s_barrier
	s_add_i32 s57, 0, 0x18000
	v_add_u32_e32 v140, s57, v159
	s_add_i32 s58, 0, 0x1c000
	ds_read_b128 v[128:131], v140
	ds_read_b128 v[160:163], v140 offset:1024
	ds_read_b128 v[168:171], v140 offset:2048
	ds_read_b128 v[172:175], v140 offset:3072
	v_add_u32_e32 v140, s58, v159
	ds_read_b128 v[176:179], v140
	ds_read_b128 v[180:183], v140 offset:1024
	ds_read_b128 v[184:187], v140 offset:2048
	ds_read_b128 v[188:191], v140 offset:3072
	s_add_u32 s34, s34, 0x20000
	s_addc_u32 s35, s35, 0
	s_mov_b32 m0, s41
	ds_read_b128 v[192:195], v166 offset:32768
	ds_read_b128 v[196:199], v166 offset:33792
	ds_read_b128 v[200:203], v166 offset:34816
	ds_read_b128 v[204:207], v166 offset:35840
	ds_read_b128 v[208:211], v166 offset:36864
	ds_read_b128 v[212:215], v166 offset:37888
	ds_read_b128 v[216:219], v166 offset:38912
	ds_read_b128 v[220:223], v166 offset:39936
	global_load_lds_dwordx4 v132, s[34:35]
	v_lshl_add_u64 v[230:231], s[34:35], 0, v[136:137]
	s_mov_b32 m0, s42
	s_nop 0
	global_load_lds_dwordx4 v[230:231], off
	s_waitcnt vmcnt(8)
	s_waitcnt lgkmcnt(0)
	s_barrier
	s_waitcnt lgkmcnt(0)
	v_mfma_f32_16x16x32_bf16 v[124:127], v[128:131], v[192:195], v[124:127]
	v_mfma_f32_16x16x32_bf16 v[120:123], v[168:171], v[192:195], v[120:123]
	v_mfma_f32_16x16x32_bf16 v[108:111], v[128:131], v[200:203], v[108:111]
	v_mfma_f32_16x16x32_bf16 v[104:107], v[168:171], v[200:203], v[104:107]
	v_mfma_f32_16x16x32_bf16 v[92:95], v[128:131], v[208:211], v[92:95]
	v_mfma_f32_16x16x32_bf16 v[88:91], v[168:171], v[208:211], v[88:91]
	v_mfma_f32_16x16x32_bf16 v[76:79], v[128:131], v[216:219], v[76:79]
	v_mfma_f32_16x16x32_bf16 v[72:75], v[168:171], v[216:219], v[72:75]
	v_mfma_f32_16x16x32_bf16 v[124:127], v[160:163], v[196:199], v[124:127]
	v_mfma_f32_16x16x32_bf16 v[120:123], v[172:175], v[196:199], v[120:123]
	v_mfma_f32_16x16x32_bf16 v[108:111], v[160:163], v[204:207], v[108:111]
	v_mfma_f32_16x16x32_bf16 v[104:107], v[172:175], v[204:207], v[104:107]
	v_mfma_f32_16x16x32_bf16 v[92:95], v[160:163], v[212:215], v[92:95]
	v_mfma_f32_16x16x32_bf16 v[88:91], v[172:175], v[212:215], v[88:91]
	v_mfma_f32_16x16x32_bf16 v[76:79], v[160:163], v[220:223], v[76:79]
	v_mfma_f32_16x16x32_bf16 v[72:75], v[172:175], v[220:223], v[72:75]
	v_mfma_f32_16x16x32_bf16 v[116:119], v[176:179], v[192:195], v[116:119]
	v_mfma_f32_16x16x32_bf16 v[112:115], v[184:187], v[192:195], v[112:115]
	v_mfma_f32_16x16x32_bf16 v[100:103], v[176:179], v[200:203], v[100:103]
	v_mfma_f32_16x16x32_bf16 v[96:99], v[184:187], v[200:203], v[96:99]
	v_mfma_f32_16x16x32_bf16 v[84:87], v[176:179], v[208:211], v[84:87]
	v_mfma_f32_16x16x32_bf16 v[80:83], v[184:187], v[208:211], v[80:83]
	v_mfma_f32_16x16x32_bf16 v[68:71], v[176:179], v[216:219], v[68:71]
	v_mfma_f32_16x16x32_bf16 v[64:67], v[184:187], v[216:219], v[64:67]
	v_mfma_f32_16x16x32_bf16 v[116:119], v[180:183], v[196:199], v[116:119]
	v_mfma_f32_16x16x32_bf16 v[112:115], v[188:191], v[196:199], v[112:115]
	v_mfma_f32_16x16x32_bf16 v[100:103], v[180:183], v[204:207], v[100:103]
	v_mfma_f32_16x16x32_bf16 v[96:99], v[188:191], v[204:207], v[96:99]
	v_mfma_f32_16x16x32_bf16 v[84:87], v[180:183], v[212:215], v[84:87]
	v_mfma_f32_16x16x32_bf16 v[80:83], v[188:191], v[212:215], v[80:83]
	v_mfma_f32_16x16x32_bf16 v[68:71], v[180:183], v[220:223], v[68:71]
	v_mfma_f32_16x16x32_bf16 v[64:67], v[188:191], v[220:223], v[64:67]
	s_barrier
	s_add_i32 s34, s57, s38
	v_lshl_add_u64 v[156:157], v[156:157], 0, s[14:15]
	s_mov_b32 m0, s34
	ds_read_b128 v[192:195], v166 offset:49152
	ds_read_b128 v[196:199], v166 offset:50176
	ds_read_b128 v[200:203], v166 offset:51200
	ds_read_b128 v[204:207], v166 offset:52224
	ds_read_b128 v[208:211], v166 offset:53248
	ds_read_b128 v[212:215], v166 offset:54272
	ds_read_b128 v[216:219], v166 offset:55296
	ds_read_b128 v[220:223], v166 offset:56320
	global_load_lds_dwordx4 v[156:157], off
	s_add_i32 m0, s34, 0x2000
	s_add_u32 s30, s30, 0x20080
	v_lshl_add_u64 v[156:157], v[224:225], 0, s[14:15]
	s_addc_u32 s31, s31, 0
	s_add_i32 s34, s58, s38
	global_load_lds_dwordx4 v[156:157], off
	s_mov_b32 m0, s34
	s_nop 0
	global_load_lds_dwordx4 v134, s[30:31]
	s_add_i32 m0, s34, 0x2000
	s_nop 0
	global_load_lds_dwordx4 v138, s[30:31]
	v_lshl_add_u64 v[156:157], v[226:227], 0, s[14:15]
	s_mov_b32 m0, s44
	s_nop 0
	global_load_lds_dwordx4 v[156:157], off
	v_lshl_add_u64 v[156:157], v[228:229], 0, s[14:15]
	s_mov_b32 m0, s45
	s_nop 0
	global_load_lds_dwordx4 v[156:157], off
	s_waitcnt vmcnt(8)
	s_waitcnt lgkmcnt(0)
	s_barrier
	s_waitcnt lgkmcnt(0)
	v_mfma_f32_16x16x32_bf16 v[60:63], v[128:131], v[192:195], v[60:63]
	v_mfma_f32_16x16x32_bf16 v[56:59], v[168:171], v[192:195], v[56:59]
	v_mfma_f32_16x16x32_bf16 v[44:47], v[128:131], v[200:203], v[44:47]
	v_mfma_f32_16x16x32_bf16 v[40:43], v[168:171], v[200:203], v[40:43]
	v_mfma_f32_16x16x32_bf16 v[28:31], v[128:131], v[208:211], v[28:31]
	v_mfma_f32_16x16x32_bf16 v[24:27], v[168:171], v[208:211], v[24:27]
	v_mfma_f32_16x16x32_bf16 v[12:15], v[128:131], v[216:219], v[12:15]
	v_mfma_f32_16x16x32_bf16 v[8:11], v[168:171], v[216:219], v[8:11]
	v_mfma_f32_16x16x32_bf16 v[60:63], v[160:163], v[196:199], v[60:63]
	v_mfma_f32_16x16x32_bf16 v[56:59], v[172:175], v[196:199], v[56:59]
	v_mfma_f32_16x16x32_bf16 v[44:47], v[160:163], v[204:207], v[44:47]
	v_mfma_f32_16x16x32_bf16 v[40:43], v[172:175], v[204:207], v[40:43]
	v_mfma_f32_16x16x32_bf16 v[28:31], v[160:163], v[212:215], v[28:31]
	v_mfma_f32_16x16x32_bf16 v[24:27], v[172:175], v[212:215], v[24:27]
	v_mfma_f32_16x16x32_bf16 v[12:15], v[160:163], v[220:223], v[12:15]
	v_mfma_f32_16x16x32_bf16 v[8:11], v[172:175], v[220:223], v[8:11]
	v_mfma_f32_16x16x32_bf16 v[52:55], v[176:179], v[192:195], v[52:55]
	v_mfma_f32_16x16x32_bf16 v[48:51], v[184:187], v[192:195], v[48:51]
	v_mfma_f32_16x16x32_bf16 v[36:39], v[176:179], v[200:203], v[36:39]
	v_mfma_f32_16x16x32_bf16 v[32:35], v[184:187], v[200:203], v[32:35]
	v_mfma_f32_16x16x32_bf16 v[20:23], v[176:179], v[208:211], v[20:23]
	v_mfma_f32_16x16x32_bf16 v[16:19], v[184:187], v[208:211], v[16:19]
	v_mfma_f32_16x16x32_bf16 v[4:7], v[176:179], v[216:219], v[4:7]
	v_mfma_f32_16x16x32_bf16 v[0:3], v[184:187], v[216:219], v[0:3]
	v_mfma_f32_16x16x32_bf16 v[52:55], v[180:183], v[196:199], v[52:55]
	v_mfma_f32_16x16x32_bf16 v[48:51], v[188:191], v[196:199], v[48:51]
	v_mfma_f32_16x16x32_bf16 v[36:39], v[180:183], v[204:207], v[36:39]
	v_mfma_f32_16x16x32_bf16 v[32:35], v[188:191], v[204:207], v[32:35]
	v_mfma_f32_16x16x32_bf16 v[20:23], v[180:183], v[212:215], v[20:23]
	v_mfma_f32_16x16x32_bf16 v[16:19], v[188:191], v[212:215], v[16:19]
	v_mfma_f32_16x16x32_bf16 v[4:7], v[180:183], v[220:223], v[4:7]
	v_mfma_f32_16x16x32_bf16 v[0:3], v[188:191], v[220:223], v[0:3]
	s_add_i32 s56, s56, 2
	s_add_u32 s28, s28, 0x100
	s_addc_u32 s29, s29, 0
	s_add_u32 s54, s54, 0x100
	s_addc_u32 s55, s55, 0
	s_cmp_gt_u32 s56, 5
	s_barrier
	s_cbranch_scc0 .LBB0_1403
	s_and_b64 vcc, exec, s[16:17]
	s_cbranch_vccz .LBB0_1406
	s_barrier

.LBB0_1540:
	s_andn2_b64 vcc, exec, s[4:5]
	s_cbranch_vccnz .LBB0_1576
	v_ashrrev_i32_e32 v2, 31, v0
	v_lshrrev_b32_e32 v2, 26, v2
	v_lshlrev_b32_e32 v1, 4, v0
	v_add_u32_e32 v2, v0, v2
	v_bfe_i32 v0, v0, 27, 1
	v_lshrrev_b32_e32 v0, 22, v0
	v_add_u32_e32 v0, v1, v0
	v_and_b32_e32 v0, 0xfffffc00, v0
	v_sub_u32_e32 v0, v1, v0
	v_ashrrev_i32_e32 v9, 6, v2
	v_lshrrev_b32_e32 v2, 4, v0
	v_bitop3_b32 v0, v2, v0, 32 bitop3:0x6c
	v_ashrrev_i32_e32 v3, 31, v0
	v_lshrrev_b32_e32 v3, 26, v3
	v_add_u32_e32 v3, v0, v3
	v_ashrrev_i32_e32 v10, 6, v3
	v_and_b32_e32 v3, 0xc0, v3
	v_sub_u32_e32 v0, v0, v3
	v_mov_b32_e32 v3, 1
	v_lshlrev_b32_e32 v2, 3, v9
	v_lshlrev_b32_e32 v4, 5, v9
	v_ashrrev_i16_sdwa v0, v3, sext(v0) dst_sel:DWORD dst_unused:UNUSED_PAD src0_sel:DWORD src1_sel:BYTE_0
	v_and_b32_e32 v2, 0x1ffff0, v2
	v_and_b32_e32 v4, 32, v4
	v_bfe_i32 v11, v0, 0, 16
	v_add_u32_e32 v0, v4, v11
	v_add_lshl_u32 v2, v10, v2, 11
	s_waitcnt vmcnt(0)
	v_lshl_add_u32 v128, v0, 1, v2
	v_add_u32_e32 v0, 0x2000, v1
	v_ashrrev_i32_e32 v1, 31, v0
	v_lshrrev_b32_e32 v1, 22, v1
	v_add_u32_e32 v1, v0, v1
	v_ashrrev_i32_e32 v12, 10, v1
	v_mul_i32_i24_e32 v1, 0x400, v12
	v_sub_u32_e32 v0, v0, v1
	v_lshrrev_b32_e32 v1, 4, v0
	s_add_u32 s34, s70, 0xbc00000
	v_bitop3_b32 v0, v1, v0, 32 bitop3:0x6c
	s_addc_u32 s35, s71, 0
	v_ashrrev_i32_e32 v2, 31, v0
	s_add_u32 s36, s70, 0x5900000
	v_lshrrev_b32_e32 v2, 26, v2
	s_addc_u32 s37, s71, 0
	s_ashr_i32 s2, s14, 6
	v_add_u32_e32 v2, v0, v2
	s_ashr_i32 s25, s24, 31
	s_ashr_i32 s9, s8, 31
	v_ashrrev_i32_e32 v13, 6, v2
	v_and_b32_e32 v2, 0xc0, v2
	s_ashr_i32 s3, s14, 8
	s_lshl_b32 s38, s2, 10
	s_lshl_b64 s[4:5], s[24:25], 19
	s_lshl_b64 s[10:11], s[8:9], 19
	v_sub_u32_e32 v0, v0, v2
	s_add_u32 s28, s36, s10
	v_lshlrev_b32_e32 v1, 3, v12
	v_lshlrev_b32_e32 v4, 5, v12
	v_ashrrev_i16_sdwa v0, v3, sext(v0) dst_sel:DWORD dst_unused:UNUSED_PAD src0_sel:DWORD src1_sel:BYTE_0
	s_addc_u32 s29, s37, s11
	s_add_i32 s39, s38, 0
	v_and_b32_e32 v1, 0x1ffff0, v1
	v_and_b32_e32 v4, 32, v4
	v_bfe_i32 v14, v0, 0, 16
	s_add_i32 m0, s39, 0x10000
	v_add_u32_e32 v0, v4, v14
	v_add_lshl_u32 v1, v13, v1, 11
	global_load_lds_dwordx4 v128, s[28:29]
	s_add_i32 m0, s39, 0x12000
	v_lshl_add_u32 v130, v0, 1, v1
	s_add_u32 s10, s28, 0x40000
	global_load_lds_dwordx4 v130, s[28:29]
	s_addc_u32 s11, s29, 0
	s_add_i32 m0, s39, 0x14000
	v_mov_b32_e32 v129, 0
	global_load_lds_dwordx4 v128, s[10:11]
	s_add_i32 m0, s39, 0x16000
	s_add_u32 s26, s34, s4
	s_addc_u32 s27, s35, s5
	s_add_i32 s40, s39, 0x2000
	global_load_lds_dwordx4 v130, s[10:11]
	s_mov_b32 m0, s39
	s_add_u32 s4, s26, 0x40000
	global_load_lds_dwordx4 v128, s[26:27]
	s_mov_b32 m0, s40
	s_addc_u32 s5, s27, 0
	s_add_i32 s41, s39, 0x4000
	global_load_lds_dwordx4 v130, s[26:27]
	s_mov_b32 m0, s41
	s_add_i32 s42, s39, 0x6000
	global_load_lds_dwordx4 v128, s[4:5]
	s_mov_b32 m0, s42
	v_mov_b32_e32 v131, v129
	global_load_lds_dwordx4 v130, s[4:5]
	s_cmp_eq_u32 s3, 1
	s_mov_b32 s9, 0
	v_lshl_add_u64 v[6:7], s[28:29], 0, v[128:129]
	v_lshl_add_u64 v[4:5], s[28:29], 0, v[130:131]
	v_lshl_add_u64 v[0:1], s[26:27], 0, v[128:129]
	s_cselect_b64 s[10:11], -1, 0
	s_cmp_lg_u32 s3, 1
	v_lshl_add_u64 v[2:3], s[26:27], 0, v[130:131]
	s_setprio 1
	s_cbranch_scc1 .LBB0_1543
	s_barrier
	s_setprio 0

.LBB0_1553:
	ds_read_b128 v[140:143], v147
	ds_read_b128 v[152:155], v147 offset:1024
	ds_read_b128 v[156:159], v147 offset:2048
	ds_read_b128 v[160:163], v147 offset:3072
	ds_read_b128 v[164:167], v148
	ds_read_b128 v[168:171], v148 offset:1024
	ds_read_b128 v[172:175], v148 offset:2048
	ds_read_b128 v[176:179], v148 offset:3072
	s_add_u32 s28, s26, 0xfffc0080
	s_addc_u32 s29, s27, -1
	s_cmp_eq_u32 s54, 12
	s_cselect_b32 s31, s19, s29
	s_cselect_b32 s30, s25, s28
	s_cselect_b32 s29, s17, s53
	s_cselect_b32 s28, s51, s52
	s_add_i32 m0, s39, 0xc000
	ds_read_b128 v[180:183], v149
	ds_read_b128 v[184:187], v149 offset:1024
	ds_read_b128 v[188:191], v149 offset:2048
	ds_read_b128 v[192:195], v149 offset:3072
	ds_read_b128 v[196:199], v149 offset:4096
	ds_read_b128 v[200:203], v149 offset:5120
	ds_read_b128 v[204:207], v149 offset:6144
	ds_read_b128 v[208:211], v149 offset:7168
	global_load_lds_dwordx4 v132, s[26:27]
	s_add_i32 m0, s39, 0xe000
	s_nop 0
	global_load_lds_dwordx4 v134, s[26:27]
	s_waitcnt vmcnt(8)
	s_waitcnt lgkmcnt(0)
	s_barrier
	s_waitcnt lgkmcnt(0)
	v_mfma_f32_16x16x32_bf16 v[124:127], v[140:143], v[180:183], v[124:127]
	v_mfma_f32_16x16x32_bf16 v[120:123], v[156:159], v[180:183], v[120:123]
	v_mfma_f32_16x16x32_bf16 v[108:111], v[140:143], v[188:191], v[108:111]
	v_mfma_f32_16x16x32_bf16 v[104:107], v[156:159], v[188:191], v[104:107]
	v_mfma_f32_16x16x32_bf16 v[92:95], v[140:143], v[196:199], v[92:95]
	v_mfma_f32_16x16x32_bf16 v[88:91], v[156:159], v[196:199], v[88:91]
	v_mfma_f32_16x16x32_bf16 v[76:79], v[140:143], v[204:207], v[76:79]
	v_mfma_f32_16x16x32_bf16 v[72:75], v[156:159], v[204:207], v[72:75]
	v_mfma_f32_16x16x32_bf16 v[124:127], v[152:155], v[184:187], v[124:127]
	v_mfma_f32_16x16x32_bf16 v[120:123], v[160:163], v[184:187], v[120:123]
	v_mfma_f32_16x16x32_bf16 v[108:111], v[152:155], v[192:195], v[108:111]
	v_mfma_f32_16x16x32_bf16 v[104:107], v[160:163], v[192:195], v[104:107]
	v_mfma_f32_16x16x32_bf16 v[92:95], v[152:155], v[200:203], v[92:95]
	v_mfma_f32_16x16x32_bf16 v[88:91], v[160:163], v[200:203], v[88:91]
	v_mfma_f32_16x16x32_bf16 v[76:79], v[152:155], v[208:211], v[76:79]
	v_mfma_f32_16x16x32_bf16 v[72:75], v[160:163], v[208:211], v[72:75]
	v_mfma_f32_16x16x32_bf16 v[116:119], v[164:167], v[180:183], v[116:119]
	v_mfma_f32_16x16x32_bf16 v[112:115], v[172:175], v[180:183], v[112:115]
	v_mfma_f32_16x16x32_bf16 v[100:103], v[164:167], v[188:191], v[100:103]
	v_mfma_f32_16x16x32_bf16 v[96:99], v[172:175], v[188:191], v[96:99]
	v_mfma_f32_16x16x32_bf16 v[84:87], v[164:167], v[196:199], v[84:87]
	v_mfma_f32_16x16x32_bf16 v[80:83], v[172:175], v[196:199], v[80:83]
	v_mfma_f32_16x16x32_bf16 v[68:71], v[164:167], v[204:207], v[68:71]
	v_mfma_f32_16x16x32_bf16 v[64:67], v[172:175], v[204:207], v[64:67]
	v_mfma_f32_16x16x32_bf16 v[116:119], v[168:171], v[184:187], v[116:119]
	v_mfma_f32_16x16x32_bf16 v[112:115], v[176:179], v[184:187], v[112:115]
	v_mfma_f32_16x16x32_bf16 v[100:103], v[168:171], v[192:195], v[100:103]
	v_mfma_f32_16x16x32_bf16 v[96:99], v[176:179], v[192:195], v[96:99]
	v_mfma_f32_16x16x32_bf16 v[84:87], v[168:171], v[200:203], v[84:87]
	v_mfma_f32_16x16x32_bf16 v[80:83], v[176:179], v[200:203], v[80:83]
	v_mfma_f32_16x16x32_bf16 v[68:71], v[168:171], v[208:211], v[68:71]
	v_mfma_f32_16x16x32_bf16 v[64:67], v[176:179], v[208:211], v[64:67]
	s_barrier
	s_add_i32 s55, s48, s38
	v_lshl_add_u64 v[212:213], s[28:29], 0, v[128:129]
	s_mov_b32 m0, s55
	ds_read_b128 v[180:183], v149 offset:16384
	ds_read_b128 v[184:187], v149 offset:17408
	ds_read_b128 v[188:191], v149 offset:18432
	ds_read_b128 v[192:195], v149 offset:19456
	ds_read_b128 v[196:199], v149 offset:20480
	ds_read_b128 v[200:203], v149 offset:21504
	ds_read_b128 v[204:207], v149 offset:22528
	ds_read_b128 v[208:211], v149 offset:23552
	global_load_lds_dwordx4 v[212:213], off
	s_add_i32 m0, s55, 0x2000
	s_add_u32 s56, s28, 0x40000
	v_lshl_add_u64 v[214:215], s[28:29], 0, v[130:131]
	s_addc_u32 s57, s29, 0
	s_add_i32 s55, s49, s38
	global_load_lds_dwordx4 v[214:215], off
	v_lshl_add_u64 v[216:217], s[56:57], 0, v[128:129]
	s_mov_b32 m0, s55
	v_lshl_add_u64 v[218:219], s[30:31], 0, v[130:131]
	global_load_lds_dwordx4 v[216:217], off
	s_add_i32 m0, s55, 0x2000
	s_nop 0
	global_load_lds_dwordx4 v130, s[56:57]
	v_lshl_add_u64 v[216:217], s[30:31], 0, v[128:129]
	s_mov_b32 m0, s39
	s_nop 0
	global_load_lds_dwordx4 v[216:217], off
	s_mov_b32 m0, s40
	s_nop 0
	global_load_lds_dwordx4 v[218:219], off
	s_waitcnt vmcnt(8)
	s_waitcnt lgkmcnt(0)
	s_barrier
	s_waitcnt lgkmcnt(0)
	v_mfma_f32_16x16x32_bf16 v[60:63], v[140:143], v[180:183], v[60:63]
	v_mfma_f32_16x16x32_bf16 v[56:59], v[156:159], v[180:183], v[56:59]
	v_mfma_f32_16x16x32_bf16 v[44:47], v[140:143], v[188:191], v[44:47]
	v_mfma_f32_16x16x32_bf16 v[40:43], v[156:159], v[188:191], v[40:43]
	v_mfma_f32_16x16x32_bf16 v[28:31], v[140:143], v[196:199], v[28:31]
	v_mfma_f32_16x16x32_bf16 v[24:27], v[156:159], v[196:199], v[24:27]
	v_mfma_f32_16x16x32_bf16 v[12:15], v[140:143], v[204:207], v[12:15]
	v_mfma_f32_16x16x32_bf16 v[8:11], v[156:159], v[204:207], v[8:11]
	v_mfma_f32_16x16x32_bf16 v[60:63], v[152:155], v[184:187], v[60:63]
	v_mfma_f32_16x16x32_bf16 v[56:59], v[160:163], v[184:187], v[56:59]
	v_mfma_f32_16x16x32_bf16 v[44:47], v[152:155], v[192:195], v[44:47]
	v_mfma_f32_16x16x32_bf16 v[40:43], v[160:163], v[192:195], v[40:43]
	v_mfma_f32_16x16x32_bf16 v[28:31], v[152:155], v[200:203], v[28:31]
	v_mfma_f32_16x16x32_bf16 v[24:27], v[160:163], v[200:203], v[24:27]
	v_mfma_f32_16x16x32_bf16 v[12:15], v[152:155], v[208:211], v[12:15]
	v_mfma_f32_16x16x32_bf16 v[8:11], v[160:163], v[208:211], v[8:11]
	v_mfma_f32_16x16x32_bf16 v[52:55], v[164:167], v[180:183], v[52:55]
	v_mfma_f32_16x16x32_bf16 v[48:51], v[172:175], v[180:183], v[48:51]
	v_mfma_f32_16x16x32_bf16 v[36:39], v[164:167], v[188:191], v[36:39]
	v_mfma_f32_16x16x32_bf16 v[32:35], v[172:175], v[188:191], v[32:35]
	v_mfma_f32_16x16x32_bf16 v[20:23], v[164:167], v[196:199], v[20:23]
	v_mfma_f32_16x16x32_bf16 v[16:19], v[172:175], v[196:199], v[16:19]
	v_mfma_f32_16x16x32_bf16 v[4:7], v[164:167], v[204:207], v[4:7]
	v_mfma_f32_16x16x32_bf16 v[0:3], v[172:175], v[204:207], v[0:3]
	v_mfma_f32_16x16x32_bf16 v[52:55], v[168:171], v[184:187], v[52:55]
	v_mfma_f32_16x16x32_bf16 v[48:51], v[176:179], v[184:187], v[48:51]
	v_mfma_f32_16x16x32_bf16 v[36:39], v[168:171], v[192:195], v[36:39]
	v_mfma_f32_16x16x32_bf16 v[32:35], v[176:179], v[192:195], v[32:35]
	v_mfma_f32_16x16x32_bf16 v[20:23], v[168:171], v[200:203], v[20:23]
	v_mfma_f32_16x16x32_bf16 v[16:19], v[176:179], v[200:203], v[16:19]
	v_mfma_f32_16x16x32_bf16 v[4:7], v[168:171], v[208:211], v[4:7]
	v_mfma_f32_16x16x32_bf16 v[0:3], v[176:179], v[208:211], v[0:3]
	s_barrier
	s_add_i32 s55, 0, 0x18000
	v_add_u32_e32 v151, s55, v145
	s_add_i32 s56, 0, 0x1c000
	ds_read_b128 v[140:143], v151
	ds_read_b128 v[152:155], v151 offset:1024
	ds_read_b128 v[156:159], v151 offset:2048
	ds_read_b128 v[160:163], v151 offset:3072
	v_add_u32_e32 v151, s56, v145
	ds_read_b128 v[164:167], v151
	ds_read_b128 v[168:171], v151 offset:1024
	ds_read_b128 v[172:175], v151 offset:2048
	ds_read_b128 v[176:179], v151 offset:3072
	s_add_u32 s30, s30, 0x40000
	s_addc_u32 s31, s31, 0
	s_mov_b32 m0, s41
	v_lshl_add_u64 v[220:221], s[30:31], 0, v[128:129]
	ds_read_b128 v[180:183], v149 offset:32768
	ds_read_b128 v[184:187], v149 offset:33792
	ds_read_b128 v[188:191], v149 offset:34816
	ds_read_b128 v[192:195], v149 offset:35840
	ds_read_b128 v[196:199], v149 offset:36864
	ds_read_b128 v[200:203], v149 offset:37888
	ds_read_b128 v[204:207], v149 offset:38912
	ds_read_b128 v[208:211], v149 offset:39936
	global_load_lds_dwordx4 v[220:221], off
	v_lshl_add_u64 v[220:221], s[30:31], 0, v[130:131]
	s_mov_b32 m0, s42
	s_nop 0
	global_load_lds_dwordx4 v[220:221], off
	s_waitcnt vmcnt(8)
	s_waitcnt lgkmcnt(0)
	s_barrier
	s_waitcnt lgkmcnt(0)
	v_mfma_f32_16x16x32_bf16 v[124:127], v[140:143], v[180:183], v[124:127]
	v_mfma_f32_16x16x32_bf16 v[120:123], v[156:159], v[180:183], v[120:123]
	v_mfma_f32_16x16x32_bf16 v[108:111], v[140:143], v[188:191], v[108:111]
	v_mfma_f32_16x16x32_bf16 v[104:107], v[156:159], v[188:191], v[104:107]
	v_mfma_f32_16x16x32_bf16 v[92:95], v[140:143], v[196:199], v[92:95]
	v_mfma_f32_16x16x32_bf16 v[88:91], v[156:159], v[196:199], v[88:91]
	v_mfma_f32_16x16x32_bf16 v[76:79], v[140:143], v[204:207], v[76:79]
	v_mfma_f32_16x16x32_bf16 v[72:75], v[156:159], v[204:207], v[72:75]
	v_mfma_f32_16x16x32_bf16 v[124:127], v[152:155], v[184:187], v[124:127]
	v_mfma_f32_16x16x32_bf16 v[120:123], v[160:163], v[184:187], v[120:123]
	v_mfma_f32_16x16x32_bf16 v[108:111], v[152:155], v[192:195], v[108:111]
	v_mfma_f32_16x16x32_bf16 v[104:107], v[160:163], v[192:195], v[104:107]
	v_mfma_f32_16x16x32_bf16 v[92:95], v[152:155], v[200:203], v[92:95]
	v_mfma_f32_16x16x32_bf16 v[88:91], v[160:163], v[200:203], v[88:91]
	v_mfma_f32_16x16x32_bf16 v[76:79], v[152:155], v[208:211], v[76:79]
	v_mfma_f32_16x16x32_bf16 v[72:75], v[160:163], v[208:211], v[72:75]
	v_mfma_f32_16x16x32_bf16 v[116:119], v[164:167], v[180:183], v[116:119]
	v_mfma_f32_16x16x32_bf16 v[112:115], v[172:175], v[180:183], v[112:115]
	v_mfma_f32_16x16x32_bf16 v[100:103], v[164:167], v[188:191], v[100:103]
	v_mfma_f32_16x16x32_bf16 v[96:99], v[172:175], v[188:191], v[96:99]
	v_mfma_f32_16x16x32_bf16 v[84:87], v[164:167], v[196:199], v[84:87]
	v_mfma_f32_16x16x32_bf16 v[80:83], v[172:175], v[196:199], v[80:83]
	v_mfma_f32_16x16x32_bf16 v[68:71], v[164:167], v[204:207], v[68:71]
	v_mfma_f32_16x16x32_bf16 v[64:67], v[172:175], v[204:207], v[64:67]
	v_mfma_f32_16x16x32_bf16 v[116:119], v[168:171], v[184:187], v[116:119]
	v_mfma_f32_16x16x32_bf16 v[112:115], v[176:179], v[184:187], v[112:115]
	v_mfma_f32_16x16x32_bf16 v[100:103], v[168:171], v[192:195], v[100:103]
	v_mfma_f32_16x16x32_bf16 v[96:99], v[176:179], v[192:195], v[96:99]
	v_mfma_f32_16x16x32_bf16 v[84:87], v[168:171], v[200:203], v[84:87]
	v_mfma_f32_16x16x32_bf16 v[80:83], v[176:179], v[200:203], v[80:83]
	v_mfma_f32_16x16x32_bf16 v[68:71], v[168:171], v[208:211], v[68:71]
	v_mfma_f32_16x16x32_bf16 v[64:67], v[176:179], v[208:211], v[64:67]
	s_barrier
	s_add_i32 s30, s55, s38
	v_lshl_add_u64 v[212:213], v[212:213], 0, s[12:13]
	s_mov_b32 m0, s30
	ds_read_b128 v[180:183], v149 offset:49152
	ds_read_b128 v[184:187], v149 offset:50176
	ds_read_b128 v[188:191], v149 offset:51200
	ds_read_b128 v[192:195], v149 offset:52224
	ds_read_b128 v[196:199], v149 offset:53248
	ds_read_b128 v[200:203], v149 offset:54272
	ds_read_b128 v[204:207], v149 offset:55296
	ds_read_b128 v[208:211], v149 offset:56320
	global_load_lds_dwordx4 v[212:213], off
	s_add_i32 m0, s30, 0x2000
	s_add_u32 s28, s28, 0x40080
	v_lshl_add_u64 v[212:213], v[214:215], 0, s[12:13]
	s_addc_u32 s29, s29, 0
	s_add_i32 s30, s56, s38
	global_load_lds_dwordx4 v[212:213], off
	v_lshl_add_u64 v[212:213], s[28:29], 0, v[128:129]
	s_mov_b32 m0, s30
	s_nop 0
	global_load_lds_dwordx4 v[212:213], off
	s_add_i32 m0, s30, 0x2000
	s_nop 0
	global_load_lds_dwordx4 v130, s[28:29]
	v_lshl_add_u64 v[212:213], v[216:217], 0, s[12:13]
	s_mov_b32 m0, s44
	s_nop 0
	global_load_lds_dwordx4 v[212:213], off
	v_lshl_add_u64 v[212:213], v[218:219], 0, s[12:13]
	s_mov_b32 m0, s45
	s_nop 0
	global_load_lds_dwordx4 v[212:213], off
	s_waitcnt vmcnt(8)
	s_waitcnt lgkmcnt(0)
	s_barrier
	s_waitcnt lgkmcnt(0)
	v_mfma_f32_16x16x32_bf16 v[60:63], v[140:143], v[180:183], v[60:63]
	v_mfma_f32_16x16x32_bf16 v[56:59], v[156:159], v[180:183], v[56:59]
	v_mfma_f32_16x16x32_bf16 v[44:47], v[140:143], v[188:191], v[44:47]
	v_mfma_f32_16x16x32_bf16 v[40:43], v[156:159], v[188:191], v[40:43]
	v_mfma_f32_16x16x32_bf16 v[28:31], v[140:143], v[196:199], v[28:31]
	v_mfma_f32_16x16x32_bf16 v[24:27], v[156:159], v[196:199], v[24:27]
	v_mfma_f32_16x16x32_bf16 v[12:15], v[140:143], v[204:207], v[12:15]
	v_mfma_f32_16x16x32_bf16 v[8:11], v[156:159], v[204:207], v[8:11]
	v_mfma_f32_16x16x32_bf16 v[60:63], v[152:155], v[184:187], v[60:63]
	v_mfma_f32_16x16x32_bf16 v[56:59], v[160:163], v[184:187], v[56:59]
	v_mfma_f32_16x16x32_bf16 v[44:47], v[152:155], v[192:195], v[44:47]
	v_mfma_f32_16x16x32_bf16 v[40:43], v[160:163], v[192:195], v[40:43]
	v_mfma_f32_16x16x32_bf16 v[28:31], v[152:155], v[200:203], v[28:31]
	v_mfma_f32_16x16x32_bf16 v[24:27], v[160:163], v[200:203], v[24:27]
	v_mfma_f32_16x16x32_bf16 v[12:15], v[152:155], v[208:211], v[12:15]
	v_mfma_f32_16x16x32_bf16 v[8:11], v[160:163], v[208:211], v[8:11]
	v_mfma_f32_16x16x32_bf16 v[52:55], v[164:167], v[180:183], v[52:55]
	v_mfma_f32_16x16x32_bf16 v[48:51], v[172:175], v[180:183], v[48:51]
	v_mfma_f32_16x16x32_bf16 v[36:39], v[164:167], v[188:191], v[36:39]
	v_mfma_f32_16x16x32_bf16 v[32:35], v[172:175], v[188:191], v[32:35]
	v_mfma_f32_16x16x32_bf16 v[20:23], v[164:167], v[196:199], v[20:23]
	v_mfma_f32_16x16x32_bf16 v[16:19], v[172:175], v[196:199], v[16:19]
	v_mfma_f32_16x16x32_bf16 v[4:7], v[164:167], v[204:207], v[4:7]
	v_mfma_f32_16x16x32_bf16 v[0:3], v[172:175], v[204:207], v[0:3]
	v_mfma_f32_16x16x32_bf16 v[52:55], v[168:171], v[184:187], v[52:55]
	v_mfma_f32_16x16x32_bf16 v[48:51], v[176:179], v[184:187], v[48:51]
	v_mfma_f32_16x16x32_bf16 v[36:39], v[168:171], v[192:195], v[36:39]
	v_mfma_f32_16x16x32_bf16 v[32:35], v[176:179], v[192:195], v[32:35]
	v_mfma_f32_16x16x32_bf16 v[20:23], v[168:171], v[200:203], v[20:23]
	v_mfma_f32_16x16x32_bf16 v[16:19], v[176:179], v[200:203], v[16:19]
	v_mfma_f32_16x16x32_bf16 v[4:7], v[168:171], v[208:211], v[4:7]
	v_mfma_f32_16x16x32_bf16 v[0:3], v[176:179], v[208:211], v[0:3]
	s_add_i32 s54, s54, 2
	s_add_u32 s26, s26, 0x100
	s_addc_u32 s27, s27, 0
	s_add_u32 s52, s52, 0x100
	s_addc_u32 s53, s53, 0
	s_cmp_gt_u32 s54, 13
	s_barrier
	s_cbranch_scc0 .LBB0_1553
	s_and_b64 vcc, exec, s[14:15]
	s_cbranch_vccz .LBB0_1556
	s_barrier

.LBB0_1610:
	s_andn2_b64 vcc, exec, s[4:5]
	s_cbranch_vccnz .LBB0_1652
	v_ashrrev_i32_e32 v2, 31, v0
	v_lshrrev_b32_e32 v2, 26, v2
	v_lshlrev_b32_e32 v1, 4, v0
	v_add_u32_e32 v2, v0, v2
	v_bfe_i32 v0, v0, 27, 1
	v_lshrrev_b32_e32 v0, 22, v0
	v_add_u32_e32 v0, v1, v0
	v_and_b32_e32 v0, 0xfffffc00, v0
	v_sub_u32_e32 v0, v1, v0
	v_ashrrev_i32_e32 v9, 6, v2
	v_lshrrev_b32_e32 v2, 4, v0
	v_bitop3_b32 v0, v2, v0, 32 bitop3:0x6c
	v_ashrrev_i32_e32 v3, 31, v0
	v_lshrrev_b32_e32 v3, 26, v3
	v_add_u32_e32 v3, v0, v3
	v_lshlrev_b32_e32 v2, 3, v9
	v_ashrrev_i32_e32 v10, 6, v3
	v_and_b32_e32 v3, 0xc0, v3
	v_and_b32_e32 v2, -16, v2
	v_sub_u32_e32 v0, v0, v3
	v_mov_b32_e32 v3, 1
	v_add_u32_e32 v2, v10, v2
	v_ashrrev_i16_sdwa v0, v3, sext(v0) dst_sel:DWORD dst_unused:UNUSED_PAD src0_sel:DWORD src1_sel:BYTE_0
	v_lshlrev_b32_e32 v4, 5, v9
	v_bfe_i32 v11, v0, 0, 16
	v_lshlrev_b32_e32 v0, 1, v2
	v_lshrrev_b32_e32 v5, 2, v2
	v_and_b32_e32 v6, 3, v10
	s_mov_b32 s3, 0x1fffe0
	v_and_b32_e32 v4, 32, v4
	v_and_b32_e32 v0, 24, v0
	v_and_b32_e32 v5, 4, v5
	v_and_or_b32 v6, v2, s3, v6
	v_or3_b32 v0, v6, v5, v0
	v_add_lshl_u32 v4, v4, v11, 1
	s_waitcnt vmcnt(0)
	v_lshl_add_u32 v130, v0, 11, v4
	v_add_u32_e32 v0, 0x2000, v1
	v_ashrrev_i32_e32 v1, 31, v0
	v_lshrrev_b32_e32 v1, 22, v1
	v_add_u32_e32 v1, v0, v1
	v_ashrrev_i32_e32 v12, 10, v1
	v_mul_i32_i24_e32 v1, 0x400, v12
	v_sub_u32_e32 v0, v0, v1
	v_lshrrev_b32_e32 v1, 4, v0
	v_bitop3_b32 v0, v1, v0, 32 bitop3:0x6c
	v_lshl_add_u32 v128, v2, 11, v4
	v_ashrrev_i32_e32 v2, 31, v0
	v_lshrrev_b32_e32 v2, 26, v2
	v_add_u32_e32 v2, v0, v2
	v_lshlrev_b32_e32 v1, 3, v12
	v_ashrrev_i32_e32 v13, 6, v2
	v_and_b32_e32 v2, 0xc0, v2
	s_add_u32 s36, s70, 0x2800000
	v_and_b32_e32 v1, -16, v1
	v_sub_u32_e32 v0, v0, v2
	s_addc_u32 s37, s71, 0
	s_ashr_i32 s2, s6, 6
	v_add_u32_e32 v1, v13, v1
	v_ashrrev_i16_sdwa v0, v3, sext(v0) dst_sel:DWORD dst_unused:UNUSED_PAD src0_sel:DWORD src1_sel:BYTE_0
	v_and_b32_e32 v3, 3, v13
	s_ashr_i32 s27, s26, 31
	s_ashr_i32 s25, s24, 31
	v_and_or_b32 v3, v1, s3, v3
	s_ashr_i32 s3, s6, 8
	s_lshl_b32 s38, s2, 10
	s_lshl_b64 s[4:5], s[26:27], 19
	s_lshl_b64 s[8:9], s[24:25], 19
	s_add_u32 s30, s36, s8
	v_lshlrev_b32_e32 v4, 5, v12
	v_bfe_i32 v14, v0, 0, 16
	v_lshlrev_b32_e32 v0, 1, v1
	v_lshrrev_b32_e32 v2, 2, v1
	s_addc_u32 s31, s37, s9
	s_add_i32 s39, s38, 0
	v_and_b32_e32 v4, 32, v4
	v_and_b32_e32 v0, 24, v0
	v_and_b32_e32 v2, 4, v2
	s_add_i32 m0, s39, 0x10000
	v_or3_b32 v0, v3, v2, v0
	v_add_lshl_u32 v2, v4, v14, 1
	global_load_lds_dwordx4 v130, s[30:31]
	s_add_i32 m0, s39, 0x12000
	v_lshl_add_u32 v134, v0, 11, v2
	s_add_u32 s8, s30, 0x40000
	global_load_lds_dwordx4 v134, s[30:31]
	s_addc_u32 s9, s31, 0
	s_add_i32 m0, s39, 0x14000
	v_lshl_add_u32 v132, v1, 11, v2
	global_load_lds_dwordx4 v130, s[8:9]
	s_add_i32 m0, s39, 0x16000
	s_add_u32 s28, s76, s4
	s_addc_u32 s29, s77, s5
	s_add_i32 s40, s39, 0x2000
	global_load_lds_dwordx4 v134, s[8:9]
	s_mov_b32 m0, s39
	s_add_u32 s4, s28, 0x40000
	global_load_lds_dwordx4 v128, s[28:29]
	s_mov_b32 m0, s40
	s_addc_u32 s5, s29, 0
	s_add_i32 s41, s39, 0x4000
	global_load_lds_dwordx4 v132, s[28:29]
	s_mov_b32 m0, s41
	s_add_i32 s42, s39, 0x6000
	global_load_lds_dwordx4 v128, s[4:5]
	s_mov_b32 m0, s42
	v_mov_b32_e32 v137, 0
	global_load_lds_dwordx4 v132, s[4:5]
	v_mov_b32_e32 v131, v137
	v_mov_b32_e32 v135, v137
	v_mov_b32_e32 v129, v137
	v_mov_b32_e32 v133, v137
	s_cmp_eq_u32 s3, 1
	s_mov_b32 s7, 0
	v_lshl_add_u64 v[6:7], s[30:31], 0, v[130:131]
	v_lshl_add_u64 v[4:5], s[30:31], 0, v[134:135]
	v_lshl_add_u64 v[0:1], s[28:29], 0, v[128:129]
	s_cselect_b64 s[8:9], -1, 0
	s_cmp_lg_u32 s3, 1
	v_lshl_add_u64 v[2:3], s[28:29], 0, v[132:133]
	s_setprio 1
	s_cbranch_scc1 .LBB0_1613
	s_barrier
	s_setprio 0

.LBB0_1619:
	ds_read_b128 v[152:155], v143
	ds_read_b128 v[162:165], v143 offset:1024
	ds_read_b128 v[166:169], v143 offset:2048
	ds_read_b128 v[170:173], v143 offset:3072
	ds_read_b128 v[174:177], v158
	ds_read_b128 v[178:181], v158 offset:1024
	ds_read_b128 v[182:185], v158 offset:2048
	ds_read_b128 v[186:189], v158 offset:3072
	s_add_u32 s30, s28, 0xfffc0080
	s_addc_u32 s31, s29, -1
	s_cmp_eq_u32 s55, 12
	s_cselect_b32 s35, s19, s31
	s_cselect_b32 s34, s25, s30
	s_cselect_b32 s31, s17, s54
	s_cselect_b32 s30, s27, s53
	s_waitcnt lgkmcnt(0)
	s_add_i32 m0, s39, 0xc000
	ds_read_b128 v[190:193], v159
	ds_read_b128 v[194:197], v159 offset:1024
	ds_read_b128 v[198:201], v159 offset:2048
	ds_read_b128 v[202:205], v159 offset:3072
	ds_read_b128 v[206:209], v159 offset:4096
	ds_read_b128 v[210:213], v159 offset:5120
	ds_read_b128 v[214:217], v159 offset:6144
	ds_read_b128 v[218:221], v159 offset:7168
	global_load_lds_dwordx4 v144, s[28:29]
	s_add_i32 m0, s39, 0xe000
	s_nop 0
	global_load_lds_dwordx4 v146, s[28:29]
	s_waitcnt vmcnt(8)
	s_waitcnt lgkmcnt(0)
	s_barrier
	s_waitcnt lgkmcnt(0)
	v_mfma_f32_16x16x32_bf16 v[116:119], v[152:155], v[190:193], v[116:119]
	v_mfma_f32_16x16x32_bf16 v[112:115], v[166:169], v[190:193], v[112:115]
	v_mfma_f32_16x16x32_bf16 v[100:103], v[152:155], v[198:201], v[100:103]
	v_mfma_f32_16x16x32_bf16 v[96:99], v[166:169], v[198:201], v[96:99]
	v_mfma_f32_16x16x32_bf16 v[88:91], v[152:155], v[206:209], v[88:91]
	v_mfma_f32_16x16x32_bf16 v[84:87], v[166:169], v[206:209], v[84:87]
	v_mfma_f32_16x16x32_bf16 v[72:75], v[152:155], v[214:217], v[72:75]
	v_mfma_f32_16x16x32_bf16 v[68:71], v[166:169], v[214:217], v[68:71]
	v_mfma_f32_16x16x32_bf16 v[116:119], v[162:165], v[194:197], v[116:119]
	v_mfma_f32_16x16x32_bf16 v[112:115], v[170:173], v[194:197], v[112:115]
	v_mfma_f32_16x16x32_bf16 v[100:103], v[162:165], v[202:205], v[100:103]
	v_mfma_f32_16x16x32_bf16 v[96:99], v[170:173], v[202:205], v[96:99]
	v_mfma_f32_16x16x32_bf16 v[88:91], v[162:165], v[210:213], v[88:91]
	v_mfma_f32_16x16x32_bf16 v[84:87], v[170:173], v[210:213], v[84:87]
	v_mfma_f32_16x16x32_bf16 v[72:75], v[162:165], v[218:221], v[72:75]
	v_mfma_f32_16x16x32_bf16 v[68:71], v[170:173], v[218:221], v[68:71]
	v_mfma_f32_16x16x32_bf16 v[124:127], v[174:177], v[190:193], v[124:127]
	v_mfma_f32_16x16x32_bf16 v[120:123], v[182:185], v[190:193], v[120:123]
	v_mfma_f32_16x16x32_bf16 v[108:111], v[174:177], v[198:201], v[108:111]
	v_mfma_f32_16x16x32_bf16 v[104:107], v[182:185], v[198:201], v[104:107]
	v_mfma_f32_16x16x32_bf16 v[92:95], v[174:177], v[206:209], v[92:95]
	v_mfma_f32_16x16x32_bf16 v[80:83], v[182:185], v[206:209], v[80:83]
	v_mfma_f32_16x16x32_bf16 v[76:79], v[174:177], v[214:217], v[76:79]
	v_mfma_f32_16x16x32_bf16 v[64:67], v[182:185], v[214:217], v[64:67]
	v_mfma_f32_16x16x32_bf16 v[124:127], v[178:181], v[194:197], v[124:127]
	v_mfma_f32_16x16x32_bf16 v[120:123], v[186:189], v[194:197], v[120:123]
	v_mfma_f32_16x16x32_bf16 v[108:111], v[178:181], v[202:205], v[108:111]
	v_mfma_f32_16x16x32_bf16 v[104:107], v[186:189], v[202:205], v[104:107]
	v_mfma_f32_16x16x32_bf16 v[92:95], v[178:181], v[210:213], v[92:95]
	v_mfma_f32_16x16x32_bf16 v[80:83], v[186:189], v[210:213], v[80:83]
	v_mfma_f32_16x16x32_bf16 v[76:79], v[178:181], v[218:221], v[76:79]
	v_mfma_f32_16x16x32_bf16 v[64:67], v[186:189], v[218:221], v[64:67]
	s_barrier
	s_add_i32 s56, s49, s38
	v_lshl_add_u64 v[156:157], s[30:31], 0, v[130:131]
	s_mov_b32 m0, s56
	ds_read_b128 v[190:193], v159 offset:16384
	ds_read_b128 v[194:197], v159 offset:17408
	ds_read_b128 v[198:201], v159 offset:18432
	ds_read_b128 v[202:205], v159 offset:19456
	ds_read_b128 v[206:209], v159 offset:20480
	ds_read_b128 v[210:213], v159 offset:21504
	ds_read_b128 v[214:217], v159 offset:22528
	ds_read_b128 v[218:221], v159 offset:23552
	global_load_lds_dwordx4 v[156:157], off
	s_add_i32 m0, s56, 0x2000
	s_add_u32 s56, s30, 0x40000
	v_lshl_add_u64 v[222:223], s[30:31], 0, v[134:135]
	s_addc_u32 s57, s31, 0
	s_add_i32 s58, s50, s38
	global_load_lds_dwordx4 v[222:223], off
	s_mov_b32 m0, s58
	v_lshl_add_u64 v[226:227], s[34:35], 0, v[132:133]
	global_load_lds_dwordx4 v130, s[56:57]
	s_add_i32 m0, s58, 0x2000
	s_nop 0
	global_load_lds_dwordx4 v134, s[56:57]
	v_lshl_add_u64 v[224:225], s[34:35], 0, v[128:129]
	s_mov_b32 m0, s39
	s_nop 0
	global_load_lds_dwordx4 v[224:225], off
	s_mov_b32 m0, s40
	s_nop 0
	global_load_lds_dwordx4 v[226:227], off
	s_waitcnt vmcnt(8)
	s_waitcnt lgkmcnt(0)
	s_barrier
	s_waitcnt lgkmcnt(0)
	v_mfma_f32_16x16x32_bf16 v[56:59], v[152:155], v[190:193], v[56:59]
	v_mfma_f32_16x16x32_bf16 v[52:55], v[166:169], v[190:193], v[52:55]
	v_mfma_f32_16x16x32_bf16 v[40:43], v[152:155], v[198:201], v[40:43]
	v_mfma_f32_16x16x32_bf16 v[36:39], v[166:169], v[198:201], v[36:39]
	v_mfma_f32_16x16x32_bf16 v[24:27], v[152:155], v[206:209], v[24:27]
	v_mfma_f32_16x16x32_bf16 v[20:23], v[166:169], v[206:209], v[20:23]
	v_mfma_f32_16x16x32_bf16 v[8:11], v[152:155], v[214:217], v[8:11]
	v_mfma_f32_16x16x32_bf16 v[4:7], v[166:169], v[214:217], v[4:7]
	v_mfma_f32_16x16x32_bf16 v[56:59], v[162:165], v[194:197], v[56:59]
	v_mfma_f32_16x16x32_bf16 v[52:55], v[170:173], v[194:197], v[52:55]
	v_mfma_f32_16x16x32_bf16 v[40:43], v[162:165], v[202:205], v[40:43]
	v_mfma_f32_16x16x32_bf16 v[36:39], v[170:173], v[202:205], v[36:39]
	v_mfma_f32_16x16x32_bf16 v[24:27], v[162:165], v[210:213], v[24:27]
	v_mfma_f32_16x16x32_bf16 v[20:23], v[170:173], v[210:213], v[20:23]
	v_mfma_f32_16x16x32_bf16 v[8:11], v[162:165], v[218:221], v[8:11]
	v_mfma_f32_16x16x32_bf16 v[4:7], v[170:173], v[218:221], v[4:7]
	v_mfma_f32_16x16x32_bf16 v[60:63], v[174:177], v[190:193], v[60:63]
	v_mfma_f32_16x16x32_bf16 v[48:51], v[182:185], v[190:193], v[48:51]
	v_mfma_f32_16x16x32_bf16 v[44:47], v[174:177], v[198:201], v[44:47]
	v_mfma_f32_16x16x32_bf16 v[32:35], v[182:185], v[198:201], v[32:35]
	v_mfma_f32_16x16x32_bf16 v[28:31], v[174:177], v[206:209], v[28:31]
	v_mfma_f32_16x16x32_bf16 v[16:19], v[182:185], v[206:209], v[16:19]
	v_mfma_f32_16x16x32_bf16 v[12:15], v[174:177], v[214:217], v[12:15]
	v_mfma_f32_16x16x32_bf16 v[0:3], v[182:185], v[214:217], v[0:3]
	v_mfma_f32_16x16x32_bf16 v[60:63], v[178:181], v[194:197], v[60:63]
	v_mfma_f32_16x16x32_bf16 v[48:51], v[186:189], v[194:197], v[48:51]
	v_mfma_f32_16x16x32_bf16 v[44:47], v[178:181], v[202:205], v[44:47]
	v_mfma_f32_16x16x32_bf16 v[32:35], v[186:189], v[202:205], v[32:35]
	v_mfma_f32_16x16x32_bf16 v[28:31], v[178:181], v[210:213], v[28:31]
	v_mfma_f32_16x16x32_bf16 v[16:19], v[186:189], v[210:213], v[16:19]
	v_mfma_f32_16x16x32_bf16 v[12:15], v[178:181], v[218:221], v[12:15]
	v_mfma_f32_16x16x32_bf16 v[0:3], v[186:189], v[218:221], v[0:3]
	s_barrier
	s_add_i32 s56, 0, 0x18000
	s_add_i32 s57, 0, 0x1c000
	v_add_u32_e32 v170, s56, v141
	v_add_u32_e32 v186, s57, v141
	ds_read_b128 v[152:155], v170
	ds_read_b128 v[162:165], v170 offset:1024
	ds_read_b128 v[166:169], v170 offset:2048
	ds_read_b128 v[170:173], v170 offset:3072
	ds_read_b128 v[174:177], v186
	ds_read_b128 v[178:181], v186 offset:1024
	ds_read_b128 v[182:185], v186 offset:2048
	ds_read_b128 v[186:189], v186 offset:3072
	s_add_u32 s34, s34, 0x40000
	s_addc_u32 s35, s35, 0
	s_mov_b32 m0, s41
	ds_read_b128 v[190:193], v159 offset:32768
	ds_read_b128 v[194:197], v159 offset:33792
	ds_read_b128 v[198:201], v159 offset:34816
	ds_read_b128 v[202:205], v159 offset:35840
	ds_read_b128 v[206:209], v159 offset:36864
	ds_read_b128 v[210:213], v159 offset:37888
	ds_read_b128 v[214:217], v159 offset:38912
	ds_read_b128 v[218:221], v159 offset:39936
	global_load_lds_dwordx4 v128, s[34:35]
	v_lshl_add_u64 v[228:229], s[34:35], 0, v[132:133]
	s_mov_b32 m0, s42
	s_nop 0
	global_load_lds_dwordx4 v[228:229], off
	s_waitcnt vmcnt(8)
	s_waitcnt lgkmcnt(0)
	s_barrier
	s_waitcnt lgkmcnt(0)
	v_mfma_f32_16x16x32_bf16 v[116:119], v[152:155], v[190:193], v[116:119]
	v_mfma_f32_16x16x32_bf16 v[112:115], v[166:169], v[190:193], v[112:115]
	v_mfma_f32_16x16x32_bf16 v[100:103], v[152:155], v[198:201], v[100:103]
	v_mfma_f32_16x16x32_bf16 v[96:99], v[166:169], v[198:201], v[96:99]
	v_mfma_f32_16x16x32_bf16 v[88:91], v[152:155], v[206:209], v[88:91]
	v_mfma_f32_16x16x32_bf16 v[84:87], v[166:169], v[206:209], v[84:87]
	v_mfma_f32_16x16x32_bf16 v[72:75], v[152:155], v[214:217], v[72:75]
	v_mfma_f32_16x16x32_bf16 v[68:71], v[166:169], v[214:217], v[68:71]
	v_mfma_f32_16x16x32_bf16 v[116:119], v[162:165], v[194:197], v[116:119]
	v_mfma_f32_16x16x32_bf16 v[112:115], v[170:173], v[194:197], v[112:115]
	v_mfma_f32_16x16x32_bf16 v[100:103], v[162:165], v[202:205], v[100:103]
	v_mfma_f32_16x16x32_bf16 v[96:99], v[170:173], v[202:205], v[96:99]
	v_mfma_f32_16x16x32_bf16 v[88:91], v[162:165], v[210:213], v[88:91]
	v_mfma_f32_16x16x32_bf16 v[84:87], v[170:173], v[210:213], v[84:87]
	v_mfma_f32_16x16x32_bf16 v[72:75], v[162:165], v[218:221], v[72:75]
	v_mfma_f32_16x16x32_bf16 v[68:71], v[170:173], v[218:221], v[68:71]
	v_mfma_f32_16x16x32_bf16 v[124:127], v[174:177], v[190:193], v[124:127]
	v_mfma_f32_16x16x32_bf16 v[120:123], v[182:185], v[190:193], v[120:123]
	v_mfma_f32_16x16x32_bf16 v[108:111], v[174:177], v[198:201], v[108:111]
	v_mfma_f32_16x16x32_bf16 v[104:107], v[182:185], v[198:201], v[104:107]
	v_mfma_f32_16x16x32_bf16 v[92:95], v[174:177], v[206:209], v[92:95]
	v_mfma_f32_16x16x32_bf16 v[80:83], v[182:185], v[206:209], v[80:83]
	v_mfma_f32_16x16x32_bf16 v[76:79], v[174:177], v[214:217], v[76:79]
	v_mfma_f32_16x16x32_bf16 v[64:67], v[182:185], v[214:217], v[64:67]
	v_mfma_f32_16x16x32_bf16 v[124:127], v[178:181], v[194:197], v[124:127]
	v_mfma_f32_16x16x32_bf16 v[120:123], v[186:189], v[194:197], v[120:123]
	v_mfma_f32_16x16x32_bf16 v[108:111], v[178:181], v[202:205], v[108:111]
	v_mfma_f32_16x16x32_bf16 v[104:107], v[186:189], v[202:205], v[104:107]
	v_mfma_f32_16x16x32_bf16 v[92:95], v[178:181], v[210:213], v[92:95]
	v_mfma_f32_16x16x32_bf16 v[80:83], v[186:189], v[210:213], v[80:83]
	v_mfma_f32_16x16x32_bf16 v[76:79], v[178:181], v[218:221], v[76:79]
	v_mfma_f32_16x16x32_bf16 v[64:67], v[186:189], v[218:221], v[64:67]
	s_barrier
	s_add_i32 s34, s56, s38
	v_lshl_add_u64 v[156:157], v[156:157], 0, s[10:11]
	s_mov_b32 m0, s34
	ds_read_b128 v[190:193], v159 offset:49152
	ds_read_b128 v[194:197], v159 offset:50176
	ds_read_b128 v[198:201], v159 offset:51200
	ds_read_b128 v[202:205], v159 offset:52224
	ds_read_b128 v[206:209], v159 offset:53248
	ds_read_b128 v[210:213], v159 offset:54272
	ds_read_b128 v[214:217], v159 offset:55296
	ds_read_b128 v[218:221], v159 offset:56320
	global_load_lds_dwordx4 v[156:157], off
	s_add_i32 m0, s34, 0x2000
	s_add_u32 s30, s30, 0x40080
	v_lshl_add_u64 v[156:157], v[222:223], 0, s[10:11]
	s_addc_u32 s31, s31, 0
	s_add_i32 s34, s57, s38
	global_load_lds_dwordx4 v[156:157], off
	s_mov_b32 m0, s34
	s_nop 0
	global_load_lds_dwordx4 v130, s[30:31]
	s_add_i32 m0, s34, 0x2000
	s_nop 0
	global_load_lds_dwordx4 v134, s[30:31]
	v_lshl_add_u64 v[156:157], v[224:225], 0, s[10:11]
	s_mov_b32 m0, s43
	s_nop 0
	global_load_lds_dwordx4 v[156:157], off
	v_lshl_add_u64 v[156:157], v[226:227], 0, s[10:11]
	s_mov_b32 m0, s44
	s_nop 0
	global_load_lds_dwordx4 v[156:157], off
	s_waitcnt vmcnt(8)
	s_waitcnt lgkmcnt(0)
	s_barrier
	s_waitcnt lgkmcnt(0)
	v_mfma_f32_16x16x32_bf16 v[56:59], v[152:155], v[190:193], v[56:59]
	v_mfma_f32_16x16x32_bf16 v[52:55], v[166:169], v[190:193], v[52:55]
	v_mfma_f32_16x16x32_bf16 v[40:43], v[152:155], v[198:201], v[40:43]
	v_mfma_f32_16x16x32_bf16 v[36:39], v[166:169], v[198:201], v[36:39]
	v_mfma_f32_16x16x32_bf16 v[24:27], v[152:155], v[206:209], v[24:27]
	v_mfma_f32_16x16x32_bf16 v[20:23], v[166:169], v[206:209], v[20:23]
	v_mfma_f32_16x16x32_bf16 v[8:11], v[152:155], v[214:217], v[8:11]
	v_mfma_f32_16x16x32_bf16 v[4:7], v[166:169], v[214:217], v[4:7]
	v_mfma_f32_16x16x32_bf16 v[56:59], v[162:165], v[194:197], v[56:59]
	v_mfma_f32_16x16x32_bf16 v[52:55], v[170:173], v[194:197], v[52:55]
	v_mfma_f32_16x16x32_bf16 v[40:43], v[162:165], v[202:205], v[40:43]
	v_mfma_f32_16x16x32_bf16 v[36:39], v[170:173], v[202:205], v[36:39]
	v_mfma_f32_16x16x32_bf16 v[24:27], v[162:165], v[210:213], v[24:27]
	v_mfma_f32_16x16x32_bf16 v[20:23], v[170:173], v[210:213], v[20:23]
	v_mfma_f32_16x16x32_bf16 v[8:11], v[162:165], v[218:221], v[8:11]
	v_mfma_f32_16x16x32_bf16 v[4:7], v[170:173], v[218:221], v[4:7]
	v_mfma_f32_16x16x32_bf16 v[60:63], v[174:177], v[190:193], v[60:63]
	v_mfma_f32_16x16x32_bf16 v[48:51], v[182:185], v[190:193], v[48:51]
	v_mfma_f32_16x16x32_bf16 v[44:47], v[174:177], v[198:201], v[44:47]
	v_mfma_f32_16x16x32_bf16 v[32:35], v[182:185], v[198:201], v[32:35]
	v_mfma_f32_16x16x32_bf16 v[28:31], v[174:177], v[206:209], v[28:31]
	v_mfma_f32_16x16x32_bf16 v[16:19], v[182:185], v[206:209], v[16:19]
	v_mfma_f32_16x16x32_bf16 v[12:15], v[174:177], v[214:217], v[12:15]
	v_mfma_f32_16x16x32_bf16 v[0:3], v[182:185], v[214:217], v[0:3]
	v_mfma_f32_16x16x32_bf16 v[60:63], v[178:181], v[194:197], v[60:63]
	v_mfma_f32_16x16x32_bf16 v[48:51], v[186:189], v[194:197], v[48:51]
	v_mfma_f32_16x16x32_bf16 v[44:47], v[178:181], v[202:205], v[44:47]
	v_mfma_f32_16x16x32_bf16 v[32:35], v[186:189], v[202:205], v[32:35]
	v_mfma_f32_16x16x32_bf16 v[28:31], v[178:181], v[210:213], v[28:31]
	v_mfma_f32_16x16x32_bf16 v[16:19], v[186:189], v[210:213], v[16:19]
	v_mfma_f32_16x16x32_bf16 v[12:15], v[178:181], v[218:221], v[12:15]
	v_mfma_f32_16x16x32_bf16 v[0:3], v[186:189], v[218:221], v[0:3]
	s_add_i32 s55, s55, 2
	s_add_u32 s28, s28, 0x100
	s_addc_u32 s29, s29, 0
	s_add_u32 s53, s53, 0x100
	s_addc_u32 s54, s54, 0
	s_cmp_gt_u32 s55, 13
	s_barrier
	s_cbranch_scc0 .LBB0_1619
	s_and_b64 vcc, exec, s[12:13]
	s_cbranch_vccz .LBB0_1624
	s_barrier
	v_lshl_add_u32 v152, s26, 8, v139
	s_cmp_gt_i32 s24, 21
	s_mov_b64 s[26:27], -1
	s_cbranch_scc1 .LBB0_1625

.LBB0_1689:
	v_ashrrev_i32_e32 v2, 31, v0
	v_lshrrev_b32_e32 v2, 26, v2
	v_lshlrev_b32_e32 v1, 4, v0
	v_add_u32_e32 v2, v0, v2
	v_bfe_i32 v0, v0, 27, 1
	v_lshrrev_b32_e32 v0, 22, v0
	v_add_u32_e32 v0, v1, v0
	v_and_b32_e32 v0, 0xfffffc00, v0
	v_sub_u32_e32 v0, v1, v0
	v_ashrrev_i32_e32 v9, 6, v2
	v_lshrrev_b32_e32 v2, 4, v0
	v_bitop3_b32 v0, v2, v0, 32 bitop3:0x6c
	v_ashrrev_i32_e32 v3, 31, v0
	v_lshrrev_b32_e32 v3, 26, v3
	v_add_u32_e32 v3, v0, v3
	v_lshlrev_b32_e32 v2, 3, v9
	v_ashrrev_i32_e32 v11, 6, v3
	v_and_b32_e32 v3, 0xc0, v3
	v_and_b32_e32 v2, 0xfffff0, v2
	v_sub_u32_e32 v0, v0, v3
	v_mov_b32_e32 v3, 1
	v_add_u32_e32 v2, v11, v2
	v_lshlrev_b32_e32 v4, 5, v9
	v_ashrrev_i16_sdwa v0, v3, sext(v0) dst_sel:DWORD dst_unused:UNUSED_PAD src0_sel:DWORD src1_sel:BYTE_0
	s_movk_i32 s2, 0xb00
	s_add_u32 s35, s70, 0x4480000
	v_and_b32_e32 v10, 32, v4
	v_bfe_i32 v12, v0, 0, 16
	v_mul_lo_u32 v0, v2, s2
	s_addc_u32 s36, s71, 0
	v_or_b32_e32 v0, v0, v10
	s_add_i32 s6, s6, s7
	s_waitcnt vmcnt(0)
	v_add_lshl_u32 v128, v0, v12, 1
	v_add_u32_e32 v0, 0x2000, v1
	s_ashr_i32 s7, s6, 31
	v_ashrrev_i32_e32 v1, 31, v0
	s_lshr_b32 s7, s7, 27
	v_lshrrev_b32_e32 v1, 22, v1
	s_add_i32 s7, s6, s7
	v_add_u32_e32 v1, v0, v1
	s_ashr_i32 s8, s7, 5
	s_and_b32 s7, s7, 0xffe0
	v_ashrrev_i32_e32 v13, 10, v1
	s_sub_i32 s6, s6, s7
	v_mul_i32_i24_e32 v1, 0x400, v13
	s_bfe_i32 s7, s6, 0x80000
	v_sub_u32_e32 v0, v0, v1
	s_bfe_u32 s7, s7, 0x3000c
	v_lshrrev_b32_e32 v1, 4, v0
	s_add_i32 s7, s6, s7
	v_bitop3_b32 v0, v1, v0, 32 bitop3:0x6c
	s_bfe_i32 s9, s7, 0x80000
	s_and_b32 s7, s7, 0xf8
	v_ashrrev_i32_e32 v2, 31, v0
	s_sub_i32 s6, s6, s7
	v_lshrrev_b32_e32 v2, 26, v2
	s_lshl_b32 s8, s8, 3
	s_sext_i32_i16 s9, s9
	s_sext_i32_i8 s6, s6
	s_ashr_i32 s3, s4, 6
	v_add_u32_e32 v2, v0, v2
	s_add_i32 s54, s8, s6
	s_ashr_i32 s6, s9, 3
	v_lshlrev_b32_e32 v1, 3, v13
	v_ashrrev_i32_e32 v14, 6, v2
	v_and_b32_e32 v2, 0xc0, v2
	s_ashr_i32 s5, s4, 8
	s_lshl_b32 s37, s3, 10
	s_lshr_b32 s14, s9, 3
	s_mul_hi_i32 s7, s6, 0x160000
	s_mul_i32 s6, s6, 0x160000
	v_and_b32_e32 v1, 0xfffff0, v1
	v_sub_u32_e32 v0, v0, v2
	s_add_u32 s26, s35, s6
	v_add_u32_e32 v1, v14, v1
	v_lshlrev_b32_e32 v4, 5, v13
	v_ashrrev_i16_sdwa v0, v3, sext(v0) dst_sel:DWORD dst_unused:UNUSED_PAD src0_sel:DWORD src1_sel:BYTE_0
	s_addc_u32 s27, s36, s7
	s_add_i32 s38, s37, 0
	v_and_b32_e32 v15, 32, v4
	v_bfe_i32 v16, v0, 0, 16
	v_mul_lo_u32 v0, v1, s2
	s_add_i32 m0, s38, 0x10000
	v_or_b32_e32 v0, v0, v15
	global_load_lds_dwordx4 v128, s[26:27]
	s_add_i32 m0, s38, 0x12000
	v_add_lshl_u32 v130, v0, v16, 1
	s_add_u32 s6, s26, 0xb0000
	global_load_lds_dwordx4 v130, s[26:27]
	s_addc_u32 s7, s27, 0
	s_add_i32 m0, s38, 0x14000
	s_mul_i32 s10, s54, 0x160000
	global_load_lds_dwordx4 v128, s[6:7]
	s_add_i32 m0, s38, 0x16000
	s_mul_hi_i32 s8, s54, 0x160000
	s_add_u32 s24, s72, s10
	s_addc_u32 s25, s73, s8
	s_add_i32 s39, s38, 0x2000
	global_load_lds_dwordx4 v130, s[6:7]
	s_mov_b32 m0, s38
	s_add_u32 s6, s24, 0xb0000
	global_load_lds_dwordx4 v128, s[24:25]
	s_mov_b32 m0, s39
	s_addc_u32 s7, s25, 0
	s_add_i32 s40, s38, 0x4000
	global_load_lds_dwordx4 v130, s[24:25]
	s_mov_b32 m0, s40
	s_add_i32 s41, s38, 0x6000
	global_load_lds_dwordx4 v128, s[6:7]
	s_mov_b32 m0, s41
	v_mov_b32_e32 v129, 0
	global_load_lds_dwordx4 v130, s[6:7]
	s_load_dwordx2 s[6:7], s[0:1], 0x110
	v_mov_b32_e32 v131, v129
	s_cmp_eq_u32 s5, 1
	s_mov_b32 s42, 0
	v_lshl_add_u64 v[6:7], s[26:27], 0, v[128:129]
	v_lshl_add_u64 v[4:5], s[26:27], 0, v[130:131]
	s_mov_b64 s[8:9], 0xb0000
	v_lshl_add_u64 v[0:1], s[24:25], 0, v[128:129]
	s_cselect_b64 s[10:11], -1, 0
	s_cmp_lg_u32 s5, 1
	v_lshl_add_u64 v[2:3], s[24:25], 0, v[130:131]
	s_setprio 1
	s_cbranch_scc1 .LBB0_1691
	s_barrier
	s_setprio 0

.LBB0_1705:
	ds_read_b128 v[148:151], v145
	ds_read_b128 v[152:155], v145 offset:1024
	ds_read_b128 v[156:159], v145 offset:2048
	ds_read_b128 v[160:163], v145 offset:3072
	ds_read_b128 v[164:167], v146
	ds_read_b128 v[168:171], v146 offset:1024
	ds_read_b128 v[172:175], v146 offset:2048
	ds_read_b128 v[176:179], v146 offset:3072
	s_add_u32 s26, s24, 0x100
	s_addc_u32 s27, s25, 0
	s_cmp_eq_u32 s58, 40
	s_cselect_b32 s31, s5, s27
	s_cselect_b32 s30, s4, s26
	s_cselect_b32 s29, s23, s57
	s_cselect_b32 s28, s22, s56
	v_lshl_add_u64 v[140:141], s[24:25], 0, v[132:133]
	s_add_i32 m0, s38, 0xc000
	ds_read_b128 v[180:183], v147
	ds_read_b128 v[184:187], v147 offset:1024
	ds_read_b128 v[188:191], v147 offset:2048
	ds_read_b128 v[192:195], v147 offset:3072
	ds_read_b128 v[196:199], v147 offset:4096
	ds_read_b128 v[200:203], v147 offset:5120
	ds_read_b128 v[204:207], v147 offset:6144
	ds_read_b128 v[208:211], v147 offset:7168
	global_load_lds_dwordx4 v[140:141], off
	v_lshl_add_u64 v[140:141], s[24:25], 0, v[134:135]
	s_add_i32 m0, s38, 0xe000
	s_nop 0
	global_load_lds_dwordx4 v[140:141], off
	s_waitcnt vmcnt(8)
	s_waitcnt lgkmcnt(0)
	s_barrier
	s_waitcnt lgkmcnt(0)
	v_mfma_f32_16x16x32_bf16 v[124:127], v[148:151], v[180:183], v[124:127]
	v_mfma_f32_16x16x32_bf16 v[120:123], v[156:159], v[180:183], v[120:123]
	v_mfma_f32_16x16x32_bf16 v[116:119], v[148:151], v[188:191], v[116:119]
	v_mfma_f32_16x16x32_bf16 v[112:115], v[156:159], v[188:191], v[112:115]
	v_mfma_f32_16x16x32_bf16 v[92:95], v[148:151], v[196:199], v[92:95]
	v_mfma_f32_16x16x32_bf16 v[88:91], v[156:159], v[196:199], v[88:91]
	v_mfma_f32_16x16x32_bf16 v[84:87], v[148:151], v[204:207], v[84:87]
	v_mfma_f32_16x16x32_bf16 v[80:83], v[156:159], v[204:207], v[80:83]
	v_mfma_f32_16x16x32_bf16 v[124:127], v[152:155], v[184:187], v[124:127]
	v_mfma_f32_16x16x32_bf16 v[120:123], v[160:163], v[184:187], v[120:123]
	v_mfma_f32_16x16x32_bf16 v[116:119], v[152:155], v[192:195], v[116:119]
	v_mfma_f32_16x16x32_bf16 v[112:115], v[160:163], v[192:195], v[112:115]
	v_mfma_f32_16x16x32_bf16 v[92:95], v[152:155], v[200:203], v[92:95]
	v_mfma_f32_16x16x32_bf16 v[88:91], v[160:163], v[200:203], v[88:91]
	v_mfma_f32_16x16x32_bf16 v[84:87], v[152:155], v[208:211], v[84:87]
	v_mfma_f32_16x16x32_bf16 v[80:83], v[160:163], v[208:211], v[80:83]
	v_mfma_f32_16x16x32_bf16 v[108:111], v[164:167], v[180:183], v[108:111]
	v_mfma_f32_16x16x32_bf16 v[104:107], v[172:175], v[180:183], v[104:107]
	v_mfma_f32_16x16x32_bf16 v[100:103], v[164:167], v[188:191], v[100:103]
	v_mfma_f32_16x16x32_bf16 v[96:99], v[172:175], v[188:191], v[96:99]
	v_mfma_f32_16x16x32_bf16 v[76:79], v[164:167], v[196:199], v[76:79]
	v_mfma_f32_16x16x32_bf16 v[72:75], v[172:175], v[196:199], v[72:75]
	v_mfma_f32_16x16x32_bf16 v[68:71], v[164:167], v[204:207], v[68:71]
	v_mfma_f32_16x16x32_bf16 v[64:67], v[172:175], v[204:207], v[64:67]
	v_mfma_f32_16x16x32_bf16 v[108:111], v[168:171], v[184:187], v[108:111]
	v_mfma_f32_16x16x32_bf16 v[104:107], v[176:179], v[184:187], v[104:107]
	v_mfma_f32_16x16x32_bf16 v[100:103], v[168:171], v[192:195], v[100:103]
	v_mfma_f32_16x16x32_bf16 v[96:99], v[176:179], v[192:195], v[96:99]
	v_mfma_f32_16x16x32_bf16 v[76:79], v[168:171], v[200:203], v[76:79]
	v_mfma_f32_16x16x32_bf16 v[72:75], v[176:179], v[200:203], v[72:75]
	v_mfma_f32_16x16x32_bf16 v[68:71], v[168:171], v[208:211], v[68:71]
	v_mfma_f32_16x16x32_bf16 v[64:67], v[176:179], v[208:211], v[64:67]
	s_barrier
	s_add_i32 s24, s46, s37
	v_lshl_add_u64 v[140:141], s[28:29], 0, v[128:129]
	s_mov_b32 m0, s24
	ds_read_b128 v[180:183], v147 offset:16384
	ds_read_b128 v[184:187], v147 offset:17408
	ds_read_b128 v[188:191], v147 offset:18432
	ds_read_b128 v[192:195], v147 offset:19456
	ds_read_b128 v[196:199], v147 offset:20480
	ds_read_b128 v[200:203], v147 offset:21504
	ds_read_b128 v[204:207], v147 offset:22528
	ds_read_b128 v[208:211], v147 offset:23552
	global_load_lds_dwordx4 v[140:141], off
	s_add_i32 m0, s24, 0x2000
	s_add_u32 s24, s28, 0xb0000
	v_lshl_add_u64 v[212:213], s[28:29], 0, v[130:131]
	s_addc_u32 s25, s29, 0
	s_add_i32 s59, s47, s37
	global_load_lds_dwordx4 v[212:213], off
	v_lshl_add_u64 v[214:215], s[24:25], 0, v[128:129]
	s_mov_b32 m0, s59
	v_lshl_add_u64 v[216:217], s[30:31], 0, v[130:131]
	global_load_lds_dwordx4 v[214:215], off
	s_add_i32 m0, s59, 0x2000
	s_nop 0
	global_load_lds_dwordx4 v130, s[24:25]
	v_lshl_add_u64 v[214:215], s[30:31], 0, v[128:129]
	s_mov_b32 m0, s38
	s_nop 0
	global_load_lds_dwordx4 v[214:215], off
	s_mov_b32 m0, s39
	s_nop 0
	global_load_lds_dwordx4 v[216:217], off
	s_waitcnt vmcnt(8)
	s_waitcnt lgkmcnt(0)
	s_barrier
	s_waitcnt lgkmcnt(0)
	v_mfma_f32_16x16x32_bf16 v[60:63], v[148:151], v[180:183], v[60:63]
	v_mfma_f32_16x16x32_bf16 v[56:59], v[156:159], v[180:183], v[56:59]
	v_mfma_f32_16x16x32_bf16 v[52:55], v[148:151], v[188:191], v[52:55]
	v_mfma_f32_16x16x32_bf16 v[48:51], v[156:159], v[188:191], v[48:51]
	v_mfma_f32_16x16x32_bf16 v[28:31], v[148:151], v[196:199], v[28:31]
	v_mfma_f32_16x16x32_bf16 v[24:27], v[156:159], v[196:199], v[24:27]
	v_mfma_f32_16x16x32_bf16 v[20:23], v[148:151], v[204:207], v[20:23]
	v_mfma_f32_16x16x32_bf16 v[16:19], v[156:159], v[204:207], v[16:19]
	v_mfma_f32_16x16x32_bf16 v[60:63], v[152:155], v[184:187], v[60:63]
	v_mfma_f32_16x16x32_bf16 v[56:59], v[160:163], v[184:187], v[56:59]
	v_mfma_f32_16x16x32_bf16 v[52:55], v[152:155], v[192:195], v[52:55]
	v_mfma_f32_16x16x32_bf16 v[48:51], v[160:163], v[192:195], v[48:51]
	v_mfma_f32_16x16x32_bf16 v[28:31], v[152:155], v[200:203], v[28:31]
	v_mfma_f32_16x16x32_bf16 v[24:27], v[160:163], v[200:203], v[24:27]
	v_mfma_f32_16x16x32_bf16 v[20:23], v[152:155], v[208:211], v[20:23]
	v_mfma_f32_16x16x32_bf16 v[16:19], v[160:163], v[208:211], v[16:19]
	v_mfma_f32_16x16x32_bf16 v[44:47], v[164:167], v[180:183], v[44:47]
	v_mfma_f32_16x16x32_bf16 v[40:43], v[172:175], v[180:183], v[40:43]
	v_mfma_f32_16x16x32_bf16 v[36:39], v[164:167], v[188:191], v[36:39]
	v_mfma_f32_16x16x32_bf16 v[32:35], v[172:175], v[188:191], v[32:35]
	v_mfma_f32_16x16x32_bf16 v[12:15], v[164:167], v[196:199], v[12:15]
	v_mfma_f32_16x16x32_bf16 v[8:11], v[172:175], v[196:199], v[8:11]
	v_mfma_f32_16x16x32_bf16 v[4:7], v[164:167], v[204:207], v[4:7]
	v_mfma_f32_16x16x32_bf16 v[0:3], v[172:175], v[204:207], v[0:3]
	v_mfma_f32_16x16x32_bf16 v[44:47], v[168:171], v[184:187], v[44:47]
	v_mfma_f32_16x16x32_bf16 v[40:43], v[176:179], v[184:187], v[40:43]
	v_mfma_f32_16x16x32_bf16 v[36:39], v[168:171], v[192:195], v[36:39]
	v_mfma_f32_16x16x32_bf16 v[32:35], v[176:179], v[192:195], v[32:35]
	v_mfma_f32_16x16x32_bf16 v[12:15], v[168:171], v[200:203], v[12:15]
	v_mfma_f32_16x16x32_bf16 v[8:11], v[176:179], v[200:203], v[8:11]
	v_mfma_f32_16x16x32_bf16 v[4:7], v[168:171], v[208:211], v[4:7]
	v_mfma_f32_16x16x32_bf16 v[0:3], v[176:179], v[208:211], v[0:3]
	s_barrier
	s_add_i32 s59, 0, 0x18000
	s_add_i32 s60, 0, 0x1c000
	v_add_u32_e32 v160, s59, v143
	v_add_u32_e32 v176, s60, v143
	ds_read_b128 v[148:151], v160
	ds_read_b128 v[152:155], v160 offset:1024
	ds_read_b128 v[156:159], v160 offset:2048
	ds_read_b128 v[160:163], v160 offset:3072
	ds_read_b128 v[164:167], v176
	ds_read_b128 v[168:171], v176 offset:1024
	ds_read_b128 v[172:175], v176 offset:2048
	ds_read_b128 v[176:179], v176 offset:3072
	s_add_u32 s24, s30, 0xb0000
	s_addc_u32 s25, s31, 0
	s_mov_b32 m0, s40
	v_lshl_add_u64 v[218:219], s[24:25], 0, v[128:129]
	ds_read_b128 v[180:183], v147 offset:32768
	ds_read_b128 v[184:187], v147 offset:33792
	ds_read_b128 v[188:191], v147 offset:34816
	ds_read_b128 v[192:195], v147 offset:35840
	ds_read_b128 v[196:199], v147 offset:36864
	ds_read_b128 v[200:203], v147 offset:37888
	ds_read_b128 v[204:207], v147 offset:38912
	ds_read_b128 v[208:211], v147 offset:39936
	global_load_lds_dwordx4 v[218:219], off
	v_lshl_add_u64 v[218:219], s[24:25], 0, v[130:131]
	s_mov_b32 m0, s41
	s_nop 0
	global_load_lds_dwordx4 v[218:219], off
	s_waitcnt vmcnt(8)
	s_waitcnt lgkmcnt(0)
	s_barrier
	s_waitcnt lgkmcnt(0)
	v_mfma_f32_16x16x32_bf16 v[124:127], v[148:151], v[180:183], v[124:127]
	v_mfma_f32_16x16x32_bf16 v[120:123], v[156:159], v[180:183], v[120:123]
	v_mfma_f32_16x16x32_bf16 v[116:119], v[148:151], v[188:191], v[116:119]
	v_mfma_f32_16x16x32_bf16 v[112:115], v[156:159], v[188:191], v[112:115]
	v_mfma_f32_16x16x32_bf16 v[92:95], v[148:151], v[196:199], v[92:95]
	v_mfma_f32_16x16x32_bf16 v[88:91], v[156:159], v[196:199], v[88:91]
	v_mfma_f32_16x16x32_bf16 v[84:87], v[148:151], v[204:207], v[84:87]
	v_mfma_f32_16x16x32_bf16 v[80:83], v[156:159], v[204:207], v[80:83]
	v_mfma_f32_16x16x32_bf16 v[124:127], v[152:155], v[184:187], v[124:127]
	v_mfma_f32_16x16x32_bf16 v[120:123], v[160:163], v[184:187], v[120:123]
	v_mfma_f32_16x16x32_bf16 v[116:119], v[152:155], v[192:195], v[116:119]
	v_mfma_f32_16x16x32_bf16 v[112:115], v[160:163], v[192:195], v[112:115]
	v_mfma_f32_16x16x32_bf16 v[92:95], v[152:155], v[200:203], v[92:95]
	v_mfma_f32_16x16x32_bf16 v[88:91], v[160:163], v[200:203], v[88:91]
	v_mfma_f32_16x16x32_bf16 v[84:87], v[152:155], v[208:211], v[84:87]
	v_mfma_f32_16x16x32_bf16 v[80:83], v[160:163], v[208:211], v[80:83]
	v_mfma_f32_16x16x32_bf16 v[108:111], v[164:167], v[180:183], v[108:111]
	v_mfma_f32_16x16x32_bf16 v[104:107], v[172:175], v[180:183], v[104:107]
	v_mfma_f32_16x16x32_bf16 v[100:103], v[164:167], v[188:191], v[100:103]
	v_mfma_f32_16x16x32_bf16 v[96:99], v[172:175], v[188:191], v[96:99]
	v_mfma_f32_16x16x32_bf16 v[76:79], v[164:167], v[196:199], v[76:79]
	v_mfma_f32_16x16x32_bf16 v[72:75], v[172:175], v[196:199], v[72:75]
	v_mfma_f32_16x16x32_bf16 v[68:71], v[164:167], v[204:207], v[68:71]
	v_mfma_f32_16x16x32_bf16 v[64:67], v[172:175], v[204:207], v[64:67]
	v_mfma_f32_16x16x32_bf16 v[108:111], v[168:171], v[184:187], v[108:111]
	v_mfma_f32_16x16x32_bf16 v[104:107], v[176:179], v[184:187], v[104:107]
	v_mfma_f32_16x16x32_bf16 v[100:103], v[168:171], v[192:195], v[100:103]
	v_mfma_f32_16x16x32_bf16 v[96:99], v[176:179], v[192:195], v[96:99]
	v_mfma_f32_16x16x32_bf16 v[76:79], v[168:171], v[200:203], v[76:79]
	v_mfma_f32_16x16x32_bf16 v[72:75], v[176:179], v[200:203], v[72:75]
	v_mfma_f32_16x16x32_bf16 v[68:71], v[168:171], v[208:211], v[68:71]
	v_mfma_f32_16x16x32_bf16 v[64:67], v[176:179], v[208:211], v[64:67]
	s_barrier
	s_add_i32 s24, s59, s37
	v_lshl_add_u64 v[140:141], v[140:141], 0, s[12:13]
	s_mov_b32 m0, s24
	ds_read_b128 v[180:183], v147 offset:49152
	ds_read_b128 v[184:187], v147 offset:50176
	ds_read_b128 v[188:191], v147 offset:51200
	ds_read_b128 v[192:195], v147 offset:52224
	ds_read_b128 v[196:199], v147 offset:53248
	ds_read_b128 v[200:203], v147 offset:54272
	ds_read_b128 v[204:207], v147 offset:55296
	ds_read_b128 v[208:211], v147 offset:56320
	global_load_lds_dwordx4 v[140:141], off
	s_add_i32 m0, s24, 0x2000
	s_add_u32 s24, s28, 0xb0080
	v_lshl_add_u64 v[140:141], v[212:213], 0, s[12:13]
	s_addc_u32 s25, s29, 0
	s_add_i32 s28, s60, s37
	global_load_lds_dwordx4 v[140:141], off
	v_lshl_add_u64 v[140:141], s[24:25], 0, v[128:129]
	s_mov_b32 m0, s28
	s_nop 0
	global_load_lds_dwordx4 v[140:141], off
	s_add_i32 m0, s28, 0x2000
	s_nop 0
	global_load_lds_dwordx4 v130, s[24:25]
	v_lshl_add_u64 v[140:141], v[214:215], 0, s[12:13]
	s_mov_b32 m0, s43
	s_nop 0
	global_load_lds_dwordx4 v[140:141], off
	v_lshl_add_u64 v[140:141], v[216:217], 0, s[12:13]
	s_mov_b32 m0, s44
	s_nop 0
	global_load_lds_dwordx4 v[140:141], off
	s_waitcnt vmcnt(8)
	s_waitcnt lgkmcnt(0)
	s_barrier
	s_waitcnt lgkmcnt(0)
	v_mfma_f32_16x16x32_bf16 v[60:63], v[148:151], v[180:183], v[60:63]
	v_mfma_f32_16x16x32_bf16 v[56:59], v[156:159], v[180:183], v[56:59]
	v_mfma_f32_16x16x32_bf16 v[52:55], v[148:151], v[188:191], v[52:55]
	v_mfma_f32_16x16x32_bf16 v[48:51], v[156:159], v[188:191], v[48:51]
	v_mfma_f32_16x16x32_bf16 v[28:31], v[148:151], v[196:199], v[28:31]
	v_mfma_f32_16x16x32_bf16 v[24:27], v[156:159], v[196:199], v[24:27]
	v_mfma_f32_16x16x32_bf16 v[20:23], v[148:151], v[204:207], v[20:23]
	v_mfma_f32_16x16x32_bf16 v[16:19], v[156:159], v[204:207], v[16:19]
	v_mfma_f32_16x16x32_bf16 v[60:63], v[152:155], v[184:187], v[60:63]
	v_mfma_f32_16x16x32_bf16 v[56:59], v[160:163], v[184:187], v[56:59]
	v_mfma_f32_16x16x32_bf16 v[52:55], v[152:155], v[192:195], v[52:55]
	v_mfma_f32_16x16x32_bf16 v[48:51], v[160:163], v[192:195], v[48:51]
	v_mfma_f32_16x16x32_bf16 v[28:31], v[152:155], v[200:203], v[28:31]
	v_mfma_f32_16x16x32_bf16 v[24:27], v[160:163], v[200:203], v[24:27]
	v_mfma_f32_16x16x32_bf16 v[20:23], v[152:155], v[208:211], v[20:23]
	v_mfma_f32_16x16x32_bf16 v[16:19], v[160:163], v[208:211], v[16:19]
	v_mfma_f32_16x16x32_bf16 v[44:47], v[164:167], v[180:183], v[44:47]
	v_mfma_f32_16x16x32_bf16 v[40:43], v[172:175], v[180:183], v[40:43]
	v_mfma_f32_16x16x32_bf16 v[36:39], v[164:167], v[188:191], v[36:39]
	v_mfma_f32_16x16x32_bf16 v[32:35], v[172:175], v[188:191], v[32:35]
	v_mfma_f32_16x16x32_bf16 v[12:15], v[164:167], v[196:199], v[12:15]
	v_mfma_f32_16x16x32_bf16 v[8:11], v[172:175], v[196:199], v[8:11]
	v_mfma_f32_16x16x32_bf16 v[4:7], v[164:167], v[204:207], v[4:7]
	v_mfma_f32_16x16x32_bf16 v[0:3], v[172:175], v[204:207], v[0:3]
	v_mfma_f32_16x16x32_bf16 v[44:47], v[168:171], v[184:187], v[44:47]
	v_mfma_f32_16x16x32_bf16 v[40:43], v[176:179], v[184:187], v[40:43]
	v_mfma_f32_16x16x32_bf16 v[36:39], v[168:171], v[192:195], v[36:39]
	v_mfma_f32_16x16x32_bf16 v[32:35], v[176:179], v[192:195], v[32:35]
	v_mfma_f32_16x16x32_bf16 v[12:15], v[168:171], v[200:203], v[12:15]
	v_mfma_f32_16x16x32_bf16 v[8:11], v[176:179], v[200:203], v[8:11]
	v_mfma_f32_16x16x32_bf16 v[4:7], v[168:171], v[208:211], v[4:7]
	v_mfma_f32_16x16x32_bf16 v[0:3], v[176:179], v[208:211], v[0:3]
	s_add_i32 s58, s58, 2
	s_add_u32 s56, s56, 0x100
	s_addc_u32 s57, s57, 0
	s_cmp_gt_u32 s58, 41
	s_mov_b64 s[24:25], s[26:27]
	s_barrier
	s_cbranch_scc0 .LBB0_1705
	s_and_b64 vcc, exec, s[14:15]
	s_cbranch_vccz .LBB0_1708
	s_barrier
